# k5 plus 72 provably redundant s_waitcnt lgkmcnt(0) removed after the pre-MFMA barrier in GEMM loops
# baseline (speedup 1.0000x reference)
; #define PG8_STAGE(bufoff, gbase, voff) do { _Pragma("unroll") for (int _i = 0; _i < 2; ++_i) \
;         __builtin_amdgcn_global_load_lds((const unsigned*)((const char*)(gbase) + (voff)[_i]), (PG8_LAS unsigned*)(lds + (bufoff) + ldsw + _i * 8192), 16, 0, 0); } while (0)
; #define PG8_LDA(dst, b, h) do { _Pragma("unroll") for (int m = 0; m < 4; ++m) _Pragma("unroll") for (int k = 0; k < 2; ++k) dst[m][k] = *(const PG8_LAS bf16x8*)(lds + PG8_SA(b, h) + aoff + m * 2048 + k * 1024); } while (0)
; #define PG8_LDB(dst, b, h) do { _Pragma("unroll") for (int n = 0; n < 2; ++n) _Pragma("unroll") for (int k = 0; k < 2; ++k) dst[n][k] = *(const PG8_LAS bf16x8*)(lds + PG8_SB(b, h) + boff + n * 2048 + k * 1024); } while (0)
; #define PG8_MMA(ai, bj, At, Bt) do { __builtin_amdgcn_s_setprio(1); _Pragma("unroll") for (int m = 0; m < 4; ++m) _Pragma("unroll") for (int n = 0; n < 2; ++n) _Pragma("unroll") for (int k = 0; k < 2; ++k) \
;         acc[ai][bj][m][n] = __builtin_amdgcn_mfma_f32_16x16x32_bf16(Bt[n][k], At[m][k], acc[ai][bj][m][n], 0, 0, 0); __builtin_amdgcn_s_setprio(0); } while (0)
; template <class Epi, class Sched, bool ALIGN_EPI = false, bool SP2 = false>
; __device__ __forceinline__ void gemm_phase(PG8_LAS unsigned char* lds, const Gemm g, const Sched& S, const Epi& E, const int wv0) {
;     ...
;             if constexpr (SP2) {
;             PG8_LDB(B0, 0, 0); PG8_LDB(B1, 0, 1); PG8_SCHED; PG8_LDA(At, 0, 0); PG8_STAGE(PG8_SA(1, 1), a1 + hstepA, voffA);
;             PG8_WAIT_V(8); PG8_WAIT_L(0); PG8_BAR; PG8_MMA(0, 0, At, B0); PG8_MMA(0, 1, At, B1); PG8_BAR; PG8_SCHED;
;             PG8_LDA(At, 0, 1); PG8_STAGE(PG8_SB(0, 0), b2, voffB); PG8_STAGE(PG8_SB(0, 1), b2 + hstepB, voffB); PG8_STAGE(PG8_SA(0, 0), a2, voffA);
;             PG8_WAIT_V(8); PG8_WAIT_L(0); PG8_BAR; PG8_MMA(1, 0, At, B0); PG8_MMA(1, 1, At, B1); PG8_BAR; PG8_SCHED;
;             PG8_LDB(B0, 1, 0); PG8_LDB(B1, 1, 1); PG8_SCHED; PG8_LDA(At, 1, 0); PG8_STAGE(PG8_SA(0, 1), a2 + hstepA, voffA);
;             PG8_WAIT_V(8); PG8_WAIT_L(0); PG8_BAR; PG8_MMA(0, 0, At, B0); PG8_MMA(0, 1, At, B1); PG8_BAR; PG8_SCHED;
;             PG8_LDA(At, 1, 1); PG8_STAGE(PG8_SB(1, 0), b3, voffB); PG8_STAGE(PG8_SB(1, 1), b3 + hstepB, voffB); PG8_STAGE(PG8_SA(1, 0), a3, voffA);
;             PG8_WAIT_V(8); PG8_WAIT_L(0); PG8_BAR; PG8_MMA(1, 0, At, B0); PG8_MMA(1, 1, At, B1); PG8_BAR; PG8_SCHED;
.LBB0_82:
	ds_read_b128 v[156:159], v152
	ds_read_b128 v[160:163], v152 offset:1024
	ds_read_b128 v[164:167], v152 offset:2048
	ds_read_b128 v[168:171], v152 offset:3072
	ds_read_b128 v[172:175], v153
	ds_read_b128 v[176:179], v153 offset:1024
	ds_read_b128 v[180:183], v153 offset:2048
	ds_read_b128 v[184:187], v153 offset:3072
	s_add_u32 s34, s30, 0xfff80080
	s_addc_u32 s35, s31, -1
	s_cmp_eq_u32 s38, 28
	s_cselect_b32 s37, s25, s35
	s_cselect_b32 s36, s24, s34
	s_cselect_b32 s35, s27, s23
	s_cselect_b32 s34, s26, s21
	v_lshl_add_u64 v[146:147], s[30:31], 0, v[140:141]
	s_add_i32 m0, s29, 0xc000
	ds_read_b128 v[188:191], v154
	ds_read_b128 v[192:195], v154 offset:1024
	ds_read_b128 v[196:199], v154 offset:2048
	ds_read_b128 v[200:203], v154 offset:3072
	ds_read_b128 v[206:209], v154 offset:4096
	ds_read_b128 v[210:213], v154 offset:5120
	ds_read_b128 v[214:217], v154 offset:6144
	ds_read_b128 v[218:221], v154 offset:7168
	global_load_lds_dwordx4 v[146:147], off
	v_lshl_add_u64 v[146:147], s[30:31], 0, v[138:139]
	s_add_i32 m0, s29, 0xe000
	s_nop 0
	global_load_lds_dwordx4 v[146:147], off
	s_waitcnt vmcnt(8)
	s_waitcnt lgkmcnt(0)
	s_barrier
	s_setprio 1
	v_mfma_f32_16x16x32_bf16 v[124:127], v[156:159], v[188:191], v[124:127]
	v_mfma_f32_16x16x32_bf16 v[120:123], v[164:167], v[188:191], v[120:123]
	v_mfma_f32_16x16x32_bf16 v[116:119], v[156:159], v[196:199], v[116:119]
	v_mfma_f32_16x16x32_bf16 v[108:111], v[164:167], v[196:199], v[108:111]
	v_mfma_f32_16x16x32_bf16 v[100:103], v[156:159], v[206:209], v[100:103]
	v_mfma_f32_16x16x32_bf16 v[92:95], v[164:167], v[206:209], v[92:95]
	v_mfma_f32_16x16x32_bf16 v[84:87], v[156:159], v[214:217], v[84:87]
	v_mfma_f32_16x16x32_bf16 v[76:79], v[164:167], v[214:217], v[76:79]
	v_mfma_f32_16x16x32_bf16 v[124:127], v[160:163], v[192:195], v[124:127]
	v_mfma_f32_16x16x32_bf16 v[120:123], v[168:171], v[192:195], v[120:123]
	v_mfma_f32_16x16x32_bf16 v[116:119], v[160:163], v[200:203], v[116:119]
	v_mfma_f32_16x16x32_bf16 v[108:111], v[168:171], v[200:203], v[108:111]
	v_mfma_f32_16x16x32_bf16 v[100:103], v[160:163], v[210:213], v[100:103]
	v_mfma_f32_16x16x32_bf16 v[92:95], v[168:171], v[210:213], v[92:95]
	v_mfma_f32_16x16x32_bf16 v[84:87], v[160:163], v[218:221], v[84:87]
	v_mfma_f32_16x16x32_bf16 v[76:79], v[168:171], v[218:221], v[76:79]
	s_setprio 0
	s_setprio 1
	v_mfma_f32_16x16x32_bf16 v[112:115], v[172:175], v[188:191], v[112:115]
	v_mfma_f32_16x16x32_bf16 v[104:107], v[180:183], v[188:191], v[104:107]
	v_mfma_f32_16x16x32_bf16 v[96:99], v[172:175], v[196:199], v[96:99]
	v_mfma_f32_16x16x32_bf16 v[88:91], v[180:183], v[196:199], v[88:91]
	v_mfma_f32_16x16x32_bf16 v[80:83], v[172:175], v[206:209], v[80:83]
	v_mfma_f32_16x16x32_bf16 v[72:75], v[180:183], v[206:209], v[72:75]
	v_mfma_f32_16x16x32_bf16 v[68:71], v[172:175], v[214:217], v[68:71]
	v_mfma_f32_16x16x32_bf16 v[64:67], v[180:183], v[214:217], v[64:67]
	v_mfma_f32_16x16x32_bf16 v[112:115], v[176:179], v[192:195], v[112:115]
	v_mfma_f32_16x16x32_bf16 v[104:107], v[184:187], v[192:195], v[104:107]
	v_mfma_f32_16x16x32_bf16 v[96:99], v[176:179], v[200:203], v[96:99]
	v_mfma_f32_16x16x32_bf16 v[88:91], v[184:187], v[200:203], v[88:91]
	v_mfma_f32_16x16x32_bf16 v[80:83], v[176:179], v[210:213], v[80:83]
	v_mfma_f32_16x16x32_bf16 v[72:75], v[184:187], v[210:213], v[72:75]
	v_mfma_f32_16x16x32_bf16 v[68:71], v[176:179], v[218:221], v[68:71]
	v_mfma_f32_16x16x32_bf16 v[64:67], v[184:187], v[218:221], v[64:67]
	s_setprio 0
	s_barrier
	s_add_i32 s39, s62, s47
	v_lshl_add_u64 v[146:147], s[34:35], 0, v[132:133]
	s_mov_b32 m0, s39
	ds_read_b128 v[188:191], v154 offset:16384
	ds_read_b128 v[192:195], v154 offset:17408
	ds_read_b128 v[196:199], v154 offset:18432
	ds_read_b128 v[200:203], v154 offset:19456
	ds_read_b128 v[206:209], v154 offset:20480
	ds_read_b128 v[210:213], v154 offset:21504
	ds_read_b128 v[214:217], v154 offset:22528
	ds_read_b128 v[218:221], v154 offset:23552
	global_load_lds_dwordx4 v[146:147], off
	s_add_i32 m0, s39, 0x2000
	s_add_u32 s68, s34, 0x80000
	v_lshl_add_u64 v[222:223], s[34:35], 0, v[128:129]
	s_addc_u32 s69, s35, 0
	s_add_i32 s39, s63, s47
	global_load_lds_dwordx4 v[222:223], off
	v_lshl_add_u64 v[224:225], s[68:69], 0, v[132:133]
	s_mov_b32 m0, s39
	v_lshl_add_u64 v[226:227], s[36:37], 0, v[130:131]
	global_load_lds_dwordx4 v[224:225], off
	v_lshl_add_u64 v[224:225], s[68:69], 0, v[128:129]
	s_add_i32 m0, s39, 0x2000
	s_nop 0
	global_load_lds_dwordx4 v[224:225], off
	v_lshl_add_u64 v[224:225], s[36:37], 0, v[134:135]
	s_mov_b32 m0, s29
	s_nop 0
	global_load_lds_dwordx4 v[224:225], off
	s_mov_b32 m0, s49
	s_nop 0
	global_load_lds_dwordx4 v[226:227], off
	s_waitcnt vmcnt(8)
	s_waitcnt lgkmcnt(0)
	s_barrier
; #define PG8_STAGE(bufoff, gbase, voff) do { _Pragma("unroll") for (int _i = 0; _i < 2; ++_i) \
;         __builtin_amdgcn_global_load_lds((const unsigned*)((const char*)(gbase) + (voff)[_i]), (PG8_LAS unsigned*)(lds + (bufoff) + ldsw + _i * 8192), 16, 0, 0); } while (0)
; #define PG8_LDA(dst, b, h) do { _Pragma("unroll") for (int m = 0; m < 4; ++m) _Pragma("unroll") for (int k = 0; k < 2; ++k) dst[m][k] = *(const PG8_LAS bf16x8*)(lds + PG8_SA(b, h) + aoff + m * 2048 + k * 1024); } while (0)
; #define PG8_LDB(dst, b, h) do { _Pragma("unroll") for (int n = 0; n < 2; ++n) _Pragma("unroll") for (int k = 0; k < 2; ++k) dst[n][k] = *(const PG8_LAS bf16x8*)(lds + PG8_SB(b, h) + boff + n * 2048 + k * 1024); } while (0)
; #define PG8_MMA(ai, bj, At, Bt) do { __builtin_amdgcn_s_setprio(1); _Pragma("unroll") for (int m = 0; m < 4; ++m) _Pragma("unroll") for (int n = 0; n < 2; ++n) _Pragma("unroll") for (int k = 0; k < 2; ++k) \
;         acc[ai][bj][m][n] = __builtin_amdgcn_mfma_f32_16x16x32_bf16(Bt[n][k], At[m][k], acc[ai][bj][m][n], 0, 0, 0); __builtin_amdgcn_s_setprio(0); } while (0)
; #define PG8_WAIT_V(n) asm volatile("s_waitcnt vmcnt(" #n ")" ::: "memory")
; #define PG8_WAIT_L(n) asm volatile("s_waitcnt lgkmcnt(" #n ")" ::: "memory")
; template <class Epi, class Sched, bool ALIGN_EPI = false, bool SP2 = false>
; __device__ __forceinline__ void gemm_phase(PG8_LAS unsigned char* lds, const Gemm g, const Sched& S, const Epi& E, const int wv0) {
;     ...
;             PG8_WAIT_V(8); PG8_WAIT_L(0); PG8_BAR; PG8_MMA(0, 0, At, B0); PG8_MMA(0, 1, At, B1); PG8_BAR; PG8_SCHED;
;             PG8_LDA(At, 0, 1); PG8_STAGE(PG8_SB(0, 0), b2, voffB); PG8_STAGE(PG8_SB(0, 1), b2 + hstepB, voffB); PG8_STAGE(PG8_SA(0, 0), a2, voffA);
;             PG8_WAIT_V(8); PG8_WAIT_L(0); PG8_BAR; PG8_MMA(1, 0, At, B0); PG8_MMA(1, 1, At, B1); PG8_BAR; PG8_SCHED;
;             PG8_LDB(B0, 1, 0); PG8_LDB(B1, 1, 1); PG8_SCHED; PG8_LDA(At, 1, 0); PG8_STAGE(PG8_SA(0, 1), a2 + hstepA, voffA);
;             PG8_WAIT_V(8); PG8_WAIT_L(0); PG8_BAR; PG8_MMA(0, 0, At, B0); PG8_MMA(0, 1, At, B1); PG8_BAR; PG8_SCHED;
;             PG8_LDA(At, 1, 1); PG8_STAGE(PG8_SB(1, 0), b3, voffB); PG8_STAGE(PG8_SB(1, 1), b3 + hstepB, voffB); PG8_STAGE(PG8_SA(1, 0), a3, voffA);
;             PG8_WAIT_V(8); PG8_WAIT_L(0); PG8_BAR; PG8_MMA(1, 0, At, B0); PG8_MMA(1, 1, At, B1); PG8_BAR; PG8_SCHED;
	s_setprio 1
	v_mfma_f32_16x16x32_bf16 v[60:63], v[156:159], v[188:191], v[60:63]
	v_mfma_f32_16x16x32_bf16 v[56:59], v[164:167], v[188:191], v[56:59]
	v_mfma_f32_16x16x32_bf16 v[52:55], v[156:159], v[196:199], v[52:55]
	v_mfma_f32_16x16x32_bf16 v[44:47], v[164:167], v[196:199], v[44:47]
	v_mfma_f32_16x16x32_bf16 v[36:39], v[156:159], v[206:209], v[36:39]
	v_mfma_f32_16x16x32_bf16 v[28:31], v[164:167], v[206:209], v[28:31]
	v_mfma_f32_16x16x32_bf16 v[20:23], v[156:159], v[214:217], v[20:23]
	v_mfma_f32_16x16x32_bf16 v[12:15], v[164:167], v[214:217], v[12:15]
	v_mfma_f32_16x16x32_bf16 v[60:63], v[160:163], v[192:195], v[60:63]
	v_mfma_f32_16x16x32_bf16 v[56:59], v[168:171], v[192:195], v[56:59]
	v_mfma_f32_16x16x32_bf16 v[52:55], v[160:163], v[200:203], v[52:55]
	v_mfma_f32_16x16x32_bf16 v[44:47], v[168:171], v[200:203], v[44:47]
	v_mfma_f32_16x16x32_bf16 v[36:39], v[160:163], v[210:213], v[36:39]
	v_mfma_f32_16x16x32_bf16 v[28:31], v[168:171], v[210:213], v[28:31]
	v_mfma_f32_16x16x32_bf16 v[20:23], v[160:163], v[218:221], v[20:23]
	v_mfma_f32_16x16x32_bf16 v[12:15], v[168:171], v[218:221], v[12:15]
	s_setprio 0
	s_setprio 1
	v_mfma_f32_16x16x32_bf16 v[48:51], v[172:175], v[188:191], v[48:51]
	v_mfma_f32_16x16x32_bf16 v[40:43], v[180:183], v[188:191], v[40:43]
	v_mfma_f32_16x16x32_bf16 v[32:35], v[172:175], v[196:199], v[32:35]
	v_mfma_f32_16x16x32_bf16 v[24:27], v[180:183], v[196:199], v[24:27]
	v_mfma_f32_16x16x32_bf16 v[16:19], v[172:175], v[206:209], v[16:19]
	v_mfma_f32_16x16x32_bf16 v[8:11], v[180:183], v[206:209], v[8:11]
	v_mfma_f32_16x16x32_bf16 v[4:7], v[172:175], v[214:217], v[4:7]
	v_mfma_f32_16x16x32_bf16 v[0:3], v[180:183], v[214:217], v[0:3]
	v_mfma_f32_16x16x32_bf16 v[48:51], v[176:179], v[192:195], v[48:51]
	v_mfma_f32_16x16x32_bf16 v[40:43], v[184:187], v[192:195], v[40:43]
	v_mfma_f32_16x16x32_bf16 v[32:35], v[176:179], v[200:203], v[32:35]
	v_mfma_f32_16x16x32_bf16 v[24:27], v[184:187], v[200:203], v[24:27]
	v_mfma_f32_16x16x32_bf16 v[16:19], v[176:179], v[210:213], v[16:19]
	v_mfma_f32_16x16x32_bf16 v[8:11], v[184:187], v[210:213], v[8:11]
	v_mfma_f32_16x16x32_bf16 v[4:7], v[176:179], v[218:221], v[4:7]
	v_mfma_f32_16x16x32_bf16 v[0:3], v[184:187], v[218:221], v[0:3]
	s_setprio 0
	s_barrier
	s_add_i32 s39, 0, 0x18000
	v_add_u32_e32 v155, s39, v150
	s_add_i32 s68, 0, 0x1c000
	ds_read_b128 v[156:159], v155
	ds_read_b128 v[160:163], v155 offset:1024
	ds_read_b128 v[164:167], v155 offset:2048
	ds_read_b128 v[168:171], v155 offset:3072
	v_add_u32_e32 v155, s68, v150
	ds_read_b128 v[172:175], v155
	ds_read_b128 v[176:179], v155 offset:1024
	ds_read_b128 v[180:183], v155 offset:2048
	ds_read_b128 v[184:187], v155 offset:3072
	s_add_u32 s36, s36, 0x80000
	s_addc_u32 s37, s37, 0
	s_mov_b32 m0, s50
	v_lshl_add_u64 v[228:229], s[36:37], 0, v[134:135]
	ds_read_b128 v[188:191], v154 offset:32768
	ds_read_b128 v[192:195], v154 offset:33792
	ds_read_b128 v[196:199], v154 offset:34816
	ds_read_b128 v[200:203], v154 offset:35840
	ds_read_b128 v[206:209], v154 offset:36864
	ds_read_b128 v[210:213], v154 offset:37888
	ds_read_b128 v[214:217], v154 offset:38912
	ds_read_b128 v[218:221], v154 offset:39936
	global_load_lds_dwordx4 v[228:229], off
	v_lshl_add_u64 v[228:229], s[36:37], 0, v[130:131]
	s_mov_b32 m0, s51
	s_nop 0
	global_load_lds_dwordx4 v[228:229], off
	s_waitcnt vmcnt(8)
	s_waitcnt lgkmcnt(0)
	s_barrier
	s_setprio 1
	v_mfma_f32_16x16x32_bf16 v[124:127], v[156:159], v[188:191], v[124:127]
	v_mfma_f32_16x16x32_bf16 v[120:123], v[164:167], v[188:191], v[120:123]
	v_mfma_f32_16x16x32_bf16 v[116:119], v[156:159], v[196:199], v[116:119]
	v_mfma_f32_16x16x32_bf16 v[108:111], v[164:167], v[196:199], v[108:111]
	v_mfma_f32_16x16x32_bf16 v[100:103], v[156:159], v[206:209], v[100:103]
	v_mfma_f32_16x16x32_bf16 v[92:95], v[164:167], v[206:209], v[92:95]
	v_mfma_f32_16x16x32_bf16 v[84:87], v[156:159], v[214:217], v[84:87]
	v_mfma_f32_16x16x32_bf16 v[76:79], v[164:167], v[214:217], v[76:79]
	v_mfma_f32_16x16x32_bf16 v[124:127], v[160:163], v[192:195], v[124:127]
	v_mfma_f32_16x16x32_bf16 v[120:123], v[168:171], v[192:195], v[120:123]
	v_mfma_f32_16x16x32_bf16 v[116:119], v[160:163], v[200:203], v[116:119]
	v_mfma_f32_16x16x32_bf16 v[108:111], v[168:171], v[200:203], v[108:111]
	v_mfma_f32_16x16x32_bf16 v[100:103], v[160:163], v[210:213], v[100:103]
	v_mfma_f32_16x16x32_bf16 v[92:95], v[168:171], v[210:213], v[92:95]
	v_mfma_f32_16x16x32_bf16 v[84:87], v[160:163], v[218:221], v[84:87]
	v_mfma_f32_16x16x32_bf16 v[76:79], v[168:171], v[218:221], v[76:79]
	s_setprio 0
	s_setprio 1
	v_mfma_f32_16x16x32_bf16 v[112:115], v[172:175], v[188:191], v[112:115]
	v_mfma_f32_16x16x32_bf16 v[104:107], v[180:183], v[188:191], v[104:107]
	v_mfma_f32_16x16x32_bf16 v[96:99], v[172:175], v[196:199], v[96:99]
	v_mfma_f32_16x16x32_bf16 v[88:91], v[180:183], v[196:199], v[88:91]
	v_mfma_f32_16x16x32_bf16 v[80:83], v[172:175], v[206:209], v[80:83]
	v_mfma_f32_16x16x32_bf16 v[72:75], v[180:183], v[206:209], v[72:75]
	v_mfma_f32_16x16x32_bf16 v[68:71], v[172:175], v[214:217], v[68:71]
	v_mfma_f32_16x16x32_bf16 v[64:67], v[180:183], v[214:217], v[64:67]
	v_mfma_f32_16x16x32_bf16 v[112:115], v[176:179], v[192:195], v[112:115]
	v_mfma_f32_16x16x32_bf16 v[104:107], v[184:187], v[192:195], v[104:107]
	v_mfma_f32_16x16x32_bf16 v[96:99], v[176:179], v[200:203], v[96:99]
	v_mfma_f32_16x16x32_bf16 v[88:91], v[184:187], v[200:203], v[88:91]
	v_mfma_f32_16x16x32_bf16 v[80:83], v[176:179], v[210:213], v[80:83]
	v_mfma_f32_16x16x32_bf16 v[72:75], v[184:187], v[210:213], v[72:75]
	v_mfma_f32_16x16x32_bf16 v[68:71], v[176:179], v[218:221], v[68:71]
	v_mfma_f32_16x16x32_bf16 v[64:67], v[184:187], v[218:221], v[64:67]
	s_setprio 0
	s_barrier
; #define PG8_STAGE(bufoff, gbase, voff) do { _Pragma("unroll") for (int _i = 0; _i < 2; ++_i) \
;         __builtin_amdgcn_global_load_lds((const unsigned*)((const char*)(gbase) + (voff)[_i]), (PG8_LAS unsigned*)(lds + (bufoff) + ldsw + _i * 8192), 16, 0, 0); } while (0)
; #define PG8_LDA(dst, b, h) do { _Pragma("unroll") for (int m = 0; m < 4; ++m) _Pragma("unroll") for (int k = 0; k < 2; ++k) dst[m][k] = *(const PG8_LAS bf16x8*)(lds + PG8_SA(b, h) + aoff + m * 2048 + k * 1024); } while (0)
; #define PG8_MMA(ai, bj, At, Bt) do { __builtin_amdgcn_s_setprio(1); _Pragma("unroll") for (int m = 0; m < 4; ++m) _Pragma("unroll") for (int n = 0; n < 2; ++n) _Pragma("unroll") for (int k = 0; k < 2; ++k) \
;         acc[ai][bj][m][n] = __builtin_amdgcn_mfma_f32_16x16x32_bf16(Bt[n][k], At[m][k], acc[ai][bj][m][n], 0, 0, 0); __builtin_amdgcn_s_setprio(0); } while (0)
; #define PG8_WAIT_V(n) asm volatile("s_waitcnt vmcnt(" #n ")" ::: "memory")
; #define PG8_WAIT_L(n) asm volatile("s_waitcnt lgkmcnt(" #n ")" ::: "memory")
; #define PG8_BAR __builtin_amdgcn_s_barrier()
; #define PG8_SCHED __builtin_amdgcn_sched_barrier(0)
; template <class Epi, class Sched, bool ALIGN_EPI = false, bool SP2 = false>
; __device__ __forceinline__ void gemm_phase(PG8_LAS unsigned char* lds, const Gemm g, const Sched& S, const Epi& E, const int wv0) {
;     ...
;         for (int t = 0; t < nt; t += 2) {
;     ...
;             PG8_WAIT_V(8); PG8_WAIT_L(0); PG8_BAR; PG8_MMA(0, 0, At, B0); PG8_MMA(0, 1, At, B1); PG8_BAR; PG8_SCHED;
;             PG8_LDA(At, 1, 1); PG8_STAGE(PG8_SB(1, 0), b3, voffB); PG8_STAGE(PG8_SB(1, 1), b3 + hstepB, voffB); PG8_STAGE(PG8_SA(1, 0), a3, voffA);
;             PG8_WAIT_V(8); PG8_WAIT_L(0); PG8_BAR; PG8_MMA(1, 0, At, B0); PG8_MMA(1, 1, At, B1); PG8_BAR; PG8_SCHED;
	s_add_i32 s36, s39, s47
	v_lshl_add_u64 v[146:147], v[146:147], 0, s[14:15]
	s_mov_b32 m0, s36
	ds_read_b128 v[188:191], v154 offset:49152
	ds_read_b128 v[192:195], v154 offset:50176
	ds_read_b128 v[196:199], v154 offset:51200
	ds_read_b128 v[200:203], v154 offset:52224
	ds_read_b128 v[206:209], v154 offset:53248
	ds_read_b128 v[210:213], v154 offset:54272
	ds_read_b128 v[214:217], v154 offset:55296
	ds_read_b128 v[218:221], v154 offset:56320
	global_load_lds_dwordx4 v[146:147], off
	s_add_i32 m0, s36, 0x2000
	s_add_u32 s34, s34, 0x80080
	v_lshl_add_u64 v[146:147], v[222:223], 0, s[14:15]
	s_addc_u32 s35, s35, 0
	s_add_i32 s36, s68, s47
	global_load_lds_dwordx4 v[146:147], off
	v_lshl_add_u64 v[146:147], s[34:35], 0, v[132:133]
	s_mov_b32 m0, s36
	s_nop 0
	global_load_lds_dwordx4 v[146:147], off
	v_lshl_add_u64 v[146:147], s[34:35], 0, v[128:129]
	s_add_i32 m0, s36, 0x2000
	s_nop 0
	global_load_lds_dwordx4 v[146:147], off
	v_lshl_add_u64 v[146:147], v[224:225], 0, s[14:15]
	s_mov_b32 m0, s58
	s_nop 0
	global_load_lds_dwordx4 v[146:147], off
	v_lshl_add_u64 v[146:147], v[226:227], 0, s[14:15]
	s_mov_b32 m0, s59
	s_nop 0
	global_load_lds_dwordx4 v[146:147], off
	s_waitcnt vmcnt(8)
	s_waitcnt lgkmcnt(0)
	s_barrier
	s_setprio 1
	v_mfma_f32_16x16x32_bf16 v[60:63], v[156:159], v[188:191], v[60:63]
	v_mfma_f32_16x16x32_bf16 v[56:59], v[164:167], v[188:191], v[56:59]
	v_mfma_f32_16x16x32_bf16 v[52:55], v[156:159], v[196:199], v[52:55]
	v_mfma_f32_16x16x32_bf16 v[44:47], v[164:167], v[196:199], v[44:47]
	v_mfma_f32_16x16x32_bf16 v[36:39], v[156:159], v[206:209], v[36:39]
	v_mfma_f32_16x16x32_bf16 v[28:31], v[164:167], v[206:209], v[28:31]
	v_mfma_f32_16x16x32_bf16 v[20:23], v[156:159], v[214:217], v[20:23]
	v_mfma_f32_16x16x32_bf16 v[12:15], v[164:167], v[214:217], v[12:15]
	v_mfma_f32_16x16x32_bf16 v[60:63], v[160:163], v[192:195], v[60:63]
	v_mfma_f32_16x16x32_bf16 v[56:59], v[168:171], v[192:195], v[56:59]
	v_mfma_f32_16x16x32_bf16 v[52:55], v[160:163], v[200:203], v[52:55]
	v_mfma_f32_16x16x32_bf16 v[44:47], v[168:171], v[200:203], v[44:47]
	v_mfma_f32_16x16x32_bf16 v[36:39], v[160:163], v[210:213], v[36:39]
	v_mfma_f32_16x16x32_bf16 v[28:31], v[168:171], v[210:213], v[28:31]
	v_mfma_f32_16x16x32_bf16 v[20:23], v[160:163], v[218:221], v[20:23]
	v_mfma_f32_16x16x32_bf16 v[12:15], v[168:171], v[218:221], v[12:15]
	s_setprio 0
	s_setprio 1
	v_mfma_f32_16x16x32_bf16 v[48:51], v[172:175], v[188:191], v[48:51]
	v_mfma_f32_16x16x32_bf16 v[40:43], v[180:183], v[188:191], v[40:43]
	v_mfma_f32_16x16x32_bf16 v[32:35], v[172:175], v[196:199], v[32:35]
	v_mfma_f32_16x16x32_bf16 v[24:27], v[180:183], v[196:199], v[24:27]
	v_mfma_f32_16x16x32_bf16 v[16:19], v[172:175], v[206:209], v[16:19]
	v_mfma_f32_16x16x32_bf16 v[8:11], v[180:183], v[206:209], v[8:11]
	v_mfma_f32_16x16x32_bf16 v[4:7], v[172:175], v[214:217], v[4:7]
	v_mfma_f32_16x16x32_bf16 v[0:3], v[180:183], v[214:217], v[0:3]
	v_mfma_f32_16x16x32_bf16 v[48:51], v[176:179], v[192:195], v[48:51]
	v_mfma_f32_16x16x32_bf16 v[40:43], v[184:187], v[192:195], v[40:43]
	v_mfma_f32_16x16x32_bf16 v[32:35], v[176:179], v[200:203], v[32:35]
	v_mfma_f32_16x16x32_bf16 v[24:27], v[184:187], v[200:203], v[24:27]
	v_mfma_f32_16x16x32_bf16 v[16:19], v[176:179], v[210:213], v[16:19]
	v_mfma_f32_16x16x32_bf16 v[8:11], v[184:187], v[210:213], v[8:11]
	v_mfma_f32_16x16x32_bf16 v[4:7], v[176:179], v[218:221], v[4:7]
	v_mfma_f32_16x16x32_bf16 v[0:3], v[184:187], v[218:221], v[0:3]
	s_setprio 0
	s_barrier
	s_add_i32 s38, s38, 2
	s_add_u32 s21, s21, 0x100
	s_addc_u32 s23, s23, 0
	s_add_u32 s30, s30, 0x100
	s_addc_u32 s31, s31, 0
	s_cmp_gt_u32 s38, 29
	s_cbranch_scc0 .LBB0_82
	s_and_b64 vcc, exec, s[18:19]
	s_cbranch_vccz .LBB0_85
	s_barrier

; #define PG8_STAGE(bufoff, gbase, voff) do { _Pragma("unroll") for (int _i = 0; _i < 2; ++_i) \
;         __builtin_amdgcn_global_load_lds((const unsigned*)((const char*)(gbase) + (voff)[_i]), (PG8_LAS unsigned*)(lds + (bufoff) + ldsw + _i * 8192), 16, 0, 0); } while (0)
; #define PG8_LDA(dst, b, h) do { _Pragma("unroll") for (int m = 0; m < 4; ++m) _Pragma("unroll") for (int k = 0; k < 2; ++k) dst[m][k] = *(const PG8_LAS bf16x8*)(lds + PG8_SA(b, h) + aoff + m * 2048 + k * 1024); } while (0)
; #define PG8_LDB(dst, b, h) do { _Pragma("unroll") for (int n = 0; n < 2; ++n) _Pragma("unroll") for (int k = 0; k < 2; ++k) dst[n][k] = *(const PG8_LAS bf16x8*)(lds + PG8_SB(b, h) + boff + n * 2048 + k * 1024); } while (0)
; #define PG8_MMA(ai, bj, At, Bt) do { __builtin_amdgcn_s_setprio(1); _Pragma("unroll") for (int m = 0; m < 4; ++m) _Pragma("unroll") for (int n = 0; n < 2; ++n) _Pragma("unroll") for (int k = 0; k < 2; ++k) \
;         acc[ai][bj][m][n] = __builtin_amdgcn_mfma_f32_16x16x32_bf16(Bt[n][k], At[m][k], acc[ai][bj][m][n], 0, 0, 0); __builtin_amdgcn_s_setprio(0); } while (0)
; #define PG8_WAIT_V(n) asm volatile("s_waitcnt vmcnt(" #n ")" ::: "memory")
; #define PG8_WAIT_L(n) asm volatile("s_waitcnt lgkmcnt(" #n ")" ::: "memory")
; #define PG8_BAR __builtin_amdgcn_s_barrier()
; #define PG8_SCHED __builtin_amdgcn_sched_barrier(0)
; template <class Epi, class Sched, bool ALIGN_EPI = false, bool SP2 = false>
; __device__ __forceinline__ void gemm_phase(PG8_LAS unsigned char* lds, const Gemm g, const Sched& S, const Epi& E, const int wv0) {
;     ...
;     if constexpr (SP2) {
;         PG8_STAGE(PG8_SB(0, 0), cB, voffB); PG8_STAGE(PG8_SB(0, 1), cB + hstepB, voffB); PG8_STAGE(PG8_SA(0, 0), cA, voffA); PG8_STAGE(PG8_SA(0, 1), cA + hstepA, voffA);
;         if (wr == 1) PG8_BAR;
;         PG8_WAIT_V(2); PG8_BAR;
;         PG8_STAGE(PG8_SB(1, 0), cB + kstep, voffB); PG8_STAGE(PG8_SA(1, 0), cA + kstep, voffA); PG8_STAGE(PG8_SB(1, 1), cB + hstepB + kstep, voffB);
;         PG8_WAIT_V(6); PG8_BAR;
;     ...
;             if constexpr (SP2) {
;             PG8_LDB(B0, 0, 0); PG8_LDB(B1, 0, 1); PG8_SCHED; PG8_LDA(At, 0, 0); PG8_STAGE(PG8_SA(1, 1), a1 + hstepA, voffA);
;             PG8_WAIT_V(8); PG8_WAIT_L(0); PG8_BAR; PG8_MMA(0, 0, At, B0); PG8_MMA(0, 1, At, B1); PG8_BAR; PG8_SCHED;
.LBB0_358:
	s_add_i32 s53, s36, s66
	s_and_b32 s51, s47, 3
	v_lshl_add_u64 v[2:3], v[26:27], 0, s[8:9]
	s_mov_b32 m0, s53
	s_add_i32 s55, s53, 0x2000
	s_lshl_b32 s63, s50, 13
	s_lshl_b32 s47, s51, 12
	s_waitcnt vmcnt(2)
	s_barrier
	global_load_lds_dwordx4 v[2:3], off
	v_lshl_add_u64 v[4:5], v[28:29], 0, s[8:9]
	s_mov_b32 m0, s55
	s_add_i32 s54, s61, 0x8000
	s_add_i32 s56, s61, 0xa000
	global_load_lds_dwordx4 v[4:5], off
	v_lshl_add_u64 v[0:1], v[20:21], 0, s[8:9]
	s_mov_b32 m0, s54
	s_add_u32 s64, s24, 0x10080
	global_load_lds_dwordx4 v[0:1], off
	v_lshl_add_u64 v[6:7], v[22:23], 0, s[8:9]
	s_mov_b32 m0, s56
	s_addc_u32 s65, s25, 0
	s_add_i32 s58, s37, s66
	global_load_lds_dwordx4 v[6:7], off
	v_lshl_add_u64 v[8:9], s[64:65], 0, v[128:129]
	s_mov_b32 m0, s58
	s_add_i32 s60, s58, 0x2000
	global_load_lds_dwordx4 v[8:9], off
	v_lshl_add_u64 v[10:11], s[64:65], 0, v[32:33]
	s_mov_b32 m0, s60
	v_bfe_u32 v144, v34, 4, 2
	global_load_lds_dwordx4 v[10:11], off
	v_and_b32_e32 v143, 15, v34
	v_lshlrev_b32_e32 v35, 4, v144
	v_lshlrev_b32_e32 v34, 2, v34
	v_lshl_or_b32 v66, v143, 6, v35
	v_and_b32_e32 v67, 32, v34
	v_bitop3_b32 v68, v66, s47, v67 bitop3:0xde
	s_add_i32 s48, 0, 0x10000
	s_add_i32 s47, 0, 0x14000
	v_add_u32_e32 v202, s48, v68
	s_waitcnt vmcnt(6)
	s_barrier
	v_add_u32_e32 v145, s47, v68
	ds_read_b128 v[34:37], v202
	ds_read_b128 v[38:41], v202 offset:1024
	ds_read_b128 v[42:45], v202 offset:2048
	ds_read_b128 v[46:49], v202 offset:3072
	ds_read_b128 v[50:53], v145
	ds_read_b128 v[54:57], v145 offset:1024
	ds_read_b128 v[58:61], v145 offset:2048
	ds_read_b128 v[62:65], v145 offset:3072
	v_bitop3_b32 v66, v66, s63, v67 bitop3:0xde
	v_add_u32_e32 v203, 0, v66
	v_add_u32_e32 v246, s37, v68
	v_add_u32_e32 v247, s36, v68
	s_add_u32 s64, s22, 0x40080
	s_addc_u32 s65, s23, 0
	s_add_i32 s68, s61, 0xc000
	v_lshl_add_u64 v[98:99], s[64:65], 0, v[16:17]
	s_mov_b32 m0, s68
	s_add_i32 s63, s61, 0xe000
	ds_read_b128 v[66:69], v203
	ds_read_b128 v[70:73], v203 offset:1024
	ds_read_b128 v[74:77], v203 offset:2048
	ds_read_b128 v[78:81], v203 offset:3072
	ds_read_b128 v[82:85], v203 offset:4096
	ds_read_b128 v[86:89], v203 offset:5120
	ds_read_b128 v[90:93], v203 offset:6144
	ds_read_b128 v[94:97], v203 offset:7168
	global_load_lds_dwordx4 v[98:99], off
	v_lshl_add_u64 v[98:99], s[64:65], 0, v[30:31]
	s_mov_b32 m0, s63
	s_nop 0
	global_load_lds_dwordx4 v[98:99], off
	s_waitcnt vmcnt(8)
	s_waitcnt lgkmcnt(0)
	s_barrier
	s_setprio 1
	v_mfma_f32_16x16x32_bf16 v[98:101], v[34:37], v[66:69], 0
	v_mfma_f32_16x16x32_bf16 v[102:105], v[42:45], v[66:69], 0
	v_mfma_f32_16x16x32_bf16 v[106:109], v[34:37], v[74:77], 0
	v_mfma_f32_16x16x32_bf16 v[110:113], v[42:45], v[74:77], 0
	v_mfma_f32_16x16x32_bf16 v[114:117], v[34:37], v[82:85], 0
	v_mfma_f32_16x16x32_bf16 v[118:121], v[42:45], v[82:85], 0
	v_mfma_f32_16x16x32_bf16 v[122:125], v[34:37], v[90:93], 0
	v_mfma_f32_16x16x32_bf16 v[98:101], v[38:41], v[70:73], v[98:101]
	v_mfma_f32_16x16x32_bf16 v[102:105], v[46:49], v[70:73], v[102:105]
	v_mfma_f32_16x16x32_bf16 v[106:109], v[38:41], v[78:81], v[106:109]
	v_mfma_f32_16x16x32_bf16 v[110:113], v[46:49], v[78:81], v[110:113]
	v_mfma_f32_16x16x32_bf16 v[114:117], v[38:41], v[86:89], v[114:117]
	v_mfma_f32_16x16x32_bf16 v[118:121], v[46:49], v[86:89], v[118:121]
	v_mfma_f32_16x16x32_bf16 v[122:125], v[38:41], v[94:97], v[122:125]
	v_mfma_f32_16x16x32_bf16 v[130:133], v[42:45], v[90:93], 0
	v_mfma_f32_16x16x32_bf16 v[130:133], v[46:49], v[94:97], v[130:133]
	s_setprio 0
	s_setprio 1
	v_mfma_f32_16x16x32_bf16 v[134:137], v[50:53], v[66:69], 0
	v_mfma_f32_16x16x32_bf16 v[66:69], v[58:61], v[66:69], 0
	v_mfma_f32_16x16x32_bf16 v[134:137], v[54:57], v[70:73], v[134:137]
	v_mfma_f32_16x16x32_bf16 v[66:69], v[62:65], v[70:73], v[66:69]
	v_mfma_f32_16x16x32_bf16 v[70:73], v[50:53], v[74:77], 0
	v_mfma_f32_16x16x32_bf16 v[74:77], v[58:61], v[74:77], 0
	v_mfma_f32_16x16x32_bf16 v[70:73], v[54:57], v[78:81], v[70:73]
	v_mfma_f32_16x16x32_bf16 v[74:77], v[62:65], v[78:81], v[74:77]
	v_mfma_f32_16x16x32_bf16 v[78:81], v[50:53], v[82:85], 0
	v_mfma_f32_16x16x32_bf16 v[82:85], v[58:61], v[82:85], 0
	v_mfma_f32_16x16x32_bf16 v[78:81], v[54:57], v[86:89], v[78:81]
	v_mfma_f32_16x16x32_bf16 v[82:85], v[62:65], v[86:89], v[82:85]
	v_mfma_f32_16x16x32_bf16 v[86:89], v[50:53], v[90:93], 0
	v_mfma_f32_16x16x32_bf16 v[90:93], v[58:61], v[90:93], 0
	v_mfma_f32_16x16x32_bf16 v[86:89], v[54:57], v[94:97], v[86:89]
	v_mfma_f32_16x16x32_bf16 v[90:93], v[62:65], v[94:97], v[90:93]
	s_setprio 0
	s_barrier
	s_add_i32 s64, s48, s66
	s_add_i32 s65, s64, 0x2000
	v_lshl_add_u64 v[126:127], v[26:27], 0, s[10:11]
	s_mov_b32 m0, s64
	s_add_u32 s70, s24, 0x10100
	ds_read_b128 v[94:97], v203 offset:16384
	ds_read_b128 v[138:141], v203 offset:17408
	ds_read_b128 v[146:149], v203 offset:18432
	ds_read_b128 v[150:153], v203 offset:19456
	ds_read_b128 v[154:157], v203 offset:20480
	ds_read_b128 v[158:161], v203 offset:21504
	ds_read_b128 v[162:165], v203 offset:22528
	ds_read_b128 v[166:169], v203 offset:23552
	global_load_lds_dwordx4 v[126:127], off
	v_lshl_add_u64 v[126:127], v[28:29], 0, s[10:11]
	s_mov_b32 m0, s65
	s_addc_u32 s71, s25, 0
	s_add_i32 s66, s47, s66
	global_load_lds_dwordx4 v[126:127], off
	v_lshl_add_u64 v[126:127], s[70:71], 0, v[128:129]
	s_mov_b32 m0, s66
	s_add_i32 s67, s66, 0x2000
	global_load_lds_dwordx4 v[126:127], off
	v_lshl_add_u64 v[126:127], s[70:71], 0, v[32:33]
	s_mov_b32 m0, s67
	s_nop 0
	global_load_lds_dwordx4 v[126:127], off
	v_lshl_add_u64 v[126:127], v[20:21], 0, s[10:11]
	s_mov_b32 m0, s61
	s_nop 0
	global_load_lds_dwordx4 v[126:127], off
	v_lshl_add_u64 v[126:127], v[22:23], 0, s[10:11]
	s_mov_b32 m0, s62
	s_nop 0
	global_load_lds_dwordx4 v[126:127], off
	s_waitcnt vmcnt(8)
	s_waitcnt lgkmcnt(0)
	s_barrier
; #define PG8_STAGE(bufoff, gbase, voff) do { _Pragma("unroll") for (int _i = 0; _i < 2; ++_i) \
;         __builtin_amdgcn_global_load_lds((const unsigned*)((const char*)(gbase) + (voff)[_i]), (PG8_LAS unsigned*)(lds + (bufoff) + ldsw + _i * 8192), 16, 0, 0); } while (0)
; #define PG8_LDA(dst, b, h) do { _Pragma("unroll") for (int m = 0; m < 4; ++m) _Pragma("unroll") for (int k = 0; k < 2; ++k) dst[m][k] = *(const PG8_LAS bf16x8*)(lds + PG8_SA(b, h) + aoff + m * 2048 + k * 1024); } while (0)
; #define PG8_LDB(dst, b, h) do { _Pragma("unroll") for (int n = 0; n < 2; ++n) _Pragma("unroll") for (int k = 0; k < 2; ++k) dst[n][k] = *(const PG8_LAS bf16x8*)(lds + PG8_SB(b, h) + boff + n * 2048 + k * 1024); } while (0)
; #define PG8_MMA(ai, bj, At, Bt) do { __builtin_amdgcn_s_setprio(1); _Pragma("unroll") for (int m = 0; m < 4; ++m) _Pragma("unroll") for (int n = 0; n < 2; ++n) _Pragma("unroll") for (int k = 0; k < 2; ++k) \
;         acc[ai][bj][m][n] = __builtin_amdgcn_mfma_f32_16x16x32_bf16(Bt[n][k], At[m][k], acc[ai][bj][m][n], 0, 0, 0); __builtin_amdgcn_s_setprio(0); } while (0)
; #define PG8_WAIT_V(n) asm volatile("s_waitcnt vmcnt(" #n ")" ::: "memory")
; #define PG8_WAIT_L(n) asm volatile("s_waitcnt lgkmcnt(" #n ")" ::: "memory")
; #define PG8_BAR __builtin_amdgcn_s_barrier()
; #define PG8_SCHED __builtin_amdgcn_sched_barrier(0)
; template <class Epi, class Sched, bool ALIGN_EPI = false, bool SP2 = false>
; __device__ __forceinline__ void gemm_phase(PG8_LAS unsigned char* lds, const Gemm g, const Sched& S, const Epi& E, const int wv0) {
;     ...
;             PG8_WAIT_V(8); PG8_WAIT_L(0); PG8_BAR; PG8_MMA(0, 0, At, B0); PG8_MMA(0, 1, At, B1); PG8_BAR; PG8_SCHED;
;             PG8_LDA(At, 0, 1); PG8_STAGE(PG8_SB(0, 0), b2, voffB); PG8_STAGE(PG8_SB(0, 1), b2 + hstepB, voffB); PG8_STAGE(PG8_SA(0, 0), a2, voffA);
;             PG8_WAIT_V(8); PG8_WAIT_L(0); PG8_BAR; PG8_MMA(1, 0, At, B0); PG8_MMA(1, 1, At, B1); PG8_BAR; PG8_SCHED;
;             PG8_LDB(B0, 1, 0); PG8_LDB(B1, 1, 1); PG8_SCHED; PG8_LDA(At, 1, 0); PG8_STAGE(PG8_SA(0, 1), a2 + hstepA, voffA);
;             PG8_WAIT_V(8); PG8_WAIT_L(0); PG8_BAR; PG8_MMA(0, 0, At, B0); PG8_MMA(0, 1, At, B1); PG8_BAR; PG8_SCHED;
	s_setprio 1
	v_mfma_f32_16x16x32_bf16 v[170:173], v[34:37], v[94:97], 0
	v_mfma_f32_16x16x32_bf16 v[178:181], v[34:37], v[146:149], 0
	v_mfma_f32_16x16x32_bf16 v[186:189], v[34:37], v[154:157], 0
	v_mfma_f32_16x16x32_bf16 v[34:37], v[34:37], v[162:165], 0
	v_mfma_f32_16x16x32_bf16 v[170:173], v[38:41], v[138:141], v[170:173]
	v_mfma_f32_16x16x32_bf16 v[178:181], v[38:41], v[150:153], v[178:181]
	v_mfma_f32_16x16x32_bf16 v[186:189], v[38:41], v[158:161], v[186:189]
	v_mfma_f32_16x16x32_bf16 v[34:37], v[38:41], v[166:169], v[34:37]
	v_mfma_f32_16x16x32_bf16 v[38:41], v[42:45], v[162:165], 0
	v_mfma_f32_16x16x32_bf16 v[174:177], v[42:45], v[94:97], 0
	v_mfma_f32_16x16x32_bf16 v[182:185], v[42:45], v[146:149], 0
	v_mfma_f32_16x16x32_bf16 v[190:193], v[42:45], v[154:157], 0
	v_mfma_f32_16x16x32_bf16 v[38:41], v[46:49], v[166:169], v[38:41]
	v_mfma_f32_16x16x32_bf16 v[174:177], v[46:49], v[138:141], v[174:177]
	v_mfma_f32_16x16x32_bf16 v[182:185], v[46:49], v[150:153], v[182:185]
	v_mfma_f32_16x16x32_bf16 v[190:193], v[46:49], v[158:161], v[190:193]
	s_setprio 0
	s_setprio 1
	v_mfma_f32_16x16x32_bf16 v[42:45], v[50:53], v[94:97], 0
	v_mfma_f32_16x16x32_bf16 v[46:49], v[58:61], v[94:97], 0
	v_mfma_f32_16x16x32_bf16 v[42:45], v[54:57], v[138:141], v[42:45]
	v_mfma_f32_16x16x32_bf16 v[46:49], v[62:65], v[138:141], v[46:49]
	v_mfma_f32_16x16x32_bf16 v[94:97], v[50:53], v[146:149], 0
	v_mfma_f32_16x16x32_bf16 v[138:141], v[58:61], v[146:149], 0
	v_mfma_f32_16x16x32_bf16 v[146:149], v[50:53], v[154:157], 0
	v_mfma_f32_16x16x32_bf16 v[50:53], v[50:53], v[162:165], 0
	v_mfma_f32_16x16x32_bf16 v[94:97], v[54:57], v[150:153], v[94:97]
	v_mfma_f32_16x16x32_bf16 v[146:149], v[54:57], v[158:161], v[146:149]
	v_mfma_f32_16x16x32_bf16 v[50:53], v[54:57], v[166:169], v[50:53]
	v_mfma_f32_16x16x32_bf16 v[54:57], v[58:61], v[162:165], 0
	v_mfma_f32_16x16x32_bf16 v[138:141], v[62:65], v[150:153], v[138:141]
	v_mfma_f32_16x16x32_bf16 v[150:153], v[58:61], v[154:157], 0
	v_mfma_f32_16x16x32_bf16 v[54:57], v[62:65], v[166:169], v[54:57]
	v_mfma_f32_16x16x32_bf16 v[150:153], v[62:65], v[158:161], v[150:153]
	s_setprio 0
	s_barrier
	ds_read_b128 v[58:61], v247
	ds_read_b128 v[62:65], v247 offset:1024
	ds_read_b128 v[154:157], v247 offset:2048
	ds_read_b128 v[158:161], v247 offset:3072
	ds_read_b128 v[162:165], v246
	ds_read_b128 v[166:169], v246 offset:1024
	ds_read_b128 v[194:197], v246 offset:2048
	ds_read_b128 v[198:201], v246 offset:3072
	s_add_u32 s70, s22, 0x40100
	s_addc_u32 s71, s23, 0
	s_mov_b32 m0, s57
	v_lshl_add_u64 v[126:127], s[70:71], 0, v[16:17]
	ds_read_b128 v[206:209], v203 offset:32768
	ds_read_b128 v[210:213], v203 offset:33792
	ds_read_b128 v[214:217], v203 offset:34816
	ds_read_b128 v[218:221], v203 offset:35840
	ds_read_b128 v[222:225], v203 offset:36864
	ds_read_b128 v[226:229], v203 offset:37888
	ds_read_b128 v[230:233], v203 offset:38912
	ds_read_b128 v[234:237], v203 offset:39936
	global_load_lds_dwordx4 v[126:127], off
	v_lshl_add_u64 v[126:127], s[70:71], 0, v[30:31]
	s_mov_b32 m0, s59
	s_nop 0
	global_load_lds_dwordx4 v[126:127], off
	s_waitcnt vmcnt(8)
	s_waitcnt lgkmcnt(0)
	s_barrier
	s_setprio 1
	v_mfma_f32_16x16x32_bf16 v[98:101], v[58:61], v[206:209], v[98:101]
	v_mfma_f32_16x16x32_bf16 v[102:105], v[154:157], v[206:209], v[102:105]
	v_mfma_f32_16x16x32_bf16 v[106:109], v[58:61], v[214:217], v[106:109]
	v_mfma_f32_16x16x32_bf16 v[110:113], v[154:157], v[214:217], v[110:113]
	v_mfma_f32_16x16x32_bf16 v[114:117], v[58:61], v[222:225], v[114:117]
	v_mfma_f32_16x16x32_bf16 v[118:121], v[154:157], v[222:225], v[118:121]
	v_mfma_f32_16x16x32_bf16 v[122:125], v[58:61], v[230:233], v[122:125]
	v_mfma_f32_16x16x32_bf16 v[98:101], v[62:65], v[210:213], v[98:101]
	v_mfma_f32_16x16x32_bf16 v[102:105], v[158:161], v[210:213], v[102:105]
	v_mfma_f32_16x16x32_bf16 v[106:109], v[62:65], v[218:221], v[106:109]
	v_mfma_f32_16x16x32_bf16 v[110:113], v[158:161], v[218:221], v[110:113]
	v_mfma_f32_16x16x32_bf16 v[114:117], v[62:65], v[226:229], v[114:117]
	v_mfma_f32_16x16x32_bf16 v[118:121], v[158:161], v[226:229], v[118:121]
	v_mfma_f32_16x16x32_bf16 v[122:125], v[62:65], v[234:237], v[122:125]
	v_mfma_f32_16x16x32_bf16 v[130:133], v[154:157], v[230:233], v[130:133]
	v_mfma_f32_16x16x32_bf16 v[130:133], v[158:161], v[234:237], v[130:133]
	s_setprio 0
	s_setprio 1
	v_mfma_f32_16x16x32_bf16 v[66:69], v[194:197], v[206:209], v[66:69]
	v_mfma_f32_16x16x32_bf16 v[70:73], v[162:165], v[214:217], v[70:73]
	v_mfma_f32_16x16x32_bf16 v[74:77], v[194:197], v[214:217], v[74:77]
	v_mfma_f32_16x16x32_bf16 v[78:81], v[162:165], v[222:225], v[78:81]
	v_mfma_f32_16x16x32_bf16 v[82:85], v[194:197], v[222:225], v[82:85]
	v_mfma_f32_16x16x32_bf16 v[86:89], v[162:165], v[230:233], v[86:89]
	v_mfma_f32_16x16x32_bf16 v[90:93], v[194:197], v[230:233], v[90:93]
	v_mfma_f32_16x16x32_bf16 v[134:137], v[162:165], v[206:209], v[134:137]
	v_mfma_f32_16x16x32_bf16 v[66:69], v[198:201], v[210:213], v[66:69]
	v_mfma_f32_16x16x32_bf16 v[70:73], v[166:169], v[218:221], v[70:73]
	v_mfma_f32_16x16x32_bf16 v[74:77], v[198:201], v[218:221], v[74:77]
	v_mfma_f32_16x16x32_bf16 v[78:81], v[166:169], v[226:229], v[78:81]
	v_mfma_f32_16x16x32_bf16 v[82:85], v[198:201], v[226:229], v[82:85]
	v_mfma_f32_16x16x32_bf16 v[86:89], v[166:169], v[234:237], v[86:89]
	v_mfma_f32_16x16x32_bf16 v[90:93], v[198:201], v[234:237], v[90:93]
	v_mfma_f32_16x16x32_bf16 v[134:137], v[166:169], v[210:213], v[134:137]
	s_setprio 0
	s_barrier
; #define PG8_STAGE(bufoff, gbase, voff) do { _Pragma("unroll") for (int _i = 0; _i < 2; ++_i) \
;         __builtin_amdgcn_global_load_lds((const unsigned*)((const char*)(gbase) + (voff)[_i]), (PG8_LAS unsigned*)(lds + (bufoff) + ldsw + _i * 8192), 16, 0, 0); } while (0)
; #define PG8_LDA(dst, b, h) do { _Pragma("unroll") for (int m = 0; m < 4; ++m) _Pragma("unroll") for (int k = 0; k < 2; ++k) dst[m][k] = *(const PG8_LAS bf16x8*)(lds + PG8_SA(b, h) + aoff + m * 2048 + k * 1024); } while (0)
; #define PG8_LDB(dst, b, h) do { _Pragma("unroll") for (int n = 0; n < 2; ++n) _Pragma("unroll") for (int k = 0; k < 2; ++k) dst[n][k] = *(const PG8_LAS bf16x8*)(lds + PG8_SB(b, h) + boff + n * 2048 + k * 1024); } while (0)
; #define PG8_MMA(ai, bj, At, Bt) do { __builtin_amdgcn_s_setprio(1); _Pragma("unroll") for (int m = 0; m < 4; ++m) _Pragma("unroll") for (int n = 0; n < 2; ++n) _Pragma("unroll") for (int k = 0; k < 2; ++k) \
;         acc[ai][bj][m][n] = __builtin_amdgcn_mfma_f32_16x16x32_bf16(Bt[n][k], At[m][k], acc[ai][bj][m][n], 0, 0, 0); __builtin_amdgcn_s_setprio(0); } while (0)
; #define PG8_WAIT_V(n) asm volatile("s_waitcnt vmcnt(" #n ")" ::: "memory")
; #define PG8_WAIT_L(n) asm volatile("s_waitcnt lgkmcnt(" #n ")" ::: "memory")
; #define PG8_BAR __builtin_amdgcn_s_barrier()
; #define PG8_SCHED __builtin_amdgcn_sched_barrier(0)
; template <class Epi, class Sched, bool ALIGN_EPI = false, bool SP2 = false>
; __device__ __forceinline__ void gemm_phase(PG8_LAS unsigned char* lds, const Gemm g, const Sched& S, const Epi& E, const int wv0) {
;     ...
;             PG8_LDB(B0, 0, 0); PG8_LDB(B1, 0, 1); PG8_SCHED; PG8_LDA(At, 0, 0); PG8_STAGE(PG8_SA(1, 1), a1 + hstepA, voffA);
;             PG8_WAIT_V(8); PG8_WAIT_L(0); PG8_BAR; PG8_MMA(0, 0, At, B0); PG8_MMA(0, 1, At, B1); PG8_BAR; PG8_SCHED;
;     ...
;             PG8_WAIT_V(8); PG8_WAIT_L(0); PG8_BAR; PG8_MMA(0, 0, At, B0); PG8_MMA(0, 1, At, B1); PG8_BAR; PG8_SCHED;
;             PG8_LDA(At, 1, 1); PG8_STAGE(PG8_SB(1, 0), b3, voffB); PG8_STAGE(PG8_SB(1, 1), b3 + hstepB, voffB); PG8_STAGE(PG8_SA(1, 0), a3, voffA);
;             PG8_WAIT_V(8); PG8_WAIT_L(0); PG8_BAR; PG8_MMA(1, 0, At, B0); PG8_MMA(1, 1, At, B1); PG8_BAR; PG8_SCHED;
	s_mov_b32 m0, s53
	v_lshl_add_u64 v[126:127], v[26:27], 0, s[12:13]
	s_add_u32 s24, s24, 0x10180
	ds_read_b128 v[206:209], v203 offset:49152
	ds_read_b128 v[210:213], v203 offset:50176
	ds_read_b128 v[214:217], v203 offset:51200
	ds_read_b128 v[218:221], v203 offset:52224
	ds_read_b128 v[222:225], v203 offset:53248
	ds_read_b128 v[226:229], v203 offset:54272
	ds_read_b128 v[230:233], v203 offset:55296
	ds_read_b128 v[234:237], v203 offset:56320
	global_load_lds_dwordx4 v[126:127], off
	v_lshl_add_u64 v[126:127], v[28:29], 0, s[12:13]
	s_mov_b32 m0, s55
	s_addc_u32 s25, s25, 0
	global_load_lds_dwordx4 v[126:127], off
	v_lshl_add_u64 v[126:127], s[24:25], 0, v[128:129]
	s_mov_b32 m0, s58
	v_lshl_add_u64 v[32:33], s[24:25], 0, v[32:33]
	global_load_lds_dwordx4 v[126:127], off
	s_mov_b32 m0, s60
	s_nop 0
	global_load_lds_dwordx4 v[32:33], off
	v_lshl_add_u64 v[32:33], v[20:21], 0, s[12:13]
	s_mov_b32 m0, s54
	s_nop 0
	global_load_lds_dwordx4 v[32:33], off
	v_lshl_add_u64 v[32:33], v[22:23], 0, s[12:13]
	s_mov_b32 m0, s56
	s_nop 0
	global_load_lds_dwordx4 v[32:33], off
	s_waitcnt vmcnt(8)
	s_waitcnt lgkmcnt(0)
	s_barrier
	s_setprio 1
	v_mfma_f32_16x16x32_bf16 v[32:35], v[58:61], v[230:233], v[34:37]
	v_mfma_f32_16x16x32_bf16 v[36:39], v[154:157], v[230:233], v[38:41]
	v_mfma_f32_16x16x32_bf16 v[170:173], v[58:61], v[206:209], v[170:173]
	v_mfma_f32_16x16x32_bf16 v[174:177], v[154:157], v[206:209], v[174:177]
	v_mfma_f32_16x16x32_bf16 v[178:181], v[58:61], v[214:217], v[178:181]
	v_mfma_f32_16x16x32_bf16 v[182:185], v[154:157], v[214:217], v[182:185]
	v_mfma_f32_16x16x32_bf16 v[186:189], v[58:61], v[222:225], v[186:189]
	v_mfma_f32_16x16x32_bf16 v[190:193], v[154:157], v[222:225], v[190:193]
	v_mfma_f32_16x16x32_bf16 v[32:35], v[62:65], v[234:237], v[32:35]
	v_mfma_f32_16x16x32_bf16 v[36:39], v[158:161], v[234:237], v[36:39]
	v_mfma_f32_16x16x32_bf16 v[170:173], v[62:65], v[210:213], v[170:173]
	v_mfma_f32_16x16x32_bf16 v[174:177], v[158:161], v[210:213], v[174:177]
	v_mfma_f32_16x16x32_bf16 v[178:181], v[62:65], v[218:221], v[178:181]
	v_mfma_f32_16x16x32_bf16 v[182:185], v[158:161], v[218:221], v[182:185]
	v_mfma_f32_16x16x32_bf16 v[186:189], v[62:65], v[226:229], v[186:189]
	v_mfma_f32_16x16x32_bf16 v[190:193], v[158:161], v[226:229], v[190:193]
	s_setprio 0
	s_setprio 1
	v_mfma_f32_16x16x32_bf16 v[40:43], v[162:165], v[206:209], v[42:45]
	v_mfma_f32_16x16x32_bf16 v[44:47], v[194:197], v[206:209], v[46:49]
	v_mfma_f32_16x16x32_bf16 v[58:61], v[162:165], v[214:217], v[94:97]
	v_mfma_f32_16x16x32_bf16 v[62:65], v[194:197], v[214:217], v[138:141]
	v_mfma_f32_16x16x32_bf16 v[94:97], v[162:165], v[222:225], v[146:149]
	v_mfma_f32_16x16x32_bf16 v[48:51], v[162:165], v[230:233], v[50:53]
	v_mfma_f32_16x16x32_bf16 v[52:55], v[194:197], v[230:233], v[54:57]
	v_mfma_f32_16x16x32_bf16 v[40:43], v[166:169], v[210:213], v[40:43]
	v_mfma_f32_16x16x32_bf16 v[44:47], v[198:201], v[210:213], v[44:47]
	v_mfma_f32_16x16x32_bf16 v[58:61], v[166:169], v[218:221], v[58:61]
	v_mfma_f32_16x16x32_bf16 v[62:65], v[198:201], v[218:221], v[62:65]
	v_mfma_f32_16x16x32_bf16 v[94:97], v[166:169], v[226:229], v[94:97]
	v_mfma_f32_16x16x32_bf16 v[138:141], v[194:197], v[222:225], v[150:153]
	v_mfma_f32_16x16x32_bf16 v[48:51], v[166:169], v[234:237], v[48:51]
	v_mfma_f32_16x16x32_bf16 v[52:55], v[198:201], v[234:237], v[52:55]
	v_mfma_f32_16x16x32_bf16 v[138:141], v[198:201], v[226:229], v[138:141]
	s_setprio 0
	s_barrier
	ds_read_b128 v[146:149], v202
	ds_read_b128 v[150:153], v202 offset:1024
	ds_read_b128 v[154:157], v202 offset:2048
	ds_read_b128 v[158:161], v202 offset:3072
	ds_read_b128 v[162:165], v145
	ds_read_b128 v[166:169], v145 offset:1024
	ds_read_b128 v[194:197], v145 offset:2048
	ds_read_b128 v[198:201], v145 offset:3072
	s_add_u32 s22, s22, 0x40180
	s_addc_u32 s23, s23, 0
	s_mov_b32 m0, s68
	v_lshl_add_u64 v[16:17], s[22:23], 0, v[16:17]
	ds_read_b128 v[206:209], v203
	ds_read_b128 v[210:213], v203 offset:1024
	ds_read_b128 v[214:217], v203 offset:2048
	ds_read_b128 v[218:221], v203 offset:3072
	ds_read_b128 v[222:225], v203 offset:4096
	ds_read_b128 v[226:229], v203 offset:5120
	ds_read_b128 v[230:233], v203 offset:6144
	ds_read_b128 v[234:237], v203 offset:7168
	global_load_lds_dwordx4 v[16:17], off
	v_lshl_add_u64 v[16:17], s[22:23], 0, v[30:31]
	s_mov_b32 m0, s63
	s_nop 0
	global_load_lds_dwordx4 v[16:17], off
	s_waitcnt vmcnt(8)
	s_waitcnt lgkmcnt(0)
	s_barrier
	s_setprio 1
	v_mfma_f32_16x16x32_bf16 v[114:117], v[146:149], v[222:225], v[114:117]
	v_mfma_f32_16x16x32_bf16 v[238:241], v[150:153], v[226:229], v[114:117]
	v_mfma_f32_16x16x32_bf16 v[114:117], v[154:157], v[222:225], v[118:121]
	v_mfma_f32_16x16x32_bf16 v[98:101], v[146:149], v[206:209], v[98:101]
	v_mfma_f32_16x16x32_bf16 v[102:105], v[154:157], v[206:209], v[102:105]
	v_mfma_f32_16x16x32_bf16 v[106:109], v[146:149], v[214:217], v[106:109]
	v_mfma_f32_16x16x32_bf16 v[110:113], v[154:157], v[214:217], v[110:113]
	v_mfma_f32_16x16x32_bf16 v[242:245], v[158:161], v[226:229], v[114:117]
	v_mfma_f32_16x16x32_bf16 v[114:117], v[146:149], v[230:233], v[122:125]
	v_mfma_f32_16x16x32_bf16 v[98:101], v[150:153], v[210:213], v[98:101]
	v_mfma_f32_16x16x32_bf16 v[102:105], v[158:161], v[210:213], v[102:105]
	v_mfma_f32_16x16x32_bf16 v[106:109], v[150:153], v[218:221], v[106:109]
	v_mfma_f32_16x16x32_bf16 v[110:113], v[158:161], v[218:221], v[110:113]
	v_mfma_f32_16x16x32_bf16 v[124:127], v[150:153], v[234:237], v[114:117]
	v_mfma_f32_16x16x32_bf16 v[114:117], v[154:157], v[230:233], v[130:133]
	v_mfma_f32_16x16x32_bf16 v[130:133], v[158:161], v[234:237], v[114:117]
	s_setprio 0
	s_setprio 1
	v_mfma_f32_16x16x32_bf16 v[66:69], v[194:197], v[206:209], v[66:69]
	v_mfma_f32_16x16x32_bf16 v[114:117], v[162:165], v[206:209], v[134:137]
	v_mfma_f32_16x16x32_bf16 v[206:209], v[198:201], v[210:213], v[66:69]
	v_mfma_f32_16x16x32_bf16 v[66:69], v[162:165], v[214:217], v[70:73]
	v_mfma_f32_16x16x32_bf16 v[134:137], v[166:169], v[210:213], v[114:117]
	v_mfma_f32_16x16x32_bf16 v[210:213], v[166:169], v[218:221], v[66:69]
	v_mfma_f32_16x16x32_bf16 v[66:69], v[194:197], v[214:217], v[74:77]
	v_mfma_f32_16x16x32_bf16 v[214:217], v[198:201], v[218:221], v[66:69]
	v_mfma_f32_16x16x32_bf16 v[66:69], v[162:165], v[222:225], v[78:81]
	v_mfma_f32_16x16x32_bf16 v[76:79], v[166:169], v[226:229], v[66:69]
	v_mfma_f32_16x16x32_bf16 v[66:69], v[194:197], v[222:225], v[82:85]
	v_mfma_f32_16x16x32_bf16 v[80:83], v[198:201], v[226:229], v[66:69]
	v_mfma_f32_16x16x32_bf16 v[66:69], v[162:165], v[230:233], v[86:89]
	v_mfma_f32_16x16x32_bf16 v[218:221], v[166:169], v[234:237], v[66:69]
	v_mfma_f32_16x16x32_bf16 v[66:69], v[194:197], v[230:233], v[90:93]
	v_mfma_f32_16x16x32_bf16 v[222:225], v[198:201], v[234:237], v[66:69]
	s_setprio 0
	s_barrier
; #define PG8_STAGE(bufoff, gbase, voff) do { _Pragma("unroll") for (int _i = 0; _i < 2; ++_i) \
;         __builtin_amdgcn_global_load_lds((const unsigned*)((const char*)(gbase) + (voff)[_i]), (PG8_LAS unsigned*)(lds + (bufoff) + ldsw + _i * 8192), 16, 0, 0); } while (0)
; #define PG8_LDA(dst, b, h) do { _Pragma("unroll") for (int m = 0; m < 4; ++m) _Pragma("unroll") for (int k = 0; k < 2; ++k) dst[m][k] = *(const PG8_LAS bf16x8*)(lds + PG8_SA(b, h) + aoff + m * 2048 + k * 1024); } while (0)
; #define PG8_LDB(dst, b, h) do { _Pragma("unroll") for (int n = 0; n < 2; ++n) _Pragma("unroll") for (int k = 0; k < 2; ++k) dst[n][k] = *(const PG8_LAS bf16x8*)(lds + PG8_SB(b, h) + boff + n * 2048 + k * 1024); } while (0)
; #define PG8_MMA(ai, bj, At, Bt) do { __builtin_amdgcn_s_setprio(1); _Pragma("unroll") for (int m = 0; m < 4; ++m) _Pragma("unroll") for (int n = 0; n < 2; ++n) _Pragma("unroll") for (int k = 0; k < 2; ++k) \
;         acc[ai][bj][m][n] = __builtin_amdgcn_mfma_f32_16x16x32_bf16(Bt[n][k], At[m][k], acc[ai][bj][m][n], 0, 0, 0); __builtin_amdgcn_s_setprio(0); } while (0)
; #define PG8_WAIT_V(n) asm volatile("s_waitcnt vmcnt(" #n ")" ::: "memory")
; #define PG8_WAIT_L(n) asm volatile("s_waitcnt lgkmcnt(" #n ")" ::: "memory")
; #define PG8_BAR __builtin_amdgcn_s_barrier()
; #define PG8_SCHED __builtin_amdgcn_sched_barrier(0)
; template <class Epi, class Sched, bool ALIGN_EPI = false, bool SP2 = false>
; __device__ __forceinline__ void gemm_phase(PG8_LAS unsigned char* lds, const Gemm g, const Sched& S, const Epi& E, const int wv0) {
;     ...
;             PG8_LDA(At, 0, 1); PG8_STAGE(PG8_SB(0, 0), b2, voffB); PG8_STAGE(PG8_SB(0, 1), b2 + hstepB, voffB); PG8_STAGE(PG8_SA(0, 0), a2, voffA);
;             PG8_WAIT_V(8); PG8_WAIT_L(0); PG8_BAR; PG8_MMA(1, 0, At, B0); PG8_MMA(1, 1, At, B1); PG8_BAR; PG8_SCHED;
;             PG8_LDB(B0, 1, 0); PG8_LDB(B1, 1, 1); PG8_SCHED; PG8_LDA(At, 1, 0); PG8_STAGE(PG8_SA(0, 1), a2 + hstepA, voffA);
;             PG8_WAIT_V(8); PG8_WAIT_L(0); PG8_BAR; PG8_MMA(0, 0, At, B0); PG8_MMA(0, 1, At, B1); PG8_BAR; PG8_SCHED;
	s_mov_b32 m0, s64
	s_nop 3
	ds_read_b128 v[66:69], v203 offset:16384
	ds_read_b128 v[70:73], v203 offset:17408
	ds_read_b128 v[84:87], v203 offset:18432
	ds_read_b128 v[88:91], v203 offset:19456
	ds_read_b128 v[114:117], v203 offset:20480
	ds_read_b128 v[118:121], v203 offset:21504
	ds_read_b128 v[226:229], v203 offset:22528
	ds_read_b128 v[230:233], v203 offset:23552
	global_load_lds_dwordx4 v[26:27], off
	s_mov_b32 m0, s65
	s_nop 0
	global_load_lds_dwordx4 v[28:29], off
	s_mov_b32 m0, s66
	s_nop 0
	global_load_lds_dwordx4 v[24:25], off
	s_mov_b32 m0, s67
	s_nop 0
	global_load_lds_dwordx4 v[18:19], off
	s_mov_b32 m0, s61
	s_nop 0
	global_load_lds_dwordx4 v[20:21], off
	s_mov_b32 m0, s62
	s_nop 0
	global_load_lds_dwordx4 v[22:23], off
	s_waitcnt vmcnt(8)
	s_waitcnt lgkmcnt(0)
	s_barrier
	s_setprio 1
	v_mfma_f32_16x16x32_bf16 v[16:19], v[146:149], v[66:69], v[170:173]
	v_mfma_f32_16x16x32_bf16 v[20:23], v[154:157], v[66:69], v[174:177]
	v_mfma_f32_16x16x32_bf16 v[24:27], v[146:149], v[84:87], v[178:181]
	v_mfma_f32_16x16x32_bf16 v[28:31], v[154:157], v[84:87], v[182:185]
	v_mfma_f32_16x16x32_bf16 v[32:35], v[146:149], v[226:229], v[32:35]
	v_mfma_f32_16x16x32_bf16 v[16:19], v[150:153], v[70:73], v[16:19]
	v_mfma_f32_16x16x32_bf16 v[20:23], v[158:161], v[70:73], v[20:23]
	v_mfma_f32_16x16x32_bf16 v[24:27], v[150:153], v[88:91], v[24:27]
	v_mfma_f32_16x16x32_bf16 v[28:31], v[158:161], v[88:91], v[28:31]
	v_mfma_f32_16x16x32_bf16 v[170:173], v[146:149], v[114:117], v[186:189]
	v_mfma_f32_16x16x32_bf16 v[174:177], v[154:157], v[114:117], v[190:193]
	v_mfma_f32_16x16x32_bf16 v[32:35], v[150:153], v[230:233], v[32:35]
	v_mfma_f32_16x16x32_bf16 v[36:39], v[154:157], v[226:229], v[36:39]
	v_mfma_f32_16x16x32_bf16 v[170:173], v[150:153], v[118:121], v[170:173]
	v_mfma_f32_16x16x32_bf16 v[174:177], v[158:161], v[118:121], v[174:177]
	v_mfma_f32_16x16x32_bf16 v[146:149], v[158:161], v[230:233], v[36:39]
	s_setprio 0
	s_setprio 1
	v_mfma_f32_16x16x32_bf16 v[36:39], v[162:165], v[66:69], v[40:43]
	v_mfma_f32_16x16x32_bf16 v[150:153], v[166:169], v[70:73], v[36:39]
	v_mfma_f32_16x16x32_bf16 v[36:39], v[194:197], v[66:69], v[44:47]
	v_mfma_f32_16x16x32_bf16 v[44:47], v[198:201], v[70:73], v[36:39]
	v_mfma_f32_16x16x32_bf16 v[36:39], v[162:165], v[84:87], v[58:61]
	v_mfma_f32_16x16x32_bf16 v[154:157], v[166:169], v[88:91], v[36:39]
	v_mfma_f32_16x16x32_bf16 v[36:39], v[194:197], v[84:87], v[62:65]
	v_mfma_f32_16x16x32_bf16 v[158:161], v[198:201], v[88:91], v[36:39]
	v_mfma_f32_16x16x32_bf16 v[36:39], v[162:165], v[114:117], v[94:97]
	v_mfma_f32_16x16x32_bf16 v[178:181], v[166:169], v[118:121], v[36:39]
	v_mfma_f32_16x16x32_bf16 v[36:39], v[194:197], v[114:117], v[138:141]
	v_mfma_f32_16x16x32_bf16 v[138:141], v[198:201], v[118:121], v[36:39]
	v_mfma_f32_16x16x32_bf16 v[36:39], v[162:165], v[226:229], v[48:51]
	v_mfma_f32_16x16x32_bf16 v[162:165], v[166:169], v[230:233], v[36:39]
	v_mfma_f32_16x16x32_bf16 v[36:39], v[194:197], v[226:229], v[52:55]
	v_mfma_f32_16x16x32_bf16 v[166:169], v[198:201], v[230:233], v[36:39]
	s_setprio 0
	s_barrier
	ds_read_b128 v[48:51], v247
	ds_read_b128 v[64:67], v247 offset:1024
	ds_read_b128 v[182:185], v247 offset:2048
	ds_read_b128 v[186:189], v247 offset:3072
	ds_read_b128 v[190:193], v246
	ds_read_b128 v[194:197], v246 offset:1024
	ds_read_b128 v[198:201], v246 offset:2048
	ds_read_b128 v[226:229], v246 offset:3072
	s_mov_b32 m0, s57
	ds_read_b128 v[36:39], v203 offset:32768
	ds_read_b128 v[40:43], v203 offset:33792
	ds_read_b128 v[52:55], v203 offset:34816
	ds_read_b128 v[56:59], v203 offset:35840
	ds_read_b128 v[60:63], v203 offset:36864
	ds_read_b128 v[230:233], v203 offset:37888
	ds_read_b128 v[234:237], v203 offset:38912
	ds_read_b128 v[246:249], v203 offset:39936
	global_load_lds_dwordx4 v[12:13], off
	s_mov_b32 m0, s59
	s_nop 0
	global_load_lds_dwordx4 v[14:15], off
	s_waitcnt vmcnt(8)
	s_waitcnt lgkmcnt(0)
	s_barrier
; #define PG8_STAGE(bufoff, gbase, voff) do { _Pragma("unroll") for (int _i = 0; _i < 2; ++_i) \
;         __builtin_amdgcn_global_load_lds((const unsigned*)((const char*)(gbase) + (voff)[_i]), (PG8_LAS unsigned*)(lds + (bufoff) + ldsw + _i * 8192), 16, 0, 0); } while (0)
; #define PG8_LDA(dst, b, h) do { _Pragma("unroll") for (int m = 0; m < 4; ++m) _Pragma("unroll") for (int k = 0; k < 2; ++k) dst[m][k] = *(const PG8_LAS bf16x8*)(lds + PG8_SA(b, h) + aoff + m * 2048 + k * 1024); } while (0)
; #define PG8_MMA(ai, bj, At, Bt) do { __builtin_amdgcn_s_setprio(1); _Pragma("unroll") for (int m = 0; m < 4; ++m) _Pragma("unroll") for (int n = 0; n < 2; ++n) _Pragma("unroll") for (int k = 0; k < 2; ++k) \
;         acc[ai][bj][m][n] = __builtin_amdgcn_mfma_f32_16x16x32_bf16(Bt[n][k], At[m][k], acc[ai][bj][m][n], 0, 0, 0); __builtin_amdgcn_s_setprio(0); } while (0)
; #define PG8_WAIT_V(n) asm volatile("s_waitcnt vmcnt(" #n ")" ::: "memory")
; #define PG8_WAIT_L(n) asm volatile("s_waitcnt lgkmcnt(" #n ")" ::: "memory")
; #define PG8_BAR __builtin_amdgcn_s_barrier()
; #define PG8_SCHED __builtin_amdgcn_sched_barrier(0)
; template <class Epi, class Sched, bool ALIGN_EPI = false, bool SP2 = false>
; __device__ __forceinline__ void gemm_phase(PG8_LAS unsigned char* lds, const Gemm g, const Sched& S, const Epi& E, const int wv0) {
;     ...
;             PG8_WAIT_V(8); PG8_WAIT_L(0); PG8_BAR; PG8_MMA(0, 0, At, B0); PG8_MMA(0, 1, At, B1); PG8_BAR; PG8_SCHED;
;             PG8_LDA(At, 1, 1); PG8_STAGE(PG8_SB(1, 0), b3, voffB); PG8_STAGE(PG8_SB(1, 1), b3 + hstepB, voffB); PG8_STAGE(PG8_SA(1, 0), a3, voffA);
;             PG8_WAIT_V(8); PG8_WAIT_L(0); PG8_BAR; PG8_MMA(1, 0, At, B0); PG8_MMA(1, 1, At, B1); PG8_BAR; PG8_SCHED;
;     ...
;     PG8_WAIT_V(0);
;     if constexpr (!ALIGN_EPI) { if (wr == 0) PG8_BAR; }
	s_setprio 1
	v_mfma_f32_16x16x32_bf16 v[12:15], v[48:51], v[36:39], v[98:101]
	v_mfma_f32_16x16x32_bf16 v[120:123], v[64:67], v[40:43], v[12:15]
	v_mfma_f32_16x16x32_bf16 v[12:15], v[182:185], v[36:39], v[102:105]
	v_mfma_f32_16x16x32_bf16 v[116:119], v[186:189], v[40:43], v[12:15]
	v_mfma_f32_16x16x32_bf16 v[12:15], v[48:51], v[52:55], v[106:109]
	v_mfma_f32_16x16x32_bf16 v[104:107], v[64:67], v[56:59], v[12:15]
	v_mfma_f32_16x16x32_bf16 v[12:15], v[182:185], v[52:55], v[110:113]
	v_mfma_f32_16x16x32_bf16 v[100:103], v[186:189], v[56:59], v[12:15]
	v_mfma_f32_16x16x32_bf16 v[12:15], v[48:51], v[60:63], v[238:241]
	v_mfma_f32_16x16x32_bf16 v[88:91], v[64:67], v[230:233], v[12:15]
	v_mfma_f32_16x16x32_bf16 v[12:15], v[182:185], v[60:63], v[242:245]
	v_mfma_f32_16x16x32_bf16 v[84:87], v[186:189], v[230:233], v[12:15]
	v_mfma_f32_16x16x32_bf16 v[12:15], v[48:51], v[234:237], v[124:127]
	v_mfma_f32_16x16x32_bf16 v[72:75], v[64:67], v[246:249], v[12:15]
	v_mfma_f32_16x16x32_bf16 v[12:15], v[182:185], v[234:237], v[130:133]
	v_mfma_f32_16x16x32_bf16 v[68:71], v[186:189], v[246:249], v[12:15]
	s_setprio 0
	s_setprio 1
	v_mfma_f32_16x16x32_bf16 v[12:15], v[190:193], v[36:39], v[134:137]
	v_mfma_f32_16x16x32_bf16 v[124:127], v[194:197], v[40:43], v[12:15]
	v_mfma_f32_16x16x32_bf16 v[12:15], v[198:201], v[36:39], v[206:209]
	v_mfma_f32_16x16x32_bf16 v[112:115], v[226:229], v[40:43], v[12:15]
	v_mfma_f32_16x16x32_bf16 v[12:15], v[190:193], v[52:55], v[210:213]
	v_mfma_f32_16x16x32_bf16 v[108:111], v[194:197], v[56:59], v[12:15]
	v_mfma_f32_16x16x32_bf16 v[12:15], v[198:201], v[52:55], v[214:217]
	v_mfma_f32_16x16x32_bf16 v[96:99], v[226:229], v[56:59], v[12:15]
	v_mfma_f32_16x16x32_bf16 v[12:15], v[190:193], v[60:63], v[76:79]
	v_mfma_f32_16x16x32_bf16 v[92:95], v[194:197], v[230:233], v[12:15]
	v_mfma_f32_16x16x32_bf16 v[12:15], v[198:201], v[60:63], v[80:83]
	v_mfma_f32_16x16x32_bf16 v[80:83], v[226:229], v[230:233], v[12:15]
	v_mfma_f32_16x16x32_bf16 v[12:15], v[190:193], v[234:237], v[218:221]
	v_mfma_f32_16x16x32_bf16 v[76:79], v[194:197], v[246:249], v[12:15]
	v_mfma_f32_16x16x32_bf16 v[12:15], v[198:201], v[234:237], v[222:225]
	v_mfma_f32_16x16x32_bf16 v[56:59], v[226:229], v[246:249], v[12:15]
	s_setprio 0
	s_barrier
	s_mov_b32 m0, s53
	s_nop 3
	ds_read_b128 v[12:15], v203 offset:49152
	ds_read_b128 v[130:133], v203 offset:50176
	ds_read_b128 v[134:137], v203 offset:51200
	ds_read_b128 v[206:209], v203 offset:52224
	ds_read_b128 v[210:213], v203 offset:53248
	ds_read_b128 v[214:217], v203 offset:54272
	ds_read_b128 v[218:221], v203 offset:55296
	ds_read_b128 v[222:225], v203 offset:56320
	global_load_lds_dwordx4 v[2:3], off
	s_mov_b32 m0, s55
	s_nop 0
	global_load_lds_dwordx4 v[4:5], off
	s_mov_b32 m0, s58
	s_nop 0
	global_load_lds_dwordx4 v[8:9], off
	s_mov_b32 m0, s60
	s_nop 0
	global_load_lds_dwordx4 v[10:11], off
	s_mov_b32 m0, s54
	s_nop 0
	global_load_lds_dwordx4 v[0:1], off
	s_mov_b32 m0, s56
	s_nop 0
	global_load_lds_dwordx4 v[6:7], off
	s_waitcnt vmcnt(8)
	s_waitcnt lgkmcnt(0)
	s_barrier
	s_setprio 1
	v_mfma_f32_16x16x32_bf16 v[0:3], v[48:51], v[12:15], v[16:19]
	v_mfma_f32_16x16x32_bf16 v[60:63], v[64:67], v[130:133], v[0:3]
	v_mfma_f32_16x16x32_bf16 v[0:3], v[182:185], v[12:15], v[20:23]
	v_mfma_f32_16x16x32_bf16 v[52:55], v[186:189], v[130:133], v[0:3]
	v_mfma_f32_16x16x32_bf16 v[0:3], v[48:51], v[134:137], v[24:27]
	v_mfma_f32_16x16x32_bf16 v[40:43], v[64:67], v[206:209], v[0:3]
	v_mfma_f32_16x16x32_bf16 v[0:3], v[182:185], v[134:137], v[28:31]
	v_mfma_f32_16x16x32_bf16 v[36:39], v[186:189], v[206:209], v[0:3]
	v_mfma_f32_16x16x32_bf16 v[0:3], v[48:51], v[210:213], v[170:173]
	v_mfma_f32_16x16x32_bf16 v[24:27], v[64:67], v[214:217], v[0:3]
	v_mfma_f32_16x16x32_bf16 v[0:3], v[182:185], v[210:213], v[174:177]
	v_mfma_f32_16x16x32_bf16 v[20:23], v[186:189], v[214:217], v[0:3]
	v_mfma_f32_16x16x32_bf16 v[0:3], v[48:51], v[218:221], v[32:35]
	v_mfma_f32_16x16x32_bf16 v[8:11], v[64:67], v[222:225], v[0:3]
	v_mfma_f32_16x16x32_bf16 v[0:3], v[182:185], v[218:221], v[146:149]
	v_mfma_f32_16x16x32_bf16 v[4:7], v[186:189], v[222:225], v[0:3]
	s_setprio 0
	s_setprio 1
	v_mfma_f32_16x16x32_bf16 v[0:3], v[190:193], v[12:15], v[150:153]
	v_mfma_f32_16x16x32_bf16 v[64:67], v[194:197], v[130:133], v[0:3]
	v_mfma_f32_16x16x32_bf16 v[0:3], v[198:201], v[12:15], v[44:47]
	v_mfma_f32_16x16x32_bf16 v[48:51], v[226:229], v[130:133], v[0:3]
	v_mfma_f32_16x16x32_bf16 v[0:3], v[190:193], v[134:137], v[154:157]
	v_mfma_f32_16x16x32_bf16 v[44:47], v[194:197], v[206:209], v[0:3]
	v_mfma_f32_16x16x32_bf16 v[0:3], v[198:201], v[134:137], v[158:161]
	v_mfma_f32_16x16x32_bf16 v[32:35], v[226:229], v[206:209], v[0:3]
	v_mfma_f32_16x16x32_bf16 v[0:3], v[190:193], v[210:213], v[178:181]
	v_mfma_f32_16x16x32_bf16 v[28:31], v[194:197], v[214:217], v[0:3]
	v_mfma_f32_16x16x32_bf16 v[0:3], v[198:201], v[210:213], v[138:141]
	v_mfma_f32_16x16x32_bf16 v[16:19], v[226:229], v[214:217], v[0:3]
	v_mfma_f32_16x16x32_bf16 v[0:3], v[190:193], v[218:221], v[162:165]
	v_mfma_f32_16x16x32_bf16 v[12:15], v[194:197], v[222:225], v[0:3]
	v_mfma_f32_16x16x32_bf16 v[0:3], v[198:201], v[218:221], v[166:169]
	v_mfma_f32_16x16x32_bf16 v[0:3], v[226:229], v[222:225], v[0:3]
	s_setprio 0
	s_barrier
	s_waitcnt vmcnt(0)
	s_cmpk_gt_u32 s52, 0xff
	s_cbranch_scc1 .LBB0_360
	s_barrier

; #define PG8_STAGE(bufoff, gbase, voff) do { _Pragma("unroll") for (int _i = 0; _i < 2; ++_i) \
;         __builtin_amdgcn_global_load_lds((const unsigned*)((const char*)(gbase) + (voff)[_i]), (PG8_LAS unsigned*)(lds + (bufoff) + ldsw + _i * 8192), 16, 0, 0); } while (0)
; #define PG8_LDA(dst, b, h) do { _Pragma("unroll") for (int m = 0; m < 4; ++m) _Pragma("unroll") for (int k = 0; k < 2; ++k) dst[m][k] = *(const PG8_LAS bf16x8*)(lds + PG8_SA(b, h) + aoff + m * 2048 + k * 1024); } while (0)
; #define PG8_LDB(dst, b, h) do { _Pragma("unroll") for (int n = 0; n < 2; ++n) _Pragma("unroll") for (int k = 0; k < 2; ++k) dst[n][k] = *(const PG8_LAS bf16x8*)(lds + PG8_SB(b, h) + boff + n * 2048 + k * 1024); } while (0)
; #define PG8_MMA(ai, bj, At, Bt) do { __builtin_amdgcn_s_setprio(1); _Pragma("unroll") for (int m = 0; m < 4; ++m) _Pragma("unroll") for (int n = 0; n < 2; ++n) _Pragma("unroll") for (int k = 0; k < 2; ++k) \
;         acc[ai][bj][m][n] = __builtin_amdgcn_mfma_f32_16x16x32_bf16(Bt[n][k], At[m][k], acc[ai][bj][m][n], 0, 0, 0); __builtin_amdgcn_s_setprio(0); } while (0)
; #define PG8_WAIT_V(n) asm volatile("s_waitcnt vmcnt(" #n ")" ::: "memory")
; #define PG8_WAIT_L(n) asm volatile("s_waitcnt lgkmcnt(" #n ")" ::: "memory")
; #define PG8_BAR __builtin_amdgcn_s_barrier()
; #define PG8_SCHED __builtin_amdgcn_sched_barrier(0)
; template <class Epi, class Sched, bool ALIGN_EPI = false, bool SP2 = false>
; __device__ __forceinline__ void gemm_phase(PG8_LAS unsigned char* lds, const Gemm g, const Sched& S, const Epi& E, const int wv0) {
;     ...
;     if constexpr (SP2) {
;         PG8_STAGE(PG8_SB(0, 0), cB, voffB); PG8_STAGE(PG8_SB(0, 1), cB + hstepB, voffB); PG8_STAGE(PG8_SA(0, 0), cA, voffA); PG8_STAGE(PG8_SA(0, 1), cA + hstepA, voffA);
;         if (wr == 1) PG8_BAR;
;         PG8_WAIT_V(2); PG8_BAR;
;         PG8_STAGE(PG8_SB(1, 0), cB + kstep, voffB); PG8_STAGE(PG8_SA(1, 0), cA + kstep, voffA); PG8_STAGE(PG8_SB(1, 1), cB + hstepB + kstep, voffB);
;         PG8_WAIT_V(6); PG8_BAR;
;     ...
;             if constexpr (SP2) {
;             PG8_LDB(B0, 0, 0); PG8_LDB(B1, 0, 1); PG8_SCHED; PG8_LDA(At, 0, 0); PG8_STAGE(PG8_SA(1, 1), a1 + hstepA, voffA);
;             PG8_WAIT_V(8); PG8_WAIT_L(0); PG8_BAR; PG8_MMA(0, 0, At, B0); PG8_MMA(0, 1, At, B1); PG8_BAR; PG8_SCHED;
.LBB0_378:
	s_lshl_b32 s50, s50, 5
	s_add_i32 s51, s36, s63
	s_and_b32 s50, s50, 0x60
	v_lshl_add_u64 v[2:3], v[26:27], 0, s[8:9]
	s_mov_b32 m0, s51
	s_add_i32 s53, s51, 0x2000
	s_lshl_b32 s62, s61, 13
	s_lshl_b32 s66, s50, 7
	s_waitcnt vmcnt(2)
	s_barrier
	global_load_lds_dwordx4 v[2:3], off
	v_lshl_add_u64 v[4:5], v[28:29], 0, s[8:9]
	s_mov_b32 m0, s53
	s_add_i32 s52, s59, 0x8000
	s_add_i32 s54, s59, 0xa000
	global_load_lds_dwordx4 v[4:5], off
	v_lshl_add_u64 v[0:1], v[20:21], 0, s[8:9]
	s_mov_b32 m0, s52
	s_add_u32 s64, s22, 0x10080
	global_load_lds_dwordx4 v[0:1], off
	v_lshl_add_u64 v[6:7], v[22:23], 0, s[8:9]
	s_mov_b32 m0, s54
	s_addc_u32 s65, s23, 0
	s_add_i32 s57, s37, s63
	global_load_lds_dwordx4 v[6:7], off
	v_lshl_add_u64 v[8:9], s[64:65], 0, v[128:129]
	s_mov_b32 m0, s57
	s_add_i32 s58, s57, 0x2000
	global_load_lds_dwordx4 v[8:9], off
	v_lshl_add_u64 v[10:11], s[64:65], 0, v[32:33]
	s_mov_b32 m0, s58
	v_lshrrev_b32_e32 v37, 1, v34
	global_load_lds_dwordx4 v[10:11], off
	v_and_b32_e32 v37, 24, v37
	v_and_b32_e32 v35, 15, v34
	v_lshlrev_b32_e32 v38, 1, v37
	v_lshlrev_b32_e32 v34, 2, v34
	v_lshl_or_b32 v36, s61, 6, v35
	v_lshl_or_b32 v35, v35, 6, v38
	v_and_b32_e32 v34, 32, v34
	v_bitop3_b32 v70, v35, s66, v34 bitop3:0xde
	v_add_u32_e32 v127, s48, v70
	s_waitcnt vmcnt(6)
	s_barrier
	v_add_u32_e32 v126, s47, v70
	ds_read_b128 v[38:41], v127
	ds_read_b128 v[42:45], v127 offset:1024
	ds_read_b128 v[46:49], v127 offset:2048
	ds_read_b128 v[50:53], v127 offset:3072
	ds_read_b128 v[54:57], v126
	ds_read_b128 v[58:61], v126 offset:1024
	ds_read_b128 v[62:65], v126 offset:2048
	ds_read_b128 v[66:69], v126 offset:3072
	v_bitop3_b32 v34, v35, s62, v34 bitop3:0xde
	v_add_u32_e32 v143, 0, v34
	v_add_u32_e32 v238, s37, v70
	v_add_u32_e32 v239, s36, v70
	s_add_u32 s66, s20, 0x40080
	s_addc_u32 s67, s21, 0
	s_add_i32 s64, s59, 0xc000
	v_lshl_add_u64 v[34:35], s[66:67], 0, v[16:17]
	s_mov_b32 m0, s64
	s_add_i32 s61, s59, 0xe000
	ds_read_b128 v[70:73], v143
	ds_read_b128 v[74:77], v143 offset:1024
	ds_read_b128 v[78:81], v143 offset:2048
	ds_read_b128 v[82:85], v143 offset:3072
	ds_read_b128 v[86:89], v143 offset:4096
	ds_read_b128 v[90:93], v143 offset:5120
	ds_read_b128 v[94:97], v143 offset:6144
	ds_read_b128 v[98:101], v143 offset:7168
	global_load_lds_dwordx4 v[34:35], off
	v_lshl_add_u64 v[34:35], s[66:67], 0, v[30:31]
	s_mov_b32 m0, s61
	s_nop 0
	global_load_lds_dwordx4 v[34:35], off
	s_waitcnt vmcnt(8)
	s_waitcnt lgkmcnt(0)
	s_barrier
	s_setprio 1
	v_mfma_f32_16x16x32_bf16 v[102:105], v[38:41], v[70:73], 0
	v_mfma_f32_16x16x32_bf16 v[106:109], v[46:49], v[70:73], 0
	v_mfma_f32_16x16x32_bf16 v[110:113], v[38:41], v[78:81], 0
	v_mfma_f32_16x16x32_bf16 v[114:117], v[46:49], v[78:81], 0
	v_mfma_f32_16x16x32_bf16 v[118:121], v[38:41], v[86:89], 0
	v_mfma_f32_16x16x32_bf16 v[122:125], v[46:49], v[86:89], 0
	v_mfma_f32_16x16x32_bf16 v[130:133], v[38:41], v[94:97], 0
	v_mfma_f32_16x16x32_bf16 v[134:137], v[46:49], v[94:97], 0
	v_mfma_f32_16x16x32_bf16 v[102:105], v[42:45], v[74:77], v[102:105]
	v_mfma_f32_16x16x32_bf16 v[106:109], v[50:53], v[74:77], v[106:109]
	v_mfma_f32_16x16x32_bf16 v[110:113], v[42:45], v[82:85], v[110:113]
	v_mfma_f32_16x16x32_bf16 v[114:117], v[50:53], v[82:85], v[114:117]
	v_mfma_f32_16x16x32_bf16 v[118:121], v[42:45], v[90:93], v[118:121]
	v_mfma_f32_16x16x32_bf16 v[122:125], v[50:53], v[90:93], v[122:125]
	v_mfma_f32_16x16x32_bf16 v[130:133], v[42:45], v[98:101], v[130:133]
	v_mfma_f32_16x16x32_bf16 v[134:137], v[50:53], v[98:101], v[134:137]
	s_setprio 0
	s_setprio 1
	v_mfma_f32_16x16x32_bf16 v[138:141], v[54:57], v[70:73], 0
	v_mfma_f32_16x16x32_bf16 v[70:73], v[62:65], v[70:73], 0
	v_mfma_f32_16x16x32_bf16 v[138:141], v[58:61], v[74:77], v[138:141]
	v_mfma_f32_16x16x32_bf16 v[70:73], v[66:69], v[74:77], v[70:73]
	v_mfma_f32_16x16x32_bf16 v[74:77], v[54:57], v[78:81], 0
	v_mfma_f32_16x16x32_bf16 v[78:81], v[62:65], v[78:81], 0
	v_mfma_f32_16x16x32_bf16 v[74:77], v[58:61], v[82:85], v[74:77]
	v_mfma_f32_16x16x32_bf16 v[78:81], v[66:69], v[82:85], v[78:81]
	v_mfma_f32_16x16x32_bf16 v[82:85], v[54:57], v[86:89], 0
	v_mfma_f32_16x16x32_bf16 v[86:89], v[62:65], v[86:89], 0
	v_mfma_f32_16x16x32_bf16 v[82:85], v[58:61], v[90:93], v[82:85]
	v_mfma_f32_16x16x32_bf16 v[86:89], v[66:69], v[90:93], v[86:89]
	v_mfma_f32_16x16x32_bf16 v[90:93], v[54:57], v[94:97], 0
	v_mfma_f32_16x16x32_bf16 v[94:97], v[62:65], v[94:97], 0
	v_mfma_f32_16x16x32_bf16 v[90:93], v[58:61], v[98:101], v[90:93]
	v_mfma_f32_16x16x32_bf16 v[94:97], v[66:69], v[98:101], v[94:97]
	s_setprio 0
	s_barrier
	s_add_i32 s48, s48, s63
	s_add_i32 s62, s48, 0x2000
	v_lshl_add_u64 v[34:35], v[26:27], 0, s[10:11]
	s_mov_b32 m0, s48
	s_add_u32 s66, s22, 0x10100
	ds_read_b128 v[98:101], v143 offset:16384
	ds_read_b128 v[144:147], v143 offset:17408
	ds_read_b128 v[148:151], v143 offset:18432
	ds_read_b128 v[152:155], v143 offset:19456
	ds_read_b128 v[156:159], v143 offset:20480
	ds_read_b128 v[160:163], v143 offset:21504
	ds_read_b128 v[164:167], v143 offset:22528
	ds_read_b128 v[168:171], v143 offset:23552
	global_load_lds_dwordx4 v[34:35], off
	v_lshl_add_u64 v[34:35], v[28:29], 0, s[10:11]
	s_mov_b32 m0, s62
	s_addc_u32 s67, s23, 0
	s_add_i32 s47, s47, s63
	global_load_lds_dwordx4 v[34:35], off
	v_lshl_add_u64 v[34:35], s[66:67], 0, v[128:129]
	s_mov_b32 m0, s47
	s_add_i32 s63, s47, 0x2000
	global_load_lds_dwordx4 v[34:35], off
	v_lshl_add_u64 v[34:35], s[66:67], 0, v[32:33]
	s_mov_b32 m0, s63
	s_nop 0
	global_load_lds_dwordx4 v[34:35], off
	v_lshl_add_u64 v[34:35], v[20:21], 0, s[10:11]
	s_mov_b32 m0, s59
	s_nop 0
	global_load_lds_dwordx4 v[34:35], off
	v_lshl_add_u64 v[34:35], v[22:23], 0, s[10:11]
	s_mov_b32 m0, s60
	s_nop 0
	global_load_lds_dwordx4 v[34:35], off
	s_waitcnt vmcnt(8)
	s_waitcnt lgkmcnt(0)
	s_barrier
; #define PG8_STAGE(bufoff, gbase, voff) do { _Pragma("unroll") for (int _i = 0; _i < 2; ++_i) \
;         __builtin_amdgcn_global_load_lds((const unsigned*)((const char*)(gbase) + (voff)[_i]), (PG8_LAS unsigned*)(lds + (bufoff) + ldsw + _i * 8192), 16, 0, 0); } while (0)
; #define PG8_LDA(dst, b, h) do { _Pragma("unroll") for (int m = 0; m < 4; ++m) _Pragma("unroll") for (int k = 0; k < 2; ++k) dst[m][k] = *(const PG8_LAS bf16x8*)(lds + PG8_SA(b, h) + aoff + m * 2048 + k * 1024); } while (0)
; #define PG8_LDB(dst, b, h) do { _Pragma("unroll") for (int n = 0; n < 2; ++n) _Pragma("unroll") for (int k = 0; k < 2; ++k) dst[n][k] = *(const PG8_LAS bf16x8*)(lds + PG8_SB(b, h) + boff + n * 2048 + k * 1024); } while (0)
; #define PG8_MMA(ai, bj, At, Bt) do { __builtin_amdgcn_s_setprio(1); _Pragma("unroll") for (int m = 0; m < 4; ++m) _Pragma("unroll") for (int n = 0; n < 2; ++n) _Pragma("unroll") for (int k = 0; k < 2; ++k) \
;         acc[ai][bj][m][n] = __builtin_amdgcn_mfma_f32_16x16x32_bf16(Bt[n][k], At[m][k], acc[ai][bj][m][n], 0, 0, 0); __builtin_amdgcn_s_setprio(0); } while (0)
; #define PG8_WAIT_V(n) asm volatile("s_waitcnt vmcnt(" #n ")" ::: "memory")
; #define PG8_WAIT_L(n) asm volatile("s_waitcnt lgkmcnt(" #n ")" ::: "memory")
; #define PG8_BAR __builtin_amdgcn_s_barrier()
; #define PG8_SCHED __builtin_amdgcn_sched_barrier(0)
; template <class Epi, class Sched, bool ALIGN_EPI = false, bool SP2 = false>
; __device__ __forceinline__ void gemm_phase(PG8_LAS unsigned char* lds, const Gemm g, const Sched& S, const Epi& E, const int wv0) {
;     ...
;             PG8_WAIT_V(8); PG8_WAIT_L(0); PG8_BAR; PG8_MMA(0, 0, At, B0); PG8_MMA(0, 1, At, B1); PG8_BAR; PG8_SCHED;
;             PG8_LDA(At, 0, 1); PG8_STAGE(PG8_SB(0, 0), b2, voffB); PG8_STAGE(PG8_SB(0, 1), b2 + hstepB, voffB); PG8_STAGE(PG8_SA(0, 0), a2, voffA);
;             PG8_WAIT_V(8); PG8_WAIT_L(0); PG8_BAR; PG8_MMA(1, 0, At, B0); PG8_MMA(1, 1, At, B1); PG8_BAR; PG8_SCHED;
;             PG8_LDB(B0, 1, 0); PG8_LDB(B1, 1, 1); PG8_SCHED; PG8_LDA(At, 1, 0); PG8_STAGE(PG8_SA(0, 1), a2 + hstepA, voffA);
;             PG8_WAIT_V(8); PG8_WAIT_L(0); PG8_BAR; PG8_MMA(0, 0, At, B0); PG8_MMA(0, 1, At, B1); PG8_BAR; PG8_SCHED;
	s_setprio 1
	v_mfma_f32_16x16x32_bf16 v[172:175], v[38:41], v[98:101], 0
	v_mfma_f32_16x16x32_bf16 v[180:183], v[38:41], v[148:151], 0
	v_mfma_f32_16x16x32_bf16 v[188:191], v[38:41], v[156:159], 0
	v_mfma_f32_16x16x32_bf16 v[38:41], v[38:41], v[164:167], 0
	v_mfma_f32_16x16x32_bf16 v[172:175], v[42:45], v[144:147], v[172:175]
	v_mfma_f32_16x16x32_bf16 v[176:179], v[46:49], v[98:101], 0
	v_mfma_f32_16x16x32_bf16 v[180:183], v[42:45], v[152:155], v[180:183]
	v_mfma_f32_16x16x32_bf16 v[184:187], v[46:49], v[148:151], 0
	v_mfma_f32_16x16x32_bf16 v[188:191], v[42:45], v[160:163], v[188:191]
	v_mfma_f32_16x16x32_bf16 v[192:195], v[46:49], v[156:159], 0
	v_mfma_f32_16x16x32_bf16 v[38:41], v[42:45], v[168:171], v[38:41]
	v_mfma_f32_16x16x32_bf16 v[42:45], v[46:49], v[164:167], 0
	v_mfma_f32_16x16x32_bf16 v[176:179], v[50:53], v[144:147], v[176:179]
	v_mfma_f32_16x16x32_bf16 v[184:187], v[50:53], v[152:155], v[184:187]
	v_mfma_f32_16x16x32_bf16 v[192:195], v[50:53], v[160:163], v[192:195]
	v_mfma_f32_16x16x32_bf16 v[42:45], v[50:53], v[168:171], v[42:45]
	s_setprio 0
	s_setprio 1
	v_mfma_f32_16x16x32_bf16 v[46:49], v[54:57], v[98:101], 0
	v_mfma_f32_16x16x32_bf16 v[50:53], v[62:65], v[98:101], 0
	v_mfma_f32_16x16x32_bf16 v[46:49], v[58:61], v[144:147], v[46:49]
	v_mfma_f32_16x16x32_bf16 v[50:53], v[66:69], v[144:147], v[50:53]
	v_mfma_f32_16x16x32_bf16 v[98:101], v[54:57], v[148:151], 0
	v_mfma_f32_16x16x32_bf16 v[144:147], v[62:65], v[148:151], 0
	v_mfma_f32_16x16x32_bf16 v[148:151], v[54:57], v[156:159], 0
	v_mfma_f32_16x16x32_bf16 v[54:57], v[54:57], v[164:167], 0
	v_mfma_f32_16x16x32_bf16 v[98:101], v[58:61], v[152:155], v[98:101]
	v_mfma_f32_16x16x32_bf16 v[144:147], v[66:69], v[152:155], v[144:147]
	v_mfma_f32_16x16x32_bf16 v[148:151], v[58:61], v[160:163], v[148:151]
	v_mfma_f32_16x16x32_bf16 v[152:155], v[62:65], v[156:159], 0
	v_mfma_f32_16x16x32_bf16 v[54:57], v[58:61], v[168:171], v[54:57]
	v_mfma_f32_16x16x32_bf16 v[58:61], v[62:65], v[164:167], 0
	v_mfma_f32_16x16x32_bf16 v[152:155], v[66:69], v[160:163], v[152:155]
	v_mfma_f32_16x16x32_bf16 v[58:61], v[66:69], v[168:171], v[58:61]
	s_setprio 0
	s_barrier
	ds_read_b128 v[62:65], v239
	ds_read_b128 v[66:69], v239 offset:1024
	ds_read_b128 v[156:159], v239 offset:2048
	ds_read_b128 v[160:163], v239 offset:3072
	ds_read_b128 v[164:167], v238
	ds_read_b128 v[168:171], v238 offset:1024
	ds_read_b128 v[196:199], v238 offset:2048
	ds_read_b128 v[200:203], v238 offset:3072
	s_add_u32 s66, s20, 0x40100
	s_addc_u32 s67, s21, 0
	s_mov_b32 m0, s55
	v_lshl_add_u64 v[34:35], s[66:67], 0, v[16:17]
	ds_read_b128 v[206:209], v143 offset:32768
	ds_read_b128 v[210:213], v143 offset:33792
	ds_read_b128 v[214:217], v143 offset:34816
	ds_read_b128 v[218:221], v143 offset:35840
	ds_read_b128 v[222:225], v143 offset:36864
	ds_read_b128 v[226:229], v143 offset:37888
	ds_read_b128 v[230:233], v143 offset:38912
	ds_read_b128 v[234:237], v143 offset:39936
	global_load_lds_dwordx4 v[34:35], off
	v_lshl_add_u64 v[34:35], s[66:67], 0, v[30:31]
	s_mov_b32 m0, s56
	s_nop 0
	global_load_lds_dwordx4 v[34:35], off
	s_waitcnt vmcnt(8)
	s_waitcnt lgkmcnt(0)
	s_barrier
	s_setprio 1
	v_mfma_f32_16x16x32_bf16 v[102:105], v[62:65], v[206:209], v[102:105]
	v_mfma_f32_16x16x32_bf16 v[106:109], v[156:159], v[206:209], v[106:109]
	v_mfma_f32_16x16x32_bf16 v[110:113], v[62:65], v[214:217], v[110:113]
	v_mfma_f32_16x16x32_bf16 v[114:117], v[156:159], v[214:217], v[114:117]
	v_mfma_f32_16x16x32_bf16 v[118:121], v[62:65], v[222:225], v[118:121]
	v_mfma_f32_16x16x32_bf16 v[122:125], v[156:159], v[222:225], v[122:125]
	v_mfma_f32_16x16x32_bf16 v[130:133], v[62:65], v[230:233], v[130:133]
	v_mfma_f32_16x16x32_bf16 v[134:137], v[156:159], v[230:233], v[134:137]
	v_mfma_f32_16x16x32_bf16 v[102:105], v[66:69], v[210:213], v[102:105]
	v_mfma_f32_16x16x32_bf16 v[106:109], v[160:163], v[210:213], v[106:109]
	v_mfma_f32_16x16x32_bf16 v[110:113], v[66:69], v[218:221], v[110:113]
	v_mfma_f32_16x16x32_bf16 v[114:117], v[160:163], v[218:221], v[114:117]
	v_mfma_f32_16x16x32_bf16 v[118:121], v[66:69], v[226:229], v[118:121]
	v_mfma_f32_16x16x32_bf16 v[122:125], v[160:163], v[226:229], v[122:125]
	v_mfma_f32_16x16x32_bf16 v[130:133], v[66:69], v[234:237], v[130:133]
	v_mfma_f32_16x16x32_bf16 v[134:137], v[160:163], v[234:237], v[134:137]
	s_setprio 0
	s_setprio 1
	v_mfma_f32_16x16x32_bf16 v[138:141], v[164:167], v[206:209], v[138:141]
	v_mfma_f32_16x16x32_bf16 v[70:73], v[196:199], v[206:209], v[70:73]
	v_mfma_f32_16x16x32_bf16 v[74:77], v[164:167], v[214:217], v[74:77]
	v_mfma_f32_16x16x32_bf16 v[78:81], v[196:199], v[214:217], v[78:81]
	v_mfma_f32_16x16x32_bf16 v[82:85], v[164:167], v[222:225], v[82:85]
	v_mfma_f32_16x16x32_bf16 v[86:89], v[196:199], v[222:225], v[86:89]
	v_mfma_f32_16x16x32_bf16 v[90:93], v[164:167], v[230:233], v[90:93]
	v_mfma_f32_16x16x32_bf16 v[94:97], v[196:199], v[230:233], v[94:97]
	v_mfma_f32_16x16x32_bf16 v[138:141], v[168:171], v[210:213], v[138:141]
	v_mfma_f32_16x16x32_bf16 v[70:73], v[200:203], v[210:213], v[70:73]
	v_mfma_f32_16x16x32_bf16 v[74:77], v[168:171], v[218:221], v[74:77]
	v_mfma_f32_16x16x32_bf16 v[78:81], v[200:203], v[218:221], v[78:81]
	v_mfma_f32_16x16x32_bf16 v[82:85], v[168:171], v[226:229], v[82:85]
	v_mfma_f32_16x16x32_bf16 v[86:89], v[200:203], v[226:229], v[86:89]
	v_mfma_f32_16x16x32_bf16 v[90:93], v[168:171], v[234:237], v[90:93]
	v_mfma_f32_16x16x32_bf16 v[94:97], v[200:203], v[234:237], v[94:97]
	s_setprio 0
	s_barrier
; #define PG8_STAGE(bufoff, gbase, voff) do { _Pragma("unroll") for (int _i = 0; _i < 2; ++_i) \
;         __builtin_amdgcn_global_load_lds((const unsigned*)((const char*)(gbase) + (voff)[_i]), (PG8_LAS unsigned*)(lds + (bufoff) + ldsw + _i * 8192), 16, 0, 0); } while (0)
; #define PG8_LDA(dst, b, h) do { _Pragma("unroll") for (int m = 0; m < 4; ++m) _Pragma("unroll") for (int k = 0; k < 2; ++k) dst[m][k] = *(const PG8_LAS bf16x8*)(lds + PG8_SA(b, h) + aoff + m * 2048 + k * 1024); } while (0)
; #define PG8_LDB(dst, b, h) do { _Pragma("unroll") for (int n = 0; n < 2; ++n) _Pragma("unroll") for (int k = 0; k < 2; ++k) dst[n][k] = *(const PG8_LAS bf16x8*)(lds + PG8_SB(b, h) + boff + n * 2048 + k * 1024); } while (0)
; #define PG8_MMA(ai, bj, At, Bt) do { __builtin_amdgcn_s_setprio(1); _Pragma("unroll") for (int m = 0; m < 4; ++m) _Pragma("unroll") for (int n = 0; n < 2; ++n) _Pragma("unroll") for (int k = 0; k < 2; ++k) \
;         acc[ai][bj][m][n] = __builtin_amdgcn_mfma_f32_16x16x32_bf16(Bt[n][k], At[m][k], acc[ai][bj][m][n], 0, 0, 0); __builtin_amdgcn_s_setprio(0); } while (0)
; #define PG8_WAIT_V(n) asm volatile("s_waitcnt vmcnt(" #n ")" ::: "memory")
; #define PG8_WAIT_L(n) asm volatile("s_waitcnt lgkmcnt(" #n ")" ::: "memory")
; #define PG8_BAR __builtin_amdgcn_s_barrier()
; #define PG8_SCHED __builtin_amdgcn_sched_barrier(0)
; template <class Epi, class Sched, bool ALIGN_EPI = false, bool SP2 = false>
; __device__ __forceinline__ void gemm_phase(PG8_LAS unsigned char* lds, const Gemm g, const Sched& S, const Epi& E, const int wv0) {
;     ...
;             PG8_LDB(B0, 0, 0); PG8_LDB(B1, 0, 1); PG8_SCHED; PG8_LDA(At, 0, 0); PG8_STAGE(PG8_SA(1, 1), a1 + hstepA, voffA);
;             PG8_WAIT_V(8); PG8_WAIT_L(0); PG8_BAR; PG8_MMA(0, 0, At, B0); PG8_MMA(0, 1, At, B1); PG8_BAR; PG8_SCHED;
;     ...
;             PG8_WAIT_V(8); PG8_WAIT_L(0); PG8_BAR; PG8_MMA(0, 0, At, B0); PG8_MMA(0, 1, At, B1); PG8_BAR; PG8_SCHED;
;             PG8_LDA(At, 1, 1); PG8_STAGE(PG8_SB(1, 0), b3, voffB); PG8_STAGE(PG8_SB(1, 1), b3 + hstepB, voffB); PG8_STAGE(PG8_SA(1, 0), a3, voffA);
;             PG8_WAIT_V(8); PG8_WAIT_L(0); PG8_BAR; PG8_MMA(1, 0, At, B0); PG8_MMA(1, 1, At, B1); PG8_BAR; PG8_SCHED;
	s_mov_b32 m0, s51
	v_lshl_add_u64 v[34:35], v[26:27], 0, s[12:13]
	s_add_u32 s22, s22, 0x10180
	ds_read_b128 v[206:209], v143 offset:49152
	ds_read_b128 v[210:213], v143 offset:50176
	ds_read_b128 v[214:217], v143 offset:51200
	ds_read_b128 v[218:221], v143 offset:52224
	ds_read_b128 v[222:225], v143 offset:53248
	ds_read_b128 v[226:229], v143 offset:54272
	ds_read_b128 v[230:233], v143 offset:55296
	ds_read_b128 v[234:237], v143 offset:56320
	global_load_lds_dwordx4 v[34:35], off
	v_lshl_add_u64 v[34:35], v[28:29], 0, s[12:13]
	s_mov_b32 m0, s53
	s_addc_u32 s23, s23, 0
	global_load_lds_dwordx4 v[34:35], off
	v_lshl_add_u64 v[34:35], s[22:23], 0, v[128:129]
	s_mov_b32 m0, s57
	v_lshl_add_u64 v[32:33], s[22:23], 0, v[32:33]
	global_load_lds_dwordx4 v[34:35], off
	s_mov_b32 m0, s58
	s_nop 0
	global_load_lds_dwordx4 v[32:33], off
	v_lshl_add_u64 v[32:33], v[20:21], 0, s[12:13]
	s_mov_b32 m0, s52
	s_nop 0
	global_load_lds_dwordx4 v[32:33], off
	v_lshl_add_u64 v[32:33], v[22:23], 0, s[12:13]
	s_mov_b32 m0, s54
	s_nop 0
	global_load_lds_dwordx4 v[32:33], off
	s_waitcnt vmcnt(8)
	s_waitcnt lgkmcnt(0)
	s_barrier
	s_setprio 1
	v_mfma_f32_16x16x32_bf16 v[32:35], v[62:65], v[206:209], v[172:175]
	v_mfma_f32_16x16x32_bf16 v[172:175], v[156:159], v[206:209], v[176:179]
	v_mfma_f32_16x16x32_bf16 v[176:179], v[62:65], v[214:217], v[180:183]
	v_mfma_f32_16x16x32_bf16 v[180:183], v[156:159], v[214:217], v[184:187]
	v_mfma_f32_16x16x32_bf16 v[184:187], v[62:65], v[222:225], v[188:191]
	v_mfma_f32_16x16x32_bf16 v[188:191], v[156:159], v[222:225], v[192:195]
	v_mfma_f32_16x16x32_bf16 v[38:41], v[62:65], v[230:233], v[38:41]
	v_mfma_f32_16x16x32_bf16 v[42:45], v[156:159], v[230:233], v[42:45]
	v_mfma_f32_16x16x32_bf16 v[32:35], v[66:69], v[210:213], v[32:35]
	v_mfma_f32_16x16x32_bf16 v[172:175], v[160:163], v[210:213], v[172:175]
	v_mfma_f32_16x16x32_bf16 v[176:179], v[66:69], v[218:221], v[176:179]
	v_mfma_f32_16x16x32_bf16 v[180:183], v[160:163], v[218:221], v[180:183]
	v_mfma_f32_16x16x32_bf16 v[184:187], v[66:69], v[226:229], v[184:187]
	v_mfma_f32_16x16x32_bf16 v[188:191], v[160:163], v[226:229], v[188:191]
	v_mfma_f32_16x16x32_bf16 v[38:41], v[66:69], v[234:237], v[38:41]
	v_mfma_f32_16x16x32_bf16 v[42:45], v[160:163], v[234:237], v[42:45]
	s_setprio 0
	s_setprio 1
	v_mfma_f32_16x16x32_bf16 v[46:49], v[164:167], v[206:209], v[46:49]
	v_mfma_f32_16x16x32_bf16 v[50:53], v[196:199], v[206:209], v[50:53]
	v_mfma_f32_16x16x32_bf16 v[62:65], v[164:167], v[214:217], v[98:101]
	v_mfma_f32_16x16x32_bf16 v[66:69], v[196:199], v[214:217], v[144:147]
	v_mfma_f32_16x16x32_bf16 v[98:101], v[164:167], v[222:225], v[148:151]
	v_mfma_f32_16x16x32_bf16 v[144:147], v[196:199], v[222:225], v[152:155]
	v_mfma_f32_16x16x32_bf16 v[54:57], v[164:167], v[230:233], v[54:57]
	v_mfma_f32_16x16x32_bf16 v[58:61], v[196:199], v[230:233], v[58:61]
	v_mfma_f32_16x16x32_bf16 v[46:49], v[168:171], v[210:213], v[46:49]
	v_mfma_f32_16x16x32_bf16 v[50:53], v[200:203], v[210:213], v[50:53]
	v_mfma_f32_16x16x32_bf16 v[62:65], v[168:171], v[218:221], v[62:65]
	v_mfma_f32_16x16x32_bf16 v[66:69], v[200:203], v[218:221], v[66:69]
	v_mfma_f32_16x16x32_bf16 v[98:101], v[168:171], v[226:229], v[98:101]
	v_mfma_f32_16x16x32_bf16 v[144:147], v[200:203], v[226:229], v[144:147]
	v_mfma_f32_16x16x32_bf16 v[54:57], v[168:171], v[234:237], v[54:57]
	v_mfma_f32_16x16x32_bf16 v[58:61], v[200:203], v[234:237], v[58:61]
	s_setprio 0
	s_barrier
	ds_read_b128 v[148:151], v127
	ds_read_b128 v[152:155], v127 offset:1024
	ds_read_b128 v[156:159], v127 offset:2048
	ds_read_b128 v[160:163], v127 offset:3072
	ds_read_b128 v[164:167], v126
	ds_read_b128 v[168:171], v126 offset:1024
	ds_read_b128 v[192:195], v126 offset:2048
	ds_read_b128 v[196:199], v126 offset:3072
	s_add_u32 s20, s20, 0x40180
	s_addc_u32 s21, s21, 0
	s_mov_b32 m0, s64
	v_lshl_add_u64 v[16:17], s[20:21], 0, v[16:17]
	ds_read_b128 v[200:203], v143
	ds_read_b128 v[206:209], v143 offset:1024
	ds_read_b128 v[210:213], v143 offset:2048
	ds_read_b128 v[214:217], v143 offset:3072
	ds_read_b128 v[218:221], v143 offset:4096
	ds_read_b128 v[222:225], v143 offset:5120
	ds_read_b128 v[226:229], v143 offset:6144
	ds_read_b128 v[230:233], v143 offset:7168
	global_load_lds_dwordx4 v[16:17], off
	v_lshl_add_u64 v[16:17], s[20:21], 0, v[30:31]
	s_mov_b32 m0, s61
	s_nop 0
	global_load_lds_dwordx4 v[16:17], off
	s_waitcnt vmcnt(8)
	s_waitcnt lgkmcnt(0)
	s_barrier
	s_setprio 1
	v_mfma_f32_16x16x32_bf16 v[102:105], v[148:151], v[200:203], v[102:105]
	v_mfma_f32_16x16x32_bf16 v[106:109], v[156:159], v[200:203], v[106:109]
	v_mfma_f32_16x16x32_bf16 v[110:113], v[148:151], v[210:213], v[110:113]
	v_mfma_f32_16x16x32_bf16 v[114:117], v[156:159], v[210:213], v[114:117]
	v_mfma_f32_16x16x32_bf16 v[118:121], v[148:151], v[218:221], v[118:121]
	v_mfma_f32_16x16x32_bf16 v[122:125], v[156:159], v[218:221], v[122:125]
	v_mfma_f32_16x16x32_bf16 v[130:133], v[148:151], v[226:229], v[130:133]
	v_mfma_f32_16x16x32_bf16 v[134:137], v[156:159], v[226:229], v[134:137]
	v_mfma_f32_16x16x32_bf16 v[102:105], v[152:155], v[206:209], v[102:105]
	v_mfma_f32_16x16x32_bf16 v[106:109], v[160:163], v[206:209], v[106:109]
	v_mfma_f32_16x16x32_bf16 v[110:113], v[152:155], v[214:217], v[110:113]
	v_mfma_f32_16x16x32_bf16 v[114:117], v[160:163], v[214:217], v[114:117]
	v_mfma_f32_16x16x32_bf16 v[118:121], v[152:155], v[222:225], v[118:121]
	v_mfma_f32_16x16x32_bf16 v[122:125], v[160:163], v[222:225], v[122:125]
	v_mfma_f32_16x16x32_bf16 v[130:133], v[152:155], v[230:233], v[130:133]
	v_mfma_f32_16x16x32_bf16 v[134:137], v[160:163], v[230:233], v[134:137]
	s_setprio 0
	s_setprio 1
	v_mfma_f32_16x16x32_bf16 v[138:141], v[164:167], v[200:203], v[138:141]
	v_mfma_f32_16x16x32_bf16 v[70:73], v[192:195], v[200:203], v[70:73]
	v_mfma_f32_16x16x32_bf16 v[74:77], v[164:167], v[210:213], v[74:77]
	v_mfma_f32_16x16x32_bf16 v[78:81], v[192:195], v[210:213], v[78:81]
	v_mfma_f32_16x16x32_bf16 v[82:85], v[164:167], v[218:221], v[82:85]
	v_mfma_f32_16x16x32_bf16 v[86:89], v[192:195], v[218:221], v[86:89]
	v_mfma_f32_16x16x32_bf16 v[90:93], v[164:167], v[226:229], v[90:93]
	v_mfma_f32_16x16x32_bf16 v[94:97], v[192:195], v[226:229], v[94:97]
	v_mfma_f32_16x16x32_bf16 v[138:141], v[168:171], v[206:209], v[138:141]
	v_mfma_f32_16x16x32_bf16 v[70:73], v[196:199], v[206:209], v[70:73]
	v_mfma_f32_16x16x32_bf16 v[74:77], v[168:171], v[214:217], v[74:77]
	v_mfma_f32_16x16x32_bf16 v[78:81], v[196:199], v[214:217], v[78:81]
	v_mfma_f32_16x16x32_bf16 v[82:85], v[168:171], v[222:225], v[82:85]
	v_mfma_f32_16x16x32_bf16 v[86:89], v[196:199], v[222:225], v[86:89]
	v_mfma_f32_16x16x32_bf16 v[90:93], v[168:171], v[230:233], v[90:93]
	v_mfma_f32_16x16x32_bf16 v[94:97], v[196:199], v[230:233], v[94:97]
	s_setprio 0
	s_barrier
; #define PG8_STAGE(bufoff, gbase, voff) do { _Pragma("unroll") for (int _i = 0; _i < 2; ++_i) \
;         __builtin_amdgcn_global_load_lds((const unsigned*)((const char*)(gbase) + (voff)[_i]), (PG8_LAS unsigned*)(lds + (bufoff) + ldsw + _i * 8192), 16, 0, 0); } while (0)
; #define PG8_LDA(dst, b, h) do { _Pragma("unroll") for (int m = 0; m < 4; ++m) _Pragma("unroll") for (int k = 0; k < 2; ++k) dst[m][k] = *(const PG8_LAS bf16x8*)(lds + PG8_SA(b, h) + aoff + m * 2048 + k * 1024); } while (0)
; #define PG8_LDB(dst, b, h) do { _Pragma("unroll") for (int n = 0; n < 2; ++n) _Pragma("unroll") for (int k = 0; k < 2; ++k) dst[n][k] = *(const PG8_LAS bf16x8*)(lds + PG8_SB(b, h) + boff + n * 2048 + k * 1024); } while (0)
; #define PG8_MMA(ai, bj, At, Bt) do { __builtin_amdgcn_s_setprio(1); _Pragma("unroll") for (int m = 0; m < 4; ++m) _Pragma("unroll") for (int n = 0; n < 2; ++n) _Pragma("unroll") for (int k = 0; k < 2; ++k) \
;         acc[ai][bj][m][n] = __builtin_amdgcn_mfma_f32_16x16x32_bf16(Bt[n][k], At[m][k], acc[ai][bj][m][n], 0, 0, 0); __builtin_amdgcn_s_setprio(0); } while (0)
; #define PG8_WAIT_V(n) asm volatile("s_waitcnt vmcnt(" #n ")" ::: "memory")
; #define PG8_WAIT_L(n) asm volatile("s_waitcnt lgkmcnt(" #n ")" ::: "memory")
; #define PG8_BAR __builtin_amdgcn_s_barrier()
; #define PG8_SCHED __builtin_amdgcn_sched_barrier(0)
; template <class Epi, class Sched, bool ALIGN_EPI = false, bool SP2 = false>
; __device__ __forceinline__ void gemm_phase(PG8_LAS unsigned char* lds, const Gemm g, const Sched& S, const Epi& E, const int wv0) {
;     ...
;             PG8_LDA(At, 0, 1); PG8_STAGE(PG8_SB(0, 0), b2, voffB); PG8_STAGE(PG8_SB(0, 1), b2 + hstepB, voffB); PG8_STAGE(PG8_SA(0, 0), a2, voffA);
;             PG8_WAIT_V(8); PG8_WAIT_L(0); PG8_BAR; PG8_MMA(1, 0, At, B0); PG8_MMA(1, 1, At, B1); PG8_BAR; PG8_SCHED;
;             PG8_LDB(B0, 1, 0); PG8_LDB(B1, 1, 1); PG8_SCHED; PG8_LDA(At, 1, 0); PG8_STAGE(PG8_SA(0, 1), a2 + hstepA, voffA);
;             PG8_WAIT_V(8); PG8_WAIT_L(0); PG8_BAR; PG8_MMA(0, 0, At, B0); PG8_MMA(0, 1, At, B1); PG8_BAR; PG8_SCHED;
;             PG8_LDA(At, 1, 1); PG8_STAGE(PG8_SB(1, 0), b3, voffB); PG8_STAGE(PG8_SB(1, 1), b3 + hstepB, voffB); PG8_STAGE(PG8_SA(1, 0), a3, voffA);
;             PG8_WAIT_V(8); PG8_WAIT_L(0); PG8_BAR; PG8_MMA(1, 0, At, B0); PG8_MMA(1, 1, At, B1); PG8_BAR; PG8_SCHED;
	s_mov_b32 m0, s48
	ds_read_b128 v[200:203], v143 offset:16384
	ds_read_b128 v[206:209], v143 offset:17408
	ds_read_b128 v[210:213], v143 offset:18432
	ds_read_b128 v[214:217], v143 offset:19456
	ds_read_b128 v[218:221], v143 offset:20480
	ds_read_b128 v[222:225], v143 offset:21504
	ds_read_b128 v[226:229], v143 offset:22528
	ds_read_b128 v[230:233], v143 offset:23552
	global_load_lds_dwordx4 v[26:27], off
	s_mov_b32 m0, s62
	s_nop 0
	global_load_lds_dwordx4 v[28:29], off
	s_mov_b32 m0, s47
	s_nop 0
	global_load_lds_dwordx4 v[24:25], off
	s_mov_b32 m0, s63
	s_nop 0
	global_load_lds_dwordx4 v[18:19], off
	s_mov_b32 m0, s59
	s_nop 0
	global_load_lds_dwordx4 v[20:21], off
	s_mov_b32 m0, s60
	s_nop 0
	global_load_lds_dwordx4 v[22:23], off
	s_waitcnt vmcnt(8)
	s_waitcnt lgkmcnt(0)
	s_barrier
	s_setprio 1
	v_mfma_f32_16x16x32_bf16 v[16:19], v[148:151], v[200:203], v[32:35]
	v_mfma_f32_16x16x32_bf16 v[20:23], v[156:159], v[200:203], v[172:175]
	v_mfma_f32_16x16x32_bf16 v[24:27], v[148:151], v[210:213], v[176:179]
	v_mfma_f32_16x16x32_bf16 v[28:31], v[156:159], v[210:213], v[180:183]
	v_mfma_f32_16x16x32_bf16 v[32:35], v[148:151], v[218:221], v[184:187]
	v_mfma_f32_16x16x32_bf16 v[172:175], v[156:159], v[218:221], v[188:191]
	v_mfma_f32_16x16x32_bf16 v[38:41], v[148:151], v[226:229], v[38:41]
	v_mfma_f32_16x16x32_bf16 v[42:45], v[156:159], v[226:229], v[42:45]
	v_mfma_f32_16x16x32_bf16 v[16:19], v[152:155], v[206:209], v[16:19]
	v_mfma_f32_16x16x32_bf16 v[20:23], v[160:163], v[206:209], v[20:23]
	v_mfma_f32_16x16x32_bf16 v[24:27], v[152:155], v[214:217], v[24:27]
	v_mfma_f32_16x16x32_bf16 v[28:31], v[160:163], v[214:217], v[28:31]
	v_mfma_f32_16x16x32_bf16 v[32:35], v[152:155], v[222:225], v[32:35]
	v_mfma_f32_16x16x32_bf16 v[172:175], v[160:163], v[222:225], v[172:175]
	v_mfma_f32_16x16x32_bf16 v[38:41], v[152:155], v[230:233], v[38:41]
	v_mfma_f32_16x16x32_bf16 v[42:45], v[160:163], v[230:233], v[42:45]
	s_setprio 0
	s_setprio 1
	v_mfma_f32_16x16x32_bf16 v[46:49], v[164:167], v[200:203], v[46:49]
	v_mfma_f32_16x16x32_bf16 v[50:53], v[192:195], v[200:203], v[50:53]
	v_mfma_f32_16x16x32_bf16 v[62:65], v[164:167], v[210:213], v[62:65]
	v_mfma_f32_16x16x32_bf16 v[66:69], v[192:195], v[210:213], v[66:69]
	v_mfma_f32_16x16x32_bf16 v[98:101], v[164:167], v[218:221], v[98:101]
	v_mfma_f32_16x16x32_bf16 v[144:147], v[192:195], v[218:221], v[144:147]
	v_mfma_f32_16x16x32_bf16 v[54:57], v[164:167], v[226:229], v[54:57]
	v_mfma_f32_16x16x32_bf16 v[58:61], v[192:195], v[226:229], v[58:61]
	v_mfma_f32_16x16x32_bf16 v[46:49], v[168:171], v[206:209], v[46:49]
	v_mfma_f32_16x16x32_bf16 v[50:53], v[196:199], v[206:209], v[50:53]
	v_mfma_f32_16x16x32_bf16 v[62:65], v[168:171], v[214:217], v[62:65]
	v_mfma_f32_16x16x32_bf16 v[66:69], v[196:199], v[214:217], v[66:69]
	v_mfma_f32_16x16x32_bf16 v[98:101], v[168:171], v[222:225], v[98:101]
	v_mfma_f32_16x16x32_bf16 v[144:147], v[196:199], v[222:225], v[144:147]
	v_mfma_f32_16x16x32_bf16 v[54:57], v[168:171], v[230:233], v[54:57]
	v_mfma_f32_16x16x32_bf16 v[58:61], v[196:199], v[230:233], v[58:61]
	s_setprio 0
	s_barrier
	ds_read_b128 v[148:151], v239
	ds_read_b128 v[152:155], v239 offset:1024
	ds_read_b128 v[156:159], v239 offset:2048
	ds_read_b128 v[160:163], v239 offset:3072
	ds_read_b128 v[164:167], v238
	ds_read_b128 v[168:171], v238 offset:1024
	ds_read_b128 v[176:179], v238 offset:2048
	ds_read_b128 v[180:183], v238 offset:3072
	s_mov_b32 m0, s55
	ds_read_b128 v[184:187], v143 offset:32768
	ds_read_b128 v[188:191], v143 offset:33792
	ds_read_b128 v[192:195], v143 offset:34816
	ds_read_b128 v[196:199], v143 offset:35840
	ds_read_b128 v[200:203], v143 offset:36864
	ds_read_b128 v[206:209], v143 offset:37888
	ds_read_b128 v[210:213], v143 offset:38912
	ds_read_b128 v[214:217], v143 offset:39936
	global_load_lds_dwordx4 v[12:13], off
	s_mov_b32 m0, s56
	s_nop 0
	global_load_lds_dwordx4 v[14:15], off
	s_waitcnt vmcnt(8)
	s_waitcnt lgkmcnt(0)
	s_barrier
	s_setprio 1
	v_mfma_f32_16x16x32_bf16 v[12:15], v[148:151], v[184:187], v[102:105]
	v_mfma_f32_16x16x32_bf16 v[102:105], v[152:155], v[188:191], v[12:15]
	v_mfma_f32_16x16x32_bf16 v[12:15], v[156:159], v[184:187], v[106:109]
	v_mfma_f32_16x16x32_bf16 v[106:109], v[160:163], v[188:191], v[12:15]
	v_mfma_f32_16x16x32_bf16 v[12:15], v[148:151], v[192:195], v[110:113]
	v_mfma_f32_16x16x32_bf16 v[110:113], v[152:155], v[196:199], v[12:15]
	v_mfma_f32_16x16x32_bf16 v[12:15], v[156:159], v[192:195], v[114:117]
	v_mfma_f32_16x16x32_bf16 v[114:117], v[160:163], v[196:199], v[12:15]
	v_mfma_f32_16x16x32_bf16 v[12:15], v[148:151], v[200:203], v[118:121]
	v_mfma_f32_16x16x32_bf16 v[118:121], v[152:155], v[206:209], v[12:15]
	v_mfma_f32_16x16x32_bf16 v[12:15], v[156:159], v[200:203], v[122:125]
	v_mfma_f32_16x16x32_bf16 v[122:125], v[160:163], v[206:209], v[12:15]
	v_mfma_f32_16x16x32_bf16 v[12:15], v[148:151], v[210:213], v[130:133]
	v_mfma_f32_16x16x32_bf16 v[130:133], v[152:155], v[214:217], v[12:15]
	v_mfma_f32_16x16x32_bf16 v[12:15], v[156:159], v[210:213], v[134:137]
	v_mfma_f32_16x16x32_bf16 v[134:137], v[160:163], v[214:217], v[12:15]
	s_setprio 0
	s_setprio 1
	v_mfma_f32_16x16x32_bf16 v[12:15], v[164:167], v[184:187], v[138:141]
	v_mfma_f32_16x16x32_bf16 v[138:141], v[168:171], v[188:191], v[12:15]
	v_mfma_f32_16x16x32_bf16 v[12:15], v[176:179], v[184:187], v[70:73]
	v_mfma_f32_16x16x32_bf16 v[70:73], v[180:183], v[188:191], v[12:15]
	v_mfma_f32_16x16x32_bf16 v[12:15], v[164:167], v[192:195], v[74:77]
	v_mfma_f32_16x16x32_bf16 v[74:77], v[168:171], v[196:199], v[12:15]
	v_mfma_f32_16x16x32_bf16 v[12:15], v[176:179], v[192:195], v[78:81]
	v_mfma_f32_16x16x32_bf16 v[78:81], v[180:183], v[196:199], v[12:15]
	v_mfma_f32_16x16x32_bf16 v[12:15], v[164:167], v[200:203], v[82:85]
	v_mfma_f32_16x16x32_bf16 v[82:85], v[168:171], v[206:209], v[12:15]
	v_mfma_f32_16x16x32_bf16 v[12:15], v[176:179], v[200:203], v[86:89]
	v_mfma_f32_16x16x32_bf16 v[86:89], v[180:183], v[206:209], v[12:15]
	v_mfma_f32_16x16x32_bf16 v[12:15], v[164:167], v[210:213], v[90:93]
	v_mfma_f32_16x16x32_bf16 v[90:93], v[168:171], v[214:217], v[12:15]
	v_mfma_f32_16x16x32_bf16 v[12:15], v[176:179], v[210:213], v[94:97]
	v_mfma_f32_16x16x32_bf16 v[94:97], v[180:183], v[214:217], v[12:15]
	s_setprio 0
	s_barrier
; #define PG8_STAGE(bufoff, gbase, voff) do { _Pragma("unroll") for (int _i = 0; _i < 2; ++_i) \
;         __builtin_amdgcn_global_load_lds((const unsigned*)((const char*)(gbase) + (voff)[_i]), (PG8_LAS unsigned*)(lds + (bufoff) + ldsw + _i * 8192), 16, 0, 0); } while (0)
; #define PG8_LDA(dst, b, h) do { _Pragma("unroll") for (int m = 0; m < 4; ++m) _Pragma("unroll") for (int k = 0; k < 2; ++k) dst[m][k] = *(const PG8_LAS bf16x8*)(lds + PG8_SA(b, h) + aoff + m * 2048 + k * 1024); } while (0)
; #define PG8_MMA(ai, bj, At, Bt) do { __builtin_amdgcn_s_setprio(1); _Pragma("unroll") for (int m = 0; m < 4; ++m) _Pragma("unroll") for (int n = 0; n < 2; ++n) _Pragma("unroll") for (int k = 0; k < 2; ++k) \
;         acc[ai][bj][m][n] = __builtin_amdgcn_mfma_f32_16x16x32_bf16(Bt[n][k], At[m][k], acc[ai][bj][m][n], 0, 0, 0); __builtin_amdgcn_s_setprio(0); } while (0)
; #define PG8_WAIT_V(n) asm volatile("s_waitcnt vmcnt(" #n ")" ::: "memory")
; #define PG8_WAIT_L(n) asm volatile("s_waitcnt lgkmcnt(" #n ")" ::: "memory")
; #define PG8_BAR __builtin_amdgcn_s_barrier()
; #define PG8_SCHED __builtin_amdgcn_sched_barrier(0)
; template <class Epi, class Sched, bool ALIGN_EPI = false, bool SP2 = false>
; __device__ __forceinline__ void gemm_phase(PG8_LAS unsigned char* lds, const Gemm g, const Sched& S, const Epi& E, const int wv0) {
;     ...
;             PG8_WAIT_V(8); PG8_WAIT_L(0); PG8_BAR; PG8_MMA(0, 0, At, B0); PG8_MMA(0, 1, At, B1); PG8_BAR; PG8_SCHED;
;             PG8_LDA(At, 1, 1); PG8_STAGE(PG8_SB(1, 0), b3, voffB); PG8_STAGE(PG8_SB(1, 1), b3 + hstepB, voffB); PG8_STAGE(PG8_SA(1, 0), a3, voffA);
;             PG8_WAIT_V(8); PG8_WAIT_L(0); PG8_BAR; PG8_MMA(1, 0, At, B0); PG8_MMA(1, 1, At, B1); PG8_BAR; PG8_SCHED;
	s_mov_b32 m0, s51
	ds_read_b128 v[184:187], v143 offset:49152
	ds_read_b128 v[188:191], v143 offset:50176
	ds_read_b128 v[192:195], v143 offset:51200
	ds_read_b128 v[196:199], v143 offset:52224
	ds_read_b128 v[200:203], v143 offset:53248
	ds_read_b128 v[206:209], v143 offset:54272
	ds_read_b128 v[210:213], v143 offset:55296
	ds_read_b128 v[214:217], v143 offset:56320
	global_load_lds_dwordx4 v[2:3], off
	s_mov_b32 m0, s53
	s_nop 0
	global_load_lds_dwordx4 v[4:5], off
	s_mov_b32 m0, s57
	s_nop 0
	global_load_lds_dwordx4 v[8:9], off
	s_mov_b32 m0, s58
	s_nop 0
	global_load_lds_dwordx4 v[10:11], off
	s_mov_b32 m0, s52
	s_nop 0
	global_load_lds_dwordx4 v[0:1], off
	s_mov_b32 m0, s54
	s_nop 0
	global_load_lds_dwordx4 v[6:7], off
	s_waitcnt vmcnt(8)
	s_waitcnt lgkmcnt(0)
	s_barrier
	s_setprio 1
	v_mfma_f32_16x16x32_bf16 v[0:3], v[148:151], v[184:187], v[16:19]
	v_mfma_f32_16x16x32_bf16 v[218:221], v[152:155], v[188:191], v[0:3]
	v_mfma_f32_16x16x32_bf16 v[0:3], v[156:159], v[184:187], v[20:23]
	v_mfma_f32_16x16x32_bf16 v[222:225], v[160:163], v[188:191], v[0:3]
	v_mfma_f32_16x16x32_bf16 v[0:3], v[148:151], v[192:195], v[24:27]
	v_mfma_f32_16x16x32_bf16 v[226:229], v[152:155], v[196:199], v[0:3]
	v_mfma_f32_16x16x32_bf16 v[0:3], v[156:159], v[192:195], v[28:31]
	v_mfma_f32_16x16x32_bf16 v[230:233], v[160:163], v[196:199], v[0:3]
	v_mfma_f32_16x16x32_bf16 v[0:3], v[148:151], v[200:203], v[32:35]
	v_mfma_f32_16x16x32_bf16 v[28:31], v[152:155], v[206:209], v[0:3]
	v_mfma_f32_16x16x32_bf16 v[0:3], v[156:159], v[200:203], v[172:175]
	v_mfma_f32_16x16x32_bf16 v[20:23], v[160:163], v[206:209], v[0:3]
	v_mfma_f32_16x16x32_bf16 v[0:3], v[148:151], v[210:213], v[38:41]
	v_mfma_f32_16x16x32_bf16 v[12:15], v[152:155], v[214:217], v[0:3]
	v_mfma_f32_16x16x32_bf16 v[0:3], v[156:159], v[210:213], v[42:45]
	v_mfma_f32_16x16x32_bf16 v[4:7], v[160:163], v[214:217], v[0:3]
	s_setprio 0
	s_setprio 1
	v_mfma_f32_16x16x32_bf16 v[0:3], v[164:167], v[184:187], v[46:49]
	v_mfma_f32_16x16x32_bf16 v[38:41], v[168:171], v[188:191], v[0:3]
	v_mfma_f32_16x16x32_bf16 v[0:3], v[176:179], v[184:187], v[50:53]
	v_mfma_f32_16x16x32_bf16 v[42:45], v[180:183], v[188:191], v[0:3]
	v_mfma_f32_16x16x32_bf16 v[0:3], v[164:167], v[192:195], v[62:65]
	v_mfma_f32_16x16x32_bf16 v[46:49], v[168:171], v[196:199], v[0:3]
	v_mfma_f32_16x16x32_bf16 v[0:3], v[176:179], v[192:195], v[66:69]
	v_mfma_f32_16x16x32_bf16 v[32:35], v[180:183], v[196:199], v[0:3]
	v_mfma_f32_16x16x32_bf16 v[0:3], v[164:167], v[200:203], v[98:101]
	v_mfma_f32_16x16x32_bf16 v[24:27], v[168:171], v[206:209], v[0:3]
	v_mfma_f32_16x16x32_bf16 v[0:3], v[176:179], v[200:203], v[144:147]
	v_mfma_f32_16x16x32_bf16 v[16:19], v[180:183], v[206:209], v[0:3]
	v_mfma_f32_16x16x32_bf16 v[0:3], v[164:167], v[210:213], v[54:57]
	v_mfma_f32_16x16x32_bf16 v[8:11], v[168:171], v[214:217], v[0:3]
	v_mfma_f32_16x16x32_bf16 v[0:3], v[176:179], v[210:213], v[58:61]
	v_mfma_f32_16x16x32_bf16 v[0:3], v[180:183], v[214:217], v[0:3]
	s_setprio 0
	s_barrier
; __device__ __forceinline__ unsigned cvtpk(float lo, float hi) { unsigned r; asm volatile("v_cvt_pk_bf16_f32 %0, %1, %2" : "=v"(r) : "v"(lo), "v"(hi)); return r; }
; #define PG8_WAIT_V(n) asm volatile("s_waitcnt vmcnt(" #n ")" ::: "memory")
; #define PG8_BAR __builtin_amdgcn_s_barrier()
;     __device__ __forceinline__ void operator()(const f32x4 (&acc)[2][2][4][2], const Unit& u, int wr, int wc, int fr, int fq) const {
;         const int row0 = u.pm * BM + wr * 64 + fr; const int col0 = u.pn * BM + wc * 32 + 8 * fq;
; #pragma unroll
;         for (int ai = 0; ai < 2; ++ai)
; #pragma unroll
;             for (int m = 0; m < 4; ++m) { bf16* rowp = O + (size_t)(row0 + ai * HALF + m * 16) * ldc + col0;
; #pragma unroll
;                 for (int bj = 0; bj < 2; ++bj) { const f32x4 v0 = acc[ai][bj][m][0], v1 = acc[ai][bj][m][1];
;                     u32x4 w; w.x = cvtpk(v0[0], v0[1]); w.y = cvtpk(v0[2], v0[3]); w.z = cvtpk(v1[0], v1[1]); w.w = cvtpk(v1[2], v1[3]);
;                     *(u32x4*)(rowp + bj * HALF) = w; } }
; template <class Epi, class Sched, bool ALIGN_EPI = false, bool SP2 = false>
; __device__ __forceinline__ void gemm_phase(PG8_LAS unsigned char* lds, const Gemm g, const Sched& S, const Epi& E, const int wv0) {
;     ...
;         if constexpr (ALIGN_EPI) { if (wr == 1) PG8_BAR; }
;     }
;     PG8_WAIT_V(0);
;     if constexpr (!ALIGN_EPI) { if (wr == 0) PG8_BAR; }
;     PG8_BAR;
	v_add_u32_e32 v54, s24, v36
	v_or_b32_e32 v36, s49, v37
	v_ashrrev_i32_e32 v55, 31, v54
	v_or_b32_e32 v50, s50, v36
	v_lshlrev_b64 v[36:37], 11, v[54:55]
	v_lshl_add_u64 v[36:37], s[4:5], 0, v[36:37]
	v_lshlrev_b32_e32 v128, 1, v50
	v_lshl_add_u64 v[36:37], v[36:37], 0, v[128:129]
	v_cvt_pk_bf16_f32 v50, v102, v103
	v_cvt_pk_bf16_f32 v51, v104, v105
	v_cvt_pk_bf16_f32 v52, v106, v107
	v_cvt_pk_bf16_f32 v53, v108, v109
	global_store_dwordx4 v[36:37], v[50:53], off
	s_cmpk_gt_u32 s25, 0xff
	s_nop 0
	v_cvt_pk_bf16_f32 v50, v138, v139
	v_cvt_pk_bf16_f32 v51, v140, v141
	v_cvt_pk_bf16_f32 v52, v70, v71
	v_cvt_pk_bf16_f32 v53, v72, v73
	global_store_dwordx4 v[36:37], v[50:53], off offset:256
	s_nop 1
	v_or_b32_e32 v50, 16, v54
	v_ashrrev_i32_e32 v51, 31, v50
	v_lshlrev_b64 v[50:51], 11, v[50:51]
	v_lshl_add_u64 v[50:51], s[4:5], 0, v[50:51]
	v_lshl_add_u64 v[56:57], v[50:51], 0, v[128:129]
	v_cvt_pk_bf16_f32 v50, v110, v111
	v_cvt_pk_bf16_f32 v51, v112, v113
	v_cvt_pk_bf16_f32 v52, v114, v115
	v_cvt_pk_bf16_f32 v53, v116, v117
	global_store_dwordx4 v[56:57], v[50:53], off
	s_nop 1
	v_cvt_pk_bf16_f32 v50, v74, v75
	v_cvt_pk_bf16_f32 v51, v76, v77
	v_cvt_pk_bf16_f32 v52, v78, v79
	v_cvt_pk_bf16_f32 v53, v80, v81
	global_store_dwordx4 v[56:57], v[50:53], off offset:256
	s_nop 1
	v_or_b32_e32 v50, 32, v54
	v_ashrrev_i32_e32 v51, 31, v50
	v_lshlrev_b64 v[50:51], 11, v[50:51]
	v_lshl_add_u64 v[50:51], s[4:5], 0, v[50:51]
	v_lshl_add_u64 v[56:57], v[50:51], 0, v[128:129]
	v_cvt_pk_bf16_f32 v50, v118, v119
	v_cvt_pk_bf16_f32 v51, v120, v121
	v_cvt_pk_bf16_f32 v52, v122, v123
	v_cvt_pk_bf16_f32 v53, v124, v125
	global_store_dwordx4 v[56:57], v[50:53], off
	s_nop 1
	v_cvt_pk_bf16_f32 v50, v82, v83
	v_cvt_pk_bf16_f32 v51, v84, v85
	v_cvt_pk_bf16_f32 v52, v86, v87
	v_cvt_pk_bf16_f32 v53, v88, v89
	global_store_dwordx4 v[56:57], v[50:53], off offset:256
	v_add_co_u32_e32 v56, vcc, s39, v36
	s_nop 0
	v_or_b32_e32 v50, 48, v54
	v_ashrrev_i32_e32 v51, 31, v50
	v_lshlrev_b64 v[50:51], 11, v[50:51]
	v_lshl_add_u64 v[50:51], s[4:5], 0, v[50:51]
	v_lshl_add_u64 v[54:55], v[50:51], 0, v[128:129]
	v_cvt_pk_bf16_f32 v50, v130, v131
	v_cvt_pk_bf16_f32 v51, v132, v133
	v_cvt_pk_bf16_f32 v52, v134, v135
	v_cvt_pk_bf16_f32 v53, v136, v137
	global_store_dwordx4 v[54:55], v[50:53], off
	v_addc_co_u32_e32 v57, vcc, 0, v37, vcc
	s_nop 0
	v_cvt_pk_bf16_f32 v50, v90, v91
	v_cvt_pk_bf16_f32 v51, v92, v93
	v_cvt_pk_bf16_f32 v52, v94, v95
	v_cvt_pk_bf16_f32 v53, v96, v97
	global_store_dwordx4 v[54:55], v[50:53], off offset:256
	v_lshl_add_u64 v[54:55], v[36:37], 0, s[6:7]
	s_nop 0
	v_cvt_pk_bf16_f32 v50, v218, v219
	v_cvt_pk_bf16_f32 v51, v220, v221
	v_cvt_pk_bf16_f32 v52, v222, v223
	v_cvt_pk_bf16_f32 v53, v224, v225
	global_store_dwordx4 v[56:57], v[50:53], off
	v_cvt_pk_bf16_f32 v38, v38, v39
	v_cvt_pk_bf16_f32 v39, v40, v41
	v_cvt_pk_bf16_f32 v40, v42, v43
	v_cvt_pk_bf16_f32 v41, v44, v45
	v_add_co_u32_e32 v44, vcc, s40, v36
	global_store_dwordx4 v[54:55], v[38:41], off offset:256
	v_lshl_add_u64 v[42:43], v[36:37], 0, s[14:15]
	v_addc_co_u32_e32 v45, vcc, 0, v37, vcc
	v_cvt_pk_bf16_f32 v38, v226, v227
	v_cvt_pk_bf16_f32 v39, v228, v229
	v_cvt_pk_bf16_f32 v40, v230, v231
	v_cvt_pk_bf16_f32 v41, v232, v233
	global_store_dwordx4 v[44:45], v[38:41], off
	s_nop 1
	v_cvt_pk_bf16_f32 v38, v46, v47
	v_cvt_pk_bf16_f32 v39, v48, v49
	v_cvt_pk_bf16_f32 v40, v32, v33
	v_cvt_pk_bf16_f32 v41, v34, v35
	global_store_dwordx4 v[42:43], v[38:41], off offset:256
	v_cvt_pk_bf16_f32 v28, v28, v29
	v_cvt_pk_bf16_f32 v29, v30, v31
	v_cvt_pk_bf16_f32 v30, v20, v21
	v_add_co_u32_e32 v20, vcc, s41, v36
	v_lshl_add_u64 v[32:33], v[36:37], 0, s[16:17]
	s_nop 0
	v_addc_co_u32_e32 v21, vcc, 0, v37, vcc
	v_cvt_pk_bf16_f32 v31, v22, v23
	global_store_dwordx4 v[20:21], v[28:31], off
	v_cvt_pk_bf16_f32 v20, v24, v25
	v_cvt_pk_bf16_f32 v21, v26, v27
	v_cvt_pk_bf16_f32 v22, v16, v17
	v_cvt_pk_bf16_f32 v23, v18, v19
	global_store_dwordx4 v[32:33], v[20:23], off offset:256
	v_cvt_pk_bf16_f32 v12, v12, v13
	v_cvt_pk_bf16_f32 v13, v14, v15
	v_cvt_pk_bf16_f32 v14, v4, v5
	v_add_co_u32_e32 v4, vcc, s45, v36
	v_lshl_add_u64 v[16:17], v[36:37], 0, s[18:19]
	s_nop 0
	v_addc_co_u32_e32 v5, vcc, 0, v37, vcc
	v_cvt_pk_bf16_f32 v15, v6, v7
	global_store_dwordx4 v[4:5], v[12:15], off
	v_cvt_pk_bf16_f32 v4, v8, v9
	v_cvt_pk_bf16_f32 v5, v10, v11
	v_cvt_pk_bf16_f32 v6, v0, v1
	v_cvt_pk_bf16_f32 v7, v2, v3
	global_store_dwordx4 v[16:17], v[4:7], off offset:256
	s_waitcnt vmcnt(0)
	s_cbranch_scc1 .LBB0_355
	s_barrier
	s_branch .LBB0_355

; #define PG8_STAGE(bufoff, gbase, voff) do { _Pragma("unroll") for (int _i = 0; _i < 2; ++_i) \
;         __builtin_amdgcn_global_load_lds((const unsigned*)((const char*)(gbase) + (voff)[_i]), (PG8_LAS unsigned*)(lds + (bufoff) + ldsw + _i * 8192), 16, 0, 0); } while (0)
; #define PG8_LDA(dst, b, h) do { _Pragma("unroll") for (int m = 0; m < 4; ++m) _Pragma("unroll") for (int k = 0; k < 2; ++k) dst[m][k] = *(const PG8_LAS bf16x8*)(lds + PG8_SA(b, h) + aoff + m * 2048 + k * 1024); } while (0)
; #define PG8_LDB(dst, b, h) do { _Pragma("unroll") for (int n = 0; n < 2; ++n) _Pragma("unroll") for (int k = 0; k < 2; ++k) dst[n][k] = *(const PG8_LAS bf16x8*)(lds + PG8_SB(b, h) + boff + n * 2048 + k * 1024); } while (0)
; #define PG8_MMA(ai, bj, At, Bt) do { __builtin_amdgcn_s_setprio(1); _Pragma("unroll") for (int m = 0; m < 4; ++m) _Pragma("unroll") for (int n = 0; n < 2; ++n) _Pragma("unroll") for (int k = 0; k < 2; ++k) \
;         acc[ai][bj][m][n] = __builtin_amdgcn_mfma_f32_16x16x32_bf16(Bt[n][k], At[m][k], acc[ai][bj][m][n], 0, 0, 0); __builtin_amdgcn_s_setprio(0); } while (0)
; #define PG8_WAIT_V(n) asm volatile("s_waitcnt vmcnt(" #n ")" ::: "memory")
; #define PG8_WAIT_L(n) asm volatile("s_waitcnt lgkmcnt(" #n ")" ::: "memory")
; #define PG8_BAR __builtin_amdgcn_s_barrier()
; #define PG8_SCHED __builtin_amdgcn_sched_barrier(0)
; template <class Epi, class Sched, bool ALIGN_EPI = false, bool SP2 = false>
; __device__ __forceinline__ void gemm_phase(PG8_LAS unsigned char* lds, const Gemm g, const Sched& S, const Epi& E, const int wv0) {
;     ...
;             if constexpr (SP2) {
;             PG8_LDB(B0, 0, 0); PG8_LDB(B1, 0, 1); PG8_SCHED; PG8_LDA(At, 0, 0); PG8_STAGE(PG8_SA(1, 1), a1 + hstepA, voffA);
;             PG8_WAIT_V(8); PG8_WAIT_L(0); PG8_BAR; PG8_MMA(0, 0, At, B0); PG8_MMA(0, 1, At, B1); PG8_BAR; PG8_SCHED;
;             PG8_LDA(At, 0, 1); PG8_STAGE(PG8_SB(0, 0), b2, voffB); PG8_STAGE(PG8_SB(0, 1), b2 + hstepB, voffB); PG8_STAGE(PG8_SA(0, 0), a2, voffA);
;             PG8_WAIT_V(8); PG8_WAIT_L(0); PG8_BAR; PG8_MMA(1, 0, At, B0); PG8_MMA(1, 1, At, B1); PG8_BAR; PG8_SCHED;
.LBB0_494:
	v_add_u32_e32 v158, s61, v207
	v_add_u32_e32 v174, s62, v207
	ds_read_b128 v[146:149], v158
	ds_read_b128 v[150:153], v158 offset:1024
	ds_read_b128 v[154:157], v158 offset:2048
	ds_read_b128 v[158:161], v158 offset:3072
	ds_read_b128 v[162:165], v174
	ds_read_b128 v[166:169], v174 offset:1024
	ds_read_b128 v[170:173], v174 offset:2048
	ds_read_b128 v[174:177], v174 offset:3072
	s_add_u32 s41, s38, 0xfffc0080
	s_addc_u32 s44, s39, -1
	s_cmp_eq_u32 s29, 12
	s_cselect_b32 s47, s5, s44
	s_cselect_b32 s46, s4, s41
	s_cselect_b32 s45, s37, s27
	s_cselect_b32 s44, s36, s25
	v_lshl_add_u64 v[202:203], s[38:39], 0, v[140:141]
	s_add_i32 m0, s55, 0xc000
	ds_read_b128 v[178:181], v209
	ds_read_b128 v[182:185], v209 offset:1024
	ds_read_b128 v[186:189], v209 offset:2048
	ds_read_b128 v[190:193], v209 offset:3072
	ds_read_b128 v[194:197], v209 offset:4096
	ds_read_b128 v[198:201], v209 offset:5120
	ds_read_b128 v[210:213], v209 offset:6144
	ds_read_b128 v[214:217], v209 offset:7168
	global_load_lds_dwordx4 v[202:203], off
	v_lshl_add_u64 v[202:203], s[38:39], 0, v[138:139]
	s_add_i32 m0, s55, 0xe000
	s_nop 0
	global_load_lds_dwordx4 v[202:203], off
	s_waitcnt vmcnt(8)
	s_waitcnt lgkmcnt(0)
	s_barrier
	s_setprio 1
	v_mfma_f32_16x16x32_bf16 v[124:127], v[146:149], v[178:181], v[124:127]
	v_mfma_f32_16x16x32_bf16 v[120:123], v[154:157], v[178:181], v[120:123]
	v_mfma_f32_16x16x32_bf16 v[108:111], v[146:149], v[186:189], v[108:111]
	v_mfma_f32_16x16x32_bf16 v[104:107], v[154:157], v[186:189], v[104:107]
	v_mfma_f32_16x16x32_bf16 v[92:95], v[146:149], v[194:197], v[92:95]
	v_mfma_f32_16x16x32_bf16 v[88:91], v[154:157], v[194:197], v[88:91]
	v_mfma_f32_16x16x32_bf16 v[76:79], v[146:149], v[210:213], v[76:79]
	v_mfma_f32_16x16x32_bf16 v[72:75], v[154:157], v[210:213], v[72:75]
	v_mfma_f32_16x16x32_bf16 v[124:127], v[150:153], v[182:185], v[124:127]
	v_mfma_f32_16x16x32_bf16 v[120:123], v[158:161], v[182:185], v[120:123]
	v_mfma_f32_16x16x32_bf16 v[108:111], v[150:153], v[190:193], v[108:111]
	v_mfma_f32_16x16x32_bf16 v[104:107], v[158:161], v[190:193], v[104:107]
	v_mfma_f32_16x16x32_bf16 v[92:95], v[150:153], v[198:201], v[92:95]
	v_mfma_f32_16x16x32_bf16 v[88:91], v[158:161], v[198:201], v[88:91]
	v_mfma_f32_16x16x32_bf16 v[76:79], v[150:153], v[214:217], v[76:79]
	v_mfma_f32_16x16x32_bf16 v[72:75], v[158:161], v[214:217], v[72:75]
	s_setprio 0
	s_setprio 1
	v_mfma_f32_16x16x32_bf16 v[116:119], v[162:165], v[178:181], v[116:119]
	v_mfma_f32_16x16x32_bf16 v[112:115], v[170:173], v[178:181], v[112:115]
	v_mfma_f32_16x16x32_bf16 v[100:103], v[162:165], v[186:189], v[100:103]
	v_mfma_f32_16x16x32_bf16 v[96:99], v[170:173], v[186:189], v[96:99]
	v_mfma_f32_16x16x32_bf16 v[84:87], v[162:165], v[194:197], v[84:87]
	v_mfma_f32_16x16x32_bf16 v[80:83], v[170:173], v[194:197], v[80:83]
	v_mfma_f32_16x16x32_bf16 v[68:71], v[162:165], v[210:213], v[68:71]
	v_mfma_f32_16x16x32_bf16 v[64:67], v[170:173], v[210:213], v[64:67]
	v_mfma_f32_16x16x32_bf16 v[116:119], v[166:169], v[182:185], v[116:119]
	v_mfma_f32_16x16x32_bf16 v[112:115], v[174:177], v[182:185], v[112:115]
	v_mfma_f32_16x16x32_bf16 v[100:103], v[166:169], v[190:193], v[100:103]
	v_mfma_f32_16x16x32_bf16 v[96:99], v[174:177], v[190:193], v[96:99]
	v_mfma_f32_16x16x32_bf16 v[84:87], v[166:169], v[198:201], v[84:87]
	v_mfma_f32_16x16x32_bf16 v[80:83], v[174:177], v[198:201], v[80:83]
	v_mfma_f32_16x16x32_bf16 v[68:71], v[166:169], v[214:217], v[68:71]
	v_mfma_f32_16x16x32_bf16 v[64:67], v[174:177], v[214:217], v[64:67]
	s_setprio 0
	s_barrier
	s_add_i32 s41, s61, s54
	v_lshl_add_u64 v[202:203], s[44:45], 0, v[130:131]
	s_mov_b32 m0, s41
	ds_read_b128 v[178:181], v209 offset:16384
	ds_read_b128 v[182:185], v209 offset:17408
	ds_read_b128 v[186:189], v209 offset:18432
	ds_read_b128 v[190:193], v209 offset:19456
	ds_read_b128 v[194:197], v209 offset:20480
	ds_read_b128 v[198:201], v209 offset:21504
	ds_read_b128 v[210:213], v209 offset:22528
	ds_read_b128 v[214:217], v209 offset:23552
	global_load_lds_dwordx4 v[202:203], off
	s_add_i32 m0, s41, 0x2000
	s_add_u32 s64, s44, 0x40000
	v_lshl_add_u64 v[218:219], s[44:45], 0, v[134:135]
	s_addc_u32 s65, s45, 0
	s_add_i32 s41, s62, s54
	global_load_lds_dwordx4 v[218:219], off
	v_lshl_add_u64 v[220:221], s[64:65], 0, v[130:131]
	s_mov_b32 m0, s41
	v_lshl_add_u64 v[222:223], s[46:47], 0, v[132:133]
	global_load_lds_dwordx4 v[220:221], off
	v_lshl_add_u64 v[220:221], s[64:65], 0, v[134:135]
	s_add_i32 m0, s41, 0x2000
	s_nop 0
	global_load_lds_dwordx4 v[220:221], off
	v_lshl_add_u64 v[220:221], s[46:47], 0, v[128:129]
	s_mov_b32 m0, s55
	s_nop 0
	global_load_lds_dwordx4 v[220:221], off
	s_mov_b32 m0, s56
	s_nop 0
	global_load_lds_dwordx4 v[222:223], off
	s_waitcnt vmcnt(8)
	s_waitcnt lgkmcnt(0)
	s_barrier
; #define PG8_STAGE(bufoff, gbase, voff) do { _Pragma("unroll") for (int _i = 0; _i < 2; ++_i) \
;         __builtin_amdgcn_global_load_lds((const unsigned*)((const char*)(gbase) + (voff)[_i]), (PG8_LAS unsigned*)(lds + (bufoff) + ldsw + _i * 8192), 16, 0, 0); } while (0)
; #define PG8_LDA(dst, b, h) do { _Pragma("unroll") for (int m = 0; m < 4; ++m) _Pragma("unroll") for (int k = 0; k < 2; ++k) dst[m][k] = *(const PG8_LAS bf16x8*)(lds + PG8_SA(b, h) + aoff + m * 2048 + k * 1024); } while (0)
; #define PG8_LDB(dst, b, h) do { _Pragma("unroll") for (int n = 0; n < 2; ++n) _Pragma("unroll") for (int k = 0; k < 2; ++k) dst[n][k] = *(const PG8_LAS bf16x8*)(lds + PG8_SB(b, h) + boff + n * 2048 + k * 1024); } while (0)
; #define PG8_MMA(ai, bj, At, Bt) do { __builtin_amdgcn_s_setprio(1); _Pragma("unroll") for (int m = 0; m < 4; ++m) _Pragma("unroll") for (int n = 0; n < 2; ++n) _Pragma("unroll") for (int k = 0; k < 2; ++k) \
;         acc[ai][bj][m][n] = __builtin_amdgcn_mfma_f32_16x16x32_bf16(Bt[n][k], At[m][k], acc[ai][bj][m][n], 0, 0, 0); __builtin_amdgcn_s_setprio(0); } while (0)
; #define PG8_WAIT_V(n) asm volatile("s_waitcnt vmcnt(" #n ")" ::: "memory")
; #define PG8_WAIT_L(n) asm volatile("s_waitcnt lgkmcnt(" #n ")" ::: "memory")
; #define PG8_BAR __builtin_amdgcn_s_barrier()
; #define PG8_SCHED __builtin_amdgcn_sched_barrier(0)
; template <class Epi, class Sched, bool ALIGN_EPI = false, bool SP2 = false>
; __device__ __forceinline__ void gemm_phase(PG8_LAS unsigned char* lds, const Gemm g, const Sched& S, const Epi& E, const int wv0) {
;     ...
;             PG8_WAIT_V(8); PG8_WAIT_L(0); PG8_BAR; PG8_MMA(1, 0, At, B0); PG8_MMA(1, 1, At, B1); PG8_BAR; PG8_SCHED;
;             PG8_LDB(B0, 1, 0); PG8_LDB(B1, 1, 1); PG8_SCHED; PG8_LDA(At, 1, 0); PG8_STAGE(PG8_SA(0, 1), a2 + hstepA, voffA);
;             PG8_WAIT_V(8); PG8_WAIT_L(0); PG8_BAR; PG8_MMA(0, 0, At, B0); PG8_MMA(0, 1, At, B1); PG8_BAR; PG8_SCHED;
	s_setprio 1
	v_mfma_f32_16x16x32_bf16 v[60:63], v[146:149], v[178:181], v[60:63]
	v_mfma_f32_16x16x32_bf16 v[56:59], v[154:157], v[178:181], v[56:59]
	v_mfma_f32_16x16x32_bf16 v[44:47], v[146:149], v[186:189], v[44:47]
	v_mfma_f32_16x16x32_bf16 v[40:43], v[154:157], v[186:189], v[40:43]
	v_mfma_f32_16x16x32_bf16 v[28:31], v[146:149], v[194:197], v[28:31]
	v_mfma_f32_16x16x32_bf16 v[24:27], v[154:157], v[194:197], v[24:27]
	v_mfma_f32_16x16x32_bf16 v[12:15], v[146:149], v[210:213], v[12:15]
	v_mfma_f32_16x16x32_bf16 v[8:11], v[154:157], v[210:213], v[8:11]
	v_mfma_f32_16x16x32_bf16 v[60:63], v[150:153], v[182:185], v[60:63]
	v_mfma_f32_16x16x32_bf16 v[56:59], v[158:161], v[182:185], v[56:59]
	v_mfma_f32_16x16x32_bf16 v[44:47], v[150:153], v[190:193], v[44:47]
	v_mfma_f32_16x16x32_bf16 v[40:43], v[158:161], v[190:193], v[40:43]
	v_mfma_f32_16x16x32_bf16 v[28:31], v[150:153], v[198:201], v[28:31]
	v_mfma_f32_16x16x32_bf16 v[24:27], v[158:161], v[198:201], v[24:27]
	v_mfma_f32_16x16x32_bf16 v[12:15], v[150:153], v[214:217], v[12:15]
	v_mfma_f32_16x16x32_bf16 v[8:11], v[158:161], v[214:217], v[8:11]
	s_setprio 0
	s_setprio 1
	v_mfma_f32_16x16x32_bf16 v[52:55], v[162:165], v[178:181], v[52:55]
	v_mfma_f32_16x16x32_bf16 v[48:51], v[170:173], v[178:181], v[48:51]
	v_mfma_f32_16x16x32_bf16 v[36:39], v[162:165], v[186:189], v[36:39]
	v_mfma_f32_16x16x32_bf16 v[32:35], v[170:173], v[186:189], v[32:35]
	v_mfma_f32_16x16x32_bf16 v[20:23], v[162:165], v[194:197], v[20:23]
	v_mfma_f32_16x16x32_bf16 v[16:19], v[170:173], v[194:197], v[16:19]
	v_mfma_f32_16x16x32_bf16 v[4:7], v[162:165], v[210:213], v[4:7]
	v_mfma_f32_16x16x32_bf16 v[0:3], v[170:173], v[210:213], v[0:3]
	v_mfma_f32_16x16x32_bf16 v[52:55], v[166:169], v[182:185], v[52:55]
	v_mfma_f32_16x16x32_bf16 v[48:51], v[174:177], v[182:185], v[48:51]
	v_mfma_f32_16x16x32_bf16 v[36:39], v[166:169], v[190:193], v[36:39]
	v_mfma_f32_16x16x32_bf16 v[32:35], v[174:177], v[190:193], v[32:35]
	v_mfma_f32_16x16x32_bf16 v[20:23], v[166:169], v[198:201], v[20:23]
	v_mfma_f32_16x16x32_bf16 v[16:19], v[174:177], v[198:201], v[16:19]
	v_mfma_f32_16x16x32_bf16 v[4:7], v[166:169], v[214:217], v[4:7]
	v_mfma_f32_16x16x32_bf16 v[0:3], v[174:177], v[214:217], v[0:3]
	s_setprio 0
	s_barrier
	s_add_i32 s41, 0, 0x18000
	s_add_i32 s64, 0, 0x1c000
	v_add_u32_e32 v158, s41, v207
	v_add_u32_e32 v174, s64, v207
	ds_read_b128 v[146:149], v158
	ds_read_b128 v[150:153], v158 offset:1024
	ds_read_b128 v[154:157], v158 offset:2048
	ds_read_b128 v[158:161], v158 offset:3072
	ds_read_b128 v[162:165], v174
	ds_read_b128 v[166:169], v174 offset:1024
	ds_read_b128 v[170:173], v174 offset:2048
	ds_read_b128 v[174:177], v174 offset:3072
	s_add_u32 s46, s46, 0x40000
	s_addc_u32 s47, s47, 0
	s_mov_b32 m0, s57
	v_lshl_add_u64 v[224:225], s[46:47], 0, v[128:129]
	ds_read_b128 v[178:181], v209 offset:32768
	ds_read_b128 v[182:185], v209 offset:33792
	ds_read_b128 v[186:189], v209 offset:34816
	ds_read_b128 v[190:193], v209 offset:35840
	ds_read_b128 v[194:197], v209 offset:36864
	ds_read_b128 v[198:201], v209 offset:37888
	ds_read_b128 v[210:213], v209 offset:38912
	ds_read_b128 v[214:217], v209 offset:39936
	global_load_lds_dwordx4 v[224:225], off
	v_lshl_add_u64 v[224:225], s[46:47], 0, v[132:133]
	s_mov_b32 m0, s58
	s_nop 0
	global_load_lds_dwordx4 v[224:225], off
	s_waitcnt vmcnt(8)
	s_waitcnt lgkmcnt(0)
	s_barrier
	s_setprio 1
	v_mfma_f32_16x16x32_bf16 v[124:127], v[146:149], v[178:181], v[124:127]
	v_mfma_f32_16x16x32_bf16 v[120:123], v[154:157], v[178:181], v[120:123]
	v_mfma_f32_16x16x32_bf16 v[108:111], v[146:149], v[186:189], v[108:111]
	v_mfma_f32_16x16x32_bf16 v[104:107], v[154:157], v[186:189], v[104:107]
	v_mfma_f32_16x16x32_bf16 v[92:95], v[146:149], v[194:197], v[92:95]
	v_mfma_f32_16x16x32_bf16 v[88:91], v[154:157], v[194:197], v[88:91]
	v_mfma_f32_16x16x32_bf16 v[76:79], v[146:149], v[210:213], v[76:79]
	v_mfma_f32_16x16x32_bf16 v[72:75], v[154:157], v[210:213], v[72:75]
	v_mfma_f32_16x16x32_bf16 v[124:127], v[150:153], v[182:185], v[124:127]
	v_mfma_f32_16x16x32_bf16 v[120:123], v[158:161], v[182:185], v[120:123]
	v_mfma_f32_16x16x32_bf16 v[108:111], v[150:153], v[190:193], v[108:111]
	v_mfma_f32_16x16x32_bf16 v[104:107], v[158:161], v[190:193], v[104:107]
	v_mfma_f32_16x16x32_bf16 v[92:95], v[150:153], v[198:201], v[92:95]
	v_mfma_f32_16x16x32_bf16 v[88:91], v[158:161], v[198:201], v[88:91]
	v_mfma_f32_16x16x32_bf16 v[76:79], v[150:153], v[214:217], v[76:79]
	v_mfma_f32_16x16x32_bf16 v[72:75], v[158:161], v[214:217], v[72:75]
	s_setprio 0
	s_setprio 1
	v_mfma_f32_16x16x32_bf16 v[116:119], v[162:165], v[178:181], v[116:119]
	v_mfma_f32_16x16x32_bf16 v[112:115], v[170:173], v[178:181], v[112:115]
	v_mfma_f32_16x16x32_bf16 v[100:103], v[162:165], v[186:189], v[100:103]
	v_mfma_f32_16x16x32_bf16 v[96:99], v[170:173], v[186:189], v[96:99]
	v_mfma_f32_16x16x32_bf16 v[84:87], v[162:165], v[194:197], v[84:87]
	v_mfma_f32_16x16x32_bf16 v[80:83], v[170:173], v[194:197], v[80:83]
	v_mfma_f32_16x16x32_bf16 v[68:71], v[162:165], v[210:213], v[68:71]
	v_mfma_f32_16x16x32_bf16 v[64:67], v[170:173], v[210:213], v[64:67]
	v_mfma_f32_16x16x32_bf16 v[116:119], v[166:169], v[182:185], v[116:119]
	v_mfma_f32_16x16x32_bf16 v[112:115], v[174:177], v[182:185], v[112:115]
	v_mfma_f32_16x16x32_bf16 v[100:103], v[166:169], v[190:193], v[100:103]
	v_mfma_f32_16x16x32_bf16 v[96:99], v[174:177], v[190:193], v[96:99]
	v_mfma_f32_16x16x32_bf16 v[84:87], v[166:169], v[198:201], v[84:87]
	v_mfma_f32_16x16x32_bf16 v[80:83], v[174:177], v[198:201], v[80:83]
	v_mfma_f32_16x16x32_bf16 v[68:71], v[166:169], v[214:217], v[68:71]
	v_mfma_f32_16x16x32_bf16 v[64:67], v[174:177], v[214:217], v[64:67]
	s_setprio 0
	s_barrier
; #define PG8_STAGE(bufoff, gbase, voff) do { _Pragma("unroll") for (int _i = 0; _i < 2; ++_i) \
;         __builtin_amdgcn_global_load_lds((const unsigned*)((const char*)(gbase) + (voff)[_i]), (PG8_LAS unsigned*)(lds + (bufoff) + ldsw + _i * 8192), 16, 0, 0); } while (0)
; #define PG8_LDA(dst, b, h) do { _Pragma("unroll") for (int m = 0; m < 4; ++m) _Pragma("unroll") for (int k = 0; k < 2; ++k) dst[m][k] = *(const PG8_LAS bf16x8*)(lds + PG8_SA(b, h) + aoff + m * 2048 + k * 1024); } while (0)
; #define PG8_MMA(ai, bj, At, Bt) do { __builtin_amdgcn_s_setprio(1); _Pragma("unroll") for (int m = 0; m < 4; ++m) _Pragma("unroll") for (int n = 0; n < 2; ++n) _Pragma("unroll") for (int k = 0; k < 2; ++k) \
;         acc[ai][bj][m][n] = __builtin_amdgcn_mfma_f32_16x16x32_bf16(Bt[n][k], At[m][k], acc[ai][bj][m][n], 0, 0, 0); __builtin_amdgcn_s_setprio(0); } while (0)
; #define PG8_WAIT_V(n) asm volatile("s_waitcnt vmcnt(" #n ")" ::: "memory")
; #define PG8_WAIT_L(n) asm volatile("s_waitcnt lgkmcnt(" #n ")" ::: "memory")
; #define PG8_BAR __builtin_amdgcn_s_barrier()
; #define PG8_SCHED __builtin_amdgcn_sched_barrier(0)
; template <class Epi, class Sched, bool ALIGN_EPI = false, bool SP2 = false>
; __device__ __forceinline__ void gemm_phase(PG8_LAS unsigned char* lds, const Gemm g, const Sched& S, const Epi& E, const int wv0) {
;     ...
;             PG8_LDA(At, 1, 1); PG8_STAGE(PG8_SB(1, 0), b3, voffB); PG8_STAGE(PG8_SB(1, 1), b3 + hstepB, voffB); PG8_STAGE(PG8_SA(1, 0), a3, voffA);
;             PG8_WAIT_V(8); PG8_WAIT_L(0); PG8_BAR; PG8_MMA(1, 0, At, B0); PG8_MMA(1, 1, At, B1); PG8_BAR; PG8_SCHED;
	s_add_i32 s41, s41, s54
	v_lshl_add_u64 v[202:203], v[202:203], 0, s[10:11]
	s_mov_b32 m0, s41
	ds_read_b128 v[178:181], v209 offset:49152
	ds_read_b128 v[182:185], v209 offset:50176
	ds_read_b128 v[186:189], v209 offset:51200
	ds_read_b128 v[190:193], v209 offset:52224
	ds_read_b128 v[194:197], v209 offset:53248
	ds_read_b128 v[198:201], v209 offset:54272
	ds_read_b128 v[210:213], v209 offset:55296
	ds_read_b128 v[214:217], v209 offset:56320
	global_load_lds_dwordx4 v[202:203], off
	s_add_i32 m0, s41, 0x2000
	s_add_u32 s44, s44, 0x40080
	v_lshl_add_u64 v[202:203], v[218:219], 0, s[10:11]
	s_addc_u32 s45, s45, 0
	s_add_i32 s41, s64, s54
	global_load_lds_dwordx4 v[202:203], off
	v_lshl_add_u64 v[202:203], s[44:45], 0, v[130:131]
	s_mov_b32 m0, s41
	s_nop 0
	global_load_lds_dwordx4 v[202:203], off
	v_lshl_add_u64 v[202:203], s[44:45], 0, v[134:135]
	s_add_i32 m0, s41, 0x2000
	s_nop 0
	global_load_lds_dwordx4 v[202:203], off
	v_lshl_add_u64 v[202:203], v[220:221], 0, s[10:11]
	s_mov_b32 m0, s59
	s_nop 0
	global_load_lds_dwordx4 v[202:203], off
	v_lshl_add_u64 v[202:203], v[222:223], 0, s[10:11]
	s_mov_b32 m0, s60
	s_nop 0
	global_load_lds_dwordx4 v[202:203], off
	s_waitcnt vmcnt(8)
	s_waitcnt lgkmcnt(0)
	s_barrier
	s_setprio 1
	v_mfma_f32_16x16x32_bf16 v[60:63], v[146:149], v[178:181], v[60:63]
	v_mfma_f32_16x16x32_bf16 v[56:59], v[154:157], v[178:181], v[56:59]
	v_mfma_f32_16x16x32_bf16 v[44:47], v[146:149], v[186:189], v[44:47]
	v_mfma_f32_16x16x32_bf16 v[40:43], v[154:157], v[186:189], v[40:43]
	v_mfma_f32_16x16x32_bf16 v[28:31], v[146:149], v[194:197], v[28:31]
	v_mfma_f32_16x16x32_bf16 v[24:27], v[154:157], v[194:197], v[24:27]
	v_mfma_f32_16x16x32_bf16 v[12:15], v[146:149], v[210:213], v[12:15]
	v_mfma_f32_16x16x32_bf16 v[8:11], v[154:157], v[210:213], v[8:11]
	v_mfma_f32_16x16x32_bf16 v[60:63], v[150:153], v[182:185], v[60:63]
	v_mfma_f32_16x16x32_bf16 v[56:59], v[158:161], v[182:185], v[56:59]
	v_mfma_f32_16x16x32_bf16 v[44:47], v[150:153], v[190:193], v[44:47]
	v_mfma_f32_16x16x32_bf16 v[40:43], v[158:161], v[190:193], v[40:43]
	v_mfma_f32_16x16x32_bf16 v[28:31], v[150:153], v[198:201], v[28:31]
	v_mfma_f32_16x16x32_bf16 v[24:27], v[158:161], v[198:201], v[24:27]
	v_mfma_f32_16x16x32_bf16 v[12:15], v[150:153], v[214:217], v[12:15]
	v_mfma_f32_16x16x32_bf16 v[8:11], v[158:161], v[214:217], v[8:11]
	s_setprio 0
	s_setprio 1
	v_mfma_f32_16x16x32_bf16 v[52:55], v[162:165], v[178:181], v[52:55]
	v_mfma_f32_16x16x32_bf16 v[48:51], v[170:173], v[178:181], v[48:51]
	v_mfma_f32_16x16x32_bf16 v[36:39], v[162:165], v[186:189], v[36:39]
	v_mfma_f32_16x16x32_bf16 v[32:35], v[170:173], v[186:189], v[32:35]
	v_mfma_f32_16x16x32_bf16 v[20:23], v[162:165], v[194:197], v[20:23]
	v_mfma_f32_16x16x32_bf16 v[16:19], v[170:173], v[194:197], v[16:19]
	v_mfma_f32_16x16x32_bf16 v[4:7], v[162:165], v[210:213], v[4:7]
	v_mfma_f32_16x16x32_bf16 v[0:3], v[170:173], v[210:213], v[0:3]
	v_mfma_f32_16x16x32_bf16 v[52:55], v[166:169], v[182:185], v[52:55]
	v_mfma_f32_16x16x32_bf16 v[48:51], v[174:177], v[182:185], v[48:51]
	v_mfma_f32_16x16x32_bf16 v[36:39], v[166:169], v[190:193], v[36:39]
	v_mfma_f32_16x16x32_bf16 v[32:35], v[174:177], v[190:193], v[32:35]
	v_mfma_f32_16x16x32_bf16 v[20:23], v[166:169], v[198:201], v[20:23]
	v_mfma_f32_16x16x32_bf16 v[16:19], v[174:177], v[198:201], v[16:19]
	v_mfma_f32_16x16x32_bf16 v[4:7], v[166:169], v[214:217], v[4:7]
	v_mfma_f32_16x16x32_bf16 v[0:3], v[174:177], v[214:217], v[0:3]
	s_setprio 0
	s_barrier
	s_add_i32 s29, s29, 2
	s_add_u32 s25, s25, 0x100
	s_addc_u32 s27, s27, 0
	s_add_u32 s38, s38, 0x100
	s_addc_u32 s39, s39, 0
	s_cmp_gt_u32 s29, 13
	s_cbranch_scc0 .LBB0_494
	s_and_b64 vcc, exec, s[12:13]
	s_cbranch_vccz .LBB0_497
	s_barrier

; #define PG8_STAGE(bufoff, gbase, voff) do { _Pragma("unroll") for (int _i = 0; _i < 2; ++_i) \
;         __builtin_amdgcn_global_load_lds((const unsigned*)((const char*)(gbase) + (voff)[_i]), (PG8_LAS unsigned*)(lds + (bufoff) + ldsw + _i * 8192), 16, 0, 0); } while (0)
; #define PG8_LDA(dst, b, h) do { _Pragma("unroll") for (int m = 0; m < 4; ++m) _Pragma("unroll") for (int k = 0; k < 2; ++k) dst[m][k] = *(const PG8_LAS bf16x8*)(lds + PG8_SA(b, h) + aoff + m * 2048 + k * 1024); } while (0)
; #define PG8_LDB(dst, b, h) do { _Pragma("unroll") for (int n = 0; n < 2; ++n) _Pragma("unroll") for (int k = 0; k < 2; ++k) dst[n][k] = *(const PG8_LAS bf16x8*)(lds + PG8_SB(b, h) + boff + n * 2048 + k * 1024); } while (0)
; #define PG8_MMA(ai, bj, At, Bt) do { __builtin_amdgcn_s_setprio(1); _Pragma("unroll") for (int m = 0; m < 4; ++m) _Pragma("unroll") for (int n = 0; n < 2; ++n) _Pragma("unroll") for (int k = 0; k < 2; ++k) \
;         acc[ai][bj][m][n] = __builtin_amdgcn_mfma_f32_16x16x32_bf16(Bt[n][k], At[m][k], acc[ai][bj][m][n], 0, 0, 0); __builtin_amdgcn_s_setprio(0); } while (0)
; #define PG8_WAIT_V(n) asm volatile("s_waitcnt vmcnt(" #n ")" ::: "memory")
; #define PG8_WAIT_L(n) asm volatile("s_waitcnt lgkmcnt(" #n ")" ::: "memory")
; #define PG8_BAR __builtin_amdgcn_s_barrier()
; #define PG8_SCHED __builtin_amdgcn_sched_barrier(0)
; template <class Epi, class Sched, bool ALIGN_EPI = false, bool SP2 = false>
; __device__ __forceinline__ void gemm_phase(PG8_LAS unsigned char* lds, const Gemm g, const Sched& S, const Epi& E, const int wv0) {
;     ...
;             const bool last = (t == nt - 2);
;             const char* a1 = cA + (size_t)(t + 1) * kstep;
;             const char* a2 = last ? nA : cA + (size_t)(t + 2) * kstep; const char* b2 = last ? nB : cB + (size_t)(t + 2) * kstep;
;             const char* a3 = a2 + kstep; const char* b3 = b2 + kstep;
;             if constexpr (SP2) {
;             PG8_LDB(B0, 0, 0); PG8_LDB(B1, 0, 1); PG8_SCHED; PG8_LDA(At, 0, 0); PG8_STAGE(PG8_SA(1, 1), a1 + hstepA, voffA);
;             PG8_WAIT_V(8); PG8_WAIT_L(0); PG8_BAR; PG8_MMA(0, 0, At, B0); PG8_MMA(0, 1, At, B1); PG8_BAR; PG8_SCHED;
;             PG8_LDA(At, 0, 1); PG8_STAGE(PG8_SB(0, 0), b2, voffB); PG8_STAGE(PG8_SB(0, 1), b2 + hstepB, voffB); PG8_STAGE(PG8_SA(0, 0), a2, voffA);
.LBB0_667:
	ds_read_b128 v[144:147], v153
	ds_read_b128 v[156:159], v153 offset:1024
	ds_read_b128 v[160:163], v153 offset:2048
	ds_read_b128 v[164:167], v153 offset:3072
	ds_read_b128 v[168:171], v154
	ds_read_b128 v[172:175], v154 offset:1024
	ds_read_b128 v[176:179], v154 offset:2048
	ds_read_b128 v[180:183], v154 offset:3072
	s_add_u32 s24, s22, 0xfff80080
	s_addc_u32 s25, s23, -1
	s_cmp_eq_u32 s50, 28
	s_cselect_b32 s27, s17, s25
	s_cselect_b32 s26, s16, s24
	s_cselect_b32 s25, s19, s15
	s_cselect_b32 s24, s18, s13
	v_lshl_add_u64 v[148:149], s[22:23], 0, v[138:139]
	s_add_i32 m0, s21, 0xc000
	ds_read_b128 v[184:187], v155
	ds_read_b128 v[188:191], v155 offset:1024
	ds_read_b128 v[192:195], v155 offset:2048
	ds_read_b128 v[196:199], v155 offset:3072
	ds_read_b128 v[200:203], v155 offset:4096
	ds_read_b128 v[206:209], v155 offset:5120
	ds_read_b128 v[210:213], v155 offset:6144
	ds_read_b128 v[214:217], v155 offset:7168
	global_load_lds_dwordx4 v[148:149], off
	v_lshl_add_u64 v[148:149], s[22:23], 0, v[136:137]
	s_add_i32 m0, s21, 0xe000
	s_nop 0
	global_load_lds_dwordx4 v[148:149], off
	s_waitcnt vmcnt(8)
	s_waitcnt lgkmcnt(0)
	s_barrier
	s_setprio 1
	v_mfma_f32_16x16x32_bf16 v[124:127], v[144:147], v[184:187], v[124:127]
	v_mfma_f32_16x16x32_bf16 v[120:123], v[160:163], v[184:187], v[120:123]
	v_mfma_f32_16x16x32_bf16 v[116:119], v[144:147], v[192:195], v[116:119]
	v_mfma_f32_16x16x32_bf16 v[112:115], v[160:163], v[192:195], v[112:115]
	v_mfma_f32_16x16x32_bf16 v[92:95], v[144:147], v[200:203], v[92:95]
	v_mfma_f32_16x16x32_bf16 v[88:91], v[160:163], v[200:203], v[88:91]
	v_mfma_f32_16x16x32_bf16 v[84:87], v[144:147], v[210:213], v[84:87]
	v_mfma_f32_16x16x32_bf16 v[80:83], v[160:163], v[210:213], v[80:83]
	v_mfma_f32_16x16x32_bf16 v[124:127], v[156:159], v[188:191], v[124:127]
	v_mfma_f32_16x16x32_bf16 v[120:123], v[164:167], v[188:191], v[120:123]
	v_mfma_f32_16x16x32_bf16 v[116:119], v[156:159], v[196:199], v[116:119]
	v_mfma_f32_16x16x32_bf16 v[112:115], v[164:167], v[196:199], v[112:115]
	v_mfma_f32_16x16x32_bf16 v[92:95], v[156:159], v[206:209], v[92:95]
	v_mfma_f32_16x16x32_bf16 v[88:91], v[164:167], v[206:209], v[88:91]
	v_mfma_f32_16x16x32_bf16 v[84:87], v[156:159], v[214:217], v[84:87]
	v_mfma_f32_16x16x32_bf16 v[80:83], v[164:167], v[214:217], v[80:83]
	s_setprio 0
	s_setprio 1
	v_mfma_f32_16x16x32_bf16 v[108:111], v[168:171], v[184:187], v[108:111]
	v_mfma_f32_16x16x32_bf16 v[104:107], v[176:179], v[184:187], v[104:107]
	v_mfma_f32_16x16x32_bf16 v[100:103], v[168:171], v[192:195], v[100:103]
	v_mfma_f32_16x16x32_bf16 v[96:99], v[176:179], v[192:195], v[96:99]
	v_mfma_f32_16x16x32_bf16 v[76:79], v[168:171], v[200:203], v[76:79]
	v_mfma_f32_16x16x32_bf16 v[72:75], v[176:179], v[200:203], v[72:75]
	v_mfma_f32_16x16x32_bf16 v[68:71], v[168:171], v[210:213], v[68:71]
	v_mfma_f32_16x16x32_bf16 v[64:67], v[176:179], v[210:213], v[64:67]
	v_mfma_f32_16x16x32_bf16 v[108:111], v[172:175], v[188:191], v[108:111]
	v_mfma_f32_16x16x32_bf16 v[104:107], v[180:183], v[188:191], v[104:107]
	v_mfma_f32_16x16x32_bf16 v[100:103], v[172:175], v[196:199], v[100:103]
	v_mfma_f32_16x16x32_bf16 v[96:99], v[180:183], v[196:199], v[96:99]
	v_mfma_f32_16x16x32_bf16 v[76:79], v[172:175], v[206:209], v[76:79]
	v_mfma_f32_16x16x32_bf16 v[72:75], v[180:183], v[206:209], v[72:75]
	v_mfma_f32_16x16x32_bf16 v[68:71], v[172:175], v[214:217], v[68:71]
	v_mfma_f32_16x16x32_bf16 v[64:67], v[180:183], v[214:217], v[64:67]
	s_setprio 0
	s_barrier
	s_add_i32 s51, s47, s37
	v_lshl_add_u64 v[148:149], s[24:25], 0, v[130:131]
	s_mov_b32 m0, s51
	ds_read_b128 v[184:187], v155 offset:16384
	ds_read_b128 v[188:191], v155 offset:17408
	ds_read_b128 v[192:195], v155 offset:18432
	ds_read_b128 v[196:199], v155 offset:19456
	ds_read_b128 v[200:203], v155 offset:20480
	ds_read_b128 v[206:209], v155 offset:21504
	ds_read_b128 v[210:213], v155 offset:22528
	ds_read_b128 v[214:217], v155 offset:23552
	global_load_lds_dwordx4 v[148:149], off
	s_add_i32 m0, s51, 0x2000
	s_add_u32 s52, s24, 0x80000
	v_lshl_add_u64 v[218:219], s[24:25], 0, v[134:135]
	s_addc_u32 s53, s25, 0
	s_add_i32 s51, s48, s37
	global_load_lds_dwordx4 v[218:219], off
	v_lshl_add_u64 v[220:221], s[52:53], 0, v[130:131]
	s_mov_b32 m0, s51
	v_lshl_add_u64 v[222:223], s[26:27], 0, v[132:133]
	global_load_lds_dwordx4 v[220:221], off
	v_lshl_add_u64 v[220:221], s[52:53], 0, v[134:135]
	s_add_i32 m0, s51, 0x2000
	s_nop 0
	global_load_lds_dwordx4 v[220:221], off
	v_lshl_add_u64 v[220:221], s[26:27], 0, v[128:129]
	s_mov_b32 m0, s21
	s_nop 0
	global_load_lds_dwordx4 v[220:221], off
	s_mov_b32 m0, s38
	s_nop 0
	global_load_lds_dwordx4 v[222:223], off
	s_waitcnt vmcnt(8)
	s_waitcnt lgkmcnt(0)
	s_barrier
; #define PG8_STAGE(bufoff, gbase, voff) do { _Pragma("unroll") for (int _i = 0; _i < 2; ++_i) \
;         __builtin_amdgcn_global_load_lds((const unsigned*)((const char*)(gbase) + (voff)[_i]), (PG8_LAS unsigned*)(lds + (bufoff) + ldsw + _i * 8192), 16, 0, 0); } while (0)
; #define PG8_LDA(dst, b, h) do { _Pragma("unroll") for (int m = 0; m < 4; ++m) _Pragma("unroll") for (int k = 0; k < 2; ++k) dst[m][k] = *(const PG8_LAS bf16x8*)(lds + PG8_SA(b, h) + aoff + m * 2048 + k * 1024); } while (0)
; #define PG8_LDB(dst, b, h) do { _Pragma("unroll") for (int n = 0; n < 2; ++n) _Pragma("unroll") for (int k = 0; k < 2; ++k) dst[n][k] = *(const PG8_LAS bf16x8*)(lds + PG8_SB(b, h) + boff + n * 2048 + k * 1024); } while (0)
; #define PG8_MMA(ai, bj, At, Bt) do { __builtin_amdgcn_s_setprio(1); _Pragma("unroll") for (int m = 0; m < 4; ++m) _Pragma("unroll") for (int n = 0; n < 2; ++n) _Pragma("unroll") for (int k = 0; k < 2; ++k) \
;         acc[ai][bj][m][n] = __builtin_amdgcn_mfma_f32_16x16x32_bf16(Bt[n][k], At[m][k], acc[ai][bj][m][n], 0, 0, 0); __builtin_amdgcn_s_setprio(0); } while (0)
; #define PG8_WAIT_V(n) asm volatile("s_waitcnt vmcnt(" #n ")" ::: "memory")
; #define PG8_WAIT_L(n) asm volatile("s_waitcnt lgkmcnt(" #n ")" ::: "memory")
; #define PG8_BAR __builtin_amdgcn_s_barrier()
; #define PG8_SCHED __builtin_amdgcn_sched_barrier(0)
; template <class Epi, class Sched, bool ALIGN_EPI = false, bool SP2 = false>
; __device__ __forceinline__ void gemm_phase(PG8_LAS unsigned char* lds, const Gemm g, const Sched& S, const Epi& E, const int wv0) {
;     ...
;             PG8_WAIT_V(8); PG8_WAIT_L(0); PG8_BAR; PG8_MMA(1, 0, At, B0); PG8_MMA(1, 1, At, B1); PG8_BAR; PG8_SCHED;
;             PG8_LDB(B0, 1, 0); PG8_LDB(B1, 1, 1); PG8_SCHED; PG8_LDA(At, 1, 0); PG8_STAGE(PG8_SA(0, 1), a2 + hstepA, voffA);
;             PG8_WAIT_V(8); PG8_WAIT_L(0); PG8_BAR; PG8_MMA(0, 0, At, B0); PG8_MMA(0, 1, At, B1); PG8_BAR; PG8_SCHED;
	s_setprio 1
	v_mfma_f32_16x16x32_bf16 v[60:63], v[144:147], v[184:187], v[60:63]
	v_mfma_f32_16x16x32_bf16 v[56:59], v[160:163], v[184:187], v[56:59]
	v_mfma_f32_16x16x32_bf16 v[52:55], v[144:147], v[192:195], v[52:55]
	v_mfma_f32_16x16x32_bf16 v[48:51], v[160:163], v[192:195], v[48:51]
	v_mfma_f32_16x16x32_bf16 v[28:31], v[144:147], v[200:203], v[28:31]
	v_mfma_f32_16x16x32_bf16 v[24:27], v[160:163], v[200:203], v[24:27]
	v_mfma_f32_16x16x32_bf16 v[20:23], v[144:147], v[210:213], v[20:23]
	v_mfma_f32_16x16x32_bf16 v[16:19], v[160:163], v[210:213], v[16:19]
	v_mfma_f32_16x16x32_bf16 v[60:63], v[156:159], v[188:191], v[60:63]
	v_mfma_f32_16x16x32_bf16 v[56:59], v[164:167], v[188:191], v[56:59]
	v_mfma_f32_16x16x32_bf16 v[52:55], v[156:159], v[196:199], v[52:55]
	v_mfma_f32_16x16x32_bf16 v[48:51], v[164:167], v[196:199], v[48:51]
	v_mfma_f32_16x16x32_bf16 v[28:31], v[156:159], v[206:209], v[28:31]
	v_mfma_f32_16x16x32_bf16 v[24:27], v[164:167], v[206:209], v[24:27]
	v_mfma_f32_16x16x32_bf16 v[20:23], v[156:159], v[214:217], v[20:23]
	v_mfma_f32_16x16x32_bf16 v[16:19], v[164:167], v[214:217], v[16:19]
	s_setprio 0
	s_setprio 1
	v_mfma_f32_16x16x32_bf16 v[44:47], v[168:171], v[184:187], v[44:47]
	v_mfma_f32_16x16x32_bf16 v[40:43], v[176:179], v[184:187], v[40:43]
	v_mfma_f32_16x16x32_bf16 v[36:39], v[168:171], v[192:195], v[36:39]
	v_mfma_f32_16x16x32_bf16 v[32:35], v[176:179], v[192:195], v[32:35]
	v_mfma_f32_16x16x32_bf16 v[12:15], v[168:171], v[200:203], v[12:15]
	v_mfma_f32_16x16x32_bf16 v[8:11], v[176:179], v[200:203], v[8:11]
	v_mfma_f32_16x16x32_bf16 v[4:7], v[168:171], v[210:213], v[4:7]
	v_mfma_f32_16x16x32_bf16 v[0:3], v[176:179], v[210:213], v[0:3]
	v_mfma_f32_16x16x32_bf16 v[44:47], v[172:175], v[188:191], v[44:47]
	v_mfma_f32_16x16x32_bf16 v[40:43], v[180:183], v[188:191], v[40:43]
	v_mfma_f32_16x16x32_bf16 v[36:39], v[172:175], v[196:199], v[36:39]
	v_mfma_f32_16x16x32_bf16 v[32:35], v[180:183], v[196:199], v[32:35]
	v_mfma_f32_16x16x32_bf16 v[12:15], v[172:175], v[206:209], v[12:15]
	v_mfma_f32_16x16x32_bf16 v[8:11], v[180:183], v[206:209], v[8:11]
	v_mfma_f32_16x16x32_bf16 v[4:7], v[172:175], v[214:217], v[4:7]
	v_mfma_f32_16x16x32_bf16 v[0:3], v[180:183], v[214:217], v[0:3]
	s_setprio 0
	s_barrier
	s_add_i32 s51, 0, 0x18000
	s_add_i32 s52, 0, 0x1c000
	v_add_u32_e32 v164, s51, v151
	v_add_u32_e32 v180, s52, v151
	ds_read_b128 v[144:147], v164
	ds_read_b128 v[156:159], v164 offset:1024
	ds_read_b128 v[160:163], v164 offset:2048
	ds_read_b128 v[164:167], v164 offset:3072
	ds_read_b128 v[168:171], v180
	ds_read_b128 v[172:175], v180 offset:1024
	ds_read_b128 v[176:179], v180 offset:2048
	ds_read_b128 v[180:183], v180 offset:3072
	s_add_u32 s26, s26, 0x80000
	s_addc_u32 s27, s27, 0
	s_mov_b32 m0, s39
	v_lshl_add_u64 v[224:225], s[26:27], 0, v[128:129]
	ds_read_b128 v[184:187], v155 offset:32768
	ds_read_b128 v[188:191], v155 offset:33792
	ds_read_b128 v[192:195], v155 offset:34816
	ds_read_b128 v[196:199], v155 offset:35840
	ds_read_b128 v[200:203], v155 offset:36864
	ds_read_b128 v[206:209], v155 offset:37888
	ds_read_b128 v[210:213], v155 offset:38912
	ds_read_b128 v[214:217], v155 offset:39936
	global_load_lds_dwordx4 v[224:225], off
	v_lshl_add_u64 v[224:225], s[26:27], 0, v[132:133]
	s_mov_b32 m0, s40
	s_nop 0
	global_load_lds_dwordx4 v[224:225], off
	s_waitcnt vmcnt(8)
	s_waitcnt lgkmcnt(0)
	s_barrier
	s_setprio 1
	v_mfma_f32_16x16x32_bf16 v[124:127], v[144:147], v[184:187], v[124:127]
	v_mfma_f32_16x16x32_bf16 v[120:123], v[160:163], v[184:187], v[120:123]
	v_mfma_f32_16x16x32_bf16 v[116:119], v[144:147], v[192:195], v[116:119]
	v_mfma_f32_16x16x32_bf16 v[112:115], v[160:163], v[192:195], v[112:115]
	v_mfma_f32_16x16x32_bf16 v[92:95], v[144:147], v[200:203], v[92:95]
	v_mfma_f32_16x16x32_bf16 v[88:91], v[160:163], v[200:203], v[88:91]
	v_mfma_f32_16x16x32_bf16 v[84:87], v[144:147], v[210:213], v[84:87]
	v_mfma_f32_16x16x32_bf16 v[80:83], v[160:163], v[210:213], v[80:83]
	v_mfma_f32_16x16x32_bf16 v[124:127], v[156:159], v[188:191], v[124:127]
	v_mfma_f32_16x16x32_bf16 v[120:123], v[164:167], v[188:191], v[120:123]
	v_mfma_f32_16x16x32_bf16 v[116:119], v[156:159], v[196:199], v[116:119]
	v_mfma_f32_16x16x32_bf16 v[112:115], v[164:167], v[196:199], v[112:115]
	v_mfma_f32_16x16x32_bf16 v[92:95], v[156:159], v[206:209], v[92:95]
	v_mfma_f32_16x16x32_bf16 v[88:91], v[164:167], v[206:209], v[88:91]
	v_mfma_f32_16x16x32_bf16 v[84:87], v[156:159], v[214:217], v[84:87]
	v_mfma_f32_16x16x32_bf16 v[80:83], v[164:167], v[214:217], v[80:83]
	s_setprio 0
	s_setprio 1
	v_mfma_f32_16x16x32_bf16 v[108:111], v[168:171], v[184:187], v[108:111]
	v_mfma_f32_16x16x32_bf16 v[104:107], v[176:179], v[184:187], v[104:107]
	v_mfma_f32_16x16x32_bf16 v[100:103], v[168:171], v[192:195], v[100:103]
	v_mfma_f32_16x16x32_bf16 v[96:99], v[176:179], v[192:195], v[96:99]
	v_mfma_f32_16x16x32_bf16 v[76:79], v[168:171], v[200:203], v[76:79]
	v_mfma_f32_16x16x32_bf16 v[72:75], v[176:179], v[200:203], v[72:75]
	v_mfma_f32_16x16x32_bf16 v[68:71], v[168:171], v[210:213], v[68:71]
	v_mfma_f32_16x16x32_bf16 v[64:67], v[176:179], v[210:213], v[64:67]
	v_mfma_f32_16x16x32_bf16 v[108:111], v[172:175], v[188:191], v[108:111]
	v_mfma_f32_16x16x32_bf16 v[104:107], v[180:183], v[188:191], v[104:107]
	v_mfma_f32_16x16x32_bf16 v[100:103], v[172:175], v[196:199], v[100:103]
	v_mfma_f32_16x16x32_bf16 v[96:99], v[180:183], v[196:199], v[96:99]
	v_mfma_f32_16x16x32_bf16 v[76:79], v[172:175], v[206:209], v[76:79]
	v_mfma_f32_16x16x32_bf16 v[72:75], v[180:183], v[206:209], v[72:75]
	v_mfma_f32_16x16x32_bf16 v[68:71], v[172:175], v[214:217], v[68:71]
	v_mfma_f32_16x16x32_bf16 v[64:67], v[180:183], v[214:217], v[64:67]
	s_setprio 0
	s_barrier
; #define PG8_STAGE(bufoff, gbase, voff) do { _Pragma("unroll") for (int _i = 0; _i < 2; ++_i) \
;         __builtin_amdgcn_global_load_lds((const unsigned*)((const char*)(gbase) + (voff)[_i]), (PG8_LAS unsigned*)(lds + (bufoff) + ldsw + _i * 8192), 16, 0, 0); } while (0)
; #define PG8_LDA(dst, b, h) do { _Pragma("unroll") for (int m = 0; m < 4; ++m) _Pragma("unroll") for (int k = 0; k < 2; ++k) dst[m][k] = *(const PG8_LAS bf16x8*)(lds + PG8_SA(b, h) + aoff + m * 2048 + k * 1024); } while (0)
; #define PG8_MMA(ai, bj, At, Bt) do { __builtin_amdgcn_s_setprio(1); _Pragma("unroll") for (int m = 0; m < 4; ++m) _Pragma("unroll") for (int n = 0; n < 2; ++n) _Pragma("unroll") for (int k = 0; k < 2; ++k) \
;         acc[ai][bj][m][n] = __builtin_amdgcn_mfma_f32_16x16x32_bf16(Bt[n][k], At[m][k], acc[ai][bj][m][n], 0, 0, 0); __builtin_amdgcn_s_setprio(0); } while (0)
; #define PG8_WAIT_V(n) asm volatile("s_waitcnt vmcnt(" #n ")" ::: "memory")
; #define PG8_WAIT_L(n) asm volatile("s_waitcnt lgkmcnt(" #n ")" ::: "memory")
; #define PG8_BAR __builtin_amdgcn_s_barrier()
; #define PG8_SCHED __builtin_amdgcn_sched_barrier(0)
; template <class Epi, class Sched, bool ALIGN_EPI = false, bool SP2 = false>
; __device__ __forceinline__ void gemm_phase(PG8_LAS unsigned char* lds, const Gemm g, const Sched& S, const Epi& E, const int wv0) {
;     ...
;             PG8_LDA(At, 1, 1); PG8_STAGE(PG8_SB(1, 0), b3, voffB); PG8_STAGE(PG8_SB(1, 1), b3 + hstepB, voffB); PG8_STAGE(PG8_SA(1, 0), a3, voffA);
;             PG8_WAIT_V(8); PG8_WAIT_L(0); PG8_BAR; PG8_MMA(1, 0, At, B0); PG8_MMA(1, 1, At, B1); PG8_BAR; PG8_SCHED;
;     ...
;         if constexpr (ALIGN_EPI) { if (wr == 0) PG8_BAR; }
	s_add_i32 s26, s51, s37
	v_lshl_add_u64 v[148:149], v[148:149], 0, s[8:9]
	s_mov_b32 m0, s26
	ds_read_b128 v[184:187], v155 offset:49152
	ds_read_b128 v[188:191], v155 offset:50176
	ds_read_b128 v[192:195], v155 offset:51200
	ds_read_b128 v[196:199], v155 offset:52224
	ds_read_b128 v[200:203], v155 offset:53248
	ds_read_b128 v[206:209], v155 offset:54272
	ds_read_b128 v[210:213], v155 offset:55296
	ds_read_b128 v[214:217], v155 offset:56320
	global_load_lds_dwordx4 v[148:149], off
	s_add_i32 m0, s26, 0x2000
	s_add_u32 s24, s24, 0x80080
	v_lshl_add_u64 v[148:149], v[218:219], 0, s[8:9]
	s_addc_u32 s25, s25, 0
	s_add_i32 s26, s52, s37
	global_load_lds_dwordx4 v[148:149], off
	v_lshl_add_u64 v[148:149], s[24:25], 0, v[130:131]
	s_mov_b32 m0, s26
	s_nop 0
	global_load_lds_dwordx4 v[148:149], off
	v_lshl_add_u64 v[148:149], s[24:25], 0, v[134:135]
	s_add_i32 m0, s26, 0x2000
	s_nop 0
	global_load_lds_dwordx4 v[148:149], off
	v_lshl_add_u64 v[148:149], v[220:221], 0, s[8:9]
	s_mov_b32 m0, s44
	s_nop 0
	global_load_lds_dwordx4 v[148:149], off
	v_lshl_add_u64 v[148:149], v[222:223], 0, s[8:9]
	s_mov_b32 m0, s45
	s_nop 0
	global_load_lds_dwordx4 v[148:149], off
	s_waitcnt vmcnt(8)
	s_waitcnt lgkmcnt(0)
	s_barrier
	s_setprio 1
	v_mfma_f32_16x16x32_bf16 v[60:63], v[144:147], v[184:187], v[60:63]
	v_mfma_f32_16x16x32_bf16 v[56:59], v[160:163], v[184:187], v[56:59]
	v_mfma_f32_16x16x32_bf16 v[52:55], v[144:147], v[192:195], v[52:55]
	v_mfma_f32_16x16x32_bf16 v[48:51], v[160:163], v[192:195], v[48:51]
	v_mfma_f32_16x16x32_bf16 v[28:31], v[144:147], v[200:203], v[28:31]
	v_mfma_f32_16x16x32_bf16 v[24:27], v[160:163], v[200:203], v[24:27]
	v_mfma_f32_16x16x32_bf16 v[20:23], v[144:147], v[210:213], v[20:23]
	v_mfma_f32_16x16x32_bf16 v[16:19], v[160:163], v[210:213], v[16:19]
	v_mfma_f32_16x16x32_bf16 v[60:63], v[156:159], v[188:191], v[60:63]
	v_mfma_f32_16x16x32_bf16 v[56:59], v[164:167], v[188:191], v[56:59]
	v_mfma_f32_16x16x32_bf16 v[52:55], v[156:159], v[196:199], v[52:55]
	v_mfma_f32_16x16x32_bf16 v[48:51], v[164:167], v[196:199], v[48:51]
	v_mfma_f32_16x16x32_bf16 v[28:31], v[156:159], v[206:209], v[28:31]
	v_mfma_f32_16x16x32_bf16 v[24:27], v[164:167], v[206:209], v[24:27]
	v_mfma_f32_16x16x32_bf16 v[20:23], v[156:159], v[214:217], v[20:23]
	v_mfma_f32_16x16x32_bf16 v[16:19], v[164:167], v[214:217], v[16:19]
	s_setprio 0
	s_setprio 1
	v_mfma_f32_16x16x32_bf16 v[44:47], v[168:171], v[184:187], v[44:47]
	v_mfma_f32_16x16x32_bf16 v[40:43], v[176:179], v[184:187], v[40:43]
	v_mfma_f32_16x16x32_bf16 v[36:39], v[168:171], v[192:195], v[36:39]
	v_mfma_f32_16x16x32_bf16 v[32:35], v[176:179], v[192:195], v[32:35]
	v_mfma_f32_16x16x32_bf16 v[12:15], v[168:171], v[200:203], v[12:15]
	v_mfma_f32_16x16x32_bf16 v[8:11], v[176:179], v[200:203], v[8:11]
	v_mfma_f32_16x16x32_bf16 v[4:7], v[168:171], v[210:213], v[4:7]
	v_mfma_f32_16x16x32_bf16 v[0:3], v[176:179], v[210:213], v[0:3]
	v_mfma_f32_16x16x32_bf16 v[44:47], v[172:175], v[188:191], v[44:47]
	v_mfma_f32_16x16x32_bf16 v[40:43], v[180:183], v[188:191], v[40:43]
	v_mfma_f32_16x16x32_bf16 v[36:39], v[172:175], v[196:199], v[36:39]
	v_mfma_f32_16x16x32_bf16 v[32:35], v[180:183], v[196:199], v[32:35]
	v_mfma_f32_16x16x32_bf16 v[12:15], v[172:175], v[206:209], v[12:15]
	v_mfma_f32_16x16x32_bf16 v[8:11], v[180:183], v[206:209], v[8:11]
	v_mfma_f32_16x16x32_bf16 v[4:7], v[172:175], v[214:217], v[4:7]
	v_mfma_f32_16x16x32_bf16 v[0:3], v[180:183], v[214:217], v[0:3]
	s_setprio 0
	s_barrier
	s_add_i32 s50, s50, 2
	s_add_u32 s13, s13, 0x100
	s_addc_u32 s15, s15, 0
	s_add_u32 s22, s22, 0x100
	s_addc_u32 s23, s23, 0
	s_cmp_gt_u32 s50, 29
	s_cbranch_scc0 .LBB0_667
	s_and_b64 vcc, exec, s[10:11]
	s_cbranch_vccz .LBB0_670
	s_barrier

; #define PG8_STAGE(bufoff, gbase, voff) do { _Pragma("unroll") for (int _i = 0; _i < 2; ++_i) \
;         __builtin_amdgcn_global_load_lds((const unsigned*)((const char*)(gbase) + (voff)[_i]), (PG8_LAS unsigned*)(lds + (bufoff) + ldsw + _i * 8192), 16, 0, 0); } while (0)
; #define PG8_LDA(dst, b, h) do { _Pragma("unroll") for (int m = 0; m < 4; ++m) _Pragma("unroll") for (int k = 0; k < 2; ++k) dst[m][k] = *(const PG8_LAS bf16x8*)(lds + PG8_SA(b, h) + aoff + m * 2048 + k * 1024); } while (0)
; #define PG8_LDB(dst, b, h) do { _Pragma("unroll") for (int n = 0; n < 2; ++n) _Pragma("unroll") for (int k = 0; k < 2; ++k) dst[n][k] = *(const PG8_LAS bf16x8*)(lds + PG8_SB(b, h) + boff + n * 2048 + k * 1024); } while (0)
; #define PG8_MMA(ai, bj, At, Bt) do { __builtin_amdgcn_s_setprio(1); _Pragma("unroll") for (int m = 0; m < 4; ++m) _Pragma("unroll") for (int n = 0; n < 2; ++n) _Pragma("unroll") for (int k = 0; k < 2; ++k) \
;         acc[ai][bj][m][n] = __builtin_amdgcn_mfma_f32_16x16x32_bf16(Bt[n][k], At[m][k], acc[ai][bj][m][n], 0, 0, 0); __builtin_amdgcn_s_setprio(0); } while (0)
; #define PG8_WAIT_V(n) asm volatile("s_waitcnt vmcnt(" #n ")" ::: "memory")
; #define PG8_WAIT_L(n) asm volatile("s_waitcnt lgkmcnt(" #n ")" ::: "memory")
; #define PG8_BAR __builtin_amdgcn_s_barrier()
; #define PG8_SCHED __builtin_amdgcn_sched_barrier(0)
; template <class Epi, class Sched, bool ALIGN_EPI = false, bool SP2 = false>
; __device__ __forceinline__ void gemm_phase(PG8_LAS unsigned char* lds, const Gemm g, const Sched& S, const Epi& E, const int wv0) {
;     ...
;             const bool last = (t == nt - 2);
;             const char* a1 = cA + (size_t)(t + 1) * kstep;
;             const char* a2 = last ? nA : cA + (size_t)(t + 2) * kstep; const char* b2 = last ? nB : cB + (size_t)(t + 2) * kstep;
;             const char* a3 = a2 + kstep; const char* b3 = b2 + kstep;
;             if constexpr (SP2) {
;             PG8_LDB(B0, 0, 0); PG8_LDB(B1, 0, 1); PG8_SCHED; PG8_LDA(At, 0, 0); PG8_STAGE(PG8_SA(1, 1), a1 + hstepA, voffA);
;             PG8_WAIT_V(8); PG8_WAIT_L(0); PG8_BAR; PG8_MMA(0, 0, At, B0); PG8_MMA(0, 1, At, B1); PG8_BAR; PG8_SCHED;
;             PG8_LDA(At, 0, 1); PG8_STAGE(PG8_SB(0, 0), b2, voffB); PG8_STAGE(PG8_SB(0, 1), b2 + hstepB, voffB); PG8_STAGE(PG8_SA(0, 0), a2, voffA);
.LBB0_790:
	ds_read_b128 v[152:155], v149
	ds_read_b128 v[156:159], v149 offset:1024
	ds_read_b128 v[160:163], v149 offset:2048
	ds_read_b128 v[164:167], v149 offset:3072
	ds_read_b128 v[168:171], v150
	ds_read_b128 v[172:175], v150 offset:1024
	ds_read_b128 v[176:179], v150 offset:2048
	ds_read_b128 v[180:183], v150 offset:3072
	s_add_u32 s22, s20, 0xfff80080
	s_addc_u32 s23, s21, -1
	s_cmp_eq_u32 s50, 28
	s_cselect_b32 s25, s15, s23
	s_cselect_b32 s24, s14, s22
	s_cselect_b32 s23, s17, s13
	s_cselect_b32 s22, s16, s11
	v_lshl_add_u64 v[144:145], s[20:21], 0, v[138:139]
	s_add_i32 m0, s19, 0xc000
	ds_read_b128 v[184:187], v151
	ds_read_b128 v[188:191], v151 offset:1024
	ds_read_b128 v[192:195], v151 offset:2048
	ds_read_b128 v[196:199], v151 offset:3072
	ds_read_b128 v[200:203], v151 offset:4096
	ds_read_b128 v[206:209], v151 offset:5120
	ds_read_b128 v[210:213], v151 offset:6144
	ds_read_b128 v[214:217], v151 offset:7168
	global_load_lds_dwordx4 v[144:145], off
	v_lshl_add_u64 v[144:145], s[20:21], 0, v[136:137]
	s_add_i32 m0, s19, 0xe000
	s_nop 0
	global_load_lds_dwordx4 v[144:145], off
	s_waitcnt vmcnt(8)
	s_waitcnt lgkmcnt(0)
	s_barrier
	s_setprio 1
	v_mfma_f32_16x16x32_bf16 v[124:127], v[152:155], v[184:187], v[124:127]
	v_mfma_f32_16x16x32_bf16 v[120:123], v[160:163], v[184:187], v[120:123]
	v_mfma_f32_16x16x32_bf16 v[108:111], v[152:155], v[192:195], v[108:111]
	v_mfma_f32_16x16x32_bf16 v[104:107], v[160:163], v[192:195], v[104:107]
	v_mfma_f32_16x16x32_bf16 v[92:95], v[152:155], v[200:203], v[92:95]
	v_mfma_f32_16x16x32_bf16 v[88:91], v[160:163], v[200:203], v[88:91]
	v_mfma_f32_16x16x32_bf16 v[76:79], v[152:155], v[210:213], v[76:79]
	v_mfma_f32_16x16x32_bf16 v[72:75], v[160:163], v[210:213], v[72:75]
	v_mfma_f32_16x16x32_bf16 v[124:127], v[156:159], v[188:191], v[124:127]
	v_mfma_f32_16x16x32_bf16 v[120:123], v[164:167], v[188:191], v[120:123]
	v_mfma_f32_16x16x32_bf16 v[108:111], v[156:159], v[196:199], v[108:111]
	v_mfma_f32_16x16x32_bf16 v[104:107], v[164:167], v[196:199], v[104:107]
	v_mfma_f32_16x16x32_bf16 v[92:95], v[156:159], v[206:209], v[92:95]
	v_mfma_f32_16x16x32_bf16 v[88:91], v[164:167], v[206:209], v[88:91]
	v_mfma_f32_16x16x32_bf16 v[76:79], v[156:159], v[214:217], v[76:79]
	v_mfma_f32_16x16x32_bf16 v[72:75], v[164:167], v[214:217], v[72:75]
	s_setprio 0
	s_setprio 1
	v_mfma_f32_16x16x32_bf16 v[116:119], v[168:171], v[184:187], v[116:119]
	v_mfma_f32_16x16x32_bf16 v[112:115], v[176:179], v[184:187], v[112:115]
	v_mfma_f32_16x16x32_bf16 v[100:103], v[168:171], v[192:195], v[100:103]
	v_mfma_f32_16x16x32_bf16 v[96:99], v[176:179], v[192:195], v[96:99]
	v_mfma_f32_16x16x32_bf16 v[84:87], v[168:171], v[200:203], v[84:87]
	v_mfma_f32_16x16x32_bf16 v[80:83], v[176:179], v[200:203], v[80:83]
	v_mfma_f32_16x16x32_bf16 v[68:71], v[168:171], v[210:213], v[68:71]
	v_mfma_f32_16x16x32_bf16 v[64:67], v[176:179], v[210:213], v[64:67]
	v_mfma_f32_16x16x32_bf16 v[116:119], v[172:175], v[188:191], v[116:119]
	v_mfma_f32_16x16x32_bf16 v[112:115], v[180:183], v[188:191], v[112:115]
	v_mfma_f32_16x16x32_bf16 v[100:103], v[172:175], v[196:199], v[100:103]
	v_mfma_f32_16x16x32_bf16 v[96:99], v[180:183], v[196:199], v[96:99]
	v_mfma_f32_16x16x32_bf16 v[84:87], v[172:175], v[206:209], v[84:87]
	v_mfma_f32_16x16x32_bf16 v[80:83], v[180:183], v[206:209], v[80:83]
	v_mfma_f32_16x16x32_bf16 v[68:71], v[172:175], v[214:217], v[68:71]
	v_mfma_f32_16x16x32_bf16 v[64:67], v[180:183], v[214:217], v[64:67]
	s_setprio 0
	s_barrier
	s_add_i32 s51, s46, s35
	v_lshl_add_u64 v[144:145], s[22:23], 0, v[132:133]
	s_mov_b32 m0, s51
	ds_read_b128 v[184:187], v151 offset:16384
	ds_read_b128 v[188:191], v151 offset:17408
	ds_read_b128 v[192:195], v151 offset:18432
	ds_read_b128 v[196:199], v151 offset:19456
	ds_read_b128 v[200:203], v151 offset:20480
	ds_read_b128 v[206:209], v151 offset:21504
	ds_read_b128 v[210:213], v151 offset:22528
	ds_read_b128 v[214:217], v151 offset:23552
	global_load_lds_dwordx4 v[144:145], off
	s_add_i32 m0, s51, 0x2000
	s_add_u32 s52, s22, 0x80000
	v_lshl_add_u64 v[218:219], s[22:23], 0, v[128:129]
	s_addc_u32 s53, s23, 0
	s_add_i32 s51, s47, s35
	global_load_lds_dwordx4 v[218:219], off
	v_lshl_add_u64 v[220:221], s[52:53], 0, v[132:133]
	s_mov_b32 m0, s51
	v_lshl_add_u64 v[222:223], s[24:25], 0, v[130:131]
	global_load_lds_dwordx4 v[220:221], off
	v_lshl_add_u64 v[220:221], s[52:53], 0, v[128:129]
	s_add_i32 m0, s51, 0x2000
	s_nop 0
	global_load_lds_dwordx4 v[220:221], off
	v_lshl_add_u64 v[220:221], s[24:25], 0, v[134:135]
	s_mov_b32 m0, s19
	s_nop 0
	global_load_lds_dwordx4 v[220:221], off
	s_mov_b32 m0, s37
	s_nop 0
	global_load_lds_dwordx4 v[222:223], off
	s_waitcnt vmcnt(8)
	s_waitcnt lgkmcnt(0)
	s_barrier
; #define PG8_STAGE(bufoff, gbase, voff) do { _Pragma("unroll") for (int _i = 0; _i < 2; ++_i) \
;         __builtin_amdgcn_global_load_lds((const unsigned*)((const char*)(gbase) + (voff)[_i]), (PG8_LAS unsigned*)(lds + (bufoff) + ldsw + _i * 8192), 16, 0, 0); } while (0)
; #define PG8_LDA(dst, b, h) do { _Pragma("unroll") for (int m = 0; m < 4; ++m) _Pragma("unroll") for (int k = 0; k < 2; ++k) dst[m][k] = *(const PG8_LAS bf16x8*)(lds + PG8_SA(b, h) + aoff + m * 2048 + k * 1024); } while (0)
; #define PG8_LDB(dst, b, h) do { _Pragma("unroll") for (int n = 0; n < 2; ++n) _Pragma("unroll") for (int k = 0; k < 2; ++k) dst[n][k] = *(const PG8_LAS bf16x8*)(lds + PG8_SB(b, h) + boff + n * 2048 + k * 1024); } while (0)
; #define PG8_MMA(ai, bj, At, Bt) do { __builtin_amdgcn_s_setprio(1); _Pragma("unroll") for (int m = 0; m < 4; ++m) _Pragma("unroll") for (int n = 0; n < 2; ++n) _Pragma("unroll") for (int k = 0; k < 2; ++k) \
;         acc[ai][bj][m][n] = __builtin_amdgcn_mfma_f32_16x16x32_bf16(Bt[n][k], At[m][k], acc[ai][bj][m][n], 0, 0, 0); __builtin_amdgcn_s_setprio(0); } while (0)
; #define PG8_WAIT_V(n) asm volatile("s_waitcnt vmcnt(" #n ")" ::: "memory")
; #define PG8_WAIT_L(n) asm volatile("s_waitcnt lgkmcnt(" #n ")" ::: "memory")
; #define PG8_BAR __builtin_amdgcn_s_barrier()
; #define PG8_SCHED __builtin_amdgcn_sched_barrier(0)
; template <class Epi, class Sched, bool ALIGN_EPI = false, bool SP2 = false>
; __device__ __forceinline__ void gemm_phase(PG8_LAS unsigned char* lds, const Gemm g, const Sched& S, const Epi& E, const int wv0) {
;     ...
;             PG8_WAIT_V(8); PG8_WAIT_L(0); PG8_BAR; PG8_MMA(1, 0, At, B0); PG8_MMA(1, 1, At, B1); PG8_BAR; PG8_SCHED;
;             PG8_LDB(B0, 1, 0); PG8_LDB(B1, 1, 1); PG8_SCHED; PG8_LDA(At, 1, 0); PG8_STAGE(PG8_SA(0, 1), a2 + hstepA, voffA);
;             PG8_WAIT_V(8); PG8_WAIT_L(0); PG8_BAR; PG8_MMA(0, 0, At, B0); PG8_MMA(0, 1, At, B1); PG8_BAR; PG8_SCHED;
	s_setprio 1
	v_mfma_f32_16x16x32_bf16 v[60:63], v[152:155], v[184:187], v[60:63]
	v_mfma_f32_16x16x32_bf16 v[56:59], v[160:163], v[184:187], v[56:59]
	v_mfma_f32_16x16x32_bf16 v[44:47], v[152:155], v[192:195], v[44:47]
	v_mfma_f32_16x16x32_bf16 v[40:43], v[160:163], v[192:195], v[40:43]
	v_mfma_f32_16x16x32_bf16 v[28:31], v[152:155], v[200:203], v[28:31]
	v_mfma_f32_16x16x32_bf16 v[24:27], v[160:163], v[200:203], v[24:27]
	v_mfma_f32_16x16x32_bf16 v[12:15], v[152:155], v[210:213], v[12:15]
	v_mfma_f32_16x16x32_bf16 v[8:11], v[160:163], v[210:213], v[8:11]
	v_mfma_f32_16x16x32_bf16 v[60:63], v[156:159], v[188:191], v[60:63]
	v_mfma_f32_16x16x32_bf16 v[56:59], v[164:167], v[188:191], v[56:59]
	v_mfma_f32_16x16x32_bf16 v[44:47], v[156:159], v[196:199], v[44:47]
	v_mfma_f32_16x16x32_bf16 v[40:43], v[164:167], v[196:199], v[40:43]
	v_mfma_f32_16x16x32_bf16 v[28:31], v[156:159], v[206:209], v[28:31]
	v_mfma_f32_16x16x32_bf16 v[24:27], v[164:167], v[206:209], v[24:27]
	v_mfma_f32_16x16x32_bf16 v[12:15], v[156:159], v[214:217], v[12:15]
	v_mfma_f32_16x16x32_bf16 v[8:11], v[164:167], v[214:217], v[8:11]
	s_setprio 0
	s_setprio 1
	v_mfma_f32_16x16x32_bf16 v[52:55], v[168:171], v[184:187], v[52:55]
	v_mfma_f32_16x16x32_bf16 v[48:51], v[176:179], v[184:187], v[48:51]
	v_mfma_f32_16x16x32_bf16 v[36:39], v[168:171], v[192:195], v[36:39]
	v_mfma_f32_16x16x32_bf16 v[32:35], v[176:179], v[192:195], v[32:35]
	v_mfma_f32_16x16x32_bf16 v[20:23], v[168:171], v[200:203], v[20:23]
	v_mfma_f32_16x16x32_bf16 v[16:19], v[176:179], v[200:203], v[16:19]
	v_mfma_f32_16x16x32_bf16 v[4:7], v[168:171], v[210:213], v[4:7]
	v_mfma_f32_16x16x32_bf16 v[0:3], v[176:179], v[210:213], v[0:3]
	v_mfma_f32_16x16x32_bf16 v[52:55], v[172:175], v[188:191], v[52:55]
	v_mfma_f32_16x16x32_bf16 v[48:51], v[180:183], v[188:191], v[48:51]
	v_mfma_f32_16x16x32_bf16 v[36:39], v[172:175], v[196:199], v[36:39]
	v_mfma_f32_16x16x32_bf16 v[32:35], v[180:183], v[196:199], v[32:35]
	v_mfma_f32_16x16x32_bf16 v[20:23], v[172:175], v[206:209], v[20:23]
	v_mfma_f32_16x16x32_bf16 v[16:19], v[180:183], v[206:209], v[16:19]
	v_mfma_f32_16x16x32_bf16 v[4:7], v[172:175], v[214:217], v[4:7]
	v_mfma_f32_16x16x32_bf16 v[0:3], v[180:183], v[214:217], v[0:3]
	s_setprio 0
	s_barrier
	s_add_i32 s51, 0, 0x18000
	s_add_i32 s52, 0, 0x1c000
	v_add_u32_e32 v164, s51, v147
	v_add_u32_e32 v180, s52, v147
	ds_read_b128 v[152:155], v164
	ds_read_b128 v[156:159], v164 offset:1024
	ds_read_b128 v[160:163], v164 offset:2048
	ds_read_b128 v[164:167], v164 offset:3072
	ds_read_b128 v[168:171], v180
	ds_read_b128 v[172:175], v180 offset:1024
	ds_read_b128 v[176:179], v180 offset:2048
	ds_read_b128 v[180:183], v180 offset:3072
	s_add_u32 s24, s24, 0x80000
	s_addc_u32 s25, s25, 0
	s_mov_b32 m0, s38
	v_lshl_add_u64 v[224:225], s[24:25], 0, v[134:135]
	ds_read_b128 v[184:187], v151 offset:32768
	ds_read_b128 v[188:191], v151 offset:33792
	ds_read_b128 v[192:195], v151 offset:34816
	ds_read_b128 v[196:199], v151 offset:35840
	ds_read_b128 v[200:203], v151 offset:36864
	ds_read_b128 v[206:209], v151 offset:37888
	ds_read_b128 v[210:213], v151 offset:38912
	ds_read_b128 v[214:217], v151 offset:39936
	global_load_lds_dwordx4 v[224:225], off
	v_lshl_add_u64 v[224:225], s[24:25], 0, v[130:131]
	s_mov_b32 m0, s39
	s_nop 0
	global_load_lds_dwordx4 v[224:225], off
	s_waitcnt vmcnt(8)
	s_waitcnt lgkmcnt(0)
	s_barrier
	s_setprio 1
	v_mfma_f32_16x16x32_bf16 v[124:127], v[152:155], v[184:187], v[124:127]
	v_mfma_f32_16x16x32_bf16 v[120:123], v[160:163], v[184:187], v[120:123]
	v_mfma_f32_16x16x32_bf16 v[108:111], v[152:155], v[192:195], v[108:111]
	v_mfma_f32_16x16x32_bf16 v[104:107], v[160:163], v[192:195], v[104:107]
	v_mfma_f32_16x16x32_bf16 v[92:95], v[152:155], v[200:203], v[92:95]
	v_mfma_f32_16x16x32_bf16 v[88:91], v[160:163], v[200:203], v[88:91]
	v_mfma_f32_16x16x32_bf16 v[76:79], v[152:155], v[210:213], v[76:79]
	v_mfma_f32_16x16x32_bf16 v[72:75], v[160:163], v[210:213], v[72:75]
	v_mfma_f32_16x16x32_bf16 v[124:127], v[156:159], v[188:191], v[124:127]
	v_mfma_f32_16x16x32_bf16 v[120:123], v[164:167], v[188:191], v[120:123]
	v_mfma_f32_16x16x32_bf16 v[108:111], v[156:159], v[196:199], v[108:111]
	v_mfma_f32_16x16x32_bf16 v[104:107], v[164:167], v[196:199], v[104:107]
	v_mfma_f32_16x16x32_bf16 v[92:95], v[156:159], v[206:209], v[92:95]
	v_mfma_f32_16x16x32_bf16 v[88:91], v[164:167], v[206:209], v[88:91]
	v_mfma_f32_16x16x32_bf16 v[76:79], v[156:159], v[214:217], v[76:79]
	v_mfma_f32_16x16x32_bf16 v[72:75], v[164:167], v[214:217], v[72:75]
	s_setprio 0
	s_setprio 1
	v_mfma_f32_16x16x32_bf16 v[116:119], v[168:171], v[184:187], v[116:119]
	v_mfma_f32_16x16x32_bf16 v[112:115], v[176:179], v[184:187], v[112:115]
	v_mfma_f32_16x16x32_bf16 v[100:103], v[168:171], v[192:195], v[100:103]
	v_mfma_f32_16x16x32_bf16 v[96:99], v[176:179], v[192:195], v[96:99]
	v_mfma_f32_16x16x32_bf16 v[84:87], v[168:171], v[200:203], v[84:87]
	v_mfma_f32_16x16x32_bf16 v[80:83], v[176:179], v[200:203], v[80:83]
	v_mfma_f32_16x16x32_bf16 v[68:71], v[168:171], v[210:213], v[68:71]
	v_mfma_f32_16x16x32_bf16 v[64:67], v[176:179], v[210:213], v[64:67]
	v_mfma_f32_16x16x32_bf16 v[116:119], v[172:175], v[188:191], v[116:119]
	v_mfma_f32_16x16x32_bf16 v[112:115], v[180:183], v[188:191], v[112:115]
	v_mfma_f32_16x16x32_bf16 v[100:103], v[172:175], v[196:199], v[100:103]
	v_mfma_f32_16x16x32_bf16 v[96:99], v[180:183], v[196:199], v[96:99]
	v_mfma_f32_16x16x32_bf16 v[84:87], v[172:175], v[206:209], v[84:87]
	v_mfma_f32_16x16x32_bf16 v[80:83], v[180:183], v[206:209], v[80:83]
	v_mfma_f32_16x16x32_bf16 v[68:71], v[172:175], v[214:217], v[68:71]
	v_mfma_f32_16x16x32_bf16 v[64:67], v[180:183], v[214:217], v[64:67]
	s_setprio 0
	s_barrier
; #define PG8_STAGE(bufoff, gbase, voff) do { _Pragma("unroll") for (int _i = 0; _i < 2; ++_i) \
;         __builtin_amdgcn_global_load_lds((const unsigned*)((const char*)(gbase) + (voff)[_i]), (PG8_LAS unsigned*)(lds + (bufoff) + ldsw + _i * 8192), 16, 0, 0); } while (0)
; #define PG8_LDA(dst, b, h) do { _Pragma("unroll") for (int m = 0; m < 4; ++m) _Pragma("unroll") for (int k = 0; k < 2; ++k) dst[m][k] = *(const PG8_LAS bf16x8*)(lds + PG8_SA(b, h) + aoff + m * 2048 + k * 1024); } while (0)
; #define PG8_MMA(ai, bj, At, Bt) do { __builtin_amdgcn_s_setprio(1); _Pragma("unroll") for (int m = 0; m < 4; ++m) _Pragma("unroll") for (int n = 0; n < 2; ++n) _Pragma("unroll") for (int k = 0; k < 2; ++k) \
;         acc[ai][bj][m][n] = __builtin_amdgcn_mfma_f32_16x16x32_bf16(Bt[n][k], At[m][k], acc[ai][bj][m][n], 0, 0, 0); __builtin_amdgcn_s_setprio(0); } while (0)
; #define PG8_WAIT_V(n) asm volatile("s_waitcnt vmcnt(" #n ")" ::: "memory")
; #define PG8_WAIT_L(n) asm volatile("s_waitcnt lgkmcnt(" #n ")" ::: "memory")
; #define PG8_BAR __builtin_amdgcn_s_barrier()
; #define PG8_SCHED __builtin_amdgcn_sched_barrier(0)
; template <class Epi, class Sched, bool ALIGN_EPI = false, bool SP2 = false>
; __device__ __forceinline__ void gemm_phase(PG8_LAS unsigned char* lds, const Gemm g, const Sched& S, const Epi& E, const int wv0) {
;     ...
;             PG8_LDA(At, 1, 1); PG8_STAGE(PG8_SB(1, 0), b3, voffB); PG8_STAGE(PG8_SB(1, 1), b3 + hstepB, voffB); PG8_STAGE(PG8_SA(1, 0), a3, voffA);
;             PG8_WAIT_V(8); PG8_WAIT_L(0); PG8_BAR; PG8_MMA(1, 0, At, B0); PG8_MMA(1, 1, At, B1); PG8_BAR; PG8_SCHED;
;     ...
;         if constexpr (ALIGN_EPI) { if (wr == 0) PG8_BAR; }
	s_add_i32 s24, s51, s35
	v_lshl_add_u64 v[144:145], v[144:145], 0, s[6:7]
	s_mov_b32 m0, s24
	ds_read_b128 v[184:187], v151 offset:49152
	ds_read_b128 v[188:191], v151 offset:50176
	ds_read_b128 v[192:195], v151 offset:51200
	ds_read_b128 v[196:199], v151 offset:52224
	ds_read_b128 v[200:203], v151 offset:53248
	ds_read_b128 v[206:209], v151 offset:54272
	ds_read_b128 v[210:213], v151 offset:55296
	ds_read_b128 v[214:217], v151 offset:56320
	global_load_lds_dwordx4 v[144:145], off
	s_add_i32 m0, s24, 0x2000
	s_add_u32 s22, s22, 0x80080
	v_lshl_add_u64 v[144:145], v[218:219], 0, s[6:7]
	s_addc_u32 s23, s23, 0
	s_add_i32 s24, s52, s35
	global_load_lds_dwordx4 v[144:145], off
	v_lshl_add_u64 v[144:145], s[22:23], 0, v[132:133]
	s_mov_b32 m0, s24
	s_nop 0
	global_load_lds_dwordx4 v[144:145], off
	v_lshl_add_u64 v[144:145], s[22:23], 0, v[128:129]
	s_add_i32 m0, s24, 0x2000
	s_nop 0
	global_load_lds_dwordx4 v[144:145], off
	v_lshl_add_u64 v[144:145], v[220:221], 0, s[6:7]
	s_mov_b32 m0, s41
	s_nop 0
	global_load_lds_dwordx4 v[144:145], off
	v_lshl_add_u64 v[144:145], v[222:223], 0, s[6:7]
	s_mov_b32 m0, s44
	s_nop 0
	global_load_lds_dwordx4 v[144:145], off
	s_waitcnt vmcnt(8)
	s_waitcnt lgkmcnt(0)
	s_barrier
	s_setprio 1
	v_mfma_f32_16x16x32_bf16 v[60:63], v[152:155], v[184:187], v[60:63]
	v_mfma_f32_16x16x32_bf16 v[56:59], v[160:163], v[184:187], v[56:59]
	v_mfma_f32_16x16x32_bf16 v[44:47], v[152:155], v[192:195], v[44:47]
	v_mfma_f32_16x16x32_bf16 v[40:43], v[160:163], v[192:195], v[40:43]
	v_mfma_f32_16x16x32_bf16 v[28:31], v[152:155], v[200:203], v[28:31]
	v_mfma_f32_16x16x32_bf16 v[24:27], v[160:163], v[200:203], v[24:27]
	v_mfma_f32_16x16x32_bf16 v[12:15], v[152:155], v[210:213], v[12:15]
	v_mfma_f32_16x16x32_bf16 v[8:11], v[160:163], v[210:213], v[8:11]
	v_mfma_f32_16x16x32_bf16 v[60:63], v[156:159], v[188:191], v[60:63]
	v_mfma_f32_16x16x32_bf16 v[56:59], v[164:167], v[188:191], v[56:59]
	v_mfma_f32_16x16x32_bf16 v[44:47], v[156:159], v[196:199], v[44:47]
	v_mfma_f32_16x16x32_bf16 v[40:43], v[164:167], v[196:199], v[40:43]
	v_mfma_f32_16x16x32_bf16 v[28:31], v[156:159], v[206:209], v[28:31]
	v_mfma_f32_16x16x32_bf16 v[24:27], v[164:167], v[206:209], v[24:27]
	v_mfma_f32_16x16x32_bf16 v[12:15], v[156:159], v[214:217], v[12:15]
	v_mfma_f32_16x16x32_bf16 v[8:11], v[164:167], v[214:217], v[8:11]
	s_setprio 0
	s_setprio 1
	v_mfma_f32_16x16x32_bf16 v[52:55], v[168:171], v[184:187], v[52:55]
	v_mfma_f32_16x16x32_bf16 v[48:51], v[176:179], v[184:187], v[48:51]
	v_mfma_f32_16x16x32_bf16 v[36:39], v[168:171], v[192:195], v[36:39]
	v_mfma_f32_16x16x32_bf16 v[32:35], v[176:179], v[192:195], v[32:35]
	v_mfma_f32_16x16x32_bf16 v[20:23], v[168:171], v[200:203], v[20:23]
	v_mfma_f32_16x16x32_bf16 v[16:19], v[176:179], v[200:203], v[16:19]
	v_mfma_f32_16x16x32_bf16 v[4:7], v[168:171], v[210:213], v[4:7]
	v_mfma_f32_16x16x32_bf16 v[0:3], v[176:179], v[210:213], v[0:3]
	v_mfma_f32_16x16x32_bf16 v[52:55], v[172:175], v[188:191], v[52:55]
	v_mfma_f32_16x16x32_bf16 v[48:51], v[180:183], v[188:191], v[48:51]
	v_mfma_f32_16x16x32_bf16 v[36:39], v[172:175], v[196:199], v[36:39]
	v_mfma_f32_16x16x32_bf16 v[32:35], v[180:183], v[196:199], v[32:35]
	v_mfma_f32_16x16x32_bf16 v[20:23], v[172:175], v[206:209], v[20:23]
	v_mfma_f32_16x16x32_bf16 v[16:19], v[180:183], v[206:209], v[16:19]
	v_mfma_f32_16x16x32_bf16 v[4:7], v[172:175], v[214:217], v[4:7]
	v_mfma_f32_16x16x32_bf16 v[0:3], v[180:183], v[214:217], v[0:3]
	s_setprio 0
	s_barrier
	s_add_i32 s50, s50, 2
	s_add_u32 s11, s11, 0x100
	s_addc_u32 s13, s13, 0
	s_add_u32 s20, s20, 0x100
	s_addc_u32 s21, s21, 0
	s_cmp_gt_u32 s50, 29
	s_cbranch_scc0 .LBB0_790
	s_and_b64 vcc, exec, s[8:9]
	s_cbranch_vccz .LBB0_793
	s_barrier

; #define PG8_STAGE(bufoff, gbase, voff) do { _Pragma("unroll") for (int _i = 0; _i < 2; ++_i) \
;         __builtin_amdgcn_global_load_lds((const unsigned*)((const char*)(gbase) + (voff)[_i]), (PG8_LAS unsigned*)(lds + (bufoff) + ldsw + _i * 8192), 16, 0, 0); } while (0)
; #define PG8_LDA(dst, b, h) do { _Pragma("unroll") for (int m = 0; m < 4; ++m) _Pragma("unroll") for (int k = 0; k < 2; ++k) dst[m][k] = *(const PG8_LAS bf16x8*)(lds + PG8_SA(b, h) + aoff + m * 2048 + k * 1024); } while (0)
; #define PG8_LDB(dst, b, h) do { _Pragma("unroll") for (int n = 0; n < 2; ++n) _Pragma("unroll") for (int k = 0; k < 2; ++k) dst[n][k] = *(const PG8_LAS bf16x8*)(lds + PG8_SB(b, h) + boff + n * 2048 + k * 1024); } while (0)
; #define PG8_MMA(ai, bj, At, Bt) do { __builtin_amdgcn_s_setprio(1); _Pragma("unroll") for (int m = 0; m < 4; ++m) _Pragma("unroll") for (int n = 0; n < 2; ++n) _Pragma("unroll") for (int k = 0; k < 2; ++k) \
;         acc[ai][bj][m][n] = __builtin_amdgcn_mfma_f32_16x16x32_bf16(Bt[n][k], At[m][k], acc[ai][bj][m][n], 0, 0, 0); __builtin_amdgcn_s_setprio(0); } while (0)
; #define PG8_WAIT_V(n) asm volatile("s_waitcnt vmcnt(" #n ")" ::: "memory")
; #define PG8_WAIT_L(n) asm volatile("s_waitcnt lgkmcnt(" #n ")" ::: "memory")
; #define PG8_BAR __builtin_amdgcn_s_barrier()
; #define PG8_SCHED __builtin_amdgcn_sched_barrier(0)
; template <class Epi, class Sched, bool ALIGN_EPI = false, bool SP2 = false>
; __device__ __forceinline__ void gemm_phase(PG8_LAS unsigned char* lds, const Gemm g, const Sched& S, const Epi& E, const int wv0) {
;     ...
;             const bool last = (t == nt - 2);
;             const char* a1 = cA + (size_t)(t + 1) * kstep;
;             const char* a2 = last ? nA : cA + (size_t)(t + 2) * kstep; const char* b2 = last ? nB : cB + (size_t)(t + 2) * kstep;
;             const char* a3 = a2 + kstep; const char* b3 = b2 + kstep;
;             if constexpr (SP2) {
;             PG8_LDB(B0, 0, 0); PG8_LDB(B1, 0, 1); PG8_SCHED; PG8_LDA(At, 0, 0); PG8_STAGE(PG8_SA(1, 1), a1 + hstepA, voffA);
;             PG8_WAIT_V(8); PG8_WAIT_L(0); PG8_BAR; PG8_MMA(0, 0, At, B0); PG8_MMA(0, 1, At, B1); PG8_BAR; PG8_SCHED;
;             PG8_LDA(At, 0, 1); PG8_STAGE(PG8_SB(0, 0), b2, voffB); PG8_STAGE(PG8_SB(0, 1), b2 + hstepB, voffB); PG8_STAGE(PG8_SA(0, 0), a2, voffA);
.LBB0_867:
	ds_read_b128 v[144:147], v155
	ds_read_b128 v[148:151], v155 offset:1024
	ds_read_b128 v[158:161], v155 offset:2048
	ds_read_b128 v[162:165], v155 offset:3072
	ds_read_b128 v[166:169], v156
	ds_read_b128 v[170:173], v156 offset:1024
	ds_read_b128 v[174:177], v156 offset:2048
	ds_read_b128 v[178:181], v156 offset:3072
	s_add_u32 s24, s22, 0x100
	s_addc_u32 s25, s23, 0
	s_cmpk_eq_i32 s58, 0x54
	s_cselect_b32 s29, s19, s25
	s_cselect_b32 s28, s18, s24
	s_cselect_b32 s27, s21, s57
	s_cselect_b32 s26, s20, s56
	v_lshl_add_u64 v[202:203], s[22:23], 0, v[138:139]
	s_add_i32 m0, s40, 0xc000
	ds_read_b128 v[182:185], v157
	ds_read_b128 v[186:189], v157 offset:1024
	ds_read_b128 v[190:193], v157 offset:2048
	ds_read_b128 v[194:197], v157 offset:3072
	ds_read_b128 v[198:201], v157 offset:4096
	ds_read_b128 v[206:209], v157 offset:5120
	ds_read_b128 v[210:213], v157 offset:6144
	ds_read_b128 v[214:217], v157 offset:7168
	global_load_lds_dwordx4 v[202:203], off
	v_lshl_add_u64 v[202:203], s[22:23], 0, v[136:137]
	s_add_i32 m0, s40, 0xe000
	s_nop 0
	global_load_lds_dwordx4 v[202:203], off
	s_waitcnt vmcnt(8)
	s_waitcnt lgkmcnt(0)
	s_barrier
	s_setprio 1
	v_mfma_f32_16x16x32_bf16 v[124:127], v[144:147], v[182:185], v[124:127]
	v_mfma_f32_16x16x32_bf16 v[120:123], v[158:161], v[182:185], v[120:123]
	v_mfma_f32_16x16x32_bf16 v[116:119], v[144:147], v[190:193], v[116:119]
	v_mfma_f32_16x16x32_bf16 v[112:115], v[158:161], v[190:193], v[112:115]
	v_mfma_f32_16x16x32_bf16 v[92:95], v[144:147], v[198:201], v[92:95]
	v_mfma_f32_16x16x32_bf16 v[88:91], v[158:161], v[198:201], v[88:91]
	v_mfma_f32_16x16x32_bf16 v[84:87], v[144:147], v[210:213], v[84:87]
	v_mfma_f32_16x16x32_bf16 v[80:83], v[158:161], v[210:213], v[80:83]
	v_mfma_f32_16x16x32_bf16 v[124:127], v[148:151], v[186:189], v[124:127]
	v_mfma_f32_16x16x32_bf16 v[120:123], v[162:165], v[186:189], v[120:123]
	v_mfma_f32_16x16x32_bf16 v[116:119], v[148:151], v[194:197], v[116:119]
	v_mfma_f32_16x16x32_bf16 v[112:115], v[162:165], v[194:197], v[112:115]
	v_mfma_f32_16x16x32_bf16 v[92:95], v[148:151], v[206:209], v[92:95]
	v_mfma_f32_16x16x32_bf16 v[88:91], v[162:165], v[206:209], v[88:91]
	v_mfma_f32_16x16x32_bf16 v[84:87], v[148:151], v[214:217], v[84:87]
	v_mfma_f32_16x16x32_bf16 v[80:83], v[162:165], v[214:217], v[80:83]
	s_setprio 0
	s_setprio 1
	v_mfma_f32_16x16x32_bf16 v[108:111], v[166:169], v[182:185], v[108:111]
	v_mfma_f32_16x16x32_bf16 v[104:107], v[174:177], v[182:185], v[104:107]
	v_mfma_f32_16x16x32_bf16 v[100:103], v[166:169], v[190:193], v[100:103]
	v_mfma_f32_16x16x32_bf16 v[96:99], v[174:177], v[190:193], v[96:99]
	v_mfma_f32_16x16x32_bf16 v[76:79], v[166:169], v[198:201], v[76:79]
	v_mfma_f32_16x16x32_bf16 v[72:75], v[174:177], v[198:201], v[72:75]
	v_mfma_f32_16x16x32_bf16 v[68:71], v[166:169], v[210:213], v[68:71]
	v_mfma_f32_16x16x32_bf16 v[64:67], v[174:177], v[210:213], v[64:67]
	v_mfma_f32_16x16x32_bf16 v[108:111], v[170:173], v[186:189], v[108:111]
	v_mfma_f32_16x16x32_bf16 v[104:107], v[178:181], v[186:189], v[104:107]
	v_mfma_f32_16x16x32_bf16 v[100:103], v[170:173], v[194:197], v[100:103]
	v_mfma_f32_16x16x32_bf16 v[96:99], v[178:181], v[194:197], v[96:99]
	v_mfma_f32_16x16x32_bf16 v[76:79], v[170:173], v[206:209], v[76:79]
	v_mfma_f32_16x16x32_bf16 v[72:75], v[178:181], v[206:209], v[72:75]
	v_mfma_f32_16x16x32_bf16 v[68:71], v[170:173], v[214:217], v[68:71]
	v_mfma_f32_16x16x32_bf16 v[64:67], v[178:181], v[214:217], v[64:67]
	s_setprio 0
	s_barrier
	s_add_i32 s22, s50, s39
	v_lshl_add_u64 v[202:203], s[26:27], 0, v[130:131]
	s_mov_b32 m0, s22
	ds_read_b128 v[182:185], v157 offset:16384
	ds_read_b128 v[186:189], v157 offset:17408
	ds_read_b128 v[190:193], v157 offset:18432
	ds_read_b128 v[194:197], v157 offset:19456
	ds_read_b128 v[198:201], v157 offset:20480
	ds_read_b128 v[206:209], v157 offset:21504
	ds_read_b128 v[210:213], v157 offset:22528
	ds_read_b128 v[214:217], v157 offset:23552
	global_load_lds_dwordx4 v[202:203], off
	s_add_i32 m0, s22, 0x2000
	s_add_u32 s22, s26, 0x160000
	v_lshl_add_u64 v[218:219], s[26:27], 0, v[134:135]
	s_addc_u32 s23, s27, 0
	s_add_i32 s59, s51, s39
	global_load_lds_dwordx4 v[218:219], off
	v_lshl_add_u64 v[220:221], s[22:23], 0, v[130:131]
	s_mov_b32 m0, s59
	v_lshl_add_u64 v[222:223], s[28:29], 0, v[132:133]
	global_load_lds_dwordx4 v[220:221], off
	v_lshl_add_u64 v[220:221], s[22:23], 0, v[134:135]
	s_add_i32 m0, s59, 0x2000
	s_nop 0
	global_load_lds_dwordx4 v[220:221], off
	v_lshl_add_u64 v[220:221], s[28:29], 0, v[128:129]
	s_mov_b32 m0, s40
	s_nop 0
	global_load_lds_dwordx4 v[220:221], off
	s_mov_b32 m0, s41
	s_nop 0
	global_load_lds_dwordx4 v[222:223], off
	s_waitcnt vmcnt(8)
	s_waitcnt lgkmcnt(0)
	s_barrier
; #define PG8_STAGE(bufoff, gbase, voff) do { _Pragma("unroll") for (int _i = 0; _i < 2; ++_i) \
;         __builtin_amdgcn_global_load_lds((const unsigned*)((const char*)(gbase) + (voff)[_i]), (PG8_LAS unsigned*)(lds + (bufoff) + ldsw + _i * 8192), 16, 0, 0); } while (0)
; #define PG8_LDA(dst, b, h) do { _Pragma("unroll") for (int m = 0; m < 4; ++m) _Pragma("unroll") for (int k = 0; k < 2; ++k) dst[m][k] = *(const PG8_LAS bf16x8*)(lds + PG8_SA(b, h) + aoff + m * 2048 + k * 1024); } while (0)
; #define PG8_LDB(dst, b, h) do { _Pragma("unroll") for (int n = 0; n < 2; ++n) _Pragma("unroll") for (int k = 0; k < 2; ++k) dst[n][k] = *(const PG8_LAS bf16x8*)(lds + PG8_SB(b, h) + boff + n * 2048 + k * 1024); } while (0)
; #define PG8_MMA(ai, bj, At, Bt) do { __builtin_amdgcn_s_setprio(1); _Pragma("unroll") for (int m = 0; m < 4; ++m) _Pragma("unroll") for (int n = 0; n < 2; ++n) _Pragma("unroll") for (int k = 0; k < 2; ++k) \
;         acc[ai][bj][m][n] = __builtin_amdgcn_mfma_f32_16x16x32_bf16(Bt[n][k], At[m][k], acc[ai][bj][m][n], 0, 0, 0); __builtin_amdgcn_s_setprio(0); } while (0)
; #define PG8_WAIT_V(n) asm volatile("s_waitcnt vmcnt(" #n ")" ::: "memory")
; #define PG8_WAIT_L(n) asm volatile("s_waitcnt lgkmcnt(" #n ")" ::: "memory")
; #define PG8_BAR __builtin_amdgcn_s_barrier()
; #define PG8_SCHED __builtin_amdgcn_sched_barrier(0)
; template <class Epi, class Sched, bool ALIGN_EPI = false, bool SP2 = false>
; __device__ __forceinline__ void gemm_phase(PG8_LAS unsigned char* lds, const Gemm g, const Sched& S, const Epi& E, const int wv0) {
;     ...
;             PG8_WAIT_V(8); PG8_WAIT_L(0); PG8_BAR; PG8_MMA(1, 0, At, B0); PG8_MMA(1, 1, At, B1); PG8_BAR; PG8_SCHED;
;             PG8_LDB(B0, 1, 0); PG8_LDB(B1, 1, 1); PG8_SCHED; PG8_LDA(At, 1, 0); PG8_STAGE(PG8_SA(0, 1), a2 + hstepA, voffA);
;             PG8_WAIT_V(8); PG8_WAIT_L(0); PG8_BAR; PG8_MMA(0, 0, At, B0); PG8_MMA(0, 1, At, B1); PG8_BAR; PG8_SCHED;
	s_setprio 1
	v_mfma_f32_16x16x32_bf16 v[60:63], v[144:147], v[182:185], v[60:63]
	v_mfma_f32_16x16x32_bf16 v[56:59], v[158:161], v[182:185], v[56:59]
	v_mfma_f32_16x16x32_bf16 v[52:55], v[144:147], v[190:193], v[52:55]
	v_mfma_f32_16x16x32_bf16 v[48:51], v[158:161], v[190:193], v[48:51]
	v_mfma_f32_16x16x32_bf16 v[28:31], v[144:147], v[198:201], v[28:31]
	v_mfma_f32_16x16x32_bf16 v[24:27], v[158:161], v[198:201], v[24:27]
	v_mfma_f32_16x16x32_bf16 v[20:23], v[144:147], v[210:213], v[20:23]
	v_mfma_f32_16x16x32_bf16 v[16:19], v[158:161], v[210:213], v[16:19]
	v_mfma_f32_16x16x32_bf16 v[60:63], v[148:151], v[186:189], v[60:63]
	v_mfma_f32_16x16x32_bf16 v[56:59], v[162:165], v[186:189], v[56:59]
	v_mfma_f32_16x16x32_bf16 v[52:55], v[148:151], v[194:197], v[52:55]
	v_mfma_f32_16x16x32_bf16 v[48:51], v[162:165], v[194:197], v[48:51]
	v_mfma_f32_16x16x32_bf16 v[28:31], v[148:151], v[206:209], v[28:31]
	v_mfma_f32_16x16x32_bf16 v[24:27], v[162:165], v[206:209], v[24:27]
	v_mfma_f32_16x16x32_bf16 v[20:23], v[148:151], v[214:217], v[20:23]
	v_mfma_f32_16x16x32_bf16 v[16:19], v[162:165], v[214:217], v[16:19]
	s_setprio 0
	s_setprio 1
	v_mfma_f32_16x16x32_bf16 v[44:47], v[166:169], v[182:185], v[44:47]
	v_mfma_f32_16x16x32_bf16 v[40:43], v[174:177], v[182:185], v[40:43]
	v_mfma_f32_16x16x32_bf16 v[36:39], v[166:169], v[190:193], v[36:39]
	v_mfma_f32_16x16x32_bf16 v[32:35], v[174:177], v[190:193], v[32:35]
	v_mfma_f32_16x16x32_bf16 v[12:15], v[166:169], v[198:201], v[12:15]
	v_mfma_f32_16x16x32_bf16 v[8:11], v[174:177], v[198:201], v[8:11]
	v_mfma_f32_16x16x32_bf16 v[4:7], v[166:169], v[210:213], v[4:7]
	v_mfma_f32_16x16x32_bf16 v[0:3], v[174:177], v[210:213], v[0:3]
	v_mfma_f32_16x16x32_bf16 v[44:47], v[170:173], v[186:189], v[44:47]
	v_mfma_f32_16x16x32_bf16 v[40:43], v[178:181], v[186:189], v[40:43]
	v_mfma_f32_16x16x32_bf16 v[36:39], v[170:173], v[194:197], v[36:39]
	v_mfma_f32_16x16x32_bf16 v[32:35], v[178:181], v[194:197], v[32:35]
	v_mfma_f32_16x16x32_bf16 v[12:15], v[170:173], v[206:209], v[12:15]
	v_mfma_f32_16x16x32_bf16 v[8:11], v[178:181], v[206:209], v[8:11]
	v_mfma_f32_16x16x32_bf16 v[4:7], v[170:173], v[214:217], v[4:7]
	v_mfma_f32_16x16x32_bf16 v[0:3], v[178:181], v[214:217], v[0:3]
	s_setprio 0
	s_barrier
	s_add_i32 s59, 0, 0x18000
	s_add_i32 s60, 0, 0x1c000
	v_add_u32_e32 v162, s59, v153
	v_add_u32_e32 v178, s60, v153
	ds_read_b128 v[144:147], v162
	ds_read_b128 v[148:151], v162 offset:1024
	ds_read_b128 v[158:161], v162 offset:2048
	ds_read_b128 v[162:165], v162 offset:3072
	ds_read_b128 v[166:169], v178
	ds_read_b128 v[170:173], v178 offset:1024
	ds_read_b128 v[174:177], v178 offset:2048
	ds_read_b128 v[178:181], v178 offset:3072
	s_add_u32 s22, s28, 0x160000
	s_addc_u32 s23, s29, 0
	s_mov_b32 m0, s44
	v_lshl_add_u64 v[224:225], s[22:23], 0, v[128:129]
	ds_read_b128 v[182:185], v157 offset:32768
	ds_read_b128 v[186:189], v157 offset:33792
	ds_read_b128 v[190:193], v157 offset:34816
	ds_read_b128 v[194:197], v157 offset:35840
	ds_read_b128 v[198:201], v157 offset:36864
	ds_read_b128 v[206:209], v157 offset:37888
	ds_read_b128 v[210:213], v157 offset:38912
	ds_read_b128 v[214:217], v157 offset:39936
	global_load_lds_dwordx4 v[224:225], off
	v_lshl_add_u64 v[224:225], s[22:23], 0, v[132:133]
	s_mov_b32 m0, s45
	s_nop 0
	global_load_lds_dwordx4 v[224:225], off
	s_waitcnt vmcnt(8)
	s_waitcnt lgkmcnt(0)
	s_barrier
	s_setprio 1
	v_mfma_f32_16x16x32_bf16 v[124:127], v[144:147], v[182:185], v[124:127]
	v_mfma_f32_16x16x32_bf16 v[120:123], v[158:161], v[182:185], v[120:123]
	v_mfma_f32_16x16x32_bf16 v[116:119], v[144:147], v[190:193], v[116:119]
	v_mfma_f32_16x16x32_bf16 v[112:115], v[158:161], v[190:193], v[112:115]
	v_mfma_f32_16x16x32_bf16 v[92:95], v[144:147], v[198:201], v[92:95]
	v_mfma_f32_16x16x32_bf16 v[88:91], v[158:161], v[198:201], v[88:91]
	v_mfma_f32_16x16x32_bf16 v[84:87], v[144:147], v[210:213], v[84:87]
	v_mfma_f32_16x16x32_bf16 v[80:83], v[158:161], v[210:213], v[80:83]
	v_mfma_f32_16x16x32_bf16 v[124:127], v[148:151], v[186:189], v[124:127]
	v_mfma_f32_16x16x32_bf16 v[120:123], v[162:165], v[186:189], v[120:123]
	v_mfma_f32_16x16x32_bf16 v[116:119], v[148:151], v[194:197], v[116:119]
	v_mfma_f32_16x16x32_bf16 v[112:115], v[162:165], v[194:197], v[112:115]
	v_mfma_f32_16x16x32_bf16 v[92:95], v[148:151], v[206:209], v[92:95]
	v_mfma_f32_16x16x32_bf16 v[88:91], v[162:165], v[206:209], v[88:91]
	v_mfma_f32_16x16x32_bf16 v[84:87], v[148:151], v[214:217], v[84:87]
	v_mfma_f32_16x16x32_bf16 v[80:83], v[162:165], v[214:217], v[80:83]
	s_setprio 0
	s_setprio 1
	v_mfma_f32_16x16x32_bf16 v[108:111], v[166:169], v[182:185], v[108:111]
	v_mfma_f32_16x16x32_bf16 v[104:107], v[174:177], v[182:185], v[104:107]
	v_mfma_f32_16x16x32_bf16 v[100:103], v[166:169], v[190:193], v[100:103]
	v_mfma_f32_16x16x32_bf16 v[96:99], v[174:177], v[190:193], v[96:99]
	v_mfma_f32_16x16x32_bf16 v[76:79], v[166:169], v[198:201], v[76:79]
	v_mfma_f32_16x16x32_bf16 v[72:75], v[174:177], v[198:201], v[72:75]
	v_mfma_f32_16x16x32_bf16 v[68:71], v[166:169], v[210:213], v[68:71]
	v_mfma_f32_16x16x32_bf16 v[64:67], v[174:177], v[210:213], v[64:67]
	v_mfma_f32_16x16x32_bf16 v[108:111], v[170:173], v[186:189], v[108:111]
	v_mfma_f32_16x16x32_bf16 v[104:107], v[178:181], v[186:189], v[104:107]
	v_mfma_f32_16x16x32_bf16 v[100:103], v[170:173], v[194:197], v[100:103]
	v_mfma_f32_16x16x32_bf16 v[96:99], v[178:181], v[194:197], v[96:99]
	v_mfma_f32_16x16x32_bf16 v[76:79], v[170:173], v[206:209], v[76:79]
	v_mfma_f32_16x16x32_bf16 v[72:75], v[178:181], v[206:209], v[72:75]
	v_mfma_f32_16x16x32_bf16 v[68:71], v[170:173], v[214:217], v[68:71]
	v_mfma_f32_16x16x32_bf16 v[64:67], v[178:181], v[214:217], v[64:67]
	s_setprio 0
	s_barrier
; #define PG8_STAGE(bufoff, gbase, voff) do { _Pragma("unroll") for (int _i = 0; _i < 2; ++_i) \
;         __builtin_amdgcn_global_load_lds((const unsigned*)((const char*)(gbase) + (voff)[_i]), (PG8_LAS unsigned*)(lds + (bufoff) + ldsw + _i * 8192), 16, 0, 0); } while (0)
; #define PG8_LDA(dst, b, h) do { _Pragma("unroll") for (int m = 0; m < 4; ++m) _Pragma("unroll") for (int k = 0; k < 2; ++k) dst[m][k] = *(const PG8_LAS bf16x8*)(lds + PG8_SA(b, h) + aoff + m * 2048 + k * 1024); } while (0)
; #define PG8_MMA(ai, bj, At, Bt) do { __builtin_amdgcn_s_setprio(1); _Pragma("unroll") for (int m = 0; m < 4; ++m) _Pragma("unroll") for (int n = 0; n < 2; ++n) _Pragma("unroll") for (int k = 0; k < 2; ++k) \
;         acc[ai][bj][m][n] = __builtin_amdgcn_mfma_f32_16x16x32_bf16(Bt[n][k], At[m][k], acc[ai][bj][m][n], 0, 0, 0); __builtin_amdgcn_s_setprio(0); } while (0)
; #define PG8_WAIT_V(n) asm volatile("s_waitcnt vmcnt(" #n ")" ::: "memory")
; #define PG8_WAIT_L(n) asm volatile("s_waitcnt lgkmcnt(" #n ")" ::: "memory")
; #define PG8_BAR __builtin_amdgcn_s_barrier()
; #define PG8_SCHED __builtin_amdgcn_sched_barrier(0)
; template <class Epi, class Sched, bool ALIGN_EPI = false, bool SP2 = false>
; __device__ __forceinline__ void gemm_phase(PG8_LAS unsigned char* lds, const Gemm g, const Sched& S, const Epi& E, const int wv0) {
;     ...
;             PG8_LDA(At, 1, 1); PG8_STAGE(PG8_SB(1, 0), b3, voffB); PG8_STAGE(PG8_SB(1, 1), b3 + hstepB, voffB); PG8_STAGE(PG8_SA(1, 0), a3, voffA);
;             PG8_WAIT_V(8); PG8_WAIT_L(0); PG8_BAR; PG8_MMA(1, 0, At, B0); PG8_MMA(1, 1, At, B1); PG8_BAR; PG8_SCHED;
;     ...
;         if constexpr (ALIGN_EPI) { if (wr == 0) PG8_BAR; }
	s_add_i32 s22, s59, s39
	v_lshl_add_u64 v[202:203], v[202:203], 0, s[6:7]
	s_mov_b32 m0, s22
	ds_read_b128 v[182:185], v157 offset:49152
	ds_read_b128 v[186:189], v157 offset:50176
	ds_read_b128 v[190:193], v157 offset:51200
	ds_read_b128 v[194:197], v157 offset:52224
	ds_read_b128 v[198:201], v157 offset:53248
	ds_read_b128 v[206:209], v157 offset:54272
	ds_read_b128 v[210:213], v157 offset:55296
	ds_read_b128 v[214:217], v157 offset:56320
	global_load_lds_dwordx4 v[202:203], off
	s_add_i32 m0, s22, 0x2000
	s_add_u32 s22, s26, 0x160080
	v_lshl_add_u64 v[202:203], v[218:219], 0, s[6:7]
	s_addc_u32 s23, s27, 0
	s_add_i32 s26, s60, s39
	global_load_lds_dwordx4 v[202:203], off
	v_lshl_add_u64 v[202:203], s[22:23], 0, v[130:131]
	s_mov_b32 m0, s26
	s_nop 0
	global_load_lds_dwordx4 v[202:203], off
	v_lshl_add_u64 v[202:203], s[22:23], 0, v[134:135]
	s_add_i32 m0, s26, 0x2000
	s_nop 0
	global_load_lds_dwordx4 v[202:203], off
	v_lshl_add_u64 v[202:203], v[220:221], 0, s[6:7]
	s_mov_b32 m0, s47
	s_nop 0
	global_load_lds_dwordx4 v[202:203], off
	v_lshl_add_u64 v[202:203], v[222:223], 0, s[6:7]
	s_mov_b32 m0, s48
	s_nop 0
	global_load_lds_dwordx4 v[202:203], off
	s_waitcnt vmcnt(8)
	s_waitcnt lgkmcnt(0)
	s_barrier
	s_setprio 1
	v_mfma_f32_16x16x32_bf16 v[60:63], v[144:147], v[182:185], v[60:63]
	v_mfma_f32_16x16x32_bf16 v[56:59], v[158:161], v[182:185], v[56:59]
	v_mfma_f32_16x16x32_bf16 v[52:55], v[144:147], v[190:193], v[52:55]
	v_mfma_f32_16x16x32_bf16 v[48:51], v[158:161], v[190:193], v[48:51]
	v_mfma_f32_16x16x32_bf16 v[28:31], v[144:147], v[198:201], v[28:31]
	v_mfma_f32_16x16x32_bf16 v[24:27], v[158:161], v[198:201], v[24:27]
	v_mfma_f32_16x16x32_bf16 v[20:23], v[144:147], v[210:213], v[20:23]
	v_mfma_f32_16x16x32_bf16 v[16:19], v[158:161], v[210:213], v[16:19]
	v_mfma_f32_16x16x32_bf16 v[60:63], v[148:151], v[186:189], v[60:63]
	v_mfma_f32_16x16x32_bf16 v[56:59], v[162:165], v[186:189], v[56:59]
	v_mfma_f32_16x16x32_bf16 v[52:55], v[148:151], v[194:197], v[52:55]
	v_mfma_f32_16x16x32_bf16 v[48:51], v[162:165], v[194:197], v[48:51]
	v_mfma_f32_16x16x32_bf16 v[28:31], v[148:151], v[206:209], v[28:31]
	v_mfma_f32_16x16x32_bf16 v[24:27], v[162:165], v[206:209], v[24:27]
	v_mfma_f32_16x16x32_bf16 v[20:23], v[148:151], v[214:217], v[20:23]
	v_mfma_f32_16x16x32_bf16 v[16:19], v[162:165], v[214:217], v[16:19]
	s_setprio 0
	s_setprio 1
	v_mfma_f32_16x16x32_bf16 v[44:47], v[166:169], v[182:185], v[44:47]
	v_mfma_f32_16x16x32_bf16 v[40:43], v[174:177], v[182:185], v[40:43]
	v_mfma_f32_16x16x32_bf16 v[36:39], v[166:169], v[190:193], v[36:39]
	v_mfma_f32_16x16x32_bf16 v[32:35], v[174:177], v[190:193], v[32:35]
	v_mfma_f32_16x16x32_bf16 v[12:15], v[166:169], v[198:201], v[12:15]
	v_mfma_f32_16x16x32_bf16 v[8:11], v[174:177], v[198:201], v[8:11]
	v_mfma_f32_16x16x32_bf16 v[4:7], v[166:169], v[210:213], v[4:7]
	v_mfma_f32_16x16x32_bf16 v[0:3], v[174:177], v[210:213], v[0:3]
	v_mfma_f32_16x16x32_bf16 v[44:47], v[170:173], v[186:189], v[44:47]
	v_mfma_f32_16x16x32_bf16 v[40:43], v[178:181], v[186:189], v[40:43]
	v_mfma_f32_16x16x32_bf16 v[36:39], v[170:173], v[194:197], v[36:39]
	v_mfma_f32_16x16x32_bf16 v[32:35], v[178:181], v[194:197], v[32:35]
	v_mfma_f32_16x16x32_bf16 v[12:15], v[170:173], v[206:209], v[12:15]
	v_mfma_f32_16x16x32_bf16 v[8:11], v[178:181], v[206:209], v[8:11]
	v_mfma_f32_16x16x32_bf16 v[4:7], v[170:173], v[214:217], v[4:7]
	v_mfma_f32_16x16x32_bf16 v[0:3], v[178:181], v[214:217], v[0:3]
	s_setprio 0
	s_barrier
	s_add_i32 s58, s58, 2
	s_add_u32 s56, s56, 0x100
	s_addc_u32 s57, s57, 0
	s_cmpk_gt_u32 s58, 0x55
	s_mov_b64 s[22:23], s[24:25]
	s_cbranch_scc0 .LBB0_867
	s_and_b64 vcc, exec, s[8:9]
	s_cbranch_vccz .LBB0_870
	s_barrier

;     __device__ __forceinline__ bool next(int i, Unit& u) const { int pm, pn; if (!to.get((long)i * G + c, pm, pn)) return false; u.pm = pm; u.pn = pn; u.aux = 0; u.a = A + (size_t)pm * ta; u.b = B + (size_t)pn * tb; return true; }
;     __device__ __forceinline__ bool next(int i, Unit& u) const { if (i != 0) return false; u = one; return true; }
; #define PG8_LDA(dst, b, h) do { _Pragma("unroll") for (int m = 0; m < 4; ++m) _Pragma("unroll") for (int k = 0; k < 2; ++k) dst[m][k] = *(const PG8_LAS bf16x8*)(lds + PG8_SA(b, h) + aoff + m * 2048 + k * 1024); } while (0)
; template <class Epi, class Sched, bool ALIGN_EPI = false, bool SP2 = false>
; __device__ __forceinline__ void gemm_phase(PG8_LAS unsigned char* lds, const Gemm g, const Sched& S, const Epi& E, const int wv0) {
;     ...
;         PG8_STAGE(PG8_SB(1, 0), cB + kstep, voffB); PG8_STAGE(PG8_SA(1, 0), cA + kstep, voffA); PG8_STAGE(PG8_SB(1, 1), cB + hstepB + kstep, voffB);
;         PG8_WAIT_V(6); PG8_BAR;
;     } else {
;         PG8_STAGE(PG8_SB(0, 0), cB, voffB); PG8_STAGE(PG8_SA(0, 0), cA, voffA); PG8_STAGE(PG8_SB(0, 1), cB + hstepB, voffB); PG8_STAGE(PG8_SA(0, 1), cA + hstepA, voffA);
;         if (wr == 1) PG8_BAR;
;         PG8_WAIT_V(4); PG8_BAR;
;         PG8_STAGE(PG8_SB(1, 0), cB + kstep, voffB); PG8_STAGE(PG8_SA(1, 0), cA + kstep, voffA); PG8_STAGE(PG8_SB(1, 1), cB + hstepB + kstep, voffB);
;         PG8_WAIT_V(6); PG8_BAR;
;     }
;     for (;;) {
;         const bool has_next = S.next(ui + 1, nxt);
;         const char* nA = has_next ? nxt.a : cA; const char* nB = has_next ? nxt.b : cB;
;         for (int t = 0; t < nt; t += 2) {
;             const bool last = (t == nt - 2);
;             const char* a1 = cA + (size_t)(t + 1) * kstep;
;             const char* a2 = last ? nA : cA + (size_t)(t + 2) * kstep; const char* b2 = last ? nB : cB + (size_t)(t + 2) * kstep;
;             const char* a3 = a2 + kstep; const char* b3 = b2 + kstep;
;             if constexpr (SP2) {
;             PG8_LDB(B0, 0, 0); PG8_LDB(B1, 0, 1); PG8_SCHED; PG8_LDA(At, 0, 0); PG8_STAGE(PG8_SA(1, 1), a1 + hstepA, voffA);
;             PG8_WAIT_V(8); PG8_WAIT_L(0); PG8_BAR; PG8_MMA(0, 0, At, B0); PG8_MMA(0, 1, At, B1); PG8_BAR; PG8_SCHED;
;             PG8_LDA(At, 0, 1); PG8_STAGE(PG8_SB(0, 0), b2, voffB); PG8_STAGE(PG8_SB(0, 1), b2 + hstepB, voffB); PG8_STAGE(PG8_SA(0, 0), a2, voffA);
.LBB0_1299:
	s_and_b32 s51, s47, 3
	s_lshl_b32 s47, s50, 13
	s_lshl_b32 s48, s51, 12
	s_add_u32 s64, s61, 0x2e280080
	s_addc_u32 s65, s62, 0
	s_add_i32 s26, s36, s66
	v_lshl_add_u64 v[2:3], s[64:65], 0, v[128:129]
	s_mov_b32 m0, s26
	s_add_i32 s53, s26, 0x2000
	s_waitcnt vmcnt(2)
	s_barrier
	global_load_lds_dwordx4 v[2:3], off
	v_lshl_add_u64 v[4:5], s[64:65], 0, v[32:33]
	s_mov_b32 m0, s53
	s_add_i32 s27, s59, 0x8000
	s_add_i32 s54, s59, 0xa000
	global_load_lds_dwordx4 v[4:5], off
	v_lshl_add_u64 v[0:1], v[20:21], 0, s[10:11]
	s_mov_b32 m0, s27
	s_add_u32 s64, s61, 0x2e290080
	global_load_lds_dwordx4 v[0:1], off
	v_lshl_add_u64 v[6:7], v[22:23], 0, s[10:11]
	s_mov_b32 m0, s54
	s_addc_u32 s65, s62, 0
	s_add_i32 s57, s37, s66
	global_load_lds_dwordx4 v[6:7], off
	v_lshl_add_u64 v[8:9], s[64:65], 0, v[128:129]
	s_mov_b32 m0, s57
	s_add_i32 s58, s57, 0x2000
	global_load_lds_dwordx4 v[8:9], off
	v_lshl_add_u64 v[10:11], s[64:65], 0, v[32:33]
	s_mov_b32 m0, s58
	v_bfe_u32 v144, v34, 4, 2
	global_load_lds_dwordx4 v[10:11], off
	v_and_b32_e32 v143, 15, v34
	v_lshlrev_b32_e32 v35, 4, v144
	v_lshlrev_b32_e32 v34, 2, v34
	v_lshl_or_b32 v35, v143, 6, v35
	v_and_b32_e32 v34, 32, v34
	v_bitop3_b32 v66, v35, s48, v34 bitop3:0xde
	s_add_i32 s48, 0, 0x10000
	v_bitop3_b32 v36, v35, s47, v34 bitop3:0xde
	s_add_i32 s47, 0, 0x14000
	v_add_u32_e32 v203, s48, v66
	s_waitcnt vmcnt(6)
	s_barrier
	v_add_u32_e32 v145, 0, v36
	v_add_u32_e32 v202, s47, v66
	ds_read_b128 v[34:37], v203
	ds_read_b128 v[38:41], v203 offset:1024
	ds_read_b128 v[42:45], v203 offset:2048
	ds_read_b128 v[46:49], v203 offset:3072
	ds_read_b128 v[50:53], v202
	ds_read_b128 v[54:57], v202 offset:1024
	ds_read_b128 v[58:61], v202 offset:2048
	ds_read_b128 v[62:65], v202 offset:3072
	s_add_u32 s70, s61, 0x2e280100
	v_add_u32_e32 v246, s37, v66
	v_add_u32_e32 v247, s36, v66
	s_addc_u32 s71, s62, 0
	s_add_u32 s64, s24, 0x40080
	s_addc_u32 s65, s25, 0
	s_add_i32 s68, s59, 0xc000
	v_lshl_add_u64 v[98:99], s[64:65], 0, v[16:17]
	s_mov_b32 m0, s68
	s_add_i32 s63, s59, 0xe000
	ds_read_b128 v[66:69], v145
	ds_read_b128 v[70:73], v145 offset:1024
	ds_read_b128 v[74:77], v145 offset:2048
	ds_read_b128 v[78:81], v145 offset:3072
	ds_read_b128 v[82:85], v145 offset:4096
	ds_read_b128 v[86:89], v145 offset:5120
	ds_read_b128 v[90:93], v145 offset:6144
	ds_read_b128 v[94:97], v145 offset:7168
	global_load_lds_dwordx4 v[98:99], off
	v_lshl_add_u64 v[98:99], s[64:65], 0, v[30:31]
	s_mov_b32 m0, s63
	s_nop 0
	global_load_lds_dwordx4 v[98:99], off
	s_waitcnt vmcnt(8)
	s_waitcnt lgkmcnt(0)
	s_barrier
	s_setprio 1
	v_mfma_f32_16x16x32_bf16 v[98:101], v[34:37], v[66:69], 0
	v_mfma_f32_16x16x32_bf16 v[102:105], v[42:45], v[66:69], 0
	v_mfma_f32_16x16x32_bf16 v[106:109], v[34:37], v[74:77], 0
	v_mfma_f32_16x16x32_bf16 v[110:113], v[42:45], v[74:77], 0
	v_mfma_f32_16x16x32_bf16 v[114:117], v[34:37], v[82:85], 0
	v_mfma_f32_16x16x32_bf16 v[118:121], v[42:45], v[82:85], 0
	v_mfma_f32_16x16x32_bf16 v[122:125], v[34:37], v[90:93], 0
	v_mfma_f32_16x16x32_bf16 v[98:101], v[38:41], v[70:73], v[98:101]
	v_mfma_f32_16x16x32_bf16 v[102:105], v[46:49], v[70:73], v[102:105]
	v_mfma_f32_16x16x32_bf16 v[106:109], v[38:41], v[78:81], v[106:109]
	v_mfma_f32_16x16x32_bf16 v[110:113], v[46:49], v[78:81], v[110:113]
	v_mfma_f32_16x16x32_bf16 v[114:117], v[38:41], v[86:89], v[114:117]
	v_mfma_f32_16x16x32_bf16 v[118:121], v[46:49], v[86:89], v[118:121]
	v_mfma_f32_16x16x32_bf16 v[122:125], v[38:41], v[94:97], v[122:125]
	v_mfma_f32_16x16x32_bf16 v[130:133], v[42:45], v[90:93], 0
	v_mfma_f32_16x16x32_bf16 v[130:133], v[46:49], v[94:97], v[130:133]
	s_setprio 0
	s_setprio 1
	v_mfma_f32_16x16x32_bf16 v[134:137], v[50:53], v[66:69], 0
	v_mfma_f32_16x16x32_bf16 v[66:69], v[58:61], v[66:69], 0
	v_mfma_f32_16x16x32_bf16 v[134:137], v[54:57], v[70:73], v[134:137]
	v_mfma_f32_16x16x32_bf16 v[66:69], v[62:65], v[70:73], v[66:69]
	v_mfma_f32_16x16x32_bf16 v[70:73], v[50:53], v[74:77], 0
	v_mfma_f32_16x16x32_bf16 v[74:77], v[58:61], v[74:77], 0
	v_mfma_f32_16x16x32_bf16 v[70:73], v[54:57], v[78:81], v[70:73]
	v_mfma_f32_16x16x32_bf16 v[74:77], v[62:65], v[78:81], v[74:77]
	v_mfma_f32_16x16x32_bf16 v[78:81], v[50:53], v[82:85], 0
	v_mfma_f32_16x16x32_bf16 v[82:85], v[58:61], v[82:85], 0
	v_mfma_f32_16x16x32_bf16 v[78:81], v[54:57], v[86:89], v[78:81]
	v_mfma_f32_16x16x32_bf16 v[82:85], v[62:65], v[86:89], v[82:85]
	v_mfma_f32_16x16x32_bf16 v[86:89], v[50:53], v[90:93], 0
	v_mfma_f32_16x16x32_bf16 v[90:93], v[58:61], v[90:93], 0
	v_mfma_f32_16x16x32_bf16 v[86:89], v[54:57], v[94:97], v[86:89]
	v_mfma_f32_16x16x32_bf16 v[90:93], v[62:65], v[94:97], v[90:93]
	s_setprio 0
	s_barrier
	s_add_i32 s64, s48, s66
	v_lshl_add_u64 v[126:127], s[70:71], 0, v[128:129]
	s_mov_b32 m0, s64
	s_add_i32 s65, s64, 0x2000
	ds_read_b128 v[94:97], v145 offset:16384
	ds_read_b128 v[138:141], v145 offset:17408
	ds_read_b128 v[146:149], v145 offset:18432
	ds_read_b128 v[150:153], v145 offset:19456
	ds_read_b128 v[154:157], v145 offset:20480
	ds_read_b128 v[158:161], v145 offset:21504
	ds_read_b128 v[162:165], v145 offset:22528
	ds_read_b128 v[166:169], v145 offset:23552
	global_load_lds_dwordx4 v[126:127], off
	v_lshl_add_u64 v[126:127], s[70:71], 0, v[32:33]
	s_add_u32 s70, s61, 0x2e290100
	s_mov_b32 m0, s65
	s_addc_u32 s71, s62, 0
	s_add_i32 s66, s47, s66
	global_load_lds_dwordx4 v[126:127], off
	v_lshl_add_u64 v[126:127], s[70:71], 0, v[128:129]
	s_mov_b32 m0, s66
	s_add_i32 s67, s66, 0x2000
	global_load_lds_dwordx4 v[126:127], off
	v_lshl_add_u64 v[126:127], s[70:71], 0, v[32:33]
	s_mov_b32 m0, s67
	s_nop 0
	global_load_lds_dwordx4 v[126:127], off
	v_lshl_add_u64 v[126:127], v[20:21], 0, s[12:13]
	s_mov_b32 m0, s59
	s_nop 0
	global_load_lds_dwordx4 v[126:127], off
	v_lshl_add_u64 v[126:127], v[22:23], 0, s[12:13]
	s_mov_b32 m0, s60
	s_nop 0
	global_load_lds_dwordx4 v[126:127], off
	s_waitcnt vmcnt(8)
	s_waitcnt lgkmcnt(0)
	s_barrier
; #define PG8_STAGE(bufoff, gbase, voff) do { _Pragma("unroll") for (int _i = 0; _i < 2; ++_i) \
;         __builtin_amdgcn_global_load_lds((const unsigned*)((const char*)(gbase) + (voff)[_i]), (PG8_LAS unsigned*)(lds + (bufoff) + ldsw + _i * 8192), 16, 0, 0); } while (0)
; #define PG8_LDA(dst, b, h) do { _Pragma("unroll") for (int m = 0; m < 4; ++m) _Pragma("unroll") for (int k = 0; k < 2; ++k) dst[m][k] = *(const PG8_LAS bf16x8*)(lds + PG8_SA(b, h) + aoff + m * 2048 + k * 1024); } while (0)
; #define PG8_LDB(dst, b, h) do { _Pragma("unroll") for (int n = 0; n < 2; ++n) _Pragma("unroll") for (int k = 0; k < 2; ++k) dst[n][k] = *(const PG8_LAS bf16x8*)(lds + PG8_SB(b, h) + boff + n * 2048 + k * 1024); } while (0)
; #define PG8_MMA(ai, bj, At, Bt) do { __builtin_amdgcn_s_setprio(1); _Pragma("unroll") for (int m = 0; m < 4; ++m) _Pragma("unroll") for (int n = 0; n < 2; ++n) _Pragma("unroll") for (int k = 0; k < 2; ++k) \
;         acc[ai][bj][m][n] = __builtin_amdgcn_mfma_f32_16x16x32_bf16(Bt[n][k], At[m][k], acc[ai][bj][m][n], 0, 0, 0); __builtin_amdgcn_s_setprio(0); } while (0)
; #define PG8_WAIT_V(n) asm volatile("s_waitcnt vmcnt(" #n ")" ::: "memory")
; #define PG8_WAIT_L(n) asm volatile("s_waitcnt lgkmcnt(" #n ")" ::: "memory")
; #define PG8_BAR __builtin_amdgcn_s_barrier()
; #define PG8_SCHED __builtin_amdgcn_sched_barrier(0)
; template <class Epi, class Sched, bool ALIGN_EPI = false, bool SP2 = false>
; __device__ __forceinline__ void gemm_phase(PG8_LAS unsigned char* lds, const Gemm g, const Sched& S, const Epi& E, const int wv0) {
;     ...
;             PG8_WAIT_V(8); PG8_WAIT_L(0); PG8_BAR; PG8_MMA(1, 0, At, B0); PG8_MMA(1, 1, At, B1); PG8_BAR; PG8_SCHED;
;             PG8_LDB(B0, 1, 0); PG8_LDB(B1, 1, 1); PG8_SCHED; PG8_LDA(At, 1, 0); PG8_STAGE(PG8_SA(0, 1), a2 + hstepA, voffA);
;             PG8_WAIT_V(8); PG8_WAIT_L(0); PG8_BAR; PG8_MMA(0, 0, At, B0); PG8_MMA(0, 1, At, B1); PG8_BAR; PG8_SCHED;
	s_setprio 1
	v_mfma_f32_16x16x32_bf16 v[170:173], v[34:37], v[94:97], 0
	v_mfma_f32_16x16x32_bf16 v[178:181], v[34:37], v[146:149], 0
	v_mfma_f32_16x16x32_bf16 v[186:189], v[34:37], v[154:157], 0
	v_mfma_f32_16x16x32_bf16 v[34:37], v[34:37], v[162:165], 0
	v_mfma_f32_16x16x32_bf16 v[170:173], v[38:41], v[138:141], v[170:173]
	v_mfma_f32_16x16x32_bf16 v[178:181], v[38:41], v[150:153], v[178:181]
	v_mfma_f32_16x16x32_bf16 v[186:189], v[38:41], v[158:161], v[186:189]
	v_mfma_f32_16x16x32_bf16 v[34:37], v[38:41], v[166:169], v[34:37]
	v_mfma_f32_16x16x32_bf16 v[38:41], v[42:45], v[162:165], 0
	v_mfma_f32_16x16x32_bf16 v[174:177], v[42:45], v[94:97], 0
	v_mfma_f32_16x16x32_bf16 v[182:185], v[42:45], v[146:149], 0
	v_mfma_f32_16x16x32_bf16 v[190:193], v[42:45], v[154:157], 0
	v_mfma_f32_16x16x32_bf16 v[38:41], v[46:49], v[166:169], v[38:41]
	v_mfma_f32_16x16x32_bf16 v[174:177], v[46:49], v[138:141], v[174:177]
	v_mfma_f32_16x16x32_bf16 v[182:185], v[46:49], v[150:153], v[182:185]
	v_mfma_f32_16x16x32_bf16 v[190:193], v[46:49], v[158:161], v[190:193]
	s_setprio 0
	s_setprio 1
	v_mfma_f32_16x16x32_bf16 v[42:45], v[50:53], v[94:97], 0
	v_mfma_f32_16x16x32_bf16 v[46:49], v[58:61], v[94:97], 0
	v_mfma_f32_16x16x32_bf16 v[42:45], v[54:57], v[138:141], v[42:45]
	v_mfma_f32_16x16x32_bf16 v[46:49], v[62:65], v[138:141], v[46:49]
	v_mfma_f32_16x16x32_bf16 v[94:97], v[50:53], v[146:149], 0
	v_mfma_f32_16x16x32_bf16 v[138:141], v[58:61], v[146:149], 0
	v_mfma_f32_16x16x32_bf16 v[146:149], v[50:53], v[154:157], 0
	v_mfma_f32_16x16x32_bf16 v[50:53], v[50:53], v[162:165], 0
	v_mfma_f32_16x16x32_bf16 v[94:97], v[54:57], v[150:153], v[94:97]
	v_mfma_f32_16x16x32_bf16 v[146:149], v[54:57], v[158:161], v[146:149]
	v_mfma_f32_16x16x32_bf16 v[50:53], v[54:57], v[166:169], v[50:53]
	v_mfma_f32_16x16x32_bf16 v[54:57], v[58:61], v[162:165], 0
	v_mfma_f32_16x16x32_bf16 v[138:141], v[62:65], v[150:153], v[138:141]
	v_mfma_f32_16x16x32_bf16 v[150:153], v[58:61], v[154:157], 0
	v_mfma_f32_16x16x32_bf16 v[54:57], v[62:65], v[166:169], v[54:57]
	v_mfma_f32_16x16x32_bf16 v[150:153], v[62:65], v[158:161], v[150:153]
	s_setprio 0
	s_barrier
	ds_read_b128 v[58:61], v247
	ds_read_b128 v[62:65], v247 offset:1024
	ds_read_b128 v[154:157], v247 offset:2048
	ds_read_b128 v[158:161], v247 offset:3072
	ds_read_b128 v[162:165], v246
	ds_read_b128 v[166:169], v246 offset:1024
	ds_read_b128 v[194:197], v246 offset:2048
	ds_read_b128 v[198:201], v246 offset:3072
	s_add_u32 s70, s24, 0x40100
	s_addc_u32 s71, s25, 0
	s_mov_b32 m0, s55
	v_lshl_add_u64 v[126:127], s[70:71], 0, v[16:17]
	ds_read_b128 v[206:209], v145 offset:32768
	ds_read_b128 v[210:213], v145 offset:33792
	ds_read_b128 v[214:217], v145 offset:34816
	ds_read_b128 v[218:221], v145 offset:35840
	ds_read_b128 v[222:225], v145 offset:36864
	ds_read_b128 v[226:229], v145 offset:37888
	ds_read_b128 v[230:233], v145 offset:38912
	ds_read_b128 v[234:237], v145 offset:39936
	global_load_lds_dwordx4 v[126:127], off
	v_lshl_add_u64 v[126:127], s[70:71], 0, v[30:31]
	s_mov_b32 m0, s56
	s_nop 0
	global_load_lds_dwordx4 v[126:127], off
	s_waitcnt vmcnt(8)
	s_waitcnt lgkmcnt(0)
	s_barrier
	s_setprio 1
	v_mfma_f32_16x16x32_bf16 v[98:101], v[58:61], v[206:209], v[98:101]
	v_mfma_f32_16x16x32_bf16 v[102:105], v[154:157], v[206:209], v[102:105]
	v_mfma_f32_16x16x32_bf16 v[106:109], v[58:61], v[214:217], v[106:109]
	v_mfma_f32_16x16x32_bf16 v[110:113], v[154:157], v[214:217], v[110:113]
	v_mfma_f32_16x16x32_bf16 v[114:117], v[58:61], v[222:225], v[114:117]
	v_mfma_f32_16x16x32_bf16 v[118:121], v[154:157], v[222:225], v[118:121]
	v_mfma_f32_16x16x32_bf16 v[122:125], v[58:61], v[230:233], v[122:125]
	v_mfma_f32_16x16x32_bf16 v[98:101], v[62:65], v[210:213], v[98:101]
	v_mfma_f32_16x16x32_bf16 v[102:105], v[158:161], v[210:213], v[102:105]
	v_mfma_f32_16x16x32_bf16 v[106:109], v[62:65], v[218:221], v[106:109]
	v_mfma_f32_16x16x32_bf16 v[110:113], v[158:161], v[218:221], v[110:113]
	v_mfma_f32_16x16x32_bf16 v[114:117], v[62:65], v[226:229], v[114:117]
	v_mfma_f32_16x16x32_bf16 v[118:121], v[158:161], v[226:229], v[118:121]
	v_mfma_f32_16x16x32_bf16 v[122:125], v[62:65], v[234:237], v[122:125]
	v_mfma_f32_16x16x32_bf16 v[130:133], v[154:157], v[230:233], v[130:133]
	v_mfma_f32_16x16x32_bf16 v[130:133], v[158:161], v[234:237], v[130:133]
	s_setprio 0
	s_setprio 1
	v_mfma_f32_16x16x32_bf16 v[66:69], v[194:197], v[206:209], v[66:69]
	v_mfma_f32_16x16x32_bf16 v[70:73], v[162:165], v[214:217], v[70:73]
	v_mfma_f32_16x16x32_bf16 v[74:77], v[194:197], v[214:217], v[74:77]
	v_mfma_f32_16x16x32_bf16 v[78:81], v[162:165], v[222:225], v[78:81]
	v_mfma_f32_16x16x32_bf16 v[82:85], v[194:197], v[222:225], v[82:85]
	v_mfma_f32_16x16x32_bf16 v[86:89], v[162:165], v[230:233], v[86:89]
	v_mfma_f32_16x16x32_bf16 v[90:93], v[194:197], v[230:233], v[90:93]
	v_mfma_f32_16x16x32_bf16 v[134:137], v[162:165], v[206:209], v[134:137]
	v_mfma_f32_16x16x32_bf16 v[66:69], v[198:201], v[210:213], v[66:69]
	v_mfma_f32_16x16x32_bf16 v[70:73], v[166:169], v[218:221], v[70:73]
	v_mfma_f32_16x16x32_bf16 v[74:77], v[198:201], v[218:221], v[74:77]
	v_mfma_f32_16x16x32_bf16 v[78:81], v[166:169], v[226:229], v[78:81]
	v_mfma_f32_16x16x32_bf16 v[82:85], v[198:201], v[226:229], v[82:85]
	v_mfma_f32_16x16x32_bf16 v[86:89], v[166:169], v[234:237], v[86:89]
	v_mfma_f32_16x16x32_bf16 v[90:93], v[198:201], v[234:237], v[90:93]
	v_mfma_f32_16x16x32_bf16 v[134:137], v[166:169], v[210:213], v[134:137]
	s_setprio 0
	s_barrier
; #define PG8_STAGE(bufoff, gbase, voff) do { _Pragma("unroll") for (int _i = 0; _i < 2; ++_i) \
;         __builtin_amdgcn_global_load_lds((const unsigned*)((const char*)(gbase) + (voff)[_i]), (PG8_LAS unsigned*)(lds + (bufoff) + ldsw + _i * 8192), 16, 0, 0); } while (0)
; #define PG8_LDA(dst, b, h) do { _Pragma("unroll") for (int m = 0; m < 4; ++m) _Pragma("unroll") for (int k = 0; k < 2; ++k) dst[m][k] = *(const PG8_LAS bf16x8*)(lds + PG8_SA(b, h) + aoff + m * 2048 + k * 1024); } while (0)
; #define PG8_LDB(dst, b, h) do { _Pragma("unroll") for (int n = 0; n < 2; ++n) _Pragma("unroll") for (int k = 0; k < 2; ++k) dst[n][k] = *(const PG8_LAS bf16x8*)(lds + PG8_SB(b, h) + boff + n * 2048 + k * 1024); } while (0)
; #define PG8_MMA(ai, bj, At, Bt) do { __builtin_amdgcn_s_setprio(1); _Pragma("unroll") for (int m = 0; m < 4; ++m) _Pragma("unroll") for (int n = 0; n < 2; ++n) _Pragma("unroll") for (int k = 0; k < 2; ++k) \
;         acc[ai][bj][m][n] = __builtin_amdgcn_mfma_f32_16x16x32_bf16(Bt[n][k], At[m][k], acc[ai][bj][m][n], 0, 0, 0); __builtin_amdgcn_s_setprio(0); } while (0)
; #define PG8_BAR __builtin_amdgcn_s_barrier()
; template <class Epi, class Sched, bool ALIGN_EPI = false, bool SP2 = false>
; __device__ __forceinline__ void gemm_phase(PG8_LAS unsigned char* lds, const Gemm g, const Sched& S, const Epi& E, const int wv0) {
;     ...
;             PG8_LDB(B0, 0, 0); PG8_LDB(B1, 0, 1); PG8_SCHED; PG8_LDA(At, 0, 0); PG8_STAGE(PG8_SA(1, 1), a1 + hstepA, voffA);
;             PG8_WAIT_V(8); PG8_WAIT_L(0); PG8_BAR; PG8_MMA(0, 0, At, B0); PG8_MMA(0, 1, At, B1); PG8_BAR; PG8_SCHED;
;             PG8_LDA(At, 0, 1); PG8_STAGE(PG8_SB(0, 0), b2, voffB); PG8_STAGE(PG8_SB(0, 1), b2 + hstepB, voffB); PG8_STAGE(PG8_SA(0, 0), a2, voffA);
;             PG8_WAIT_V(8); PG8_WAIT_L(0); PG8_BAR; PG8_MMA(1, 0, At, B0); PG8_MMA(1, 1, At, B1); PG8_BAR; PG8_SCHED;
;             PG8_LDB(B0, 1, 0); PG8_LDB(B1, 1, 1); PG8_SCHED; PG8_LDA(At, 1, 0); PG8_STAGE(PG8_SA(0, 1), a2 + hstepA, voffA);
;             PG8_WAIT_V(8); PG8_WAIT_L(0); PG8_BAR; PG8_MMA(0, 0, At, B0); PG8_MMA(0, 1, At, B1); PG8_BAR; PG8_SCHED;
;             PG8_LDA(At, 1, 1); PG8_STAGE(PG8_SB(1, 0), b3, voffB); PG8_STAGE(PG8_SB(1, 1), b3 + hstepB, voffB); PG8_STAGE(PG8_SA(1, 0), a3, voffA);
;             PG8_WAIT_V(8); PG8_WAIT_L(0); PG8_BAR; PG8_MMA(1, 0, At, B0); PG8_MMA(1, 1, At, B1); PG8_BAR; PG8_SCHED;
	s_add_u32 s70, s61, 0x2e280180
	s_addc_u32 s71, s62, 0
	s_mov_b32 m0, s26
	v_lshl_add_u64 v[126:127], s[70:71], 0, v[128:129]
	ds_read_b128 v[206:209], v145 offset:49152
	ds_read_b128 v[210:213], v145 offset:50176
	ds_read_b128 v[214:217], v145 offset:51200
	ds_read_b128 v[218:221], v145 offset:52224
	ds_read_b128 v[222:225], v145 offset:53248
	ds_read_b128 v[226:229], v145 offset:54272
	ds_read_b128 v[230:233], v145 offset:55296
	ds_read_b128 v[234:237], v145 offset:56320
	global_load_lds_dwordx4 v[126:127], off
	v_lshl_add_u64 v[126:127], s[70:71], 0, v[32:33]
	s_add_u32 s70, s61, 0x2e290180
	s_mov_b32 m0, s53
	s_addc_u32 s71, s62, 0
	global_load_lds_dwordx4 v[126:127], off
	v_lshl_add_u64 v[126:127], s[70:71], 0, v[128:129]
	s_mov_b32 m0, s57
	v_lshl_add_u64 v[32:33], s[70:71], 0, v[32:33]
	global_load_lds_dwordx4 v[126:127], off
	s_mov_b32 m0, s58
	s_nop 0
	global_load_lds_dwordx4 v[32:33], off
	v_lshl_add_u64 v[32:33], v[20:21], 0, s[14:15]
	s_mov_b32 m0, s27
	s_nop 0
	global_load_lds_dwordx4 v[32:33], off
	v_lshl_add_u64 v[32:33], v[22:23], 0, s[14:15]
	s_mov_b32 m0, s54
	s_nop 0
	global_load_lds_dwordx4 v[32:33], off
	s_waitcnt vmcnt(8)
	s_waitcnt lgkmcnt(0)
	s_barrier
	s_setprio 1
	v_mfma_f32_16x16x32_bf16 v[32:35], v[58:61], v[230:233], v[34:37]
	v_mfma_f32_16x16x32_bf16 v[36:39], v[154:157], v[230:233], v[38:41]
	v_mfma_f32_16x16x32_bf16 v[170:173], v[58:61], v[206:209], v[170:173]
	v_mfma_f32_16x16x32_bf16 v[174:177], v[154:157], v[206:209], v[174:177]
	v_mfma_f32_16x16x32_bf16 v[178:181], v[58:61], v[214:217], v[178:181]
	v_mfma_f32_16x16x32_bf16 v[182:185], v[154:157], v[214:217], v[182:185]
	v_mfma_f32_16x16x32_bf16 v[186:189], v[58:61], v[222:225], v[186:189]
	v_mfma_f32_16x16x32_bf16 v[190:193], v[154:157], v[222:225], v[190:193]
	v_mfma_f32_16x16x32_bf16 v[32:35], v[62:65], v[234:237], v[32:35]
	v_mfma_f32_16x16x32_bf16 v[36:39], v[158:161], v[234:237], v[36:39]
	v_mfma_f32_16x16x32_bf16 v[170:173], v[62:65], v[210:213], v[170:173]
	v_mfma_f32_16x16x32_bf16 v[174:177], v[158:161], v[210:213], v[174:177]
	v_mfma_f32_16x16x32_bf16 v[178:181], v[62:65], v[218:221], v[178:181]
	v_mfma_f32_16x16x32_bf16 v[182:185], v[158:161], v[218:221], v[182:185]
	v_mfma_f32_16x16x32_bf16 v[186:189], v[62:65], v[226:229], v[186:189]
	v_mfma_f32_16x16x32_bf16 v[190:193], v[158:161], v[226:229], v[190:193]
	s_setprio 0
	s_setprio 1
	v_mfma_f32_16x16x32_bf16 v[40:43], v[162:165], v[206:209], v[42:45]
	v_mfma_f32_16x16x32_bf16 v[44:47], v[194:197], v[206:209], v[46:49]
	v_mfma_f32_16x16x32_bf16 v[58:61], v[162:165], v[214:217], v[94:97]
	v_mfma_f32_16x16x32_bf16 v[62:65], v[194:197], v[214:217], v[138:141]
	v_mfma_f32_16x16x32_bf16 v[94:97], v[162:165], v[222:225], v[146:149]
	v_mfma_f32_16x16x32_bf16 v[48:51], v[162:165], v[230:233], v[50:53]
	v_mfma_f32_16x16x32_bf16 v[52:55], v[194:197], v[230:233], v[54:57]
	v_mfma_f32_16x16x32_bf16 v[40:43], v[166:169], v[210:213], v[40:43]
	v_mfma_f32_16x16x32_bf16 v[44:47], v[198:201], v[210:213], v[44:47]
	v_mfma_f32_16x16x32_bf16 v[58:61], v[166:169], v[218:221], v[58:61]
	v_mfma_f32_16x16x32_bf16 v[62:65], v[198:201], v[218:221], v[62:65]
	v_mfma_f32_16x16x32_bf16 v[94:97], v[166:169], v[226:229], v[94:97]
	v_mfma_f32_16x16x32_bf16 v[138:141], v[194:197], v[222:225], v[150:153]
	v_mfma_f32_16x16x32_bf16 v[48:51], v[166:169], v[234:237], v[48:51]
	v_mfma_f32_16x16x32_bf16 v[52:55], v[198:201], v[234:237], v[52:55]
	v_mfma_f32_16x16x32_bf16 v[138:141], v[198:201], v[226:229], v[138:141]
	s_setprio 0
	s_barrier
	ds_read_b128 v[146:149], v203
	ds_read_b128 v[150:153], v203 offset:1024
	ds_read_b128 v[154:157], v203 offset:2048
	ds_read_b128 v[158:161], v203 offset:3072
	ds_read_b128 v[162:165], v202
	ds_read_b128 v[166:169], v202 offset:1024
	ds_read_b128 v[194:197], v202 offset:2048
	ds_read_b128 v[198:201], v202 offset:3072
	s_add_u32 s24, s24, 0x40180
	s_addc_u32 s25, s25, 0
	s_mov_b32 m0, s68
	v_lshl_add_u64 v[16:17], s[24:25], 0, v[16:17]
	ds_read_b128 v[206:209], v145
	ds_read_b128 v[210:213], v145 offset:1024
	ds_read_b128 v[214:217], v145 offset:2048
	ds_read_b128 v[218:221], v145 offset:3072
	ds_read_b128 v[222:225], v145 offset:4096
	ds_read_b128 v[226:229], v145 offset:5120
	ds_read_b128 v[230:233], v145 offset:6144
	ds_read_b128 v[234:237], v145 offset:7168
	global_load_lds_dwordx4 v[16:17], off
	v_lshl_add_u64 v[16:17], s[24:25], 0, v[30:31]
	s_mov_b32 m0, s63
	s_nop 0
	global_load_lds_dwordx4 v[16:17], off
	s_waitcnt vmcnt(8)
	s_waitcnt lgkmcnt(0)
	s_barrier
; #define PG8_STAGE(bufoff, gbase, voff) do { _Pragma("unroll") for (int _i = 0; _i < 2; ++_i) \
;         __builtin_amdgcn_global_load_lds((const unsigned*)((const char*)(gbase) + (voff)[_i]), (PG8_LAS unsigned*)(lds + (bufoff) + ldsw + _i * 8192), 16, 0, 0); } while (0)
; #define PG8_LDA(dst, b, h) do { _Pragma("unroll") for (int m = 0; m < 4; ++m) _Pragma("unroll") for (int k = 0; k < 2; ++k) dst[m][k] = *(const PG8_LAS bf16x8*)(lds + PG8_SA(b, h) + aoff + m * 2048 + k * 1024); } while (0)
; #define PG8_MMA(ai, bj, At, Bt) do { __builtin_amdgcn_s_setprio(1); _Pragma("unroll") for (int m = 0; m < 4; ++m) _Pragma("unroll") for (int n = 0; n < 2; ++n) _Pragma("unroll") for (int k = 0; k < 2; ++k) \
;         acc[ai][bj][m][n] = __builtin_amdgcn_mfma_f32_16x16x32_bf16(Bt[n][k], At[m][k], acc[ai][bj][m][n], 0, 0, 0); __builtin_amdgcn_s_setprio(0); } while (0)
; #define PG8_WAIT_V(n) asm volatile("s_waitcnt vmcnt(" #n ")" ::: "memory")
; #define PG8_WAIT_L(n) asm volatile("s_waitcnt lgkmcnt(" #n ")" ::: "memory")
; #define PG8_BAR __builtin_amdgcn_s_barrier()
; #define PG8_SCHED __builtin_amdgcn_sched_barrier(0)
; template <class Epi, class Sched, bool ALIGN_EPI = false, bool SP2 = false>
; __device__ __forceinline__ void gemm_phase(PG8_LAS unsigned char* lds, const Gemm g, const Sched& S, const Epi& E, const int wv0) {
;     ...
;             PG8_WAIT_V(8); PG8_WAIT_L(0); PG8_BAR; PG8_MMA(0, 0, At, B0); PG8_MMA(0, 1, At, B1); PG8_BAR; PG8_SCHED;
;             PG8_LDA(At, 0, 1); PG8_STAGE(PG8_SB(0, 0), b2, voffB); PG8_STAGE(PG8_SB(0, 1), b2 + hstepB, voffB); PG8_STAGE(PG8_SA(0, 0), a2, voffA);
;             PG8_WAIT_V(8); PG8_WAIT_L(0); PG8_BAR; PG8_MMA(1, 0, At, B0); PG8_MMA(1, 1, At, B1); PG8_BAR; PG8_SCHED;
	s_setprio 1
	v_mfma_f32_16x16x32_bf16 v[114:117], v[146:149], v[222:225], v[114:117]
	v_mfma_f32_16x16x32_bf16 v[238:241], v[150:153], v[226:229], v[114:117]
	v_mfma_f32_16x16x32_bf16 v[114:117], v[154:157], v[222:225], v[118:121]
	v_mfma_f32_16x16x32_bf16 v[98:101], v[146:149], v[206:209], v[98:101]
	v_mfma_f32_16x16x32_bf16 v[102:105], v[154:157], v[206:209], v[102:105]
	v_mfma_f32_16x16x32_bf16 v[106:109], v[146:149], v[214:217], v[106:109]
	v_mfma_f32_16x16x32_bf16 v[110:113], v[154:157], v[214:217], v[110:113]
	v_mfma_f32_16x16x32_bf16 v[242:245], v[158:161], v[226:229], v[114:117]
	v_mfma_f32_16x16x32_bf16 v[114:117], v[146:149], v[230:233], v[122:125]
	v_mfma_f32_16x16x32_bf16 v[98:101], v[150:153], v[210:213], v[98:101]
	v_mfma_f32_16x16x32_bf16 v[102:105], v[158:161], v[210:213], v[102:105]
	v_mfma_f32_16x16x32_bf16 v[106:109], v[150:153], v[218:221], v[106:109]
	v_mfma_f32_16x16x32_bf16 v[110:113], v[158:161], v[218:221], v[110:113]
	v_mfma_f32_16x16x32_bf16 v[124:127], v[150:153], v[234:237], v[114:117]
	v_mfma_f32_16x16x32_bf16 v[114:117], v[154:157], v[230:233], v[130:133]
	v_mfma_f32_16x16x32_bf16 v[130:133], v[158:161], v[234:237], v[114:117]
	s_setprio 0
	s_setprio 1
	v_mfma_f32_16x16x32_bf16 v[66:69], v[194:197], v[206:209], v[66:69]
	v_mfma_f32_16x16x32_bf16 v[114:117], v[162:165], v[206:209], v[134:137]
	v_mfma_f32_16x16x32_bf16 v[206:209], v[198:201], v[210:213], v[66:69]
	v_mfma_f32_16x16x32_bf16 v[66:69], v[162:165], v[214:217], v[70:73]
	v_mfma_f32_16x16x32_bf16 v[134:137], v[166:169], v[210:213], v[114:117]
	v_mfma_f32_16x16x32_bf16 v[210:213], v[166:169], v[218:221], v[66:69]
	v_mfma_f32_16x16x32_bf16 v[66:69], v[194:197], v[214:217], v[74:77]
	v_mfma_f32_16x16x32_bf16 v[214:217], v[198:201], v[218:221], v[66:69]
	v_mfma_f32_16x16x32_bf16 v[66:69], v[162:165], v[222:225], v[78:81]
	v_mfma_f32_16x16x32_bf16 v[76:79], v[166:169], v[226:229], v[66:69]
	v_mfma_f32_16x16x32_bf16 v[66:69], v[194:197], v[222:225], v[82:85]
	v_mfma_f32_16x16x32_bf16 v[80:83], v[198:201], v[226:229], v[66:69]
	v_mfma_f32_16x16x32_bf16 v[66:69], v[162:165], v[230:233], v[86:89]
	v_mfma_f32_16x16x32_bf16 v[218:221], v[166:169], v[234:237], v[66:69]
	v_mfma_f32_16x16x32_bf16 v[66:69], v[194:197], v[230:233], v[90:93]
	v_mfma_f32_16x16x32_bf16 v[222:225], v[198:201], v[234:237], v[66:69]
	s_setprio 0
	s_barrier
	s_mov_b32 m0, s64
	s_nop 3
	ds_read_b128 v[66:69], v145 offset:16384
	ds_read_b128 v[70:73], v145 offset:17408
	ds_read_b128 v[84:87], v145 offset:18432
	ds_read_b128 v[88:91], v145 offset:19456
	ds_read_b128 v[114:117], v145 offset:20480
	ds_read_b128 v[118:121], v145 offset:21504
	ds_read_b128 v[226:229], v145 offset:22528
	ds_read_b128 v[230:233], v145 offset:23552
	global_load_lds_dwordx4 v[26:27], off
	s_mov_b32 m0, s65
	s_nop 0
	global_load_lds_dwordx4 v[28:29], off
	s_mov_b32 m0, s66
	s_nop 0
	global_load_lds_dwordx4 v[24:25], off
	s_mov_b32 m0, s67
	s_nop 0
	global_load_lds_dwordx4 v[18:19], off
	s_mov_b32 m0, s59
	s_nop 0
	global_load_lds_dwordx4 v[20:21], off
	s_mov_b32 m0, s60
	s_nop 0
	global_load_lds_dwordx4 v[22:23], off
	s_waitcnt vmcnt(8)
	s_waitcnt lgkmcnt(0)
	s_barrier
	s_setprio 1
	v_mfma_f32_16x16x32_bf16 v[16:19], v[146:149], v[66:69], v[170:173]
	v_mfma_f32_16x16x32_bf16 v[20:23], v[154:157], v[66:69], v[174:177]
	v_mfma_f32_16x16x32_bf16 v[24:27], v[146:149], v[84:87], v[178:181]
	v_mfma_f32_16x16x32_bf16 v[28:31], v[154:157], v[84:87], v[182:185]
	v_mfma_f32_16x16x32_bf16 v[32:35], v[146:149], v[226:229], v[32:35]
	v_mfma_f32_16x16x32_bf16 v[16:19], v[150:153], v[70:73], v[16:19]
	v_mfma_f32_16x16x32_bf16 v[20:23], v[158:161], v[70:73], v[20:23]
	v_mfma_f32_16x16x32_bf16 v[24:27], v[150:153], v[88:91], v[24:27]
	v_mfma_f32_16x16x32_bf16 v[28:31], v[158:161], v[88:91], v[28:31]
	v_mfma_f32_16x16x32_bf16 v[170:173], v[146:149], v[114:117], v[186:189]
	v_mfma_f32_16x16x32_bf16 v[174:177], v[154:157], v[114:117], v[190:193]
	v_mfma_f32_16x16x32_bf16 v[32:35], v[150:153], v[230:233], v[32:35]
	v_mfma_f32_16x16x32_bf16 v[36:39], v[154:157], v[226:229], v[36:39]
	v_mfma_f32_16x16x32_bf16 v[170:173], v[150:153], v[118:121], v[170:173]
	v_mfma_f32_16x16x32_bf16 v[174:177], v[158:161], v[118:121], v[174:177]
	v_mfma_f32_16x16x32_bf16 v[146:149], v[158:161], v[230:233], v[36:39]
	s_setprio 0
	s_setprio 1
	v_mfma_f32_16x16x32_bf16 v[36:39], v[162:165], v[66:69], v[40:43]
	v_mfma_f32_16x16x32_bf16 v[150:153], v[166:169], v[70:73], v[36:39]
	v_mfma_f32_16x16x32_bf16 v[36:39], v[194:197], v[66:69], v[44:47]
	v_mfma_f32_16x16x32_bf16 v[44:47], v[198:201], v[70:73], v[36:39]
	v_mfma_f32_16x16x32_bf16 v[36:39], v[162:165], v[84:87], v[58:61]
	v_mfma_f32_16x16x32_bf16 v[154:157], v[166:169], v[88:91], v[36:39]
	v_mfma_f32_16x16x32_bf16 v[36:39], v[194:197], v[84:87], v[62:65]
	v_mfma_f32_16x16x32_bf16 v[158:161], v[198:201], v[88:91], v[36:39]
	v_mfma_f32_16x16x32_bf16 v[36:39], v[162:165], v[114:117], v[94:97]
	v_mfma_f32_16x16x32_bf16 v[178:181], v[166:169], v[118:121], v[36:39]
	v_mfma_f32_16x16x32_bf16 v[36:39], v[194:197], v[114:117], v[138:141]
	v_mfma_f32_16x16x32_bf16 v[138:141], v[198:201], v[118:121], v[36:39]
	v_mfma_f32_16x16x32_bf16 v[36:39], v[162:165], v[226:229], v[48:51]
	v_mfma_f32_16x16x32_bf16 v[162:165], v[166:169], v[230:233], v[36:39]
	v_mfma_f32_16x16x32_bf16 v[36:39], v[194:197], v[226:229], v[52:55]
	v_mfma_f32_16x16x32_bf16 v[166:169], v[198:201], v[230:233], v[36:39]
	s_setprio 0
	s_barrier
; #define PG8_STAGE(bufoff, gbase, voff) do { _Pragma("unroll") for (int _i = 0; _i < 2; ++_i) \
;         __builtin_amdgcn_global_load_lds((const unsigned*)((const char*)(gbase) + (voff)[_i]), (PG8_LAS unsigned*)(lds + (bufoff) + ldsw + _i * 8192), 16, 0, 0); } while (0)
; #define PG8_LDA(dst, b, h) do { _Pragma("unroll") for (int m = 0; m < 4; ++m) _Pragma("unroll") for (int k = 0; k < 2; ++k) dst[m][k] = *(const PG8_LAS bf16x8*)(lds + PG8_SA(b, h) + aoff + m * 2048 + k * 1024); } while (0)
; #define PG8_LDB(dst, b, h) do { _Pragma("unroll") for (int n = 0; n < 2; ++n) _Pragma("unroll") for (int k = 0; k < 2; ++k) dst[n][k] = *(const PG8_LAS bf16x8*)(lds + PG8_SB(b, h) + boff + n * 2048 + k * 1024); } while (0)
; #define PG8_MMA(ai, bj, At, Bt) do { __builtin_amdgcn_s_setprio(1); _Pragma("unroll") for (int m = 0; m < 4; ++m) _Pragma("unroll") for (int n = 0; n < 2; ++n) _Pragma("unroll") for (int k = 0; k < 2; ++k) \
;         acc[ai][bj][m][n] = __builtin_amdgcn_mfma_f32_16x16x32_bf16(Bt[n][k], At[m][k], acc[ai][bj][m][n], 0, 0, 0); __builtin_amdgcn_s_setprio(0); } while (0)
; #define PG8_WAIT_V(n) asm volatile("s_waitcnt vmcnt(" #n ")" ::: "memory")
; #define PG8_WAIT_L(n) asm volatile("s_waitcnt lgkmcnt(" #n ")" ::: "memory")
; #define PG8_BAR __builtin_amdgcn_s_barrier()
; #define PG8_SCHED __builtin_amdgcn_sched_barrier(0)
; template <class Epi, class Sched, bool ALIGN_EPI = false, bool SP2 = false>
; __device__ __forceinline__ void gemm_phase(PG8_LAS unsigned char* lds, const Gemm g, const Sched& S, const Epi& E, const int wv0) {
;     ...
;             PG8_LDB(B0, 1, 0); PG8_LDB(B1, 1, 1); PG8_SCHED; PG8_LDA(At, 1, 0); PG8_STAGE(PG8_SA(0, 1), a2 + hstepA, voffA);
;             PG8_WAIT_V(8); PG8_WAIT_L(0); PG8_BAR; PG8_MMA(0, 0, At, B0); PG8_MMA(0, 1, At, B1); PG8_BAR; PG8_SCHED;
;             PG8_LDA(At, 1, 1); PG8_STAGE(PG8_SB(1, 0), b3, voffB); PG8_STAGE(PG8_SB(1, 1), b3 + hstepB, voffB); PG8_STAGE(PG8_SA(1, 0), a3, voffA);
;             PG8_WAIT_V(8); PG8_WAIT_L(0); PG8_BAR; PG8_MMA(1, 0, At, B0); PG8_MMA(1, 1, At, B1); PG8_BAR; PG8_SCHED;
;     ...
;     PG8_WAIT_V(0);
;     if constexpr (!ALIGN_EPI) { if (wr == 0) PG8_BAR; }
	ds_read_b128 v[48:51], v247
	ds_read_b128 v[64:67], v247 offset:1024
	ds_read_b128 v[182:185], v247 offset:2048
	ds_read_b128 v[186:189], v247 offset:3072
	ds_read_b128 v[190:193], v246
	ds_read_b128 v[194:197], v246 offset:1024
	ds_read_b128 v[198:201], v246 offset:2048
	ds_read_b128 v[226:229], v246 offset:3072
	s_mov_b32 m0, s55
	ds_read_b128 v[36:39], v145 offset:32768
	ds_read_b128 v[40:43], v145 offset:33792
	ds_read_b128 v[52:55], v145 offset:34816
	ds_read_b128 v[56:59], v145 offset:35840
	ds_read_b128 v[60:63], v145 offset:36864
	ds_read_b128 v[230:233], v145 offset:37888
	ds_read_b128 v[234:237], v145 offset:38912
	ds_read_b128 v[246:249], v145 offset:39936
	global_load_lds_dwordx4 v[12:13], off
	s_mov_b32 m0, s56
	s_nop 0
	global_load_lds_dwordx4 v[14:15], off
	s_waitcnt vmcnt(8)
	s_waitcnt lgkmcnt(0)
	s_barrier
	s_setprio 1
	v_mfma_f32_16x16x32_bf16 v[12:15], v[48:51], v[36:39], v[98:101]
	v_mfma_f32_16x16x32_bf16 v[120:123], v[64:67], v[40:43], v[12:15]
	v_mfma_f32_16x16x32_bf16 v[12:15], v[182:185], v[36:39], v[102:105]
	v_mfma_f32_16x16x32_bf16 v[116:119], v[186:189], v[40:43], v[12:15]
	v_mfma_f32_16x16x32_bf16 v[12:15], v[48:51], v[52:55], v[106:109]
	v_mfma_f32_16x16x32_bf16 v[104:107], v[64:67], v[56:59], v[12:15]
	v_mfma_f32_16x16x32_bf16 v[12:15], v[182:185], v[52:55], v[110:113]
	v_mfma_f32_16x16x32_bf16 v[100:103], v[186:189], v[56:59], v[12:15]
	v_mfma_f32_16x16x32_bf16 v[12:15], v[48:51], v[60:63], v[238:241]
	v_mfma_f32_16x16x32_bf16 v[88:91], v[64:67], v[230:233], v[12:15]
	v_mfma_f32_16x16x32_bf16 v[12:15], v[182:185], v[60:63], v[242:245]
	v_mfma_f32_16x16x32_bf16 v[84:87], v[186:189], v[230:233], v[12:15]
	v_mfma_f32_16x16x32_bf16 v[12:15], v[48:51], v[234:237], v[124:127]
	v_mfma_f32_16x16x32_bf16 v[72:75], v[64:67], v[246:249], v[12:15]
	v_mfma_f32_16x16x32_bf16 v[12:15], v[182:185], v[234:237], v[130:133]
	v_mfma_f32_16x16x32_bf16 v[68:71], v[186:189], v[246:249], v[12:15]
	s_setprio 0
	s_setprio 1
	v_mfma_f32_16x16x32_bf16 v[12:15], v[190:193], v[36:39], v[134:137]
	v_mfma_f32_16x16x32_bf16 v[124:127], v[194:197], v[40:43], v[12:15]
	v_mfma_f32_16x16x32_bf16 v[12:15], v[198:201], v[36:39], v[206:209]
	v_mfma_f32_16x16x32_bf16 v[112:115], v[226:229], v[40:43], v[12:15]
	v_mfma_f32_16x16x32_bf16 v[12:15], v[190:193], v[52:55], v[210:213]
	v_mfma_f32_16x16x32_bf16 v[108:111], v[194:197], v[56:59], v[12:15]
	v_mfma_f32_16x16x32_bf16 v[12:15], v[198:201], v[52:55], v[214:217]
	v_mfma_f32_16x16x32_bf16 v[96:99], v[226:229], v[56:59], v[12:15]
	v_mfma_f32_16x16x32_bf16 v[12:15], v[190:193], v[60:63], v[76:79]
	v_mfma_f32_16x16x32_bf16 v[92:95], v[194:197], v[230:233], v[12:15]
	v_mfma_f32_16x16x32_bf16 v[12:15], v[198:201], v[60:63], v[80:83]
	v_mfma_f32_16x16x32_bf16 v[80:83], v[226:229], v[230:233], v[12:15]
	v_mfma_f32_16x16x32_bf16 v[12:15], v[190:193], v[234:237], v[218:221]
	v_mfma_f32_16x16x32_bf16 v[76:79], v[194:197], v[246:249], v[12:15]
	v_mfma_f32_16x16x32_bf16 v[12:15], v[198:201], v[234:237], v[222:225]
	v_mfma_f32_16x16x32_bf16 v[56:59], v[226:229], v[246:249], v[12:15]
	s_setprio 0
	s_barrier
	s_mov_b32 m0, s26
	s_nop 3
	ds_read_b128 v[12:15], v145 offset:49152
	ds_read_b128 v[130:133], v145 offset:50176
	ds_read_b128 v[134:137], v145 offset:51200
	ds_read_b128 v[206:209], v145 offset:52224
	ds_read_b128 v[210:213], v145 offset:53248
	ds_read_b128 v[214:217], v145 offset:54272
	ds_read_b128 v[218:221], v145 offset:55296
	ds_read_b128 v[222:225], v145 offset:56320
	global_load_lds_dwordx4 v[2:3], off
	s_mov_b32 m0, s53
	s_nop 0
	global_load_lds_dwordx4 v[4:5], off
	s_mov_b32 m0, s57
	s_nop 0
	global_load_lds_dwordx4 v[8:9], off
	s_mov_b32 m0, s58
	s_nop 0
	global_load_lds_dwordx4 v[10:11], off
	s_mov_b32 m0, s27
	s_nop 0
	global_load_lds_dwordx4 v[0:1], off
	s_mov_b32 m0, s54
	s_nop 0
	global_load_lds_dwordx4 v[6:7], off
	s_waitcnt vmcnt(8)
	s_waitcnt lgkmcnt(0)
	s_barrier
	s_setprio 1
	v_mfma_f32_16x16x32_bf16 v[0:3], v[48:51], v[12:15], v[16:19]
	v_mfma_f32_16x16x32_bf16 v[60:63], v[64:67], v[130:133], v[0:3]
	v_mfma_f32_16x16x32_bf16 v[0:3], v[182:185], v[12:15], v[20:23]
	v_mfma_f32_16x16x32_bf16 v[52:55], v[186:189], v[130:133], v[0:3]
	v_mfma_f32_16x16x32_bf16 v[0:3], v[48:51], v[134:137], v[24:27]
	v_mfma_f32_16x16x32_bf16 v[40:43], v[64:67], v[206:209], v[0:3]
	v_mfma_f32_16x16x32_bf16 v[0:3], v[182:185], v[134:137], v[28:31]
	v_mfma_f32_16x16x32_bf16 v[36:39], v[186:189], v[206:209], v[0:3]
	v_mfma_f32_16x16x32_bf16 v[0:3], v[48:51], v[210:213], v[170:173]
	v_mfma_f32_16x16x32_bf16 v[24:27], v[64:67], v[214:217], v[0:3]
	v_mfma_f32_16x16x32_bf16 v[0:3], v[182:185], v[210:213], v[174:177]
	v_mfma_f32_16x16x32_bf16 v[20:23], v[186:189], v[214:217], v[0:3]
	v_mfma_f32_16x16x32_bf16 v[0:3], v[48:51], v[218:221], v[32:35]
	v_mfma_f32_16x16x32_bf16 v[8:11], v[64:67], v[222:225], v[0:3]
	v_mfma_f32_16x16x32_bf16 v[0:3], v[182:185], v[218:221], v[146:149]
	v_mfma_f32_16x16x32_bf16 v[4:7], v[186:189], v[222:225], v[0:3]
	s_setprio 0
	s_setprio 1
	v_mfma_f32_16x16x32_bf16 v[0:3], v[190:193], v[12:15], v[150:153]
	v_mfma_f32_16x16x32_bf16 v[64:67], v[194:197], v[130:133], v[0:3]
	v_mfma_f32_16x16x32_bf16 v[0:3], v[198:201], v[12:15], v[44:47]
	v_mfma_f32_16x16x32_bf16 v[48:51], v[226:229], v[130:133], v[0:3]
	v_mfma_f32_16x16x32_bf16 v[0:3], v[190:193], v[134:137], v[154:157]
	v_mfma_f32_16x16x32_bf16 v[44:47], v[194:197], v[206:209], v[0:3]
	v_mfma_f32_16x16x32_bf16 v[0:3], v[198:201], v[134:137], v[158:161]
	v_mfma_f32_16x16x32_bf16 v[32:35], v[226:229], v[206:209], v[0:3]
	v_mfma_f32_16x16x32_bf16 v[0:3], v[190:193], v[210:213], v[178:181]
	v_mfma_f32_16x16x32_bf16 v[28:31], v[194:197], v[214:217], v[0:3]
	v_mfma_f32_16x16x32_bf16 v[0:3], v[198:201], v[210:213], v[138:141]
	v_mfma_f32_16x16x32_bf16 v[16:19], v[226:229], v[214:217], v[0:3]
	v_mfma_f32_16x16x32_bf16 v[0:3], v[190:193], v[218:221], v[162:165]
	v_mfma_f32_16x16x32_bf16 v[12:15], v[194:197], v[222:225], v[0:3]
	v_mfma_f32_16x16x32_bf16 v[0:3], v[198:201], v[218:221], v[166:169]
	v_mfma_f32_16x16x32_bf16 v[0:3], v[226:229], v[222:225], v[0:3]
	s_setprio 0
	s_barrier
	s_waitcnt vmcnt(0)
	s_cmpk_gt_u32 s52, 0xff
	s_cbranch_scc1 .LBB0_1301
	s_barrier

;     __device__ __forceinline__ bool next(int i, Unit& u) const { int pm, pn; if (!to.get((long)i * G + c, pm, pn)) return false; u.pm = pm; u.pn = pn; u.aux = 0; u.a = A + (size_t)pm * ta; u.b = B + (size_t)pn * tb; return true; }
;     __device__ __forceinline__ bool next(int i, Unit& u) const { if (i != 0) return false; u = one; return true; }
; #define PG8_LDA(dst, b, h) do { _Pragma("unroll") for (int m = 0; m < 4; ++m) _Pragma("unroll") for (int k = 0; k < 2; ++k) dst[m][k] = *(const PG8_LAS bf16x8*)(lds + PG8_SA(b, h) + aoff + m * 2048 + k * 1024); } while (0)
; template <class Epi, class Sched, bool ALIGN_EPI = false, bool SP2 = false>
; __device__ __forceinline__ void gemm_phase(PG8_LAS unsigned char* lds, const Gemm g, const Sched& S, const Epi& E, const int wv0) {
;     ...
;         PG8_STAGE(PG8_SB(1, 0), cB + kstep, voffB); PG8_STAGE(PG8_SA(1, 0), cA + kstep, voffA); PG8_STAGE(PG8_SB(1, 1), cB + hstepB + kstep, voffB);
;         PG8_WAIT_V(6); PG8_BAR;
;     } else {
;         PG8_STAGE(PG8_SB(0, 0), cB, voffB); PG8_STAGE(PG8_SA(0, 0), cA, voffA); PG8_STAGE(PG8_SB(0, 1), cB + hstepB, voffB); PG8_STAGE(PG8_SA(0, 1), cA + hstepA, voffA);
;         if (wr == 1) PG8_BAR;
;         PG8_WAIT_V(4); PG8_BAR;
;         PG8_STAGE(PG8_SB(1, 0), cB + kstep, voffB); PG8_STAGE(PG8_SA(1, 0), cA + kstep, voffA); PG8_STAGE(PG8_SB(1, 1), cB + hstepB + kstep, voffB);
;         PG8_WAIT_V(6); PG8_BAR;
;     }
;     for (;;) {
;         const bool has_next = S.next(ui + 1, nxt);
;         const char* nA = has_next ? nxt.a : cA; const char* nB = has_next ? nxt.b : cB;
;         for (int t = 0; t < nt; t += 2) {
;             const bool last = (t == nt - 2);
;             const char* a1 = cA + (size_t)(t + 1) * kstep;
;             const char* a2 = last ? nA : cA + (size_t)(t + 2) * kstep; const char* b2 = last ? nB : cB + (size_t)(t + 2) * kstep;
;             const char* a3 = a2 + kstep; const char* b3 = b2 + kstep;
;             if constexpr (SP2) {
;             PG8_LDB(B0, 0, 0); PG8_LDB(B1, 0, 1); PG8_SCHED; PG8_LDA(At, 0, 0); PG8_STAGE(PG8_SA(1, 1), a1 + hstepA, voffA);
;             PG8_WAIT_V(8); PG8_WAIT_L(0); PG8_BAR; PG8_MMA(0, 0, At, B0); PG8_MMA(0, 1, At, B1); PG8_BAR; PG8_SCHED;
;             PG8_LDA(At, 0, 1); PG8_STAGE(PG8_SB(0, 0), b2, voffB); PG8_STAGE(PG8_SB(0, 1), b2 + hstepB, voffB); PG8_STAGE(PG8_SA(0, 0), a2, voffA);
.LBB0_1319:
	s_lshl_b32 s50, s50, 5
	s_add_i32 s51, s36, s63
	s_and_b32 s50, s50, 0x60
	v_lshl_add_u64 v[2:3], v[26:27], 0, s[10:11]
	s_mov_b32 m0, s51
	s_add_i32 s53, s51, 0x2000
	s_lshl_b32 s62, s61, 13
	s_lshl_b32 s66, s50, 7
	s_waitcnt vmcnt(2)
	s_barrier
	global_load_lds_dwordx4 v[2:3], off
	v_lshl_add_u64 v[4:5], v[28:29], 0, s[10:11]
	s_mov_b32 m0, s53
	s_add_i32 s52, s59, 0x8000
	s_add_i32 s54, s59, 0xa000
	global_load_lds_dwordx4 v[4:5], off
	v_lshl_add_u64 v[0:1], v[20:21], 0, s[10:11]
	s_mov_b32 m0, s52
	s_add_u32 s64, s24, 0x10080
	global_load_lds_dwordx4 v[0:1], off
	v_lshl_add_u64 v[6:7], v[22:23], 0, s[10:11]
	s_mov_b32 m0, s54
	s_addc_u32 s65, s25, 0
	s_add_i32 s57, s37, s63
	global_load_lds_dwordx4 v[6:7], off
	v_lshl_add_u64 v[8:9], s[64:65], 0, v[128:129]
	s_mov_b32 m0, s57
	s_add_i32 s58, s57, 0x2000
	global_load_lds_dwordx4 v[8:9], off
	v_lshl_add_u64 v[10:11], s[64:65], 0, v[32:33]
	s_mov_b32 m0, s58
	v_lshrrev_b32_e32 v37, 1, v34
	global_load_lds_dwordx4 v[10:11], off
	v_and_b32_e32 v37, 24, v37
	v_and_b32_e32 v35, 15, v34
	v_lshlrev_b32_e32 v38, 1, v37
	v_lshlrev_b32_e32 v34, 2, v34
	v_lshl_or_b32 v36, s61, 6, v35
	v_lshl_or_b32 v35, v35, 6, v38
	v_and_b32_e32 v34, 32, v34
	v_bitop3_b32 v70, v35, s66, v34 bitop3:0xde
	v_add_u32_e32 v127, s48, v70
	s_waitcnt vmcnt(6)
	s_barrier
	v_add_u32_e32 v126, s47, v70
	ds_read_b128 v[38:41], v127
	ds_read_b128 v[42:45], v127 offset:1024
	ds_read_b128 v[46:49], v127 offset:2048
	ds_read_b128 v[50:53], v127 offset:3072
	ds_read_b128 v[54:57], v126
	ds_read_b128 v[58:61], v126 offset:1024
	ds_read_b128 v[62:65], v126 offset:2048
	ds_read_b128 v[66:69], v126 offset:3072
	v_bitop3_b32 v34, v35, s62, v34 bitop3:0xde
	v_add_u32_e32 v143, 0, v34
	v_add_u32_e32 v238, s37, v70
	v_add_u32_e32 v239, s36, v70
	s_add_u32 s66, s22, 0x40080
	s_addc_u32 s67, s23, 0
	s_add_i32 s64, s59, 0xc000
	v_lshl_add_u64 v[34:35], s[66:67], 0, v[16:17]
	s_mov_b32 m0, s64
	s_add_i32 s61, s59, 0xe000
	ds_read_b128 v[70:73], v143
	ds_read_b128 v[74:77], v143 offset:1024
	ds_read_b128 v[78:81], v143 offset:2048
	ds_read_b128 v[82:85], v143 offset:3072
	ds_read_b128 v[86:89], v143 offset:4096
	ds_read_b128 v[90:93], v143 offset:5120
	ds_read_b128 v[94:97], v143 offset:6144
	ds_read_b128 v[98:101], v143 offset:7168
	global_load_lds_dwordx4 v[34:35], off
	v_lshl_add_u64 v[34:35], s[66:67], 0, v[30:31]
	s_mov_b32 m0, s61
	s_nop 0
	global_load_lds_dwordx4 v[34:35], off
	s_waitcnt vmcnt(8)
	s_waitcnt lgkmcnt(0)
	s_barrier
	s_setprio 1
	v_mfma_f32_16x16x32_bf16 v[102:105], v[38:41], v[70:73], 0
	v_mfma_f32_16x16x32_bf16 v[106:109], v[46:49], v[70:73], 0
	v_mfma_f32_16x16x32_bf16 v[110:113], v[38:41], v[78:81], 0
	v_mfma_f32_16x16x32_bf16 v[114:117], v[46:49], v[78:81], 0
	v_mfma_f32_16x16x32_bf16 v[118:121], v[38:41], v[86:89], 0
	v_mfma_f32_16x16x32_bf16 v[122:125], v[46:49], v[86:89], 0
	v_mfma_f32_16x16x32_bf16 v[130:133], v[38:41], v[94:97], 0
	v_mfma_f32_16x16x32_bf16 v[134:137], v[46:49], v[94:97], 0
	v_mfma_f32_16x16x32_bf16 v[102:105], v[42:45], v[74:77], v[102:105]
	v_mfma_f32_16x16x32_bf16 v[106:109], v[50:53], v[74:77], v[106:109]
	v_mfma_f32_16x16x32_bf16 v[110:113], v[42:45], v[82:85], v[110:113]
	v_mfma_f32_16x16x32_bf16 v[114:117], v[50:53], v[82:85], v[114:117]
	v_mfma_f32_16x16x32_bf16 v[118:121], v[42:45], v[90:93], v[118:121]
	v_mfma_f32_16x16x32_bf16 v[122:125], v[50:53], v[90:93], v[122:125]
	v_mfma_f32_16x16x32_bf16 v[130:133], v[42:45], v[98:101], v[130:133]
	v_mfma_f32_16x16x32_bf16 v[134:137], v[50:53], v[98:101], v[134:137]
	s_setprio 0
	s_setprio 1
	v_mfma_f32_16x16x32_bf16 v[138:141], v[54:57], v[70:73], 0
	v_mfma_f32_16x16x32_bf16 v[70:73], v[62:65], v[70:73], 0
	v_mfma_f32_16x16x32_bf16 v[138:141], v[58:61], v[74:77], v[138:141]
	v_mfma_f32_16x16x32_bf16 v[70:73], v[66:69], v[74:77], v[70:73]
	v_mfma_f32_16x16x32_bf16 v[74:77], v[54:57], v[78:81], 0
	v_mfma_f32_16x16x32_bf16 v[78:81], v[62:65], v[78:81], 0
	v_mfma_f32_16x16x32_bf16 v[74:77], v[58:61], v[82:85], v[74:77]
	v_mfma_f32_16x16x32_bf16 v[78:81], v[66:69], v[82:85], v[78:81]
	v_mfma_f32_16x16x32_bf16 v[82:85], v[54:57], v[86:89], 0
	v_mfma_f32_16x16x32_bf16 v[86:89], v[62:65], v[86:89], 0
	v_mfma_f32_16x16x32_bf16 v[82:85], v[58:61], v[90:93], v[82:85]
	v_mfma_f32_16x16x32_bf16 v[86:89], v[66:69], v[90:93], v[86:89]
	v_mfma_f32_16x16x32_bf16 v[90:93], v[54:57], v[94:97], 0
	v_mfma_f32_16x16x32_bf16 v[94:97], v[62:65], v[94:97], 0
	v_mfma_f32_16x16x32_bf16 v[90:93], v[58:61], v[98:101], v[90:93]
	v_mfma_f32_16x16x32_bf16 v[94:97], v[66:69], v[98:101], v[94:97]
	s_setprio 0
	s_barrier
	s_add_i32 s48, s48, s63
	s_add_i32 s62, s48, 0x2000
	v_lshl_add_u64 v[34:35], v[26:27], 0, s[12:13]
	s_mov_b32 m0, s48
	s_add_u32 s66, s24, 0x10100
	ds_read_b128 v[98:101], v143 offset:16384
	ds_read_b128 v[144:147], v143 offset:17408
	ds_read_b128 v[148:151], v143 offset:18432
	ds_read_b128 v[152:155], v143 offset:19456
	ds_read_b128 v[156:159], v143 offset:20480
	ds_read_b128 v[160:163], v143 offset:21504
	ds_read_b128 v[164:167], v143 offset:22528
	ds_read_b128 v[168:171], v143 offset:23552
	global_load_lds_dwordx4 v[34:35], off
	v_lshl_add_u64 v[34:35], v[28:29], 0, s[12:13]
	s_mov_b32 m0, s62
	s_addc_u32 s67, s25, 0
	s_add_i32 s47, s47, s63
	global_load_lds_dwordx4 v[34:35], off
	v_lshl_add_u64 v[34:35], s[66:67], 0, v[128:129]
	s_mov_b32 m0, s47
	s_add_i32 s63, s47, 0x2000
	global_load_lds_dwordx4 v[34:35], off
	v_lshl_add_u64 v[34:35], s[66:67], 0, v[32:33]
	s_mov_b32 m0, s63
	s_nop 0
	global_load_lds_dwordx4 v[34:35], off
	v_lshl_add_u64 v[34:35], v[20:21], 0, s[12:13]
	s_mov_b32 m0, s59
	s_nop 0
	global_load_lds_dwordx4 v[34:35], off
	v_lshl_add_u64 v[34:35], v[22:23], 0, s[12:13]
	s_mov_b32 m0, s60
	s_nop 0
	global_load_lds_dwordx4 v[34:35], off
	s_waitcnt vmcnt(8)
	s_waitcnt lgkmcnt(0)
	s_barrier
; #define PG8_STAGE(bufoff, gbase, voff) do { _Pragma("unroll") for (int _i = 0; _i < 2; ++_i) \
;         __builtin_amdgcn_global_load_lds((const unsigned*)((const char*)(gbase) + (voff)[_i]), (PG8_LAS unsigned*)(lds + (bufoff) + ldsw + _i * 8192), 16, 0, 0); } while (0)
; #define PG8_LDA(dst, b, h) do { _Pragma("unroll") for (int m = 0; m < 4; ++m) _Pragma("unroll") for (int k = 0; k < 2; ++k) dst[m][k] = *(const PG8_LAS bf16x8*)(lds + PG8_SA(b, h) + aoff + m * 2048 + k * 1024); } while (0)
; #define PG8_LDB(dst, b, h) do { _Pragma("unroll") for (int n = 0; n < 2; ++n) _Pragma("unroll") for (int k = 0; k < 2; ++k) dst[n][k] = *(const PG8_LAS bf16x8*)(lds + PG8_SB(b, h) + boff + n * 2048 + k * 1024); } while (0)
; #define PG8_MMA(ai, bj, At, Bt) do { __builtin_amdgcn_s_setprio(1); _Pragma("unroll") for (int m = 0; m < 4; ++m) _Pragma("unroll") for (int n = 0; n < 2; ++n) _Pragma("unroll") for (int k = 0; k < 2; ++k) \
;         acc[ai][bj][m][n] = __builtin_amdgcn_mfma_f32_16x16x32_bf16(Bt[n][k], At[m][k], acc[ai][bj][m][n], 0, 0, 0); __builtin_amdgcn_s_setprio(0); } while (0)
; #define PG8_WAIT_V(n) asm volatile("s_waitcnt vmcnt(" #n ")" ::: "memory")
; #define PG8_WAIT_L(n) asm volatile("s_waitcnt lgkmcnt(" #n ")" ::: "memory")
; #define PG8_BAR __builtin_amdgcn_s_barrier()
; #define PG8_SCHED __builtin_amdgcn_sched_barrier(0)
; template <class Epi, class Sched, bool ALIGN_EPI = false, bool SP2 = false>
; __device__ __forceinline__ void gemm_phase(PG8_LAS unsigned char* lds, const Gemm g, const Sched& S, const Epi& E, const int wv0) {
;     ...
;             PG8_WAIT_V(8); PG8_WAIT_L(0); PG8_BAR; PG8_MMA(1, 0, At, B0); PG8_MMA(1, 1, At, B1); PG8_BAR; PG8_SCHED;
;             PG8_LDB(B0, 1, 0); PG8_LDB(B1, 1, 1); PG8_SCHED; PG8_LDA(At, 1, 0); PG8_STAGE(PG8_SA(0, 1), a2 + hstepA, voffA);
;             PG8_WAIT_V(8); PG8_WAIT_L(0); PG8_BAR; PG8_MMA(0, 0, At, B0); PG8_MMA(0, 1, At, B1); PG8_BAR; PG8_SCHED;
	s_setprio 1
	v_mfma_f32_16x16x32_bf16 v[172:175], v[38:41], v[98:101], 0
	v_mfma_f32_16x16x32_bf16 v[180:183], v[38:41], v[148:151], 0
	v_mfma_f32_16x16x32_bf16 v[188:191], v[38:41], v[156:159], 0
	v_mfma_f32_16x16x32_bf16 v[38:41], v[38:41], v[164:167], 0
	v_mfma_f32_16x16x32_bf16 v[172:175], v[42:45], v[144:147], v[172:175]
	v_mfma_f32_16x16x32_bf16 v[176:179], v[46:49], v[98:101], 0
	v_mfma_f32_16x16x32_bf16 v[180:183], v[42:45], v[152:155], v[180:183]
	v_mfma_f32_16x16x32_bf16 v[184:187], v[46:49], v[148:151], 0
	v_mfma_f32_16x16x32_bf16 v[188:191], v[42:45], v[160:163], v[188:191]
	v_mfma_f32_16x16x32_bf16 v[192:195], v[46:49], v[156:159], 0
	v_mfma_f32_16x16x32_bf16 v[38:41], v[42:45], v[168:171], v[38:41]
	v_mfma_f32_16x16x32_bf16 v[42:45], v[46:49], v[164:167], 0
	v_mfma_f32_16x16x32_bf16 v[176:179], v[50:53], v[144:147], v[176:179]
	v_mfma_f32_16x16x32_bf16 v[184:187], v[50:53], v[152:155], v[184:187]
	v_mfma_f32_16x16x32_bf16 v[192:195], v[50:53], v[160:163], v[192:195]
	v_mfma_f32_16x16x32_bf16 v[42:45], v[50:53], v[168:171], v[42:45]
	s_setprio 0
	s_setprio 1
	v_mfma_f32_16x16x32_bf16 v[46:49], v[54:57], v[98:101], 0
	v_mfma_f32_16x16x32_bf16 v[50:53], v[62:65], v[98:101], 0
	v_mfma_f32_16x16x32_bf16 v[46:49], v[58:61], v[144:147], v[46:49]
	v_mfma_f32_16x16x32_bf16 v[50:53], v[66:69], v[144:147], v[50:53]
	v_mfma_f32_16x16x32_bf16 v[98:101], v[54:57], v[148:151], 0
	v_mfma_f32_16x16x32_bf16 v[144:147], v[62:65], v[148:151], 0
	v_mfma_f32_16x16x32_bf16 v[148:151], v[54:57], v[156:159], 0
	v_mfma_f32_16x16x32_bf16 v[54:57], v[54:57], v[164:167], 0
	v_mfma_f32_16x16x32_bf16 v[98:101], v[58:61], v[152:155], v[98:101]
	v_mfma_f32_16x16x32_bf16 v[144:147], v[66:69], v[152:155], v[144:147]
	v_mfma_f32_16x16x32_bf16 v[148:151], v[58:61], v[160:163], v[148:151]
	v_mfma_f32_16x16x32_bf16 v[152:155], v[62:65], v[156:159], 0
	v_mfma_f32_16x16x32_bf16 v[54:57], v[58:61], v[168:171], v[54:57]
	v_mfma_f32_16x16x32_bf16 v[58:61], v[62:65], v[164:167], 0
	v_mfma_f32_16x16x32_bf16 v[152:155], v[66:69], v[160:163], v[152:155]
	v_mfma_f32_16x16x32_bf16 v[58:61], v[66:69], v[168:171], v[58:61]
	s_setprio 0
	s_barrier
	ds_read_b128 v[62:65], v239
	ds_read_b128 v[66:69], v239 offset:1024
	ds_read_b128 v[156:159], v239 offset:2048
	ds_read_b128 v[160:163], v239 offset:3072
	ds_read_b128 v[164:167], v238
	ds_read_b128 v[168:171], v238 offset:1024
	ds_read_b128 v[196:199], v238 offset:2048
	ds_read_b128 v[200:203], v238 offset:3072
	s_add_u32 s66, s22, 0x40100
	s_addc_u32 s67, s23, 0
	s_mov_b32 m0, s55
	v_lshl_add_u64 v[34:35], s[66:67], 0, v[16:17]
	ds_read_b128 v[206:209], v143 offset:32768
	ds_read_b128 v[210:213], v143 offset:33792
	ds_read_b128 v[214:217], v143 offset:34816
	ds_read_b128 v[218:221], v143 offset:35840
	ds_read_b128 v[222:225], v143 offset:36864
	ds_read_b128 v[226:229], v143 offset:37888
	ds_read_b128 v[230:233], v143 offset:38912
	ds_read_b128 v[234:237], v143 offset:39936
	global_load_lds_dwordx4 v[34:35], off
	v_lshl_add_u64 v[34:35], s[66:67], 0, v[30:31]
	s_mov_b32 m0, s56
	s_nop 0
	global_load_lds_dwordx4 v[34:35], off
	s_waitcnt vmcnt(8)
	s_waitcnt lgkmcnt(0)
	s_barrier
	s_setprio 1
	v_mfma_f32_16x16x32_bf16 v[102:105], v[62:65], v[206:209], v[102:105]
	v_mfma_f32_16x16x32_bf16 v[106:109], v[156:159], v[206:209], v[106:109]
	v_mfma_f32_16x16x32_bf16 v[110:113], v[62:65], v[214:217], v[110:113]
	v_mfma_f32_16x16x32_bf16 v[114:117], v[156:159], v[214:217], v[114:117]
	v_mfma_f32_16x16x32_bf16 v[118:121], v[62:65], v[222:225], v[118:121]
	v_mfma_f32_16x16x32_bf16 v[122:125], v[156:159], v[222:225], v[122:125]
	v_mfma_f32_16x16x32_bf16 v[130:133], v[62:65], v[230:233], v[130:133]
	v_mfma_f32_16x16x32_bf16 v[134:137], v[156:159], v[230:233], v[134:137]
	v_mfma_f32_16x16x32_bf16 v[102:105], v[66:69], v[210:213], v[102:105]
	v_mfma_f32_16x16x32_bf16 v[106:109], v[160:163], v[210:213], v[106:109]
	v_mfma_f32_16x16x32_bf16 v[110:113], v[66:69], v[218:221], v[110:113]
	v_mfma_f32_16x16x32_bf16 v[114:117], v[160:163], v[218:221], v[114:117]
	v_mfma_f32_16x16x32_bf16 v[118:121], v[66:69], v[226:229], v[118:121]
	v_mfma_f32_16x16x32_bf16 v[122:125], v[160:163], v[226:229], v[122:125]
	v_mfma_f32_16x16x32_bf16 v[130:133], v[66:69], v[234:237], v[130:133]
	v_mfma_f32_16x16x32_bf16 v[134:137], v[160:163], v[234:237], v[134:137]
	s_setprio 0
	s_setprio 1
	v_mfma_f32_16x16x32_bf16 v[138:141], v[164:167], v[206:209], v[138:141]
	v_mfma_f32_16x16x32_bf16 v[70:73], v[196:199], v[206:209], v[70:73]
	v_mfma_f32_16x16x32_bf16 v[74:77], v[164:167], v[214:217], v[74:77]
	v_mfma_f32_16x16x32_bf16 v[78:81], v[196:199], v[214:217], v[78:81]
	v_mfma_f32_16x16x32_bf16 v[82:85], v[164:167], v[222:225], v[82:85]
	v_mfma_f32_16x16x32_bf16 v[86:89], v[196:199], v[222:225], v[86:89]
	v_mfma_f32_16x16x32_bf16 v[90:93], v[164:167], v[230:233], v[90:93]
	v_mfma_f32_16x16x32_bf16 v[94:97], v[196:199], v[230:233], v[94:97]
	v_mfma_f32_16x16x32_bf16 v[138:141], v[168:171], v[210:213], v[138:141]
	v_mfma_f32_16x16x32_bf16 v[70:73], v[200:203], v[210:213], v[70:73]
	v_mfma_f32_16x16x32_bf16 v[74:77], v[168:171], v[218:221], v[74:77]
	v_mfma_f32_16x16x32_bf16 v[78:81], v[200:203], v[218:221], v[78:81]
	v_mfma_f32_16x16x32_bf16 v[82:85], v[168:171], v[226:229], v[82:85]
	v_mfma_f32_16x16x32_bf16 v[86:89], v[200:203], v[226:229], v[86:89]
	v_mfma_f32_16x16x32_bf16 v[90:93], v[168:171], v[234:237], v[90:93]
	v_mfma_f32_16x16x32_bf16 v[94:97], v[200:203], v[234:237], v[94:97]
	s_setprio 0
	s_barrier
; #define PG8_STAGE(bufoff, gbase, voff) do { _Pragma("unroll") for (int _i = 0; _i < 2; ++_i) \
;         __builtin_amdgcn_global_load_lds((const unsigned*)((const char*)(gbase) + (voff)[_i]), (PG8_LAS unsigned*)(lds + (bufoff) + ldsw + _i * 8192), 16, 0, 0); } while (0)
; #define PG8_LDA(dst, b, h) do { _Pragma("unroll") for (int m = 0; m < 4; ++m) _Pragma("unroll") for (int k = 0; k < 2; ++k) dst[m][k] = *(const PG8_LAS bf16x8*)(lds + PG8_SA(b, h) + aoff + m * 2048 + k * 1024); } while (0)
; #define PG8_LDB(dst, b, h) do { _Pragma("unroll") for (int n = 0; n < 2; ++n) _Pragma("unroll") for (int k = 0; k < 2; ++k) dst[n][k] = *(const PG8_LAS bf16x8*)(lds + PG8_SB(b, h) + boff + n * 2048 + k * 1024); } while (0)
; #define PG8_MMA(ai, bj, At, Bt) do { __builtin_amdgcn_s_setprio(1); _Pragma("unroll") for (int m = 0; m < 4; ++m) _Pragma("unroll") for (int n = 0; n < 2; ++n) _Pragma("unroll") for (int k = 0; k < 2; ++k) \
;         acc[ai][bj][m][n] = __builtin_amdgcn_mfma_f32_16x16x32_bf16(Bt[n][k], At[m][k], acc[ai][bj][m][n], 0, 0, 0); __builtin_amdgcn_s_setprio(0); } while (0)
; #define PG8_BAR __builtin_amdgcn_s_barrier()
; template <class Epi, class Sched, bool ALIGN_EPI = false, bool SP2 = false>
; __device__ __forceinline__ void gemm_phase(PG8_LAS unsigned char* lds, const Gemm g, const Sched& S, const Epi& E, const int wv0) {
;     ...
;             PG8_LDB(B0, 0, 0); PG8_LDB(B1, 0, 1); PG8_SCHED; PG8_LDA(At, 0, 0); PG8_STAGE(PG8_SA(1, 1), a1 + hstepA, voffA);
;             PG8_WAIT_V(8); PG8_WAIT_L(0); PG8_BAR; PG8_MMA(0, 0, At, B0); PG8_MMA(0, 1, At, B1); PG8_BAR; PG8_SCHED;
;             PG8_LDA(At, 0, 1); PG8_STAGE(PG8_SB(0, 0), b2, voffB); PG8_STAGE(PG8_SB(0, 1), b2 + hstepB, voffB); PG8_STAGE(PG8_SA(0, 0), a2, voffA);
;             PG8_WAIT_V(8); PG8_WAIT_L(0); PG8_BAR; PG8_MMA(1, 0, At, B0); PG8_MMA(1, 1, At, B1); PG8_BAR; PG8_SCHED;
;             PG8_LDB(B0, 1, 0); PG8_LDB(B1, 1, 1); PG8_SCHED; PG8_LDA(At, 1, 0); PG8_STAGE(PG8_SA(0, 1), a2 + hstepA, voffA);
;             PG8_WAIT_V(8); PG8_WAIT_L(0); PG8_BAR; PG8_MMA(0, 0, At, B0); PG8_MMA(0, 1, At, B1); PG8_BAR; PG8_SCHED;
;             PG8_LDA(At, 1, 1); PG8_STAGE(PG8_SB(1, 0), b3, voffB); PG8_STAGE(PG8_SB(1, 1), b3 + hstepB, voffB); PG8_STAGE(PG8_SA(1, 0), a3, voffA);
;             PG8_WAIT_V(8); PG8_WAIT_L(0); PG8_BAR; PG8_MMA(1, 0, At, B0); PG8_MMA(1, 1, At, B1); PG8_BAR; PG8_SCHED;
	s_mov_b32 m0, s51
	v_lshl_add_u64 v[34:35], v[26:27], 0, s[14:15]
	s_add_u32 s24, s24, 0x10180
	ds_read_b128 v[206:209], v143 offset:49152
	ds_read_b128 v[210:213], v143 offset:50176
	ds_read_b128 v[214:217], v143 offset:51200
	ds_read_b128 v[218:221], v143 offset:52224
	ds_read_b128 v[222:225], v143 offset:53248
	ds_read_b128 v[226:229], v143 offset:54272
	ds_read_b128 v[230:233], v143 offset:55296
	ds_read_b128 v[234:237], v143 offset:56320
	global_load_lds_dwordx4 v[34:35], off
	v_lshl_add_u64 v[34:35], v[28:29], 0, s[14:15]
	s_mov_b32 m0, s53
	s_addc_u32 s25, s25, 0
	global_load_lds_dwordx4 v[34:35], off
	v_lshl_add_u64 v[34:35], s[24:25], 0, v[128:129]
	s_mov_b32 m0, s57
	v_lshl_add_u64 v[32:33], s[24:25], 0, v[32:33]
	global_load_lds_dwordx4 v[34:35], off
	s_mov_b32 m0, s58
	s_nop 0
	global_load_lds_dwordx4 v[32:33], off
	v_lshl_add_u64 v[32:33], v[20:21], 0, s[14:15]
	s_mov_b32 m0, s52
	s_nop 0
	global_load_lds_dwordx4 v[32:33], off
	v_lshl_add_u64 v[32:33], v[22:23], 0, s[14:15]
	s_mov_b32 m0, s54
	s_nop 0
	global_load_lds_dwordx4 v[32:33], off
	s_waitcnt vmcnt(8)
	s_waitcnt lgkmcnt(0)
	s_barrier
	s_setprio 1
	v_mfma_f32_16x16x32_bf16 v[32:35], v[62:65], v[206:209], v[172:175]
	v_mfma_f32_16x16x32_bf16 v[172:175], v[156:159], v[206:209], v[176:179]
	v_mfma_f32_16x16x32_bf16 v[176:179], v[62:65], v[214:217], v[180:183]
	v_mfma_f32_16x16x32_bf16 v[180:183], v[156:159], v[214:217], v[184:187]
	v_mfma_f32_16x16x32_bf16 v[184:187], v[62:65], v[222:225], v[188:191]
	v_mfma_f32_16x16x32_bf16 v[188:191], v[156:159], v[222:225], v[192:195]
	v_mfma_f32_16x16x32_bf16 v[38:41], v[62:65], v[230:233], v[38:41]
	v_mfma_f32_16x16x32_bf16 v[42:45], v[156:159], v[230:233], v[42:45]
	v_mfma_f32_16x16x32_bf16 v[32:35], v[66:69], v[210:213], v[32:35]
	v_mfma_f32_16x16x32_bf16 v[172:175], v[160:163], v[210:213], v[172:175]
	v_mfma_f32_16x16x32_bf16 v[176:179], v[66:69], v[218:221], v[176:179]
	v_mfma_f32_16x16x32_bf16 v[180:183], v[160:163], v[218:221], v[180:183]
	v_mfma_f32_16x16x32_bf16 v[184:187], v[66:69], v[226:229], v[184:187]
	v_mfma_f32_16x16x32_bf16 v[188:191], v[160:163], v[226:229], v[188:191]
	v_mfma_f32_16x16x32_bf16 v[38:41], v[66:69], v[234:237], v[38:41]
	v_mfma_f32_16x16x32_bf16 v[42:45], v[160:163], v[234:237], v[42:45]
	s_setprio 0
	s_setprio 1
	v_mfma_f32_16x16x32_bf16 v[46:49], v[164:167], v[206:209], v[46:49]
	v_mfma_f32_16x16x32_bf16 v[50:53], v[196:199], v[206:209], v[50:53]
	v_mfma_f32_16x16x32_bf16 v[62:65], v[164:167], v[214:217], v[98:101]
	v_mfma_f32_16x16x32_bf16 v[66:69], v[196:199], v[214:217], v[144:147]
	v_mfma_f32_16x16x32_bf16 v[98:101], v[164:167], v[222:225], v[148:151]
	v_mfma_f32_16x16x32_bf16 v[144:147], v[196:199], v[222:225], v[152:155]
	v_mfma_f32_16x16x32_bf16 v[54:57], v[164:167], v[230:233], v[54:57]
	v_mfma_f32_16x16x32_bf16 v[58:61], v[196:199], v[230:233], v[58:61]
	v_mfma_f32_16x16x32_bf16 v[46:49], v[168:171], v[210:213], v[46:49]
	v_mfma_f32_16x16x32_bf16 v[50:53], v[200:203], v[210:213], v[50:53]
	v_mfma_f32_16x16x32_bf16 v[62:65], v[168:171], v[218:221], v[62:65]
	v_mfma_f32_16x16x32_bf16 v[66:69], v[200:203], v[218:221], v[66:69]
	v_mfma_f32_16x16x32_bf16 v[98:101], v[168:171], v[226:229], v[98:101]
	v_mfma_f32_16x16x32_bf16 v[144:147], v[200:203], v[226:229], v[144:147]
	v_mfma_f32_16x16x32_bf16 v[54:57], v[168:171], v[234:237], v[54:57]
	v_mfma_f32_16x16x32_bf16 v[58:61], v[200:203], v[234:237], v[58:61]
	s_setprio 0
	s_barrier
	ds_read_b128 v[148:151], v127
	ds_read_b128 v[152:155], v127 offset:1024
	ds_read_b128 v[156:159], v127 offset:2048
	ds_read_b128 v[160:163], v127 offset:3072
	ds_read_b128 v[164:167], v126
	ds_read_b128 v[168:171], v126 offset:1024
	ds_read_b128 v[192:195], v126 offset:2048
	ds_read_b128 v[196:199], v126 offset:3072
	s_add_u32 s22, s22, 0x40180
	s_addc_u32 s23, s23, 0
	s_mov_b32 m0, s64
	v_lshl_add_u64 v[16:17], s[22:23], 0, v[16:17]
	ds_read_b128 v[200:203], v143
	ds_read_b128 v[206:209], v143 offset:1024
	ds_read_b128 v[210:213], v143 offset:2048
	ds_read_b128 v[214:217], v143 offset:3072
	ds_read_b128 v[218:221], v143 offset:4096
	ds_read_b128 v[222:225], v143 offset:5120
	ds_read_b128 v[226:229], v143 offset:6144
	ds_read_b128 v[230:233], v143 offset:7168
	global_load_lds_dwordx4 v[16:17], off
	v_lshl_add_u64 v[16:17], s[22:23], 0, v[30:31]
	s_mov_b32 m0, s61
	s_nop 0
	global_load_lds_dwordx4 v[16:17], off
	s_waitcnt vmcnt(8)
	s_waitcnt lgkmcnt(0)
	s_barrier
	s_setprio 1
	v_mfma_f32_16x16x32_bf16 v[102:105], v[148:151], v[200:203], v[102:105]
	v_mfma_f32_16x16x32_bf16 v[106:109], v[156:159], v[200:203], v[106:109]
	v_mfma_f32_16x16x32_bf16 v[110:113], v[148:151], v[210:213], v[110:113]
	v_mfma_f32_16x16x32_bf16 v[114:117], v[156:159], v[210:213], v[114:117]
	v_mfma_f32_16x16x32_bf16 v[118:121], v[148:151], v[218:221], v[118:121]
	v_mfma_f32_16x16x32_bf16 v[122:125], v[156:159], v[218:221], v[122:125]
	v_mfma_f32_16x16x32_bf16 v[130:133], v[148:151], v[226:229], v[130:133]
	v_mfma_f32_16x16x32_bf16 v[134:137], v[156:159], v[226:229], v[134:137]
	v_mfma_f32_16x16x32_bf16 v[102:105], v[152:155], v[206:209], v[102:105]
	v_mfma_f32_16x16x32_bf16 v[106:109], v[160:163], v[206:209], v[106:109]
	v_mfma_f32_16x16x32_bf16 v[110:113], v[152:155], v[214:217], v[110:113]
	v_mfma_f32_16x16x32_bf16 v[114:117], v[160:163], v[214:217], v[114:117]
	v_mfma_f32_16x16x32_bf16 v[118:121], v[152:155], v[222:225], v[118:121]
	v_mfma_f32_16x16x32_bf16 v[122:125], v[160:163], v[222:225], v[122:125]
	v_mfma_f32_16x16x32_bf16 v[130:133], v[152:155], v[230:233], v[130:133]
	v_mfma_f32_16x16x32_bf16 v[134:137], v[160:163], v[230:233], v[134:137]
	s_setprio 0
	s_setprio 1
	v_mfma_f32_16x16x32_bf16 v[138:141], v[164:167], v[200:203], v[138:141]
	v_mfma_f32_16x16x32_bf16 v[70:73], v[192:195], v[200:203], v[70:73]
	v_mfma_f32_16x16x32_bf16 v[74:77], v[164:167], v[210:213], v[74:77]
	v_mfma_f32_16x16x32_bf16 v[78:81], v[192:195], v[210:213], v[78:81]
	v_mfma_f32_16x16x32_bf16 v[82:85], v[164:167], v[218:221], v[82:85]
	v_mfma_f32_16x16x32_bf16 v[86:89], v[192:195], v[218:221], v[86:89]
	v_mfma_f32_16x16x32_bf16 v[90:93], v[164:167], v[226:229], v[90:93]
	v_mfma_f32_16x16x32_bf16 v[94:97], v[192:195], v[226:229], v[94:97]
	v_mfma_f32_16x16x32_bf16 v[138:141], v[168:171], v[206:209], v[138:141]
	v_mfma_f32_16x16x32_bf16 v[70:73], v[196:199], v[206:209], v[70:73]
	v_mfma_f32_16x16x32_bf16 v[74:77], v[168:171], v[214:217], v[74:77]
	v_mfma_f32_16x16x32_bf16 v[78:81], v[196:199], v[214:217], v[78:81]
	v_mfma_f32_16x16x32_bf16 v[82:85], v[168:171], v[222:225], v[82:85]
	v_mfma_f32_16x16x32_bf16 v[86:89], v[196:199], v[222:225], v[86:89]
	v_mfma_f32_16x16x32_bf16 v[90:93], v[168:171], v[230:233], v[90:93]
	v_mfma_f32_16x16x32_bf16 v[94:97], v[196:199], v[230:233], v[94:97]
	s_setprio 0
	s_barrier
; #define PG8_STAGE(bufoff, gbase, voff) do { _Pragma("unroll") for (int _i = 0; _i < 2; ++_i) \
;         __builtin_amdgcn_global_load_lds((const unsigned*)((const char*)(gbase) + (voff)[_i]), (PG8_LAS unsigned*)(lds + (bufoff) + ldsw + _i * 8192), 16, 0, 0); } while (0)
; #define PG8_LDA(dst, b, h) do { _Pragma("unroll") for (int m = 0; m < 4; ++m) _Pragma("unroll") for (int k = 0; k < 2; ++k) dst[m][k] = *(const PG8_LAS bf16x8*)(lds + PG8_SA(b, h) + aoff + m * 2048 + k * 1024); } while (0)
; #define PG8_LDB(dst, b, h) do { _Pragma("unroll") for (int n = 0; n < 2; ++n) _Pragma("unroll") for (int k = 0; k < 2; ++k) dst[n][k] = *(const PG8_LAS bf16x8*)(lds + PG8_SB(b, h) + boff + n * 2048 + k * 1024); } while (0)
; #define PG8_MMA(ai, bj, At, Bt) do { __builtin_amdgcn_s_setprio(1); _Pragma("unroll") for (int m = 0; m < 4; ++m) _Pragma("unroll") for (int n = 0; n < 2; ++n) _Pragma("unroll") for (int k = 0; k < 2; ++k) \
;         acc[ai][bj][m][n] = __builtin_amdgcn_mfma_f32_16x16x32_bf16(Bt[n][k], At[m][k], acc[ai][bj][m][n], 0, 0, 0); __builtin_amdgcn_s_setprio(0); } while (0)
; #define PG8_WAIT_V(n) asm volatile("s_waitcnt vmcnt(" #n ")" ::: "memory")
; #define PG8_WAIT_L(n) asm volatile("s_waitcnt lgkmcnt(" #n ")" ::: "memory")
; #define PG8_BAR __builtin_amdgcn_s_barrier()
; #define PG8_SCHED __builtin_amdgcn_sched_barrier(0)
; template <class Epi, class Sched, bool ALIGN_EPI = false, bool SP2 = false>
; __device__ __forceinline__ void gemm_phase(PG8_LAS unsigned char* lds, const Gemm g, const Sched& S, const Epi& E, const int wv0) {
;     ...
;             PG8_LDA(At, 0, 1); PG8_STAGE(PG8_SB(0, 0), b2, voffB); PG8_STAGE(PG8_SB(0, 1), b2 + hstepB, voffB); PG8_STAGE(PG8_SA(0, 0), a2, voffA);
;             PG8_WAIT_V(8); PG8_WAIT_L(0); PG8_BAR; PG8_MMA(1, 0, At, B0); PG8_MMA(1, 1, At, B1); PG8_BAR; PG8_SCHED;
;             PG8_LDB(B0, 1, 0); PG8_LDB(B1, 1, 1); PG8_SCHED; PG8_LDA(At, 1, 0); PG8_STAGE(PG8_SA(0, 1), a2 + hstepA, voffA);
;             PG8_WAIT_V(8); PG8_WAIT_L(0); PG8_BAR; PG8_MMA(0, 0, At, B0); PG8_MMA(0, 1, At, B1); PG8_BAR; PG8_SCHED;
	s_mov_b32 m0, s48
	ds_read_b128 v[200:203], v143 offset:16384
	ds_read_b128 v[206:209], v143 offset:17408
	ds_read_b128 v[210:213], v143 offset:18432
	ds_read_b128 v[214:217], v143 offset:19456
	ds_read_b128 v[218:221], v143 offset:20480
	ds_read_b128 v[222:225], v143 offset:21504
	ds_read_b128 v[226:229], v143 offset:22528
	ds_read_b128 v[230:233], v143 offset:23552
	global_load_lds_dwordx4 v[26:27], off
	s_mov_b32 m0, s62
	s_nop 0
	global_load_lds_dwordx4 v[28:29], off
	s_mov_b32 m0, s47
	s_nop 0
	global_load_lds_dwordx4 v[24:25], off
	s_mov_b32 m0, s63
	s_nop 0
	global_load_lds_dwordx4 v[18:19], off
	s_mov_b32 m0, s59
	s_nop 0
	global_load_lds_dwordx4 v[20:21], off
	s_mov_b32 m0, s60
	s_nop 0
	global_load_lds_dwordx4 v[22:23], off
	s_waitcnt vmcnt(8)
	s_waitcnt lgkmcnt(0)
	s_barrier
	s_setprio 1
	v_mfma_f32_16x16x32_bf16 v[16:19], v[148:151], v[200:203], v[32:35]
	v_mfma_f32_16x16x32_bf16 v[20:23], v[156:159], v[200:203], v[172:175]
	v_mfma_f32_16x16x32_bf16 v[24:27], v[148:151], v[210:213], v[176:179]
	v_mfma_f32_16x16x32_bf16 v[28:31], v[156:159], v[210:213], v[180:183]
	v_mfma_f32_16x16x32_bf16 v[32:35], v[148:151], v[218:221], v[184:187]
	v_mfma_f32_16x16x32_bf16 v[172:175], v[156:159], v[218:221], v[188:191]
	v_mfma_f32_16x16x32_bf16 v[38:41], v[148:151], v[226:229], v[38:41]
	v_mfma_f32_16x16x32_bf16 v[42:45], v[156:159], v[226:229], v[42:45]
	v_mfma_f32_16x16x32_bf16 v[16:19], v[152:155], v[206:209], v[16:19]
	v_mfma_f32_16x16x32_bf16 v[20:23], v[160:163], v[206:209], v[20:23]
	v_mfma_f32_16x16x32_bf16 v[24:27], v[152:155], v[214:217], v[24:27]
	v_mfma_f32_16x16x32_bf16 v[28:31], v[160:163], v[214:217], v[28:31]
	v_mfma_f32_16x16x32_bf16 v[32:35], v[152:155], v[222:225], v[32:35]
	v_mfma_f32_16x16x32_bf16 v[172:175], v[160:163], v[222:225], v[172:175]
	v_mfma_f32_16x16x32_bf16 v[38:41], v[152:155], v[230:233], v[38:41]
	v_mfma_f32_16x16x32_bf16 v[42:45], v[160:163], v[230:233], v[42:45]
	s_setprio 0
	s_setprio 1
	v_mfma_f32_16x16x32_bf16 v[46:49], v[164:167], v[200:203], v[46:49]
	v_mfma_f32_16x16x32_bf16 v[50:53], v[192:195], v[200:203], v[50:53]
	v_mfma_f32_16x16x32_bf16 v[62:65], v[164:167], v[210:213], v[62:65]
	v_mfma_f32_16x16x32_bf16 v[66:69], v[192:195], v[210:213], v[66:69]
	v_mfma_f32_16x16x32_bf16 v[98:101], v[164:167], v[218:221], v[98:101]
	v_mfma_f32_16x16x32_bf16 v[144:147], v[192:195], v[218:221], v[144:147]
	v_mfma_f32_16x16x32_bf16 v[54:57], v[164:167], v[226:229], v[54:57]
	v_mfma_f32_16x16x32_bf16 v[58:61], v[192:195], v[226:229], v[58:61]
	v_mfma_f32_16x16x32_bf16 v[46:49], v[168:171], v[206:209], v[46:49]
	v_mfma_f32_16x16x32_bf16 v[50:53], v[196:199], v[206:209], v[50:53]
	v_mfma_f32_16x16x32_bf16 v[62:65], v[168:171], v[214:217], v[62:65]
	v_mfma_f32_16x16x32_bf16 v[66:69], v[196:199], v[214:217], v[66:69]
	v_mfma_f32_16x16x32_bf16 v[98:101], v[168:171], v[222:225], v[98:101]
	v_mfma_f32_16x16x32_bf16 v[144:147], v[196:199], v[222:225], v[144:147]
	v_mfma_f32_16x16x32_bf16 v[54:57], v[168:171], v[230:233], v[54:57]
	v_mfma_f32_16x16x32_bf16 v[58:61], v[196:199], v[230:233], v[58:61]
	s_setprio 0
	s_barrier
	ds_read_b128 v[148:151], v239
	ds_read_b128 v[152:155], v239 offset:1024
	ds_read_b128 v[156:159], v239 offset:2048
	ds_read_b128 v[160:163], v239 offset:3072
	ds_read_b128 v[164:167], v238
	ds_read_b128 v[168:171], v238 offset:1024
	ds_read_b128 v[176:179], v238 offset:2048
	ds_read_b128 v[180:183], v238 offset:3072
	s_mov_b32 m0, s55
	ds_read_b128 v[184:187], v143 offset:32768
	ds_read_b128 v[188:191], v143 offset:33792
	ds_read_b128 v[192:195], v143 offset:34816
	ds_read_b128 v[196:199], v143 offset:35840
	ds_read_b128 v[200:203], v143 offset:36864
	ds_read_b128 v[206:209], v143 offset:37888
	ds_read_b128 v[210:213], v143 offset:38912
	ds_read_b128 v[214:217], v143 offset:39936
	global_load_lds_dwordx4 v[12:13], off
	s_mov_b32 m0, s56
	s_nop 0
	global_load_lds_dwordx4 v[14:15], off
	s_waitcnt vmcnt(8)
	s_waitcnt lgkmcnt(0)
	s_barrier
	s_setprio 1
	v_mfma_f32_16x16x32_bf16 v[12:15], v[148:151], v[184:187], v[102:105]
	v_mfma_f32_16x16x32_bf16 v[102:105], v[152:155], v[188:191], v[12:15]
	v_mfma_f32_16x16x32_bf16 v[12:15], v[156:159], v[184:187], v[106:109]
	v_mfma_f32_16x16x32_bf16 v[106:109], v[160:163], v[188:191], v[12:15]
	v_mfma_f32_16x16x32_bf16 v[12:15], v[148:151], v[192:195], v[110:113]
	v_mfma_f32_16x16x32_bf16 v[110:113], v[152:155], v[196:199], v[12:15]
	v_mfma_f32_16x16x32_bf16 v[12:15], v[156:159], v[192:195], v[114:117]
	v_mfma_f32_16x16x32_bf16 v[114:117], v[160:163], v[196:199], v[12:15]
	v_mfma_f32_16x16x32_bf16 v[12:15], v[148:151], v[200:203], v[118:121]
	v_mfma_f32_16x16x32_bf16 v[118:121], v[152:155], v[206:209], v[12:15]
	v_mfma_f32_16x16x32_bf16 v[12:15], v[156:159], v[200:203], v[122:125]
	v_mfma_f32_16x16x32_bf16 v[122:125], v[160:163], v[206:209], v[12:15]
	v_mfma_f32_16x16x32_bf16 v[12:15], v[148:151], v[210:213], v[130:133]
	v_mfma_f32_16x16x32_bf16 v[130:133], v[152:155], v[214:217], v[12:15]
	v_mfma_f32_16x16x32_bf16 v[12:15], v[156:159], v[210:213], v[134:137]
	v_mfma_f32_16x16x32_bf16 v[134:137], v[160:163], v[214:217], v[12:15]
	s_setprio 0
	s_setprio 1
	v_mfma_f32_16x16x32_bf16 v[12:15], v[164:167], v[184:187], v[138:141]
	v_mfma_f32_16x16x32_bf16 v[138:141], v[168:171], v[188:191], v[12:15]
	v_mfma_f32_16x16x32_bf16 v[12:15], v[176:179], v[184:187], v[70:73]
	v_mfma_f32_16x16x32_bf16 v[70:73], v[180:183], v[188:191], v[12:15]
	v_mfma_f32_16x16x32_bf16 v[12:15], v[164:167], v[192:195], v[74:77]
	v_mfma_f32_16x16x32_bf16 v[74:77], v[168:171], v[196:199], v[12:15]
	v_mfma_f32_16x16x32_bf16 v[12:15], v[176:179], v[192:195], v[78:81]
	v_mfma_f32_16x16x32_bf16 v[78:81], v[180:183], v[196:199], v[12:15]
	v_mfma_f32_16x16x32_bf16 v[12:15], v[164:167], v[200:203], v[82:85]
	v_mfma_f32_16x16x32_bf16 v[82:85], v[168:171], v[206:209], v[12:15]
	v_mfma_f32_16x16x32_bf16 v[12:15], v[176:179], v[200:203], v[86:89]
	v_mfma_f32_16x16x32_bf16 v[86:89], v[180:183], v[206:209], v[12:15]
	v_mfma_f32_16x16x32_bf16 v[12:15], v[164:167], v[210:213], v[90:93]
	v_mfma_f32_16x16x32_bf16 v[90:93], v[168:171], v[214:217], v[12:15]
	v_mfma_f32_16x16x32_bf16 v[12:15], v[176:179], v[210:213], v[94:97]
	v_mfma_f32_16x16x32_bf16 v[94:97], v[180:183], v[214:217], v[12:15]
	s_setprio 0
	s_barrier
; #define PG8_STAGE(bufoff, gbase, voff) do { _Pragma("unroll") for (int _i = 0; _i < 2; ++_i) \
;         __builtin_amdgcn_global_load_lds((const unsigned*)((const char*)(gbase) + (voff)[_i]), (PG8_LAS unsigned*)(lds + (bufoff) + ldsw + _i * 8192), 16, 0, 0); } while (0)
; #define PG8_LDA(dst, b, h) do { _Pragma("unroll") for (int m = 0; m < 4; ++m) _Pragma("unroll") for (int k = 0; k < 2; ++k) dst[m][k] = *(const PG8_LAS bf16x8*)(lds + PG8_SA(b, h) + aoff + m * 2048 + k * 1024); } while (0)
; #define PG8_MMA(ai, bj, At, Bt) do { __builtin_amdgcn_s_setprio(1); _Pragma("unroll") for (int m = 0; m < 4; ++m) _Pragma("unroll") for (int n = 0; n < 2; ++n) _Pragma("unroll") for (int k = 0; k < 2; ++k) \
;         acc[ai][bj][m][n] = __builtin_amdgcn_mfma_f32_16x16x32_bf16(Bt[n][k], At[m][k], acc[ai][bj][m][n], 0, 0, 0); __builtin_amdgcn_s_setprio(0); } while (0)
; #define PG8_WAIT_V(n) asm volatile("s_waitcnt vmcnt(" #n ")" ::: "memory")
; #define PG8_WAIT_L(n) asm volatile("s_waitcnt lgkmcnt(" #n ")" ::: "memory")
; #define PG8_BAR __builtin_amdgcn_s_barrier()
; #define PG8_SCHED __builtin_amdgcn_sched_barrier(0)
; template <class Epi, class Sched, bool ALIGN_EPI = false, bool SP2 = false>
; __device__ __forceinline__ void gemm_phase(PG8_LAS unsigned char* lds, const Gemm g, const Sched& S, const Epi& E, const int wv0) {
;     ...
;             PG8_LDA(At, 1, 1); PG8_STAGE(PG8_SB(1, 0), b3, voffB); PG8_STAGE(PG8_SB(1, 1), b3 + hstepB, voffB); PG8_STAGE(PG8_SA(1, 0), a3, voffA);
;             PG8_WAIT_V(8); PG8_WAIT_L(0); PG8_BAR; PG8_MMA(1, 0, At, B0); PG8_MMA(1, 1, At, B1); PG8_BAR; PG8_SCHED;
	s_mov_b32 m0, s51
	ds_read_b128 v[184:187], v143 offset:49152
	ds_read_b128 v[188:191], v143 offset:50176
	ds_read_b128 v[192:195], v143 offset:51200
	ds_read_b128 v[196:199], v143 offset:52224
	ds_read_b128 v[200:203], v143 offset:53248
	ds_read_b128 v[206:209], v143 offset:54272
	ds_read_b128 v[210:213], v143 offset:55296
	ds_read_b128 v[214:217], v143 offset:56320
	global_load_lds_dwordx4 v[2:3], off
	s_mov_b32 m0, s53
	s_nop 0
	global_load_lds_dwordx4 v[4:5], off
	s_mov_b32 m0, s57
	s_nop 0
	global_load_lds_dwordx4 v[8:9], off
	s_mov_b32 m0, s58
	s_nop 0
	global_load_lds_dwordx4 v[10:11], off
	s_mov_b32 m0, s52
	s_nop 0
	global_load_lds_dwordx4 v[0:1], off
	s_mov_b32 m0, s54
	s_nop 0
	global_load_lds_dwordx4 v[6:7], off
	s_waitcnt vmcnt(8)
	s_waitcnt lgkmcnt(0)
	s_barrier
	s_setprio 1
	v_mfma_f32_16x16x32_bf16 v[0:3], v[148:151], v[184:187], v[16:19]
	v_mfma_f32_16x16x32_bf16 v[218:221], v[152:155], v[188:191], v[0:3]
	v_mfma_f32_16x16x32_bf16 v[0:3], v[156:159], v[184:187], v[20:23]
	v_mfma_f32_16x16x32_bf16 v[222:225], v[160:163], v[188:191], v[0:3]
	v_mfma_f32_16x16x32_bf16 v[0:3], v[148:151], v[192:195], v[24:27]
	v_mfma_f32_16x16x32_bf16 v[226:229], v[152:155], v[196:199], v[0:3]
	v_mfma_f32_16x16x32_bf16 v[0:3], v[156:159], v[192:195], v[28:31]
	v_mfma_f32_16x16x32_bf16 v[230:233], v[160:163], v[196:199], v[0:3]
	v_mfma_f32_16x16x32_bf16 v[0:3], v[148:151], v[200:203], v[32:35]
	v_mfma_f32_16x16x32_bf16 v[28:31], v[152:155], v[206:209], v[0:3]
	v_mfma_f32_16x16x32_bf16 v[0:3], v[156:159], v[200:203], v[172:175]
	v_mfma_f32_16x16x32_bf16 v[20:23], v[160:163], v[206:209], v[0:3]
	v_mfma_f32_16x16x32_bf16 v[0:3], v[148:151], v[210:213], v[38:41]
	v_mfma_f32_16x16x32_bf16 v[12:15], v[152:155], v[214:217], v[0:3]
	v_mfma_f32_16x16x32_bf16 v[0:3], v[156:159], v[210:213], v[42:45]
	v_mfma_f32_16x16x32_bf16 v[4:7], v[160:163], v[214:217], v[0:3]
	s_setprio 0
	s_setprio 1
	v_mfma_f32_16x16x32_bf16 v[0:3], v[164:167], v[184:187], v[46:49]
	v_mfma_f32_16x16x32_bf16 v[38:41], v[168:171], v[188:191], v[0:3]
	v_mfma_f32_16x16x32_bf16 v[0:3], v[176:179], v[184:187], v[50:53]
	v_mfma_f32_16x16x32_bf16 v[42:45], v[180:183], v[188:191], v[0:3]
	v_mfma_f32_16x16x32_bf16 v[0:3], v[164:167], v[192:195], v[62:65]
	v_mfma_f32_16x16x32_bf16 v[46:49], v[168:171], v[196:199], v[0:3]
	v_mfma_f32_16x16x32_bf16 v[0:3], v[176:179], v[192:195], v[66:69]
	v_mfma_f32_16x16x32_bf16 v[32:35], v[180:183], v[196:199], v[0:3]
	v_mfma_f32_16x16x32_bf16 v[0:3], v[164:167], v[200:203], v[98:101]
	v_mfma_f32_16x16x32_bf16 v[24:27], v[168:171], v[206:209], v[0:3]
	v_mfma_f32_16x16x32_bf16 v[0:3], v[176:179], v[200:203], v[144:147]
	v_mfma_f32_16x16x32_bf16 v[16:19], v[180:183], v[206:209], v[0:3]
	v_mfma_f32_16x16x32_bf16 v[0:3], v[164:167], v[210:213], v[54:57]
	v_mfma_f32_16x16x32_bf16 v[8:11], v[168:171], v[214:217], v[0:3]
	v_mfma_f32_16x16x32_bf16 v[0:3], v[176:179], v[210:213], v[58:61]
	v_mfma_f32_16x16x32_bf16 v[0:3], v[180:183], v[214:217], v[0:3]
	s_setprio 0
	s_barrier
; __device__ __forceinline__ unsigned cvtpk(float lo, float hi) { unsigned r; asm volatile("v_cvt_pk_bf16_f32 %0, %1, %2" : "=v"(r) : "v"(lo), "v"(hi)); return r; }
; #define PG8_WAIT_V(n) asm volatile("s_waitcnt vmcnt(" #n ")" ::: "memory")
; #define PG8_BAR __builtin_amdgcn_s_barrier()
;     __device__ __forceinline__ void operator()(const f32x4 (&acc)[2][2][4][2], const Unit& u, int wr, int wc, int fr, int fq) const {
;     ...
;             for (int m = 0; m < 4; ++m) { bf16* rowp = O + (size_t)(row0 + ai * HALF + m * 16) * ldc + col0;
; #pragma unroll
;                 for (int bj = 0; bj < 2; ++bj) { const f32x4 v0 = acc[ai][bj][m][0], v1 = acc[ai][bj][m][1];
;                     u32x4 w; w.x = cvtpk(v0[0], v0[1]); w.y = cvtpk(v0[2], v0[3]); w.z = cvtpk(v1[0], v1[1]); w.w = cvtpk(v1[2], v1[3]);
;                     *(u32x4*)(rowp + bj * HALF) = w; } }
; template <class Epi, class Sched, bool ALIGN_EPI = false, bool SP2 = false>
; __device__ __forceinline__ void gemm_phase(PG8_LAS unsigned char* lds, const Gemm g, const Sched& S, const Epi& E, const int wv0) {
;     ...
;     PG8_WAIT_V(0);
;     if constexpr (!ALIGN_EPI) { if (wr == 0) PG8_BAR; }
	v_add_u32_e32 v54, s26, v36
	v_or_b32_e32 v36, s49, v37
	v_ashrrev_i32_e32 v55, 31, v54
	v_or_b32_e32 v50, s50, v36
	v_lshlrev_b64 v[36:37], 11, v[54:55]
	v_lshl_add_u64 v[36:37], s[6:7], 0, v[36:37]
	v_lshlrev_b32_e32 v128, 1, v50
	v_lshl_add_u64 v[36:37], v[36:37], 0, v[128:129]
	v_cvt_pk_bf16_f32 v50, v102, v103
	v_cvt_pk_bf16_f32 v51, v104, v105
	v_cvt_pk_bf16_f32 v52, v106, v107
	v_cvt_pk_bf16_f32 v53, v108, v109
	global_store_dwordx4 v[36:37], v[50:53], off
	s_cmpk_gt_u32 s27, 0xff
	s_nop 0
	v_cvt_pk_bf16_f32 v50, v138, v139
	v_cvt_pk_bf16_f32 v51, v140, v141
	v_cvt_pk_bf16_f32 v52, v70, v71
	v_cvt_pk_bf16_f32 v53, v72, v73
	global_store_dwordx4 v[36:37], v[50:53], off offset:256
	s_nop 1
	v_or_b32_e32 v50, 16, v54
	v_ashrrev_i32_e32 v51, 31, v50
	v_lshlrev_b64 v[50:51], 11, v[50:51]
	v_lshl_add_u64 v[50:51], s[6:7], 0, v[50:51]
	v_lshl_add_u64 v[56:57], v[50:51], 0, v[128:129]
	v_cvt_pk_bf16_f32 v50, v110, v111
	v_cvt_pk_bf16_f32 v51, v112, v113
	v_cvt_pk_bf16_f32 v52, v114, v115
	v_cvt_pk_bf16_f32 v53, v116, v117
	global_store_dwordx4 v[56:57], v[50:53], off
	s_nop 1
	v_cvt_pk_bf16_f32 v50, v74, v75
	v_cvt_pk_bf16_f32 v51, v76, v77
	v_cvt_pk_bf16_f32 v52, v78, v79
	v_cvt_pk_bf16_f32 v53, v80, v81
	global_store_dwordx4 v[56:57], v[50:53], off offset:256
	s_nop 1
	v_or_b32_e32 v50, 32, v54
	v_ashrrev_i32_e32 v51, 31, v50
	v_lshlrev_b64 v[50:51], 11, v[50:51]
	v_lshl_add_u64 v[50:51], s[6:7], 0, v[50:51]
	v_lshl_add_u64 v[56:57], v[50:51], 0, v[128:129]
	v_cvt_pk_bf16_f32 v50, v118, v119
	v_cvt_pk_bf16_f32 v51, v120, v121
	v_cvt_pk_bf16_f32 v52, v122, v123
	v_cvt_pk_bf16_f32 v53, v124, v125
	global_store_dwordx4 v[56:57], v[50:53], off
	s_nop 1
	v_cvt_pk_bf16_f32 v50, v82, v83
	v_cvt_pk_bf16_f32 v51, v84, v85
	v_cvt_pk_bf16_f32 v52, v86, v87
	v_cvt_pk_bf16_f32 v53, v88, v89
	global_store_dwordx4 v[56:57], v[50:53], off offset:256
	v_add_co_u32_e32 v56, vcc, s39, v36
	s_nop 0
	v_or_b32_e32 v50, 48, v54
	v_ashrrev_i32_e32 v51, 31, v50
	v_lshlrev_b64 v[50:51], 11, v[50:51]
	v_lshl_add_u64 v[50:51], s[6:7], 0, v[50:51]
	v_lshl_add_u64 v[54:55], v[50:51], 0, v[128:129]
	v_cvt_pk_bf16_f32 v50, v130, v131
	v_cvt_pk_bf16_f32 v51, v132, v133
	v_cvt_pk_bf16_f32 v52, v134, v135
	v_cvt_pk_bf16_f32 v53, v136, v137
	global_store_dwordx4 v[54:55], v[50:53], off
	v_addc_co_u32_e32 v57, vcc, 0, v37, vcc
	s_nop 0
	v_cvt_pk_bf16_f32 v50, v90, v91
	v_cvt_pk_bf16_f32 v51, v92, v93
	v_cvt_pk_bf16_f32 v52, v94, v95
	v_cvt_pk_bf16_f32 v53, v96, v97
	global_store_dwordx4 v[54:55], v[50:53], off offset:256
	v_lshl_add_u64 v[54:55], v[36:37], 0, s[8:9]
	s_nop 0
	v_cvt_pk_bf16_f32 v50, v218, v219
	v_cvt_pk_bf16_f32 v51, v220, v221
	v_cvt_pk_bf16_f32 v52, v222, v223
	v_cvt_pk_bf16_f32 v53, v224, v225
	global_store_dwordx4 v[56:57], v[50:53], off
	v_cvt_pk_bf16_f32 v38, v38, v39
	v_cvt_pk_bf16_f32 v39, v40, v41
	v_cvt_pk_bf16_f32 v40, v42, v43
	v_cvt_pk_bf16_f32 v41, v44, v45
	v_add_co_u32_e32 v44, vcc, s40, v36
	global_store_dwordx4 v[54:55], v[38:41], off offset:256
	v_lshl_add_u64 v[42:43], v[36:37], 0, s[16:17]
	v_addc_co_u32_e32 v45, vcc, 0, v37, vcc
	v_cvt_pk_bf16_f32 v38, v226, v227
	v_cvt_pk_bf16_f32 v39, v228, v229
	v_cvt_pk_bf16_f32 v40, v230, v231
	v_cvt_pk_bf16_f32 v41, v232, v233
	global_store_dwordx4 v[44:45], v[38:41], off
	s_nop 1
	v_cvt_pk_bf16_f32 v38, v46, v47
	v_cvt_pk_bf16_f32 v39, v48, v49
	v_cvt_pk_bf16_f32 v40, v32, v33
	v_cvt_pk_bf16_f32 v41, v34, v35
	global_store_dwordx4 v[42:43], v[38:41], off offset:256
	v_cvt_pk_bf16_f32 v28, v28, v29
	v_cvt_pk_bf16_f32 v29, v30, v31
	v_cvt_pk_bf16_f32 v30, v20, v21
	v_add_co_u32_e32 v20, vcc, s41, v36
	v_lshl_add_u64 v[32:33], v[36:37], 0, s[18:19]
	s_nop 0
	v_addc_co_u32_e32 v21, vcc, 0, v37, vcc
	v_cvt_pk_bf16_f32 v31, v22, v23
	global_store_dwordx4 v[20:21], v[28:31], off
	v_cvt_pk_bf16_f32 v20, v24, v25
	v_cvt_pk_bf16_f32 v21, v26, v27
	v_cvt_pk_bf16_f32 v22, v16, v17
	v_cvt_pk_bf16_f32 v23, v18, v19
	global_store_dwordx4 v[32:33], v[20:23], off offset:256
	v_cvt_pk_bf16_f32 v12, v12, v13
	v_cvt_pk_bf16_f32 v13, v14, v15
	v_cvt_pk_bf16_f32 v14, v4, v5
	v_add_co_u32_e32 v4, vcc, s45, v36
	v_lshl_add_u64 v[16:17], v[36:37], 0, s[20:21]
	s_nop 0
	v_addc_co_u32_e32 v5, vcc, 0, v37, vcc
	v_cvt_pk_bf16_f32 v15, v6, v7
	global_store_dwordx4 v[4:5], v[12:15], off
	v_cvt_pk_bf16_f32 v4, v8, v9
	v_cvt_pk_bf16_f32 v5, v10, v11
	v_cvt_pk_bf16_f32 v6, v0, v1
	v_cvt_pk_bf16_f32 v7, v2, v3
	global_store_dwordx4 v[16:17], v[4:7], off offset:256
	s_waitcnt vmcnt(0)
	s_cbranch_scc1 .LBB0_1296
	s_barrier
	s_branch .LBB0_1296

; #define PG8_STAGE(bufoff, gbase, voff) do { _Pragma("unroll") for (int _i = 0; _i < 2; ++_i) \
;         __builtin_amdgcn_global_load_lds((const unsigned*)((const char*)(gbase) + (voff)[_i]), (PG8_LAS unsigned*)(lds + (bufoff) + ldsw + _i * 8192), 16, 0, 0); } while (0)
; #define PG8_LDA(dst, b, h) do { _Pragma("unroll") for (int m = 0; m < 4; ++m) _Pragma("unroll") for (int k = 0; k < 2; ++k) dst[m][k] = *(const PG8_LAS bf16x8*)(lds + PG8_SA(b, h) + aoff + m * 2048 + k * 1024); } while (0)
; #define PG8_LDB(dst, b, h) do { _Pragma("unroll") for (int n = 0; n < 2; ++n) _Pragma("unroll") for (int k = 0; k < 2; ++k) dst[n][k] = *(const PG8_LAS bf16x8*)(lds + PG8_SB(b, h) + boff + n * 2048 + k * 1024); } while (0)
; #define PG8_MMA(ai, bj, At, Bt) do { __builtin_amdgcn_s_setprio(1); _Pragma("unroll") for (int m = 0; m < 4; ++m) _Pragma("unroll") for (int n = 0; n < 2; ++n) _Pragma("unroll") for (int k = 0; k < 2; ++k) \
;         acc[ai][bj][m][n] = __builtin_amdgcn_mfma_f32_16x16x32_bf16(Bt[n][k], At[m][k], acc[ai][bj][m][n], 0, 0, 0); __builtin_amdgcn_s_setprio(0); } while (0)
; #define PG8_WAIT_V(n) asm volatile("s_waitcnt vmcnt(" #n ")" ::: "memory")
; #define PG8_WAIT_L(n) asm volatile("s_waitcnt lgkmcnt(" #n ")" ::: "memory")
; #define PG8_BAR __builtin_amdgcn_s_barrier()
; #define PG8_SCHED __builtin_amdgcn_sched_barrier(0)
; template <class Epi, class Sched, bool ALIGN_EPI = false, bool SP2 = false>
; __device__ __forceinline__ void gemm_phase(PG8_LAS unsigned char* lds, const Gemm g, const Sched& S, const Epi& E, const int wv0) {
;     ...
;             const bool last = (t == nt - 2);
;             const char* a1 = cA + (size_t)(t + 1) * kstep;
;             const char* a2 = last ? nA : cA + (size_t)(t + 2) * kstep; const char* b2 = last ? nB : cB + (size_t)(t + 2) * kstep;
;             const char* a3 = a2 + kstep; const char* b3 = b2 + kstep;
;             if constexpr (SP2) {
;             PG8_LDB(B0, 0, 0); PG8_LDB(B1, 0, 1); PG8_SCHED; PG8_LDA(At, 0, 0); PG8_STAGE(PG8_SA(1, 1), a1 + hstepA, voffA);
;             PG8_WAIT_V(8); PG8_WAIT_L(0); PG8_BAR; PG8_MMA(0, 0, At, B0); PG8_MMA(0, 1, At, B1); PG8_BAR; PG8_SCHED;
;             PG8_LDA(At, 0, 1); PG8_STAGE(PG8_SB(0, 0), b2, voffB); PG8_STAGE(PG8_SB(0, 1), b2 + hstepB, voffB); PG8_STAGE(PG8_SA(0, 0), a2, voffA);
.LBB0_1608:
	ds_read_b128 v[144:147], v155
	ds_read_b128 v[148:151], v155 offset:1024
	ds_read_b128 v[158:161], v155 offset:2048
	ds_read_b128 v[162:165], v155 offset:3072
	ds_read_b128 v[166:169], v156
	ds_read_b128 v[170:173], v156 offset:1024
	ds_read_b128 v[174:177], v156 offset:2048
	ds_read_b128 v[178:181], v156 offset:3072
	s_add_u32 s30, s28, 0xfff80080
	s_addc_u32 s31, s29, -1
	s_cmp_eq_u32 s56, 28
	s_cselect_b32 s35, s23, s31
	s_cselect_b32 s34, s22, s30
	s_cselect_b32 s31, s25, s21
	s_cselect_b32 s30, s24, s19
	v_lshl_add_u64 v[202:203], s[28:29], 0, v[138:139]
	s_add_i32 m0, s27, 0xc000
	ds_read_b128 v[182:185], v157
	ds_read_b128 v[186:189], v157 offset:1024
	ds_read_b128 v[190:193], v157 offset:2048
	ds_read_b128 v[194:197], v157 offset:3072
	ds_read_b128 v[198:201], v157 offset:4096
	ds_read_b128 v[206:209], v157 offset:5120
	ds_read_b128 v[210:213], v157 offset:6144
	ds_read_b128 v[214:217], v157 offset:7168
	global_load_lds_dwordx4 v[202:203], off
	v_lshl_add_u64 v[202:203], s[28:29], 0, v[136:137]
	s_add_i32 m0, s27, 0xe000
	s_nop 0
	global_load_lds_dwordx4 v[202:203], off
	s_waitcnt vmcnt(8)
	s_waitcnt lgkmcnt(0)
	s_barrier
	s_setprio 1
	v_mfma_f32_16x16x32_bf16 v[124:127], v[144:147], v[182:185], v[124:127]
	v_mfma_f32_16x16x32_bf16 v[120:123], v[158:161], v[182:185], v[120:123]
	v_mfma_f32_16x16x32_bf16 v[116:119], v[144:147], v[190:193], v[116:119]
	v_mfma_f32_16x16x32_bf16 v[112:115], v[158:161], v[190:193], v[112:115]
	v_mfma_f32_16x16x32_bf16 v[92:95], v[144:147], v[198:201], v[92:95]
	v_mfma_f32_16x16x32_bf16 v[88:91], v[158:161], v[198:201], v[88:91]
	v_mfma_f32_16x16x32_bf16 v[84:87], v[144:147], v[210:213], v[84:87]
	v_mfma_f32_16x16x32_bf16 v[80:83], v[158:161], v[210:213], v[80:83]
	v_mfma_f32_16x16x32_bf16 v[124:127], v[148:151], v[186:189], v[124:127]
	v_mfma_f32_16x16x32_bf16 v[120:123], v[162:165], v[186:189], v[120:123]
	v_mfma_f32_16x16x32_bf16 v[116:119], v[148:151], v[194:197], v[116:119]
	v_mfma_f32_16x16x32_bf16 v[112:115], v[162:165], v[194:197], v[112:115]
	v_mfma_f32_16x16x32_bf16 v[92:95], v[148:151], v[206:209], v[92:95]
	v_mfma_f32_16x16x32_bf16 v[88:91], v[162:165], v[206:209], v[88:91]
	v_mfma_f32_16x16x32_bf16 v[84:87], v[148:151], v[214:217], v[84:87]
	v_mfma_f32_16x16x32_bf16 v[80:83], v[162:165], v[214:217], v[80:83]
	s_setprio 0
	s_setprio 1
	v_mfma_f32_16x16x32_bf16 v[108:111], v[166:169], v[182:185], v[108:111]
	v_mfma_f32_16x16x32_bf16 v[104:107], v[174:177], v[182:185], v[104:107]
	v_mfma_f32_16x16x32_bf16 v[100:103], v[166:169], v[190:193], v[100:103]
	v_mfma_f32_16x16x32_bf16 v[96:99], v[174:177], v[190:193], v[96:99]
	v_mfma_f32_16x16x32_bf16 v[76:79], v[166:169], v[198:201], v[76:79]
	v_mfma_f32_16x16x32_bf16 v[72:75], v[174:177], v[198:201], v[72:75]
	v_mfma_f32_16x16x32_bf16 v[68:71], v[166:169], v[210:213], v[68:71]
	v_mfma_f32_16x16x32_bf16 v[64:67], v[174:177], v[210:213], v[64:67]
	v_mfma_f32_16x16x32_bf16 v[108:111], v[170:173], v[186:189], v[108:111]
	v_mfma_f32_16x16x32_bf16 v[104:107], v[178:181], v[186:189], v[104:107]
	v_mfma_f32_16x16x32_bf16 v[100:103], v[170:173], v[194:197], v[100:103]
	v_mfma_f32_16x16x32_bf16 v[96:99], v[178:181], v[194:197], v[96:99]
	v_mfma_f32_16x16x32_bf16 v[76:79], v[170:173], v[206:209], v[76:79]
	v_mfma_f32_16x16x32_bf16 v[72:75], v[178:181], v[206:209], v[72:75]
	v_mfma_f32_16x16x32_bf16 v[68:71], v[170:173], v[214:217], v[68:71]
	v_mfma_f32_16x16x32_bf16 v[64:67], v[178:181], v[214:217], v[64:67]
	s_setprio 0
	s_barrier
	s_add_i32 s57, s53, s45
	v_lshl_add_u64 v[202:203], s[30:31], 0, v[130:131]
	s_mov_b32 m0, s57
	ds_read_b128 v[182:185], v157 offset:16384
	ds_read_b128 v[186:189], v157 offset:17408
	ds_read_b128 v[190:193], v157 offset:18432
	ds_read_b128 v[194:197], v157 offset:19456
	ds_read_b128 v[198:201], v157 offset:20480
	ds_read_b128 v[206:209], v157 offset:21504
	ds_read_b128 v[210:213], v157 offset:22528
	ds_read_b128 v[214:217], v157 offset:23552
	global_load_lds_dwordx4 v[202:203], off
	s_add_i32 m0, s57, 0x2000
	s_add_u32 s58, s30, 0x80000
	v_lshl_add_u64 v[218:219], s[30:31], 0, v[134:135]
	s_addc_u32 s59, s31, 0
	s_add_i32 s57, s54, s45
	global_load_lds_dwordx4 v[218:219], off
	v_lshl_add_u64 v[220:221], s[58:59], 0, v[130:131]
	s_mov_b32 m0, s57
	v_lshl_add_u64 v[222:223], s[34:35], 0, v[132:133]
	global_load_lds_dwordx4 v[220:221], off
	v_lshl_add_u64 v[220:221], s[58:59], 0, v[134:135]
	s_add_i32 m0, s57, 0x2000
	s_nop 0
	global_load_lds_dwordx4 v[220:221], off
	v_lshl_add_u64 v[220:221], s[34:35], 0, v[128:129]
	s_mov_b32 m0, s27
	s_nop 0
	global_load_lds_dwordx4 v[220:221], off
	s_mov_b32 m0, s46
	s_nop 0
	global_load_lds_dwordx4 v[222:223], off
	s_waitcnt vmcnt(8)
	s_waitcnt lgkmcnt(0)
	s_barrier
; #define PG8_STAGE(bufoff, gbase, voff) do { _Pragma("unroll") for (int _i = 0; _i < 2; ++_i) \
;         __builtin_amdgcn_global_load_lds((const unsigned*)((const char*)(gbase) + (voff)[_i]), (PG8_LAS unsigned*)(lds + (bufoff) + ldsw + _i * 8192), 16, 0, 0); } while (0)
; #define PG8_LDA(dst, b, h) do { _Pragma("unroll") for (int m = 0; m < 4; ++m) _Pragma("unroll") for (int k = 0; k < 2; ++k) dst[m][k] = *(const PG8_LAS bf16x8*)(lds + PG8_SA(b, h) + aoff + m * 2048 + k * 1024); } while (0)
; #define PG8_LDB(dst, b, h) do { _Pragma("unroll") for (int n = 0; n < 2; ++n) _Pragma("unroll") for (int k = 0; k < 2; ++k) dst[n][k] = *(const PG8_LAS bf16x8*)(lds + PG8_SB(b, h) + boff + n * 2048 + k * 1024); } while (0)
; #define PG8_MMA(ai, bj, At, Bt) do { __builtin_amdgcn_s_setprio(1); _Pragma("unroll") for (int m = 0; m < 4; ++m) _Pragma("unroll") for (int n = 0; n < 2; ++n) _Pragma("unroll") for (int k = 0; k < 2; ++k) \
;         acc[ai][bj][m][n] = __builtin_amdgcn_mfma_f32_16x16x32_bf16(Bt[n][k], At[m][k], acc[ai][bj][m][n], 0, 0, 0); __builtin_amdgcn_s_setprio(0); } while (0)
; #define PG8_WAIT_V(n) asm volatile("s_waitcnt vmcnt(" #n ")" ::: "memory")
; #define PG8_WAIT_L(n) asm volatile("s_waitcnt lgkmcnt(" #n ")" ::: "memory")
; #define PG8_BAR __builtin_amdgcn_s_barrier()
; #define PG8_SCHED __builtin_amdgcn_sched_barrier(0)
; template <class Epi, class Sched, bool ALIGN_EPI = false, bool SP2 = false>
; __device__ __forceinline__ void gemm_phase(PG8_LAS unsigned char* lds, const Gemm g, const Sched& S, const Epi& E, const int wv0) {
;     ...
;             PG8_WAIT_V(8); PG8_WAIT_L(0); PG8_BAR; PG8_MMA(1, 0, At, B0); PG8_MMA(1, 1, At, B1); PG8_BAR; PG8_SCHED;
;             PG8_LDB(B0, 1, 0); PG8_LDB(B1, 1, 1); PG8_SCHED; PG8_LDA(At, 1, 0); PG8_STAGE(PG8_SA(0, 1), a2 + hstepA, voffA);
;             PG8_WAIT_V(8); PG8_WAIT_L(0); PG8_BAR; PG8_MMA(0, 0, At, B0); PG8_MMA(0, 1, At, B1); PG8_BAR; PG8_SCHED;
	s_setprio 1
	v_mfma_f32_16x16x32_bf16 v[60:63], v[144:147], v[182:185], v[60:63]
	v_mfma_f32_16x16x32_bf16 v[56:59], v[158:161], v[182:185], v[56:59]
	v_mfma_f32_16x16x32_bf16 v[52:55], v[144:147], v[190:193], v[52:55]
	v_mfma_f32_16x16x32_bf16 v[48:51], v[158:161], v[190:193], v[48:51]
	v_mfma_f32_16x16x32_bf16 v[28:31], v[144:147], v[198:201], v[28:31]
	v_mfma_f32_16x16x32_bf16 v[24:27], v[158:161], v[198:201], v[24:27]
	v_mfma_f32_16x16x32_bf16 v[20:23], v[144:147], v[210:213], v[20:23]
	v_mfma_f32_16x16x32_bf16 v[16:19], v[158:161], v[210:213], v[16:19]
	v_mfma_f32_16x16x32_bf16 v[60:63], v[148:151], v[186:189], v[60:63]
	v_mfma_f32_16x16x32_bf16 v[56:59], v[162:165], v[186:189], v[56:59]
	v_mfma_f32_16x16x32_bf16 v[52:55], v[148:151], v[194:197], v[52:55]
	v_mfma_f32_16x16x32_bf16 v[48:51], v[162:165], v[194:197], v[48:51]
	v_mfma_f32_16x16x32_bf16 v[28:31], v[148:151], v[206:209], v[28:31]
	v_mfma_f32_16x16x32_bf16 v[24:27], v[162:165], v[206:209], v[24:27]
	v_mfma_f32_16x16x32_bf16 v[20:23], v[148:151], v[214:217], v[20:23]
	v_mfma_f32_16x16x32_bf16 v[16:19], v[162:165], v[214:217], v[16:19]
	s_setprio 0
	s_setprio 1
	v_mfma_f32_16x16x32_bf16 v[44:47], v[166:169], v[182:185], v[44:47]
	v_mfma_f32_16x16x32_bf16 v[40:43], v[174:177], v[182:185], v[40:43]
	v_mfma_f32_16x16x32_bf16 v[36:39], v[166:169], v[190:193], v[36:39]
	v_mfma_f32_16x16x32_bf16 v[32:35], v[174:177], v[190:193], v[32:35]
	v_mfma_f32_16x16x32_bf16 v[12:15], v[166:169], v[198:201], v[12:15]
	v_mfma_f32_16x16x32_bf16 v[8:11], v[174:177], v[198:201], v[8:11]
	v_mfma_f32_16x16x32_bf16 v[4:7], v[166:169], v[210:213], v[4:7]
	v_mfma_f32_16x16x32_bf16 v[0:3], v[174:177], v[210:213], v[0:3]
	v_mfma_f32_16x16x32_bf16 v[44:47], v[170:173], v[186:189], v[44:47]
	v_mfma_f32_16x16x32_bf16 v[40:43], v[178:181], v[186:189], v[40:43]
	v_mfma_f32_16x16x32_bf16 v[36:39], v[170:173], v[194:197], v[36:39]
	v_mfma_f32_16x16x32_bf16 v[32:35], v[178:181], v[194:197], v[32:35]
	v_mfma_f32_16x16x32_bf16 v[12:15], v[170:173], v[206:209], v[12:15]
	v_mfma_f32_16x16x32_bf16 v[8:11], v[178:181], v[206:209], v[8:11]
	v_mfma_f32_16x16x32_bf16 v[4:7], v[170:173], v[214:217], v[4:7]
	v_mfma_f32_16x16x32_bf16 v[0:3], v[178:181], v[214:217], v[0:3]
	s_setprio 0
	s_barrier
	s_add_i32 s57, 0, 0x18000
	s_add_i32 s58, 0, 0x1c000
	v_add_u32_e32 v162, s57, v153
	v_add_u32_e32 v178, s58, v153
	ds_read_b128 v[144:147], v162
	ds_read_b128 v[148:151], v162 offset:1024
	ds_read_b128 v[158:161], v162 offset:2048
	ds_read_b128 v[162:165], v162 offset:3072
	ds_read_b128 v[166:169], v178
	ds_read_b128 v[170:173], v178 offset:1024
	ds_read_b128 v[174:177], v178 offset:2048
	ds_read_b128 v[178:181], v178 offset:3072
	s_add_u32 s34, s34, 0x80000
	s_addc_u32 s35, s35, 0
	s_mov_b32 m0, s47
	v_lshl_add_u64 v[224:225], s[34:35], 0, v[128:129]
	ds_read_b128 v[182:185], v157 offset:32768
	ds_read_b128 v[186:189], v157 offset:33792
	ds_read_b128 v[190:193], v157 offset:34816
	ds_read_b128 v[194:197], v157 offset:35840
	ds_read_b128 v[198:201], v157 offset:36864
	ds_read_b128 v[206:209], v157 offset:37888
	ds_read_b128 v[210:213], v157 offset:38912
	ds_read_b128 v[214:217], v157 offset:39936
	global_load_lds_dwordx4 v[224:225], off
	v_lshl_add_u64 v[224:225], s[34:35], 0, v[132:133]
	s_mov_b32 m0, s48
	s_nop 0
	global_load_lds_dwordx4 v[224:225], off
	s_waitcnt vmcnt(8)
	s_waitcnt lgkmcnt(0)
	s_barrier
	s_setprio 1
	v_mfma_f32_16x16x32_bf16 v[124:127], v[144:147], v[182:185], v[124:127]
	v_mfma_f32_16x16x32_bf16 v[120:123], v[158:161], v[182:185], v[120:123]
	v_mfma_f32_16x16x32_bf16 v[116:119], v[144:147], v[190:193], v[116:119]
	v_mfma_f32_16x16x32_bf16 v[112:115], v[158:161], v[190:193], v[112:115]
	v_mfma_f32_16x16x32_bf16 v[92:95], v[144:147], v[198:201], v[92:95]
	v_mfma_f32_16x16x32_bf16 v[88:91], v[158:161], v[198:201], v[88:91]
	v_mfma_f32_16x16x32_bf16 v[84:87], v[144:147], v[210:213], v[84:87]
	v_mfma_f32_16x16x32_bf16 v[80:83], v[158:161], v[210:213], v[80:83]
	v_mfma_f32_16x16x32_bf16 v[124:127], v[148:151], v[186:189], v[124:127]
	v_mfma_f32_16x16x32_bf16 v[120:123], v[162:165], v[186:189], v[120:123]
	v_mfma_f32_16x16x32_bf16 v[116:119], v[148:151], v[194:197], v[116:119]
	v_mfma_f32_16x16x32_bf16 v[112:115], v[162:165], v[194:197], v[112:115]
	v_mfma_f32_16x16x32_bf16 v[92:95], v[148:151], v[206:209], v[92:95]
	v_mfma_f32_16x16x32_bf16 v[88:91], v[162:165], v[206:209], v[88:91]
	v_mfma_f32_16x16x32_bf16 v[84:87], v[148:151], v[214:217], v[84:87]
	v_mfma_f32_16x16x32_bf16 v[80:83], v[162:165], v[214:217], v[80:83]
	s_setprio 0
	s_setprio 1
	v_mfma_f32_16x16x32_bf16 v[108:111], v[166:169], v[182:185], v[108:111]
	v_mfma_f32_16x16x32_bf16 v[104:107], v[174:177], v[182:185], v[104:107]
	v_mfma_f32_16x16x32_bf16 v[100:103], v[166:169], v[190:193], v[100:103]
	v_mfma_f32_16x16x32_bf16 v[96:99], v[174:177], v[190:193], v[96:99]
	v_mfma_f32_16x16x32_bf16 v[76:79], v[166:169], v[198:201], v[76:79]
	v_mfma_f32_16x16x32_bf16 v[72:75], v[174:177], v[198:201], v[72:75]
	v_mfma_f32_16x16x32_bf16 v[68:71], v[166:169], v[210:213], v[68:71]
	v_mfma_f32_16x16x32_bf16 v[64:67], v[174:177], v[210:213], v[64:67]
	v_mfma_f32_16x16x32_bf16 v[108:111], v[170:173], v[186:189], v[108:111]
	v_mfma_f32_16x16x32_bf16 v[104:107], v[178:181], v[186:189], v[104:107]
	v_mfma_f32_16x16x32_bf16 v[100:103], v[170:173], v[194:197], v[100:103]
	v_mfma_f32_16x16x32_bf16 v[96:99], v[178:181], v[194:197], v[96:99]
	v_mfma_f32_16x16x32_bf16 v[76:79], v[170:173], v[206:209], v[76:79]
	v_mfma_f32_16x16x32_bf16 v[72:75], v[178:181], v[206:209], v[72:75]
	v_mfma_f32_16x16x32_bf16 v[68:71], v[170:173], v[214:217], v[68:71]
	v_mfma_f32_16x16x32_bf16 v[64:67], v[178:181], v[214:217], v[64:67]
	s_setprio 0
	s_barrier
; #define PG8_STAGE(bufoff, gbase, voff) do { _Pragma("unroll") for (int _i = 0; _i < 2; ++_i) \
;         __builtin_amdgcn_global_load_lds((const unsigned*)((const char*)(gbase) + (voff)[_i]), (PG8_LAS unsigned*)(lds + (bufoff) + ldsw + _i * 8192), 16, 0, 0); } while (0)
; #define PG8_LDA(dst, b, h) do { _Pragma("unroll") for (int m = 0; m < 4; ++m) _Pragma("unroll") for (int k = 0; k < 2; ++k) dst[m][k] = *(const PG8_LAS bf16x8*)(lds + PG8_SA(b, h) + aoff + m * 2048 + k * 1024); } while (0)
; #define PG8_LDB(dst, b, h) do { _Pragma("unroll") for (int n = 0; n < 2; ++n) _Pragma("unroll") for (int k = 0; k < 2; ++k) dst[n][k] = *(const PG8_LAS bf16x8*)(lds + PG8_SB(b, h) + boff + n * 2048 + k * 1024); } while (0)
; #define PG8_MMA(ai, bj, At, Bt) do { __builtin_amdgcn_s_setprio(1); _Pragma("unroll") for (int m = 0; m < 4; ++m) _Pragma("unroll") for (int n = 0; n < 2; ++n) _Pragma("unroll") for (int k = 0; k < 2; ++k) \
;         acc[ai][bj][m][n] = __builtin_amdgcn_mfma_f32_16x16x32_bf16(Bt[n][k], At[m][k], acc[ai][bj][m][n], 0, 0, 0); __builtin_amdgcn_s_setprio(0); } while (0)
; #define PG8_BAR __builtin_amdgcn_s_barrier()
; template <class Epi, class Sched, bool ALIGN_EPI = false, bool SP2 = false>
; __device__ __forceinline__ void gemm_phase(PG8_LAS unsigned char* lds, const Gemm g, const Sched& S, const Epi& E, const int wv0) {
;     ...
;             PG8_LDB(B0, 0, 0); PG8_LDB(B1, 0, 1); PG8_SCHED; PG8_LDA(At, 0, 0); PG8_STAGE(PG8_SA(1, 1), a1 + hstepA, voffA);
;             PG8_WAIT_V(8); PG8_WAIT_L(0); PG8_BAR; PG8_MMA(0, 0, At, B0); PG8_MMA(0, 1, At, B1); PG8_BAR; PG8_SCHED;
;             PG8_LDA(At, 0, 1); PG8_STAGE(PG8_SB(0, 0), b2, voffB); PG8_STAGE(PG8_SB(0, 1), b2 + hstepB, voffB); PG8_STAGE(PG8_SA(0, 0), a2, voffA);
;             PG8_WAIT_V(8); PG8_WAIT_L(0); PG8_BAR; PG8_MMA(1, 0, At, B0); PG8_MMA(1, 1, At, B1); PG8_BAR; PG8_SCHED;
;             PG8_LDB(B0, 1, 0); PG8_LDB(B1, 1, 1); PG8_SCHED; PG8_LDA(At, 1, 0); PG8_STAGE(PG8_SA(0, 1), a2 + hstepA, voffA);
;             PG8_WAIT_V(8); PG8_WAIT_L(0); PG8_BAR; PG8_MMA(0, 0, At, B0); PG8_MMA(0, 1, At, B1); PG8_BAR; PG8_SCHED;
;             PG8_LDA(At, 1, 1); PG8_STAGE(PG8_SB(1, 0), b3, voffB); PG8_STAGE(PG8_SB(1, 1), b3 + hstepB, voffB); PG8_STAGE(PG8_SA(1, 0), a3, voffA);
;             PG8_WAIT_V(8); PG8_WAIT_L(0); PG8_BAR; PG8_MMA(1, 0, At, B0); PG8_MMA(1, 1, At, B1); PG8_BAR; PG8_SCHED;
	s_add_i32 s34, s57, s45
	v_lshl_add_u64 v[202:203], v[202:203], 0, s[8:9]
	s_mov_b32 m0, s34
	ds_read_b128 v[182:185], v157 offset:49152
	ds_read_b128 v[186:189], v157 offset:50176
	ds_read_b128 v[190:193], v157 offset:51200
	ds_read_b128 v[194:197], v157 offset:52224
	ds_read_b128 v[198:201], v157 offset:53248
	ds_read_b128 v[206:209], v157 offset:54272
	ds_read_b128 v[210:213], v157 offset:55296
	ds_read_b128 v[214:217], v157 offset:56320
	global_load_lds_dwordx4 v[202:203], off
	s_add_i32 m0, s34, 0x2000
	s_add_u32 s30, s30, 0x80080
	v_lshl_add_u64 v[202:203], v[218:219], 0, s[8:9]
	s_addc_u32 s31, s31, 0
	s_add_i32 s34, s58, s45
	global_load_lds_dwordx4 v[202:203], off
	v_lshl_add_u64 v[202:203], s[30:31], 0, v[130:131]
	s_mov_b32 m0, s34
	s_nop 0
	global_load_lds_dwordx4 v[202:203], off
	v_lshl_add_u64 v[202:203], s[30:31], 0, v[134:135]
	s_add_i32 m0, s34, 0x2000
	s_nop 0
	global_load_lds_dwordx4 v[202:203], off
	v_lshl_add_u64 v[202:203], v[220:221], 0, s[8:9]
	s_mov_b32 m0, s50
	s_nop 0
	global_load_lds_dwordx4 v[202:203], off
	v_lshl_add_u64 v[202:203], v[222:223], 0, s[8:9]
	s_mov_b32 m0, s51
	s_nop 0
	global_load_lds_dwordx4 v[202:203], off
	s_waitcnt vmcnt(8)
	s_waitcnt lgkmcnt(0)
	s_barrier
	s_setprio 1
	v_mfma_f32_16x16x32_bf16 v[60:63], v[144:147], v[182:185], v[60:63]
	v_mfma_f32_16x16x32_bf16 v[56:59], v[158:161], v[182:185], v[56:59]
	v_mfma_f32_16x16x32_bf16 v[52:55], v[144:147], v[190:193], v[52:55]
	v_mfma_f32_16x16x32_bf16 v[48:51], v[158:161], v[190:193], v[48:51]
	v_mfma_f32_16x16x32_bf16 v[28:31], v[144:147], v[198:201], v[28:31]
	v_mfma_f32_16x16x32_bf16 v[24:27], v[158:161], v[198:201], v[24:27]
	v_mfma_f32_16x16x32_bf16 v[20:23], v[144:147], v[210:213], v[20:23]
	v_mfma_f32_16x16x32_bf16 v[16:19], v[158:161], v[210:213], v[16:19]
	v_mfma_f32_16x16x32_bf16 v[60:63], v[148:151], v[186:189], v[60:63]
	v_mfma_f32_16x16x32_bf16 v[56:59], v[162:165], v[186:189], v[56:59]
	v_mfma_f32_16x16x32_bf16 v[52:55], v[148:151], v[194:197], v[52:55]
	v_mfma_f32_16x16x32_bf16 v[48:51], v[162:165], v[194:197], v[48:51]
	v_mfma_f32_16x16x32_bf16 v[28:31], v[148:151], v[206:209], v[28:31]
	v_mfma_f32_16x16x32_bf16 v[24:27], v[162:165], v[206:209], v[24:27]
	v_mfma_f32_16x16x32_bf16 v[20:23], v[148:151], v[214:217], v[20:23]
	v_mfma_f32_16x16x32_bf16 v[16:19], v[162:165], v[214:217], v[16:19]
	s_setprio 0
	s_setprio 1
	v_mfma_f32_16x16x32_bf16 v[44:47], v[166:169], v[182:185], v[44:47]
	v_mfma_f32_16x16x32_bf16 v[40:43], v[174:177], v[182:185], v[40:43]
	v_mfma_f32_16x16x32_bf16 v[36:39], v[166:169], v[190:193], v[36:39]
	v_mfma_f32_16x16x32_bf16 v[32:35], v[174:177], v[190:193], v[32:35]
	v_mfma_f32_16x16x32_bf16 v[12:15], v[166:169], v[198:201], v[12:15]
	v_mfma_f32_16x16x32_bf16 v[8:11], v[174:177], v[198:201], v[8:11]
	v_mfma_f32_16x16x32_bf16 v[4:7], v[166:169], v[210:213], v[4:7]
	v_mfma_f32_16x16x32_bf16 v[0:3], v[174:177], v[210:213], v[0:3]
	v_mfma_f32_16x16x32_bf16 v[44:47], v[170:173], v[186:189], v[44:47]
	v_mfma_f32_16x16x32_bf16 v[40:43], v[178:181], v[186:189], v[40:43]
	v_mfma_f32_16x16x32_bf16 v[36:39], v[170:173], v[194:197], v[36:39]
	v_mfma_f32_16x16x32_bf16 v[32:35], v[178:181], v[194:197], v[32:35]
	v_mfma_f32_16x16x32_bf16 v[12:15], v[170:173], v[206:209], v[12:15]
	v_mfma_f32_16x16x32_bf16 v[8:11], v[178:181], v[206:209], v[8:11]
	v_mfma_f32_16x16x32_bf16 v[4:7], v[170:173], v[214:217], v[4:7]
	v_mfma_f32_16x16x32_bf16 v[0:3], v[178:181], v[214:217], v[0:3]
	s_setprio 0
	s_barrier
	s_add_i32 s56, s56, 2
	s_add_u32 s19, s19, 0x100
	s_addc_u32 s21, s21, 0
	s_add_u32 s28, s28, 0x100
	s_addc_u32 s29, s29, 0
	s_cmp_gt_u32 s56, 29
	s_cbranch_scc0 .LBB0_1608
	s_and_b64 vcc, exec, s[10:11]
	s_cbranch_vccz .LBB0_1611
	s_barrier

; #define PG8_STAGE(bufoff, gbase, voff) do { _Pragma("unroll") for (int _i = 0; _i < 2; ++_i) \
;         __builtin_amdgcn_global_load_lds((const unsigned*)((const char*)(gbase) + (voff)[_i]), (PG8_LAS unsigned*)(lds + (bufoff) + ldsw + _i * 8192), 16, 0, 0); } while (0)
; #define PG8_LDA(dst, b, h) do { _Pragma("unroll") for (int m = 0; m < 4; ++m) _Pragma("unroll") for (int k = 0; k < 2; ++k) dst[m][k] = *(const PG8_LAS bf16x8*)(lds + PG8_SA(b, h) + aoff + m * 2048 + k * 1024); } while (0)
; #define PG8_LDB(dst, b, h) do { _Pragma("unroll") for (int n = 0; n < 2; ++n) _Pragma("unroll") for (int k = 0; k < 2; ++k) dst[n][k] = *(const PG8_LAS bf16x8*)(lds + PG8_SB(b, h) + boff + n * 2048 + k * 1024); } while (0)
; #define PG8_MMA(ai, bj, At, Bt) do { __builtin_amdgcn_s_setprio(1); _Pragma("unroll") for (int m = 0; m < 4; ++m) _Pragma("unroll") for (int n = 0; n < 2; ++n) _Pragma("unroll") for (int k = 0; k < 2; ++k) \
;         acc[ai][bj][m][n] = __builtin_amdgcn_mfma_f32_16x16x32_bf16(Bt[n][k], At[m][k], acc[ai][bj][m][n], 0, 0, 0); __builtin_amdgcn_s_setprio(0); } while (0)
; #define PG8_BAR __builtin_amdgcn_s_barrier()
; template <class Epi, class Sched, bool ALIGN_EPI = false, bool SP2 = false>
; __device__ __forceinline__ void gemm_phase(PG8_LAS unsigned char* lds, const Gemm g, const Sched& S, const Epi& E, const int wv0) {
;     ...
;             PG8_LDB(B0, 0, 0); PG8_LDB(B1, 0, 1); PG8_SCHED; PG8_LDA(At, 0, 0); PG8_STAGE(PG8_SA(1, 1), a1 + hstepA, voffA);
;             PG8_WAIT_V(8); PG8_WAIT_L(0); PG8_BAR; PG8_MMA(0, 0, At, B0); PG8_MMA(0, 1, At, B1); PG8_BAR; PG8_SCHED;
;             PG8_LDA(At, 0, 1); PG8_STAGE(PG8_SB(0, 0), b2, voffB); PG8_STAGE(PG8_SB(0, 1), b2 + hstepB, voffB); PG8_STAGE(PG8_SA(0, 0), a2, voffA);
;             PG8_WAIT_V(8); PG8_WAIT_L(0); PG8_BAR; PG8_MMA(1, 0, At, B0); PG8_MMA(1, 1, At, B1); PG8_BAR; PG8_SCHED;
;             PG8_LDB(B0, 1, 0); PG8_LDB(B1, 1, 1); PG8_SCHED; PG8_LDA(At, 1, 0); PG8_STAGE(PG8_SA(0, 1), a2 + hstepA, voffA);
;             PG8_WAIT_V(8); PG8_WAIT_L(0); PG8_BAR; PG8_MMA(0, 0, At, B0); PG8_MMA(0, 1, At, B1); PG8_BAR; PG8_SCHED;
;             PG8_LDA(At, 1, 1); PG8_STAGE(PG8_SB(1, 0), b3, voffB); PG8_STAGE(PG8_SB(1, 1), b3 + hstepB, voffB); PG8_STAGE(PG8_SA(1, 0), a3, voffA);
;             PG8_WAIT_V(8); PG8_WAIT_L(0); PG8_BAR; PG8_MMA(1, 0, At, B0); PG8_MMA(1, 1, At, B1); PG8_BAR; PG8_SCHED;
.LBB0_1808:
	ds_read_b128 v[144:147], v153
	ds_read_b128 v[156:159], v153 offset:1024
	ds_read_b128 v[160:163], v153 offset:2048
	ds_read_b128 v[164:167], v153 offset:3072
	ds_read_b128 v[168:171], v154
	ds_read_b128 v[172:175], v154 offset:1024
	ds_read_b128 v[176:179], v154 offset:2048
	ds_read_b128 v[180:183], v154 offset:3072
	s_add_u32 s18, s16, 0x100
	s_addc_u32 s19, s17, 0
	s_cmpk_eq_i32 s48, 0x54
	s_cselect_b32 s23, s13, s19
	s_cselect_b32 s22, s12, s18
	s_cselect_b32 s21, s15, s47
	s_cselect_b32 s20, s14, s46
	v_lshl_add_u64 v[148:149], s[16:17], 0, v[138:139]
	s_add_i32 m0, s30, 0xc000
	ds_read_b128 v[184:187], v155
	ds_read_b128 v[188:191], v155 offset:1024
	ds_read_b128 v[192:195], v155 offset:2048
	ds_read_b128 v[196:199], v155 offset:3072
	ds_read_b128 v[200:203], v155 offset:4096
	ds_read_b128 v[204:207], v155 offset:5120
	ds_read_b128 v[208:211], v155 offset:6144
	ds_read_b128 v[212:215], v155 offset:7168
	global_load_lds_dwordx4 v[148:149], off
	v_lshl_add_u64 v[148:149], s[16:17], 0, v[136:137]
	s_add_i32 m0, s30, 0xe000
	s_nop 0
	global_load_lds_dwordx4 v[148:149], off
	s_waitcnt vmcnt(8)
	s_waitcnt lgkmcnt(0)
	s_barrier
	s_setprio 1
	v_mfma_f32_16x16x32_bf16 v[124:127], v[144:147], v[184:187], v[124:127]
	v_mfma_f32_16x16x32_bf16 v[120:123], v[160:163], v[184:187], v[120:123]
	v_mfma_f32_16x16x32_bf16 v[116:119], v[144:147], v[192:195], v[116:119]
	v_mfma_f32_16x16x32_bf16 v[112:115], v[160:163], v[192:195], v[112:115]
	v_mfma_f32_16x16x32_bf16 v[92:95], v[144:147], v[200:203], v[92:95]
	v_mfma_f32_16x16x32_bf16 v[88:91], v[160:163], v[200:203], v[88:91]
	v_mfma_f32_16x16x32_bf16 v[84:87], v[144:147], v[208:211], v[84:87]
	v_mfma_f32_16x16x32_bf16 v[80:83], v[160:163], v[208:211], v[80:83]
	v_mfma_f32_16x16x32_bf16 v[124:127], v[156:159], v[188:191], v[124:127]
	v_mfma_f32_16x16x32_bf16 v[120:123], v[164:167], v[188:191], v[120:123]
	v_mfma_f32_16x16x32_bf16 v[116:119], v[156:159], v[196:199], v[116:119]
	v_mfma_f32_16x16x32_bf16 v[112:115], v[164:167], v[196:199], v[112:115]
	v_mfma_f32_16x16x32_bf16 v[92:95], v[156:159], v[204:207], v[92:95]
	v_mfma_f32_16x16x32_bf16 v[88:91], v[164:167], v[204:207], v[88:91]
	v_mfma_f32_16x16x32_bf16 v[84:87], v[156:159], v[212:215], v[84:87]
	v_mfma_f32_16x16x32_bf16 v[80:83], v[164:167], v[212:215], v[80:83]
	s_setprio 0
	s_setprio 1
	v_mfma_f32_16x16x32_bf16 v[108:111], v[168:171], v[184:187], v[108:111]
	v_mfma_f32_16x16x32_bf16 v[104:107], v[176:179], v[184:187], v[104:107]
	v_mfma_f32_16x16x32_bf16 v[100:103], v[168:171], v[192:195], v[100:103]
	v_mfma_f32_16x16x32_bf16 v[96:99], v[176:179], v[192:195], v[96:99]
	v_mfma_f32_16x16x32_bf16 v[76:79], v[168:171], v[200:203], v[76:79]
	v_mfma_f32_16x16x32_bf16 v[72:75], v[176:179], v[200:203], v[72:75]
	v_mfma_f32_16x16x32_bf16 v[68:71], v[168:171], v[208:211], v[68:71]
	v_mfma_f32_16x16x32_bf16 v[64:67], v[176:179], v[208:211], v[64:67]
	v_mfma_f32_16x16x32_bf16 v[108:111], v[172:175], v[188:191], v[108:111]
	v_mfma_f32_16x16x32_bf16 v[104:107], v[180:183], v[188:191], v[104:107]
	v_mfma_f32_16x16x32_bf16 v[100:103], v[172:175], v[196:199], v[100:103]
	v_mfma_f32_16x16x32_bf16 v[96:99], v[180:183], v[196:199], v[96:99]
	v_mfma_f32_16x16x32_bf16 v[76:79], v[172:175], v[204:207], v[76:79]
	v_mfma_f32_16x16x32_bf16 v[72:75], v[180:183], v[204:207], v[72:75]
	v_mfma_f32_16x16x32_bf16 v[68:71], v[172:175], v[212:215], v[68:71]
	v_mfma_f32_16x16x32_bf16 v[64:67], v[180:183], v[212:215], v[64:67]
	s_setprio 0
	s_barrier
	s_add_i32 s16, s40, s29
	v_lshl_add_u64 v[148:149], s[20:21], 0, v[130:131]
	s_mov_b32 m0, s16
	ds_read_b128 v[184:187], v155 offset:16384
	ds_read_b128 v[188:191], v155 offset:17408
	ds_read_b128 v[192:195], v155 offset:18432
	ds_read_b128 v[196:199], v155 offset:19456
	ds_read_b128 v[200:203], v155 offset:20480
	ds_read_b128 v[204:207], v155 offset:21504
	ds_read_b128 v[208:211], v155 offset:22528
	ds_read_b128 v[212:215], v155 offset:23552
	global_load_lds_dwordx4 v[148:149], off
	s_add_i32 m0, s16, 0x2000
	s_add_u32 s16, s20, 0x160000
	v_lshl_add_u64 v[216:217], s[20:21], 0, v[134:135]
	s_addc_u32 s17, s21, 0
	s_add_i32 s49, s41, s29
	global_load_lds_dwordx4 v[216:217], off
	v_lshl_add_u64 v[218:219], s[16:17], 0, v[130:131]
	s_mov_b32 m0, s49
	v_lshl_add_u64 v[220:221], s[22:23], 0, v[132:133]
	global_load_lds_dwordx4 v[218:219], off
	v_lshl_add_u64 v[218:219], s[16:17], 0, v[134:135]
	s_add_i32 m0, s49, 0x2000
	s_nop 0
	global_load_lds_dwordx4 v[218:219], off
	v_lshl_add_u64 v[218:219], s[22:23], 0, v[128:129]
	s_mov_b32 m0, s30
	s_nop 0
	global_load_lds_dwordx4 v[218:219], off
	s_mov_b32 m0, s31
	s_nop 0
	global_load_lds_dwordx4 v[220:221], off
	s_waitcnt vmcnt(8)
	s_waitcnt lgkmcnt(0)
	s_barrier
; #define PG8_STAGE(bufoff, gbase, voff) do { _Pragma("unroll") for (int _i = 0; _i < 2; ++_i) \
;         __builtin_amdgcn_global_load_lds((const unsigned*)((const char*)(gbase) + (voff)[_i]), (PG8_LAS unsigned*)(lds + (bufoff) + ldsw + _i * 8192), 16, 0, 0); } while (0)
; #define PG8_LDA(dst, b, h) do { _Pragma("unroll") for (int m = 0; m < 4; ++m) _Pragma("unroll") for (int k = 0; k < 2; ++k) dst[m][k] = *(const PG8_LAS bf16x8*)(lds + PG8_SA(b, h) + aoff + m * 2048 + k * 1024); } while (0)
; #define PG8_LDB(dst, b, h) do { _Pragma("unroll") for (int n = 0; n < 2; ++n) _Pragma("unroll") for (int k = 0; k < 2; ++k) dst[n][k] = *(const PG8_LAS bf16x8*)(lds + PG8_SB(b, h) + boff + n * 2048 + k * 1024); } while (0)
; #define PG8_MMA(ai, bj, At, Bt) do { __builtin_amdgcn_s_setprio(1); _Pragma("unroll") for (int m = 0; m < 4; ++m) _Pragma("unroll") for (int n = 0; n < 2; ++n) _Pragma("unroll") for (int k = 0; k < 2; ++k) \
;         acc[ai][bj][m][n] = __builtin_amdgcn_mfma_f32_16x16x32_bf16(Bt[n][k], At[m][k], acc[ai][bj][m][n], 0, 0, 0); __builtin_amdgcn_s_setprio(0); } while (0)
; #define PG8_BAR __builtin_amdgcn_s_barrier()
; template <class Epi, class Sched, bool ALIGN_EPI = false, bool SP2 = false>
; __device__ __forceinline__ void gemm_phase(PG8_LAS unsigned char* lds, const Gemm g, const Sched& S, const Epi& E, const int wv0) {
;     ...
;             PG8_LDB(B0, 0, 0); PG8_LDB(B1, 0, 1); PG8_SCHED; PG8_LDA(At, 0, 0); PG8_STAGE(PG8_SA(1, 1), a1 + hstepA, voffA);
;             PG8_WAIT_V(8); PG8_WAIT_L(0); PG8_BAR; PG8_MMA(0, 0, At, B0); PG8_MMA(0, 1, At, B1); PG8_BAR; PG8_SCHED;
;             PG8_LDA(At, 0, 1); PG8_STAGE(PG8_SB(0, 0), b2, voffB); PG8_STAGE(PG8_SB(0, 1), b2 + hstepB, voffB); PG8_STAGE(PG8_SA(0, 0), a2, voffA);
;             PG8_WAIT_V(8); PG8_WAIT_L(0); PG8_BAR; PG8_MMA(1, 0, At, B0); PG8_MMA(1, 1, At, B1); PG8_BAR; PG8_SCHED;
;             PG8_LDB(B0, 1, 0); PG8_LDB(B1, 1, 1); PG8_SCHED; PG8_LDA(At, 1, 0); PG8_STAGE(PG8_SA(0, 1), a2 + hstepA, voffA);
;             PG8_WAIT_V(8); PG8_WAIT_L(0); PG8_BAR; PG8_MMA(0, 0, At, B0); PG8_MMA(0, 1, At, B1); PG8_BAR; PG8_SCHED;
;             PG8_LDA(At, 1, 1); PG8_STAGE(PG8_SB(1, 0), b3, voffB); PG8_STAGE(PG8_SB(1, 1), b3 + hstepB, voffB); PG8_STAGE(PG8_SA(1, 0), a3, voffA);
;             PG8_WAIT_V(8); PG8_WAIT_L(0); PG8_BAR; PG8_MMA(1, 0, At, B0); PG8_MMA(1, 1, At, B1); PG8_BAR; PG8_SCHED;
	s_setprio 1
	v_mfma_f32_16x16x32_bf16 v[60:63], v[144:147], v[184:187], v[60:63]
	v_mfma_f32_16x16x32_bf16 v[56:59], v[160:163], v[184:187], v[56:59]
	v_mfma_f32_16x16x32_bf16 v[52:55], v[144:147], v[192:195], v[52:55]
	v_mfma_f32_16x16x32_bf16 v[48:51], v[160:163], v[192:195], v[48:51]
	v_mfma_f32_16x16x32_bf16 v[28:31], v[144:147], v[200:203], v[28:31]
	v_mfma_f32_16x16x32_bf16 v[24:27], v[160:163], v[200:203], v[24:27]
	v_mfma_f32_16x16x32_bf16 v[20:23], v[144:147], v[208:211], v[20:23]
	v_mfma_f32_16x16x32_bf16 v[16:19], v[160:163], v[208:211], v[16:19]
	v_mfma_f32_16x16x32_bf16 v[60:63], v[156:159], v[188:191], v[60:63]
	v_mfma_f32_16x16x32_bf16 v[56:59], v[164:167], v[188:191], v[56:59]
	v_mfma_f32_16x16x32_bf16 v[52:55], v[156:159], v[196:199], v[52:55]
	v_mfma_f32_16x16x32_bf16 v[48:51], v[164:167], v[196:199], v[48:51]
	v_mfma_f32_16x16x32_bf16 v[28:31], v[156:159], v[204:207], v[28:31]
	v_mfma_f32_16x16x32_bf16 v[24:27], v[164:167], v[204:207], v[24:27]
	v_mfma_f32_16x16x32_bf16 v[20:23], v[156:159], v[212:215], v[20:23]
	v_mfma_f32_16x16x32_bf16 v[16:19], v[164:167], v[212:215], v[16:19]
	s_setprio 0
	s_setprio 1
	v_mfma_f32_16x16x32_bf16 v[44:47], v[168:171], v[184:187], v[44:47]
	v_mfma_f32_16x16x32_bf16 v[40:43], v[176:179], v[184:187], v[40:43]
	v_mfma_f32_16x16x32_bf16 v[36:39], v[168:171], v[192:195], v[36:39]
	v_mfma_f32_16x16x32_bf16 v[32:35], v[176:179], v[192:195], v[32:35]
	v_mfma_f32_16x16x32_bf16 v[12:15], v[168:171], v[200:203], v[12:15]
	v_mfma_f32_16x16x32_bf16 v[8:11], v[176:179], v[200:203], v[8:11]
	v_mfma_f32_16x16x32_bf16 v[4:7], v[168:171], v[208:211], v[4:7]
	v_mfma_f32_16x16x32_bf16 v[0:3], v[176:179], v[208:211], v[0:3]
	v_mfma_f32_16x16x32_bf16 v[44:47], v[172:175], v[188:191], v[44:47]
	v_mfma_f32_16x16x32_bf16 v[40:43], v[180:183], v[188:191], v[40:43]
	v_mfma_f32_16x16x32_bf16 v[36:39], v[172:175], v[196:199], v[36:39]
	v_mfma_f32_16x16x32_bf16 v[32:35], v[180:183], v[196:199], v[32:35]
	v_mfma_f32_16x16x32_bf16 v[12:15], v[172:175], v[204:207], v[12:15]
	v_mfma_f32_16x16x32_bf16 v[8:11], v[180:183], v[204:207], v[8:11]
	v_mfma_f32_16x16x32_bf16 v[4:7], v[172:175], v[212:215], v[4:7]
	v_mfma_f32_16x16x32_bf16 v[0:3], v[180:183], v[212:215], v[0:3]
	s_setprio 0
	s_barrier
	s_add_i32 s49, 0, 0x18000
	s_add_i32 s50, 0, 0x1c000
	v_add_u32_e32 v164, s49, v151
	v_add_u32_e32 v180, s50, v151
	ds_read_b128 v[144:147], v164
	ds_read_b128 v[156:159], v164 offset:1024
	ds_read_b128 v[160:163], v164 offset:2048
	ds_read_b128 v[164:167], v164 offset:3072
	ds_read_b128 v[168:171], v180
	ds_read_b128 v[172:175], v180 offset:1024
	ds_read_b128 v[176:179], v180 offset:2048
	ds_read_b128 v[180:183], v180 offset:3072
	s_add_u32 s16, s22, 0x160000
	s_addc_u32 s17, s23, 0
	s_mov_b32 m0, s34
	v_lshl_add_u64 v[222:223], s[16:17], 0, v[128:129]
	ds_read_b128 v[184:187], v155 offset:32768
	ds_read_b128 v[188:191], v155 offset:33792
	ds_read_b128 v[192:195], v155 offset:34816
	ds_read_b128 v[196:199], v155 offset:35840
	ds_read_b128 v[200:203], v155 offset:36864
	ds_read_b128 v[204:207], v155 offset:37888
	ds_read_b128 v[208:211], v155 offset:38912
	ds_read_b128 v[212:215], v155 offset:39936
	global_load_lds_dwordx4 v[222:223], off
	v_lshl_add_u64 v[222:223], s[16:17], 0, v[132:133]
	s_mov_b32 m0, s35
	s_nop 0
	global_load_lds_dwordx4 v[222:223], off
	s_waitcnt vmcnt(8)
	s_waitcnt lgkmcnt(0)
	s_barrier
	s_setprio 1
	v_mfma_f32_16x16x32_bf16 v[124:127], v[144:147], v[184:187], v[124:127]
	v_mfma_f32_16x16x32_bf16 v[120:123], v[160:163], v[184:187], v[120:123]
	v_mfma_f32_16x16x32_bf16 v[116:119], v[144:147], v[192:195], v[116:119]
	v_mfma_f32_16x16x32_bf16 v[112:115], v[160:163], v[192:195], v[112:115]
	v_mfma_f32_16x16x32_bf16 v[92:95], v[144:147], v[200:203], v[92:95]
	v_mfma_f32_16x16x32_bf16 v[88:91], v[160:163], v[200:203], v[88:91]
	v_mfma_f32_16x16x32_bf16 v[84:87], v[144:147], v[208:211], v[84:87]
	v_mfma_f32_16x16x32_bf16 v[80:83], v[160:163], v[208:211], v[80:83]
	v_mfma_f32_16x16x32_bf16 v[124:127], v[156:159], v[188:191], v[124:127]
	v_mfma_f32_16x16x32_bf16 v[120:123], v[164:167], v[188:191], v[120:123]
	v_mfma_f32_16x16x32_bf16 v[116:119], v[156:159], v[196:199], v[116:119]
	v_mfma_f32_16x16x32_bf16 v[112:115], v[164:167], v[196:199], v[112:115]
	v_mfma_f32_16x16x32_bf16 v[92:95], v[156:159], v[204:207], v[92:95]
	v_mfma_f32_16x16x32_bf16 v[88:91], v[164:167], v[204:207], v[88:91]
	v_mfma_f32_16x16x32_bf16 v[84:87], v[156:159], v[212:215], v[84:87]
	v_mfma_f32_16x16x32_bf16 v[80:83], v[164:167], v[212:215], v[80:83]
	s_setprio 0
	s_setprio 1
	v_mfma_f32_16x16x32_bf16 v[108:111], v[168:171], v[184:187], v[108:111]
	v_mfma_f32_16x16x32_bf16 v[104:107], v[176:179], v[184:187], v[104:107]
	v_mfma_f32_16x16x32_bf16 v[100:103], v[168:171], v[192:195], v[100:103]
	v_mfma_f32_16x16x32_bf16 v[96:99], v[176:179], v[192:195], v[96:99]
	v_mfma_f32_16x16x32_bf16 v[76:79], v[168:171], v[200:203], v[76:79]
	v_mfma_f32_16x16x32_bf16 v[72:75], v[176:179], v[200:203], v[72:75]
	v_mfma_f32_16x16x32_bf16 v[68:71], v[168:171], v[208:211], v[68:71]
	v_mfma_f32_16x16x32_bf16 v[64:67], v[176:179], v[208:211], v[64:67]
	v_mfma_f32_16x16x32_bf16 v[108:111], v[172:175], v[188:191], v[108:111]
	v_mfma_f32_16x16x32_bf16 v[104:107], v[180:183], v[188:191], v[104:107]
	v_mfma_f32_16x16x32_bf16 v[100:103], v[172:175], v[196:199], v[100:103]
	v_mfma_f32_16x16x32_bf16 v[96:99], v[180:183], v[196:199], v[96:99]
	v_mfma_f32_16x16x32_bf16 v[76:79], v[172:175], v[204:207], v[76:79]
	v_mfma_f32_16x16x32_bf16 v[72:75], v[180:183], v[204:207], v[72:75]
	v_mfma_f32_16x16x32_bf16 v[68:71], v[172:175], v[212:215], v[68:71]
	v_mfma_f32_16x16x32_bf16 v[64:67], v[180:183], v[212:215], v[64:67]
	s_setprio 0
	s_barrier
; #define PG8_STAGE(bufoff, gbase, voff) do { _Pragma("unroll") for (int _i = 0; _i < 2; ++_i) \
;         __builtin_amdgcn_global_load_lds((const unsigned*)((const char*)(gbase) + (voff)[_i]), (PG8_LAS unsigned*)(lds + (bufoff) + ldsw + _i * 8192), 16, 0, 0); } while (0)
; #define PG8_LDA(dst, b, h) do { _Pragma("unroll") for (int m = 0; m < 4; ++m) _Pragma("unroll") for (int k = 0; k < 2; ++k) dst[m][k] = *(const PG8_LAS bf16x8*)(lds + PG8_SA(b, h) + aoff + m * 2048 + k * 1024); } while (0)
; #define PG8_LDB(dst, b, h) do { _Pragma("unroll") for (int n = 0; n < 2; ++n) _Pragma("unroll") for (int k = 0; k < 2; ++k) dst[n][k] = *(const PG8_LAS bf16x8*)(lds + PG8_SB(b, h) + boff + n * 2048 + k * 1024); } while (0)
; #define PG8_MMA(ai, bj, At, Bt) do { __builtin_amdgcn_s_setprio(1); _Pragma("unroll") for (int m = 0; m < 4; ++m) _Pragma("unroll") for (int n = 0; n < 2; ++n) _Pragma("unroll") for (int k = 0; k < 2; ++k) \
;         acc[ai][bj][m][n] = __builtin_amdgcn_mfma_f32_16x16x32_bf16(Bt[n][k], At[m][k], acc[ai][bj][m][n], 0, 0, 0); __builtin_amdgcn_s_setprio(0); } while (0)
; #define PG8_BAR __builtin_amdgcn_s_barrier()
; template <class Epi, class Sched, bool ALIGN_EPI = false, bool SP2 = false>
; __device__ __forceinline__ void gemm_phase(PG8_LAS unsigned char* lds, const Gemm g, const Sched& S, const Epi& E, const int wv0) {
;     ...
;             PG8_LDB(B0, 0, 0); PG8_LDB(B1, 0, 1); PG8_SCHED; PG8_LDA(At, 0, 0); PG8_STAGE(PG8_SA(1, 1), a1 + hstepA, voffA);
;             PG8_WAIT_V(8); PG8_WAIT_L(0); PG8_BAR; PG8_MMA(0, 0, At, B0); PG8_MMA(0, 1, At, B1); PG8_BAR; PG8_SCHED;
;             PG8_LDA(At, 0, 1); PG8_STAGE(PG8_SB(0, 0), b2, voffB); PG8_STAGE(PG8_SB(0, 1), b2 + hstepB, voffB); PG8_STAGE(PG8_SA(0, 0), a2, voffA);
;             PG8_WAIT_V(8); PG8_WAIT_L(0); PG8_BAR; PG8_MMA(1, 0, At, B0); PG8_MMA(1, 1, At, B1); PG8_BAR; PG8_SCHED;
;             PG8_LDB(B0, 1, 0); PG8_LDB(B1, 1, 1); PG8_SCHED; PG8_LDA(At, 1, 0); PG8_STAGE(PG8_SA(0, 1), a2 + hstepA, voffA);
;             PG8_WAIT_V(8); PG8_WAIT_L(0); PG8_BAR; PG8_MMA(0, 0, At, B0); PG8_MMA(0, 1, At, B1); PG8_BAR; PG8_SCHED;
;             PG8_LDA(At, 1, 1); PG8_STAGE(PG8_SB(1, 0), b3, voffB); PG8_STAGE(PG8_SB(1, 1), b3 + hstepB, voffB); PG8_STAGE(PG8_SA(1, 0), a3, voffA);
;             PG8_WAIT_V(8); PG8_WAIT_L(0); PG8_BAR; PG8_MMA(1, 0, At, B0); PG8_MMA(1, 1, At, B1); PG8_BAR; PG8_SCHED;
	s_add_i32 s16, s49, s29
	v_lshl_add_u64 v[148:149], v[148:149], 0, s[8:9]
	s_mov_b32 m0, s16
	ds_read_b128 v[184:187], v155 offset:49152
	ds_read_b128 v[188:191], v155 offset:50176
	ds_read_b128 v[192:195], v155 offset:51200
	ds_read_b128 v[196:199], v155 offset:52224
	ds_read_b128 v[200:203], v155 offset:53248
	ds_read_b128 v[204:207], v155 offset:54272
	ds_read_b128 v[208:211], v155 offset:55296
	ds_read_b128 v[212:215], v155 offset:56320
	global_load_lds_dwordx4 v[148:149], off
	s_add_i32 m0, s16, 0x2000
	s_add_u32 s16, s20, 0x160080
	v_lshl_add_u64 v[148:149], v[216:217], 0, s[8:9]
	s_addc_u32 s17, s21, 0
	s_add_i32 s20, s50, s29
	global_load_lds_dwordx4 v[148:149], off
	v_lshl_add_u64 v[148:149], s[16:17], 0, v[130:131]
	s_mov_b32 m0, s20
	s_nop 0
	global_load_lds_dwordx4 v[148:149], off
	v_lshl_add_u64 v[148:149], s[16:17], 0, v[134:135]
	s_add_i32 m0, s20, 0x2000
	s_nop 0
	global_load_lds_dwordx4 v[148:149], off
	v_lshl_add_u64 v[148:149], v[218:219], 0, s[8:9]
	s_mov_b32 m0, s37
	s_nop 0
	global_load_lds_dwordx4 v[148:149], off
	v_lshl_add_u64 v[148:149], v[220:221], 0, s[8:9]
	s_mov_b32 m0, s38
	s_nop 0
	global_load_lds_dwordx4 v[148:149], off
	s_waitcnt vmcnt(8)
	s_waitcnt lgkmcnt(0)
	s_barrier
	s_setprio 1
	v_mfma_f32_16x16x32_bf16 v[60:63], v[144:147], v[184:187], v[60:63]
	v_mfma_f32_16x16x32_bf16 v[56:59], v[160:163], v[184:187], v[56:59]
	v_mfma_f32_16x16x32_bf16 v[52:55], v[144:147], v[192:195], v[52:55]
	v_mfma_f32_16x16x32_bf16 v[48:51], v[160:163], v[192:195], v[48:51]
	v_mfma_f32_16x16x32_bf16 v[28:31], v[144:147], v[200:203], v[28:31]
	v_mfma_f32_16x16x32_bf16 v[24:27], v[160:163], v[200:203], v[24:27]
	v_mfma_f32_16x16x32_bf16 v[20:23], v[144:147], v[208:211], v[20:23]
	v_mfma_f32_16x16x32_bf16 v[16:19], v[160:163], v[208:211], v[16:19]
	v_mfma_f32_16x16x32_bf16 v[60:63], v[156:159], v[188:191], v[60:63]
	v_mfma_f32_16x16x32_bf16 v[56:59], v[164:167], v[188:191], v[56:59]
	v_mfma_f32_16x16x32_bf16 v[52:55], v[156:159], v[196:199], v[52:55]
	v_mfma_f32_16x16x32_bf16 v[48:51], v[164:167], v[196:199], v[48:51]
	v_mfma_f32_16x16x32_bf16 v[28:31], v[156:159], v[204:207], v[28:31]
	v_mfma_f32_16x16x32_bf16 v[24:27], v[164:167], v[204:207], v[24:27]
	v_mfma_f32_16x16x32_bf16 v[20:23], v[156:159], v[212:215], v[20:23]
	v_mfma_f32_16x16x32_bf16 v[16:19], v[164:167], v[212:215], v[16:19]
	s_setprio 0
	s_setprio 1
	v_mfma_f32_16x16x32_bf16 v[44:47], v[168:171], v[184:187], v[44:47]
	v_mfma_f32_16x16x32_bf16 v[40:43], v[176:179], v[184:187], v[40:43]
	v_mfma_f32_16x16x32_bf16 v[36:39], v[168:171], v[192:195], v[36:39]
	v_mfma_f32_16x16x32_bf16 v[32:35], v[176:179], v[192:195], v[32:35]
	v_mfma_f32_16x16x32_bf16 v[12:15], v[168:171], v[200:203], v[12:15]
	v_mfma_f32_16x16x32_bf16 v[8:11], v[176:179], v[200:203], v[8:11]
	v_mfma_f32_16x16x32_bf16 v[4:7], v[168:171], v[208:211], v[4:7]
	v_mfma_f32_16x16x32_bf16 v[0:3], v[176:179], v[208:211], v[0:3]
	v_mfma_f32_16x16x32_bf16 v[44:47], v[172:175], v[188:191], v[44:47]
	v_mfma_f32_16x16x32_bf16 v[40:43], v[180:183], v[188:191], v[40:43]
	v_mfma_f32_16x16x32_bf16 v[36:39], v[172:175], v[196:199], v[36:39]
	v_mfma_f32_16x16x32_bf16 v[32:35], v[180:183], v[196:199], v[32:35]
	v_mfma_f32_16x16x32_bf16 v[12:15], v[172:175], v[204:207], v[12:15]
	v_mfma_f32_16x16x32_bf16 v[8:11], v[180:183], v[204:207], v[8:11]
	v_mfma_f32_16x16x32_bf16 v[4:7], v[172:175], v[212:215], v[4:7]
	v_mfma_f32_16x16x32_bf16 v[0:3], v[180:183], v[212:215], v[0:3]
	s_setprio 0
	s_barrier
	s_add_i32 s48, s48, 2
	s_add_u32 s46, s46, 0x100
	s_addc_u32 s47, s47, 0
	s_cmpk_gt_u32 s48, 0x55
	s_mov_b64 s[16:17], s[18:19]
	s_cbranch_scc0 .LBB0_1808
	s_and_b64 vcc, exec, s[10:11]
	s_cbranch_vccz .LBB0_1811
	s_barrier
